# all seams except S1 now group barriers: 7 XCD-local + 6 rendezvous without L2 writeback (ACT buffers and converted weights stored write-through), no s_sleep in polls
# speedup vs baseline: 1.0191x; 1.0099x over previous
; __device__ __forceinline__ unsigned pk_bf16(float lo, float hi) { typedef __bf16 b2_t __attribute__((ext_vector_type(2))); f32x2 v = {lo, hi}; b2_t b = __builtin_convertvector(v, b2_t); return __builtin_bit_cast(unsigned, b); }
; #define LAS __attribute__((address_space(3)))
; __device__ __forceinline__ void transpose_tile(const float* W, const float* gain, int K, int N, int k0, int n0, bf16* WT, int drow0, LAS float* scr, int lane) {
;     f32x4 v[8]; float gv[8];
;     const int r0 = lane >> 3, c4 = lane & 7;
; #pragma unroll
;     for (int i = 0; i < 8; ++i) { v[i] = *(const f32x4*)(W + (size_t)(k0 + r0 + 8 * i) * N + n0 + 4 * c4); gv[i] = gain ? gain[k0 + r0 + 8 * i] : 1.0f; }
; #pragma unroll
;     for (int i = 0; i < 8; ++i) { LAS float* d = scr + (r0 + 8 * i) * 33 + 4 * c4; d[0] = v[i][0] * gv[i]; d[1] = v[i][1] * gv[i]; d[2] = v[i][2] * gv[i]; d[3] = v[i][3] * gv[i]; }
;     asm volatile("s_waitcnt lgkmcnt(0)" ::: "memory");
;     const int c = lane & 7;
; #pragma unroll
;     for (int j = 0; j < 4; ++j) { const int n = (lane >> 3) + 8 * j; const LAS float* s = scr + (8 * c) * 33 + n;
;         v4u o; o.x = pk_bf16(s[0 * 33], s[1 * 33]); o.y = pk_bf16(s[2 * 33], s[3 * 33]); o.z = pk_bf16(s[4 * 33], s[5 * 33]); o.w = pk_bf16(s[6 * 33], s[7 * 33]);
;         *(v4u*)(WT + (size_t)(drow0 + n) * K + k0 + 8 * c) = o; }
;     asm volatile("s_waitcnt lgkmcnt(0)" ::: "memory");
; }
; template <bool SWIGLU> __device__ __forceinline__ void transpose_item(const float* W, const float* gain, int K, int N, bf16* WT, LAS float* scr, int item, int lane) {
;     const int nblk = N / 32, kb = item / nblk, nb = item % nblk, n0 = 32 * nb;
;     int drow0 = n0;
;     if (SWIGLU) { const int up = n0 >= FF, f = up ? n0 - FF : n0; drow0 = 256 * (f >> 7) + (up ? 128 : 0) + (f & 127); }
;     transpose_tile(W, gain, K, N, 64 * kb, n0, WT, drow0, scr, lane);
; }
.LBB0_117:
	s_waitcnt vmcnt(0)
	v_pk_mul_f32 v[0:1], v[0:1], v[46:47] op_sel_hi:[1,0]
	v_add_u32_e32 v53, v47, v49
	ds_write2_b32 v53, v0, v1 offset1:1
	v_pk_mul_f32 v[0:1], v[2:3], v[46:47] op_sel_hi:[1,0]
	ds_write2_b32 v53, v0, v1 offset0:2 offset1:3
	v_pk_mul_f32 v[0:1], v[4:5], v[44:45] op_sel_hi:[1,0]
	v_add_u32_e32 v2, 0x420, v53
	ds_write2_b32 v2, v0, v1 offset1:1
	v_pk_mul_f32 v[0:1], v[6:7], v[44:45] op_sel_hi:[1,0]
	v_add_u32_e32 v2, 0x428, v53
	ds_write2_b32 v2, v0, v1 offset1:1
	v_pk_mul_f32 v[0:1], v[8:9], v[52:53] op_sel_hi:[1,0]
	v_add_u32_e32 v2, 0x840, v53
	ds_write2_b32 v2, v0, v1 offset1:1
	v_pk_mul_f32 v[0:1], v[10:11], v[52:53] op_sel_hi:[1,0]
	v_add_u32_e32 v2, 0x848, v53
	ds_write2_b32 v2, v0, v1 offset1:1
	v_pk_mul_f32 v[0:1], v[12:13], v[48:49] op_sel_hi:[1,0]
	v_add_u32_e32 v2, 0xc60, v53
	ds_write2_b32 v2, v0, v1 offset1:1
	v_pk_mul_f32 v[0:1], v[14:15], v[48:49] op_sel_hi:[1,0]
	v_add_u32_e32 v2, 0xc68, v53
	ds_write2_b32 v2, v0, v1 offset1:1
	v_pk_mul_f32 v[0:1], v[16:17], v[58:59] op_sel_hi:[1,0]
	v_add_u32_e32 v2, 0x1080, v53
	ds_write2_b32 v2, v0, v1 offset1:1
	v_pk_mul_f32 v[0:1], v[18:19], v[58:59] op_sel_hi:[1,0]
	v_add_u32_e32 v2, 0x1088, v53
	ds_write2_b32 v2, v0, v1 offset1:1
	v_pk_mul_f32 v[0:1], v[20:21], v[50:51] op_sel_hi:[1,0]
	v_add_u32_e32 v2, 0x14a0, v53
	ds_write2_b32 v2, v0, v1 offset1:1
	v_pk_mul_f32 v[0:1], v[22:23], v[50:51] op_sel_hi:[1,0]
	v_add_u32_e32 v2, 0x14a8, v53
	ds_write2_b32 v2, v0, v1 offset1:1
	v_pk_mul_f32 v[0:1], v[24:25], v[60:61] op_sel_hi:[1,0]
	v_add_u32_e32 v2, 0x18c0, v53
	s_mulk_i32 s6, 0xff50
	ds_write2_b32 v2, v0, v1 offset1:1
	v_pk_mul_f32 v[0:1], v[26:27], v[60:61] op_sel_hi:[1,0]
	v_add_u32_e32 v2, 0x18c8, v53
	s_add_i32 s2, s14, s6
	s_add_i32 s3, s10, 0xfffff500
	ds_write2_b32 v2, v0, v1 offset1:1
	v_pk_mul_f32 v[0:1], v[28:29], v[54:55] op_sel_hi:[1,0]
	v_add_u32_e32 v2, 0x1ce0, v53
	s_cmpk_gt_i32 s2, 0x57
	ds_write2_b32 v2, v0, v1 offset1:1
	v_pk_mul_f32 v[0:1], v[30:31], v[54:55] op_sel_hi:[1,0]
	v_add_u32_e32 v2, 0x1ce8, v53
	s_cselect_b32 s2, s3, s10
	ds_write2_b32 v2, v0, v1 offset1:1
	s_cselect_b32 s3, 0x80, 0
	s_lshl_b32 s6, s2, 1
	s_and_b32 s2, s2, 0x60
	s_waitcnt lgkmcnt(0)
	s_and_b32 s6, s6, 0xffffff00
	s_or_b32 s2, s2, s3
	ds_read2_b32 v[4:5], v61 offset0:33 offset1:41
	ds_read2_b32 v[6:7], v61 offset1:8
	ds_read2_b32 v[8:9], v61 offset0:66 offset1:74
	ds_read2_b32 v[10:11], v61 offset0:99 offset1:107
	ds_read2_b32 v[12:13], v61 offset0:132 offset1:140
	ds_read2_b32 v[14:15], v61 offset0:165 offset1:173
	ds_read2_b32 v[16:17], v61 offset0:198 offset1:206
	ds_read2_b32 v[18:19], v61 offset0:231 offset1:239
	s_or_b32 s2, s2, s6
	v_add_u32_e32 v22, s2, v45
	s_ashr_i32 s9, s8, 31
	v_ashrrev_i32_e32 v23, 31, v22
	v_lshl_add_u64 v[20:21], s[8:9], 1, v[42:43]
	v_lshlrev_b64 v[22:23], 11, v[22:23]
	s_waitcnt lgkmcnt(6)
	v_cvt_pk_bf16_f32 v0, v6, v4
	s_waitcnt lgkmcnt(4)
	v_cvt_pk_bf16_f32 v1, v8, v10
	s_waitcnt lgkmcnt(2)
	v_cvt_pk_bf16_f32 v2, v12, v14
	s_waitcnt lgkmcnt(0)
	v_cvt_pk_bf16_f32 v3, v16, v18
	v_lshl_add_u64 v[22:23], v[20:21], 0, v[22:23]
	v_add_u32_e32 v4, s2, v51
	global_store_dwordx4 v[22:23], v[0:3], off sc1
	s_nop 1
	v_cvt_pk_bf16_f32 v0, v7, v5
	v_ashrrev_i32_e32 v5, 31, v4
	v_cvt_pk_bf16_f32 v1, v9, v11
	v_cvt_pk_bf16_f32 v2, v13, v15
	v_cvt_pk_bf16_f32 v3, v17, v19
	v_lshlrev_b64 v[4:5], 11, v[4:5]
	ds_read2_b32 v[6:7], v61 offset0:49 offset1:57
	ds_read2_b32 v[8:9], v61 offset0:16 offset1:24
	ds_read2_b32 v[10:11], v61 offset0:82 offset1:90
	ds_read2_b32 v[12:13], v61 offset0:115 offset1:123
	ds_read2_b32 v[14:15], v61 offset0:148 offset1:156
	ds_read2_b32 v[16:17], v61 offset0:181 offset1:189
	ds_read2_b32 v[18:19], v61 offset0:214 offset1:222
	ds_read2_b32 v[22:23], v61 offset0:247 offset1:255
	v_lshl_add_u64 v[4:5], v[20:21], 0, v[4:5]
	global_store_dwordx4 v[4:5], v[0:3], off sc1
	v_add_u32_e32 v4, s2, v55
	v_ashrrev_i32_e32 v5, 31, v4
	v_lshlrev_b64 v[4:5], 11, v[4:5]
	s_waitcnt lgkmcnt(6)
	v_cvt_pk_bf16_f32 v0, v8, v6
	s_waitcnt lgkmcnt(4)
	v_cvt_pk_bf16_f32 v1, v10, v12
	s_waitcnt lgkmcnt(2)
	v_cvt_pk_bf16_f32 v2, v14, v16
	s_waitcnt lgkmcnt(0)
	v_cvt_pk_bf16_f32 v3, v18, v22
	v_lshl_add_u64 v[4:5], v[20:21], 0, v[4:5]
	global_store_dwordx4 v[4:5], v[0:3], off sc1
	v_add_u32_e32 v4, s2, v59
	v_ashrrev_i32_e32 v5, 31, v4
	v_lshlrev_b64 v[4:5], 11, v[4:5]
	v_cvt_pk_bf16_f32 v0, v9, v7
	v_cvt_pk_bf16_f32 v1, v11, v13
	v_cvt_pk_bf16_f32 v2, v15, v17
	v_cvt_pk_bf16_f32 v3, v19, v23
	v_lshl_add_u64 v[4:5], v[20:21], 0, v[4:5]
	global_store_dwordx4 v[4:5], v[0:3], off sc1
	s_waitcnt lgkmcnt(0)

; __device__ __forceinline__ unsigned pk_bf16(float lo, float hi) { typedef __bf16 b2_t __attribute__((ext_vector_type(2))); f32x2 v = {lo, hi}; b2_t b = __builtin_convertvector(v, b2_t); return __builtin_bit_cast(unsigned, b); }
; #define LAS __attribute__((address_space(3)))
; __device__ __forceinline__ void transpose_tile(const float* W, const float* gain, int K, int N, int k0, int n0, bf16* WT, int drow0, LAS float* scr, int lane) {
;     f32x4 v[8]; float gv[8];
;     const int r0 = lane >> 3, c4 = lane & 7;
; #pragma unroll
;     for (int i = 0; i < 8; ++i) { v[i] = *(const f32x4*)(W + (size_t)(k0 + r0 + 8 * i) * N + n0 + 4 * c4); gv[i] = gain ? gain[k0 + r0 + 8 * i] : 1.0f; }
; #pragma unroll
;     for (int i = 0; i < 8; ++i) { LAS float* d = scr + (r0 + 8 * i) * 33 + 4 * c4; d[0] = v[i][0] * gv[i]; d[1] = v[i][1] * gv[i]; d[2] = v[i][2] * gv[i]; d[3] = v[i][3] * gv[i]; }
;     asm volatile("s_waitcnt lgkmcnt(0)" ::: "memory");
;     const int c = lane & 7;
; #pragma unroll
;     for (int j = 0; j < 4; ++j) { const int n = (lane >> 3) + 8 * j; const LAS float* s = scr + (8 * c) * 33 + n;
;         v4u o; o.x = pk_bf16(s[0 * 33], s[1 * 33]); o.y = pk_bf16(s[2 * 33], s[3 * 33]); o.z = pk_bf16(s[4 * 33], s[5 * 33]); o.w = pk_bf16(s[6 * 33], s[7 * 33]);
;         *(v4u*)(WT + (size_t)(drow0 + n) * K + k0 + 8 * c) = o; }
;     asm volatile("s_waitcnt lgkmcnt(0)" ::: "memory");
; }
; template <bool SWIGLU> __device__ __forceinline__ void transpose_item(const float* W, const float* gain, int K, int N, bf16* WT, LAS float* scr, int item, int lane) {
;     const int nblk = N / 32, kb = item / nblk, nb = item % nblk, n0 = 32 * nb;
;     int drow0 = n0;
;     if (SWIGLU) { const int up = n0 >= FF, f = up ? n0 - FF : n0; drow0 = 256 * (f >> 7) + (up ? 128 : 0) + (f & 127); }
;     transpose_tile(W, gain, K, N, 64 * kb, n0, WT, drow0, scr, lane);
; }
.LBB0_139:
	s_waitcnt vmcnt(0)
	v_pk_mul_f32 v[0:1], v[0:1], v[46:47] op_sel_hi:[1,0]
	v_add_u32_e32 v53, v47, v49
	ds_write2_b32 v53, v0, v1 offset1:1
	v_pk_mul_f32 v[0:1], v[2:3], v[46:47] op_sel_hi:[1,0]
	ds_write2_b32 v53, v0, v1 offset0:2 offset1:3
	v_pk_mul_f32 v[0:1], v[4:5], v[44:45] op_sel_hi:[1,0]
	v_add_u32_e32 v2, 0x420, v53
	ds_write2_b32 v2, v0, v1 offset1:1
	v_pk_mul_f32 v[0:1], v[6:7], v[44:45] op_sel_hi:[1,0]
	v_add_u32_e32 v2, 0x428, v53
	ds_write2_b32 v2, v0, v1 offset1:1
	v_pk_mul_f32 v[0:1], v[8:9], v[52:53] op_sel_hi:[1,0]
	v_add_u32_e32 v2, 0x840, v53
	ds_write2_b32 v2, v0, v1 offset1:1
	v_pk_mul_f32 v[0:1], v[10:11], v[52:53] op_sel_hi:[1,0]
	v_add_u32_e32 v2, 0x848, v53
	ds_write2_b32 v2, v0, v1 offset1:1
	v_pk_mul_f32 v[0:1], v[12:13], v[48:49] op_sel_hi:[1,0]
	v_add_u32_e32 v2, 0xc60, v53
	ds_write2_b32 v2, v0, v1 offset1:1
	v_pk_mul_f32 v[0:1], v[14:15], v[48:49] op_sel_hi:[1,0]
	v_add_u32_e32 v2, 0xc68, v53
	ds_write2_b32 v2, v0, v1 offset1:1
	v_pk_mul_f32 v[0:1], v[16:17], v[58:59] op_sel_hi:[1,0]
	v_add_u32_e32 v2, 0x1080, v53
	ds_write2_b32 v2, v0, v1 offset1:1
	v_pk_mul_f32 v[0:1], v[18:19], v[58:59] op_sel_hi:[1,0]
	v_add_u32_e32 v2, 0x1088, v53
	ds_write2_b32 v2, v0, v1 offset1:1
	v_pk_mul_f32 v[0:1], v[20:21], v[50:51] op_sel_hi:[1,0]
	v_add_u32_e32 v2, 0x14a0, v53
	ds_write2_b32 v2, v0, v1 offset1:1
	v_pk_mul_f32 v[0:1], v[22:23], v[50:51] op_sel_hi:[1,0]
	v_add_u32_e32 v2, 0x14a8, v53
	ds_write2_b32 v2, v0, v1 offset1:1
	v_pk_mul_f32 v[0:1], v[24:25], v[60:61] op_sel_hi:[1,0]
	v_add_u32_e32 v2, 0x18c0, v53
	s_and_b32 s2, 0xffff, s2
	ds_write2_b32 v2, v0, v1 offset1:1
	v_pk_mul_f32 v[0:1], v[26:27], v[60:61] op_sel_hi:[1,0]
	v_add_u32_e32 v2, 0x18c8, v53
	s_and_b32 s3, 0xffff, s10
	s_add_i32 s8, s2, 0xfffff500
	ds_write2_b32 v2, v0, v1 offset1:1
	v_pk_mul_f32 v[0:1], v[28:29], v[54:55] op_sel_hi:[1,0]
	v_add_u32_e32 v2, 0x1ce0, v53
	s_cmpk_gt_u32 s3, 0x57
	ds_write2_b32 v2, v0, v1 offset1:1
	v_pk_mul_f32 v[0:1], v[30:31], v[54:55] op_sel_hi:[1,0]
	v_add_u32_e32 v2, 0x1ce8, v53
	s_cselect_b32 s2, s8, s2
	ds_write2_b32 v2, v0, v1 offset1:1
	s_cselect_b32 s3, 0x80, 0
	s_lshl_b32 s8, s2, 1
	s_and_b32 s2, s2, 0x60
	s_waitcnt lgkmcnt(0)
	s_and_b32 s8, s8, 0xffffff00
	s_or_b32 s2, s2, s3
	ds_read2_b32 v[4:5], v61 offset0:33 offset1:41
	ds_read2_b32 v[6:7], v61 offset1:8
	ds_read2_b32 v[8:9], v61 offset0:66 offset1:74
	ds_read2_b32 v[10:11], v61 offset0:99 offset1:107
	ds_read2_b32 v[12:13], v61 offset0:132 offset1:140
	ds_read2_b32 v[14:15], v61 offset0:165 offset1:173
	ds_read2_b32 v[16:17], v61 offset0:198 offset1:206
	ds_read2_b32 v[18:19], v61 offset0:231 offset1:239
	s_or_b32 s2, s2, s8
	s_and_b32 s3, 0xffff, s6
	v_add_u32_e32 v22, s2, v45
	s_lshl_b32 s6, s3, 1
	v_ashrrev_i32_e32 v23, 31, v22
	v_lshl_add_u64 v[20:21], v[34:35], 0, s[6:7]
	v_lshlrev_b64 v[22:23], 11, v[22:23]
	s_waitcnt lgkmcnt(6)
	v_cvt_pk_bf16_f32 v0, v6, v4
	s_waitcnt lgkmcnt(4)
	v_cvt_pk_bf16_f32 v1, v8, v10
	s_waitcnt lgkmcnt(2)
	v_cvt_pk_bf16_f32 v2, v12, v14
	s_waitcnt lgkmcnt(0)
	v_cvt_pk_bf16_f32 v3, v16, v18
	v_lshl_add_u64 v[22:23], v[20:21], 0, v[22:23]
	v_add_u32_e32 v4, s2, v51
	global_store_dwordx4 v[22:23], v[0:3], off sc1
	s_nop 1
	v_cvt_pk_bf16_f32 v0, v7, v5
	v_ashrrev_i32_e32 v5, 31, v4
	v_cvt_pk_bf16_f32 v1, v9, v11
	v_cvt_pk_bf16_f32 v2, v13, v15
	v_cvt_pk_bf16_f32 v3, v17, v19
	v_lshlrev_b64 v[4:5], 11, v[4:5]
	ds_read2_b32 v[6:7], v61 offset0:49 offset1:57
	ds_read2_b32 v[8:9], v61 offset0:16 offset1:24
	ds_read2_b32 v[10:11], v61 offset0:82 offset1:90
	ds_read2_b32 v[12:13], v61 offset0:115 offset1:123
	ds_read2_b32 v[14:15], v61 offset0:148 offset1:156
	ds_read2_b32 v[16:17], v61 offset0:181 offset1:189
	ds_read2_b32 v[18:19], v61 offset0:214 offset1:222
	ds_read2_b32 v[22:23], v61 offset0:247 offset1:255
	v_lshl_add_u64 v[4:5], v[20:21], 0, v[4:5]
	global_store_dwordx4 v[4:5], v[0:3], off sc1
	v_add_u32_e32 v4, s2, v55
	v_ashrrev_i32_e32 v5, 31, v4
	v_lshlrev_b64 v[4:5], 11, v[4:5]
	s_waitcnt lgkmcnt(6)
	v_cvt_pk_bf16_f32 v0, v8, v6
	s_waitcnt lgkmcnt(4)
	v_cvt_pk_bf16_f32 v1, v10, v12
	s_waitcnt lgkmcnt(2)
	v_cvt_pk_bf16_f32 v2, v14, v16
	s_waitcnt lgkmcnt(0)
	v_cvt_pk_bf16_f32 v3, v18, v22
	v_lshl_add_u64 v[4:5], v[20:21], 0, v[4:5]
	global_store_dwordx4 v[4:5], v[0:3], off sc1
	v_add_u32_e32 v4, s2, v59
	v_ashrrev_i32_e32 v5, 31, v4
	v_lshlrev_b64 v[4:5], 11, v[4:5]
	v_cvt_pk_bf16_f32 v0, v9, v7
	v_cvt_pk_bf16_f32 v1, v11, v13
	v_cvt_pk_bf16_f32 v2, v15, v17
	v_cvt_pk_bf16_f32 v3, v19, v23
	v_lshl_add_u64 v[4:5], v[20:21], 0, v[4:5]
	global_store_dwordx4 v[4:5], v[0:3], off sc1
	s_waitcnt lgkmcnt(0)
	s_mov_b64 s[2:3], 0
; __device__ __forceinline__ unsigned pk_bf16(float lo, float hi) { typedef __bf16 b2_t __attribute__((ext_vector_type(2))); f32x2 v = {lo, hi}; b2_t b = __builtin_convertvector(v, b2_t); return __builtin_bit_cast(unsigned, b); }
; #define LAS __attribute__((address_space(3)))
; __device__ __forceinline__ void transpose_tile(const float* W, const float* gain, int K, int N, int k0, int n0, bf16* WT, int drow0, LAS float* scr, int lane) {
;     f32x4 v[8]; float gv[8];
;     const int r0 = lane >> 3, c4 = lane & 7;
; #pragma unroll
;     for (int i = 0; i < 8; ++i) { v[i] = *(const f32x4*)(W + (size_t)(k0 + r0 + 8 * i) * N + n0 + 4 * c4); gv[i] = gain ? gain[k0 + r0 + 8 * i] : 1.0f; }
; #pragma unroll
;     for (int i = 0; i < 8; ++i) { LAS float* d = scr + (r0 + 8 * i) * 33 + 4 * c4; d[0] = v[i][0] * gv[i]; d[1] = v[i][1] * gv[i]; d[2] = v[i][2] * gv[i]; d[3] = v[i][3] * gv[i]; }
;     asm volatile("s_waitcnt lgkmcnt(0)" ::: "memory");
;     const int c = lane & 7;
; #pragma unroll
;     for (int j = 0; j < 4; ++j) { const int n = (lane >> 3) + 8 * j; const LAS float* s = scr + (8 * c) * 33 + n;
;         v4u o; o.x = pk_bf16(s[0 * 33], s[1 * 33]); o.y = pk_bf16(s[2 * 33], s[3 * 33]); o.z = pk_bf16(s[4 * 33], s[5 * 33]); o.w = pk_bf16(s[6 * 33], s[7 * 33]);
;         *(v4u*)(WT + (size_t)(drow0 + n) * K + k0 + 8 * c) = o; }
;     asm volatile("s_waitcnt lgkmcnt(0)" ::: "memory");
; }
; template <bool SWIGLU> __device__ __forceinline__ void transpose_item(const float* W, const float* gain, int K, int N, bf16* WT, LAS float* scr, int item, int lane) {
;     const int nblk = N / 32, kb = item / nblk, nb = item % nblk, n0 = 32 * nb;
;     int drow0 = n0;
;     if (SWIGLU) { const int up = n0 >= FF, f = up ? n0 - FF : n0; drow0 = 256 * (f >> 7) + (up ? 128 : 0) + (f & 127); }
;     transpose_tile(W, gain, K, N, 64 * kb, n0, WT, drow0, scr, lane);
; }
.LBB0_140:
	s_and_b64 vcc, exec, s[2:3]
	s_cbranch_vccz .LBB0_142
	s_mov_b32 s2, 8
	s_ashr_i32 s3, s2, 31
	s_lshl_b64 s[2:3], s[2:3], 3
	s_add_u32 s2, s0, s2
	s_addc_u32 s3, s1, s3
	s_load_dwordx2 s[2:3], s[2:3], 0x0
	s_lshl_b32 s6, s14, 5
	s_and_b32 s8, s6, 0x3e0
	s_and_b32 s6, s17, 0x1ffc0
	s_lshl_b32 s9, s8, 2
	v_add_u32_e32 v0, s6, v45
	s_waitcnt lgkmcnt(0)
	s_add_u32 s2, s2, s9
	s_addc_u32 s3, s3, 0
	v_ashrrev_i32_e32 v1, 31, v0
	v_lshl_add_u64 v[2:3], s[2:3], 0, v[32:33]
	v_lshlrev_b64 v[0:1], 12, v[0:1]
	v_lshl_add_u64 v[28:29], v[2:3], 0, v[0:1]
	v_add_co_u32_e32 v4, vcc, s20, v28
	v_add_u32_e32 v44, v47, v49
	s_nop 0
	v_addc_co_u32_e32 v5, vcc, 0, v29, vcc
	v_add_co_u32_e32 v8, vcc, s21, v28
	global_load_dwordx4 v[0:3], v[28:29], off
	s_nop 0
	global_load_dwordx4 v[4:7], v[4:5], off
	v_addc_co_u32_e32 v9, vcc, 0, v29, vcc
	v_add_co_u32_e32 v12, vcc, s22, v28
	v_add_u32_e32 v46, 0x420, v44
	s_nop 0
	v_addc_co_u32_e32 v13, vcc, 0, v29, vcc
	v_add_co_u32_e32 v16, vcc, s23, v28
	global_load_dwordx4 v[8:11], v[8:9], off
	s_nop 0
	global_load_dwordx4 v[12:15], v[12:13], off
	v_addc_co_u32_e32 v17, vcc, 0, v29, vcc
	v_add_co_u32_e32 v20, vcc, s24, v28
	v_add_u32_e32 v48, 0x428, v44
	s_nop 0
	v_addc_co_u32_e32 v21, vcc, 0, v29, vcc
	global_load_dwordx4 v[16:19], v[16:17], off
	s_nop 0
	global_load_dwordx4 v[20:23], v[20:21], off
	v_add_co_u32_e32 v24, vcc, s25, v28
	v_add_u32_e32 v50, 0x840, v44
	s_nop 0
	v_addc_co_u32_e32 v25, vcc, 0, v29, vcc
	global_load_dwordx4 v[24:27], v[24:25], off
	v_add_co_u32_e32 v28, vcc, s26, v28
	v_add_u32_e32 v54, 0x848, v44
	s_nop 0
	v_addc_co_u32_e32 v29, vcc, 0, v29, vcc
	global_load_dwordx4 v[28:31], v[28:29], off
	v_add_u32_e32 v58, 0xc60, v44
	v_add_u32_e32 v60, 0xc68, v44
	v_add_u32_e32 v62, 0x1080, v44
	v_add_u32_e32 v63, 0x1088, v44
	v_add_u32_e32 v64, 0x14a0, v44
	v_add_u32_e32 v65, 0x14a8, v44
	v_add_u32_e32 v66, 0x18c0, v44
	v_add_u32_e32 v67, 0x18c8, v44
	v_add_u32_e32 v68, 0x1ce0, v44
	v_add_u32_e32 v69, 0x1ce8, v44
	v_add_u32_e32 v52, s8, v45
	v_ashrrev_i32_e32 v53, 31, v52
	s_lshl_b32 s6, s6, 1
	v_lshlrev_b64 v[52:53], 11, v[52:53]
	v_lshl_add_u64 v[56:57], v[36:37], 0, s[6:7]
	s_waitcnt vmcnt(0)
	ds_write2_b32 v44, v0, v1 offset1:1
	ds_write2_b32 v44, v2, v3 offset0:2 offset1:3
	ds_write2_b32 v46, v4, v5 offset1:1
	ds_write2_b32 v48, v6, v7 offset1:1
	ds_write2_b32 v50, v8, v9 offset1:1
	ds_write2_b32 v54, v10, v11 offset1:1
	ds_write2_b32 v58, v12, v13 offset1:1
	ds_write2_b32 v60, v14, v15 offset1:1
	ds_write2_b32 v62, v16, v17 offset1:1
	ds_write2_b32 v63, v18, v19 offset1:1
	ds_write2_b32 v64, v20, v21 offset1:1
	ds_write2_b32 v65, v22, v23 offset1:1
	ds_write2_b32 v66, v24, v25 offset1:1
	ds_write2_b32 v67, v26, v27 offset1:1
	ds_write2_b32 v68, v28, v29 offset1:1
	ds_write2_b32 v69, v30, v31 offset1:1
	s_waitcnt lgkmcnt(0)
	ds_read2_b32 v[4:5], v61 offset0:33 offset1:41
	ds_read2_b32 v[6:7], v61 offset1:8
	ds_read2_b32 v[8:9], v61 offset0:66 offset1:74
	ds_read2_b32 v[10:11], v61 offset0:99 offset1:107
	ds_read2_b32 v[12:13], v61 offset0:132 offset1:140
	ds_read2_b32 v[14:15], v61 offset0:165 offset1:173
	ds_read2_b32 v[16:17], v61 offset0:198 offset1:206
	ds_read2_b32 v[18:19], v61 offset0:231 offset1:239
	v_lshl_add_u64 v[20:21], v[56:57], 0, v[52:53]
	s_waitcnt lgkmcnt(6)
	v_cvt_pk_bf16_f32 v0, v6, v4
	s_waitcnt lgkmcnt(4)
	v_cvt_pk_bf16_f32 v1, v8, v10
	s_waitcnt lgkmcnt(2)
	v_cvt_pk_bf16_f32 v2, v12, v14
	s_waitcnt lgkmcnt(0)
	v_cvt_pk_bf16_f32 v3, v16, v18
	v_add_u32_e32 v4, s8, v51
	global_store_dwordx4 v[20:21], v[0:3], off sc1
	s_nop 1
	v_cvt_pk_bf16_f32 v0, v7, v5
	v_ashrrev_i32_e32 v5, 31, v4
	v_cvt_pk_bf16_f32 v1, v9, v11
	v_cvt_pk_bf16_f32 v2, v13, v15
	v_cvt_pk_bf16_f32 v3, v17, v19
	v_lshlrev_b64 v[4:5], 11, v[4:5]
	ds_read2_b32 v[6:7], v61 offset0:49 offset1:57
	ds_read2_b32 v[8:9], v61 offset0:16 offset1:24
	ds_read2_b32 v[10:11], v61 offset0:82 offset1:90
	ds_read2_b32 v[12:13], v61 offset0:115 offset1:123
	ds_read2_b32 v[14:15], v61 offset0:148 offset1:156
	ds_read2_b32 v[16:17], v61 offset0:181 offset1:189
	ds_read2_b32 v[18:19], v61 offset0:214 offset1:222
	ds_read2_b32 v[20:21], v61 offset0:247 offset1:255
	v_lshl_add_u64 v[4:5], v[56:57], 0, v[4:5]
	global_store_dwordx4 v[4:5], v[0:3], off sc1
	v_add_u32_e32 v4, s8, v55
	v_ashrrev_i32_e32 v5, 31, v4
	v_lshlrev_b64 v[4:5], 11, v[4:5]
	s_waitcnt lgkmcnt(6)
	v_cvt_pk_bf16_f32 v0, v8, v6
	s_waitcnt lgkmcnt(4)
	v_cvt_pk_bf16_f32 v1, v10, v12
	s_waitcnt lgkmcnt(2)
	v_cvt_pk_bf16_f32 v2, v14, v16
	s_waitcnt lgkmcnt(0)
	v_cvt_pk_bf16_f32 v3, v18, v20
	v_lshl_add_u64 v[4:5], v[56:57], 0, v[4:5]
	global_store_dwordx4 v[4:5], v[0:3], off sc1
	v_add_u32_e32 v4, s8, v59
	v_ashrrev_i32_e32 v5, 31, v4
	v_lshlrev_b64 v[4:5], 11, v[4:5]
	v_cvt_pk_bf16_f32 v0, v9, v7
	v_cvt_pk_bf16_f32 v1, v11, v13
	v_cvt_pk_bf16_f32 v2, v15, v17
	v_cvt_pk_bf16_f32 v3, v19, v21
	v_lshl_add_u64 v[4:5], v[56:57], 0, v[4:5]
	global_store_dwordx4 v[4:5], v[0:3], off sc1
	s_waitcnt lgkmcnt(0)

; __device__ __forceinline__ unsigned pk_bf16(float lo, float hi) { typedef __bf16 b2_t __attribute__((ext_vector_type(2))); f32x2 v = {lo, hi}; b2_t b = __builtin_convertvector(v, b2_t); return __builtin_bit_cast(unsigned, b); }
; #define LAS __attribute__((address_space(3)))
; __device__ __forceinline__ void transpose_tile(const float* W, const float* gain, int K, int N, int k0, int n0, bf16* WT, int drow0, LAS float* scr, int lane) {
;     f32x4 v[8]; float gv[8];
;     const int r0 = lane >> 3, c4 = lane & 7;
; #pragma unroll
;     for (int i = 0; i < 8; ++i) { v[i] = *(const f32x4*)(W + (size_t)(k0 + r0 + 8 * i) * N + n0 + 4 * c4); gv[i] = gain ? gain[k0 + r0 + 8 * i] : 1.0f; }
; #pragma unroll
;     for (int i = 0; i < 8; ++i) { LAS float* d = scr + (r0 + 8 * i) * 33 + 4 * c4; d[0] = v[i][0] * gv[i]; d[1] = v[i][1] * gv[i]; d[2] = v[i][2] * gv[i]; d[3] = v[i][3] * gv[i]; }
;     asm volatile("s_waitcnt lgkmcnt(0)" ::: "memory");
;     const int c = lane & 7;
; #pragma unroll
;     for (int j = 0; j < 4; ++j) { const int n = (lane >> 3) + 8 * j; const LAS float* s = scr + (8 * c) * 33 + n;
;         v4u o; o.x = pk_bf16(s[0 * 33], s[1 * 33]); o.y = pk_bf16(s[2 * 33], s[3 * 33]); o.z = pk_bf16(s[4 * 33], s[5 * 33]); o.w = pk_bf16(s[6 * 33], s[7 * 33]);
;         *(v4u*)(WT + (size_t)(drow0 + n) * K + k0 + 8 * c) = o; }
;     asm volatile("s_waitcnt lgkmcnt(0)" ::: "memory");
; }
; template <bool SWIGLU> __device__ __forceinline__ void transpose_item(const float* W, const float* gain, int K, int N, bf16* WT, LAS float* scr, int item, int lane) {
;     const int nblk = N / 32, kb = item / nblk, nb = item % nblk, n0 = 32 * nb;
;     int drow0 = n0;
;     if (SWIGLU) { const int up = n0 >= FF, f = up ? n0 - FF : n0; drow0 = 256 * (f >> 7) + (up ? 128 : 0) + (f & 127); }
;     transpose_tile(W, gain, K, N, 64 * kb, n0, WT, drow0, scr, lane);
; }
.LBB0_160:
	s_waitcnt vmcnt(0)
	v_pk_mul_f32 v[0:1], v[0:1], v[46:47] op_sel_hi:[1,0]
	v_add_u32_e32 v52, v47, v49
	ds_write2_b32 v52, v0, v1 offset1:1
	v_pk_mul_f32 v[0:1], v[2:3], v[46:47] op_sel_hi:[1,0]
	ds_write2_b32 v52, v0, v1 offset0:2 offset1:3
	v_pk_mul_f32 v[0:1], v[4:5], v[44:45] op_sel_hi:[1,0]
	v_add_u32_e32 v2, 0x420, v52
	ds_write2_b32 v2, v0, v1 offset1:1
	v_pk_mul_f32 v[0:1], v[6:7], v[44:45] op_sel_hi:[1,0]
	v_add_u32_e32 v2, 0x428, v52
	ds_write2_b32 v2, v0, v1 offset1:1
	v_pk_mul_f32 v[0:1], v[8:9], v[54:55] op_sel_hi:[1,0]
	v_add_u32_e32 v2, 0x840, v52
	ds_write2_b32 v2, v0, v1 offset1:1
	v_pk_mul_f32 v[0:1], v[10:11], v[54:55] op_sel_hi:[1,0]
	v_add_u32_e32 v2, 0x848, v52
	ds_write2_b32 v2, v0, v1 offset1:1
	v_pk_mul_f32 v[0:1], v[12:13], v[48:49] op_sel_hi:[1,0]
	v_add_u32_e32 v2, 0xc60, v52
	ds_write2_b32 v2, v0, v1 offset1:1
	v_pk_mul_f32 v[0:1], v[14:15], v[48:49] op_sel_hi:[1,0]
	v_add_u32_e32 v2, 0xc68, v52
	ds_write2_b32 v2, v0, v1 offset1:1
	v_pk_mul_f32 v[0:1], v[16:17], v[58:59] op_sel_hi:[1,0]
	v_add_u32_e32 v2, 0x1080, v52
	ds_write2_b32 v2, v0, v1 offset1:1
	v_pk_mul_f32 v[0:1], v[18:19], v[58:59] op_sel_hi:[1,0]
	v_add_u32_e32 v2, 0x1088, v52
	ds_write2_b32 v2, v0, v1 offset1:1
	v_pk_mul_f32 v[0:1], v[20:21], v[50:51] op_sel_hi:[1,0]
	v_add_u32_e32 v2, 0x14a0, v52
	ds_write2_b32 v2, v0, v1 offset1:1
	v_pk_mul_f32 v[0:1], v[22:23], v[50:51] op_sel_hi:[1,0]
	v_add_u32_e32 v2, 0x14a8, v52
	ds_write2_b32 v2, v0, v1 offset1:1
	v_pk_mul_f32 v[0:1], v[24:25], v[60:61] op_sel_hi:[1,0]
	v_add_u32_e32 v2, 0x18c0, v52
	ds_write2_b32 v2, v0, v1 offset1:1
	v_pk_mul_f32 v[0:1], v[26:27], v[60:61] op_sel_hi:[1,0]
	v_add_u32_e32 v2, 0x18c8, v52
	ds_write2_b32 v2, v0, v1 offset1:1
	v_pk_mul_f32 v[0:1], v[28:29], v[56:57] op_sel_hi:[1,0]
	v_add_u32_e32 v2, 0x1ce0, v52
	ds_write2_b32 v2, v0, v1 offset1:1
	v_pk_mul_f32 v[0:1], v[30:31], v[56:57] op_sel_hi:[1,0]
	v_add_u32_e32 v2, 0x1ce8, v52
	ds_write2_b32 v2, v0, v1 offset1:1
	s_waitcnt lgkmcnt(0)
	s_lshl_b32 s2, s10, 5
	ds_read2_b32 v[4:5], v61 offset0:33 offset1:41
	ds_read2_b32 v[6:7], v61 offset1:8
	ds_read2_b32 v[8:9], v61 offset0:66 offset1:74
	ds_read2_b32 v[10:11], v61 offset0:99 offset1:107
	ds_read2_b32 v[12:13], v61 offset0:132 offset1:140
	ds_read2_b32 v[14:15], v61 offset0:165 offset1:173
	ds_read2_b32 v[16:17], v61 offset0:198 offset1:206
	ds_read2_b32 v[18:19], v61 offset0:231 offset1:239
	s_and_b32 s2, 0xffff, s2
	s_and_b32 s3, 0xffff, s6
	v_add_u32_e32 v22, s2, v45
	s_lshl_b32 s6, s3, 1
	v_ashrrev_i32_e32 v23, 31, v22
	v_lshl_add_u64 v[20:21], v[38:39], 0, s[6:7]
	v_lshlrev_b64 v[22:23], 11, v[22:23]
	s_waitcnt lgkmcnt(6)
	v_cvt_pk_bf16_f32 v0, v6, v4
	s_waitcnt lgkmcnt(4)
	v_cvt_pk_bf16_f32 v1, v8, v10
	s_waitcnt lgkmcnt(2)
	v_cvt_pk_bf16_f32 v2, v12, v14
	s_waitcnt lgkmcnt(0)
	v_cvt_pk_bf16_f32 v3, v16, v18
	v_lshl_add_u64 v[22:23], v[20:21], 0, v[22:23]
	v_add_u32_e32 v4, s2, v51
	global_store_dwordx4 v[22:23], v[0:3], off sc1
	s_nop 1
	v_cvt_pk_bf16_f32 v0, v7, v5
	v_ashrrev_i32_e32 v5, 31, v4
	v_cvt_pk_bf16_f32 v1, v9, v11
	v_cvt_pk_bf16_f32 v2, v13, v15
	v_cvt_pk_bf16_f32 v3, v17, v19
	v_lshlrev_b64 v[4:5], 11, v[4:5]
	ds_read2_b32 v[6:7], v61 offset0:49 offset1:57
	ds_read2_b32 v[8:9], v61 offset0:16 offset1:24
	ds_read2_b32 v[10:11], v61 offset0:82 offset1:90
	ds_read2_b32 v[12:13], v61 offset0:115 offset1:123
	ds_read2_b32 v[14:15], v61 offset0:148 offset1:156
	ds_read2_b32 v[16:17], v61 offset0:181 offset1:189
	ds_read2_b32 v[18:19], v61 offset0:214 offset1:222
	ds_read2_b32 v[22:23], v61 offset0:247 offset1:255
	v_lshl_add_u64 v[4:5], v[20:21], 0, v[4:5]
	global_store_dwordx4 v[4:5], v[0:3], off sc1
	v_add_u32_e32 v4, s2, v55
	v_ashrrev_i32_e32 v5, 31, v4
	v_lshlrev_b64 v[4:5], 11, v[4:5]
	s_waitcnt lgkmcnt(6)
	v_cvt_pk_bf16_f32 v0, v8, v6
	s_waitcnt lgkmcnt(4)
	v_cvt_pk_bf16_f32 v1, v10, v12
	s_waitcnt lgkmcnt(2)
	v_cvt_pk_bf16_f32 v2, v14, v16
	s_waitcnt lgkmcnt(0)
	v_cvt_pk_bf16_f32 v3, v18, v22
	v_lshl_add_u64 v[4:5], v[20:21], 0, v[4:5]
	global_store_dwordx4 v[4:5], v[0:3], off sc1
	v_add_u32_e32 v4, s2, v59
	v_ashrrev_i32_e32 v5, 31, v4
	v_lshlrev_b64 v[4:5], 11, v[4:5]
	v_cvt_pk_bf16_f32 v0, v9, v7
	v_cvt_pk_bf16_f32 v1, v11, v13
	v_cvt_pk_bf16_f32 v2, v15, v17
	v_cvt_pk_bf16_f32 v3, v19, v23
	v_lshl_add_u64 v[4:5], v[20:21], 0, v[4:5]
	global_store_dwordx4 v[4:5], v[0:3], off sc1
	s_waitcnt lgkmcnt(0)

; __device__ __forceinline__ unsigned pk_bf16(float lo, float hi) { typedef __bf16 b2_t __attribute__((ext_vector_type(2))); f32x2 v = {lo, hi}; b2_t b = __builtin_convertvector(v, b2_t); return __builtin_bit_cast(unsigned, b); }
; #define LAS __attribute__((address_space(3)))
; __device__ __forceinline__ void transpose_tile(const float* W, const float* gain, int K, int N, int k0, int n0, bf16* WT, int drow0, LAS float* scr, int lane) {
;     f32x4 v[8]; float gv[8];
;     const int r0 = lane >> 3, c4 = lane & 7;
; #pragma unroll
;     for (int i = 0; i < 8; ++i) { v[i] = *(const f32x4*)(W + (size_t)(k0 + r0 + 8 * i) * N + n0 + 4 * c4); gv[i] = gain ? gain[k0 + r0 + 8 * i] : 1.0f; }
; #pragma unroll
;     for (int i = 0; i < 8; ++i) { LAS float* d = scr + (r0 + 8 * i) * 33 + 4 * c4; d[0] = v[i][0] * gv[i]; d[1] = v[i][1] * gv[i]; d[2] = v[i][2] * gv[i]; d[3] = v[i][3] * gv[i]; }
;     asm volatile("s_waitcnt lgkmcnt(0)" ::: "memory");
;     const int c = lane & 7;
; #pragma unroll
;     for (int j = 0; j < 4; ++j) { const int n = (lane >> 3) + 8 * j; const LAS float* s = scr + (8 * c) * 33 + n;
;         v4u o; o.x = pk_bf16(s[0 * 33], s[1 * 33]); o.y = pk_bf16(s[2 * 33], s[3 * 33]); o.z = pk_bf16(s[4 * 33], s[5 * 33]); o.w = pk_bf16(s[6 * 33], s[7 * 33]);
;         *(v4u*)(WT + (size_t)(drow0 + n) * K + k0 + 8 * c) = o; }
;     asm volatile("s_waitcnt lgkmcnt(0)" ::: "memory");
; }
; template <bool SWIGLU> __device__ __forceinline__ void transpose_item(const float* W, const float* gain, int K, int N, bf16* WT, LAS float* scr, int item, int lane) {
;     const int nblk = N / 32, kb = item / nblk, nb = item % nblk, n0 = 32 * nb;
;     int drow0 = n0;
;     if (SWIGLU) { const int up = n0 >= FF, f = up ? n0 - FF : n0; drow0 = 256 * (f >> 7) + (up ? 128 : 0) + (f & 127); }
;     transpose_tile(W, gain, K, N, 64 * kb, n0, WT, drow0, scr, lane);
; }
.LBB0_162:
	s_andn2_b64 vcc, exec, s[2:3]
	s_cbranch_vccnz .LBB0_164
	s_mov_b32 s2, 3
	s_ashr_i32 s3, s2, 31
	s_lshl_b64 s[2:3], s[2:3], 3
	s_add_u32 s2, s0, s2
	s_addc_u32 s3, s1, s3
	s_load_dwordx2 s[2:3], s[2:3], 0x0
	s_lshl_b32 s6, s14, 5
	s_and_b32 s8, s6, 0x3e0
	s_add_i32 s6, s17, 0x1700
	s_and_b32 s6, s6, 0x1ffc0
	s_lshl_b32 s9, s8, 2
	v_add_u32_e32 v0, s6, v45
	s_waitcnt lgkmcnt(0)
	s_add_u32 s2, s2, s9
	s_addc_u32 s3, s3, 0
	v_ashrrev_i32_e32 v1, 31, v0
	v_lshl_add_u64 v[2:3], s[2:3], 0, v[32:33]
	v_lshlrev_b64 v[0:1], 12, v[0:1]
	v_lshl_add_u64 v[28:29], v[2:3], 0, v[0:1]
	v_add_co_u32_e32 v4, vcc, s20, v28
	v_add_u32_e32 v44, v47, v49
	s_nop 0
	v_addc_co_u32_e32 v5, vcc, 0, v29, vcc
	v_add_co_u32_e32 v8, vcc, s21, v28
	global_load_dwordx4 v[0:3], v[28:29], off
	s_nop 0
	global_load_dwordx4 v[4:7], v[4:5], off
	v_addc_co_u32_e32 v9, vcc, 0, v29, vcc
	v_add_co_u32_e32 v12, vcc, s22, v28
	v_add_u32_e32 v46, 0x420, v44
	s_nop 0
	v_addc_co_u32_e32 v13, vcc, 0, v29, vcc
	v_add_co_u32_e32 v16, vcc, s23, v28
	global_load_dwordx4 v[8:11], v[8:9], off
	s_nop 0
	global_load_dwordx4 v[12:15], v[12:13], off
	v_addc_co_u32_e32 v17, vcc, 0, v29, vcc
	v_add_co_u32_e32 v20, vcc, s24, v28
	v_add_u32_e32 v48, 0x428, v44
	s_nop 0
	v_addc_co_u32_e32 v21, vcc, 0, v29, vcc
	global_load_dwordx4 v[16:19], v[16:17], off
	s_nop 0
	global_load_dwordx4 v[20:23], v[20:21], off
	v_add_co_u32_e32 v24, vcc, s25, v28
	v_add_u32_e32 v50, 0x840, v44
	s_nop 0
	v_addc_co_u32_e32 v25, vcc, 0, v29, vcc
	global_load_dwordx4 v[24:27], v[24:25], off
	v_add_co_u32_e32 v28, vcc, s26, v28
	v_add_u32_e32 v54, 0x848, v44
	s_nop 0
	v_addc_co_u32_e32 v29, vcc, 0, v29, vcc
	global_load_dwordx4 v[28:31], v[28:29], off
	v_add_u32_e32 v56, 0xc60, v44
	v_add_u32_e32 v57, 0xc68, v44
	v_add_u32_e32 v58, 0x1080, v44
	v_add_u32_e32 v60, 0x1088, v44
	v_add_u32_e32 v62, 0x14a0, v44
	v_add_u32_e32 v63, 0x14a8, v44
	v_add_u32_e32 v64, 0x18c0, v44
	v_add_u32_e32 v65, 0x18c8, v44
	v_add_u32_e32 v66, 0x1ce0, v44
	v_add_u32_e32 v67, 0x1ce8, v44
	s_lshl_b32 s6, s6, 1
	v_add_u32_e32 v68, s8, v45
	v_lshl_add_u64 v[52:53], v[40:41], 0, s[6:7]
	s_waitcnt vmcnt(0)
	ds_write2_b32 v44, v0, v1 offset1:1
	ds_write2_b32 v44, v2, v3 offset0:2 offset1:3
	ds_write2_b32 v46, v4, v5 offset1:1
	ds_write2_b32 v48, v6, v7 offset1:1
	ds_write2_b32 v50, v8, v9 offset1:1
	ds_write2_b32 v54, v10, v11 offset1:1
	ds_write2_b32 v56, v12, v13 offset1:1
	ds_write2_b32 v57, v14, v15 offset1:1
	ds_write2_b32 v58, v16, v17 offset1:1
	ds_write2_b32 v60, v18, v19 offset1:1
	ds_write2_b32 v62, v20, v21 offset1:1
	ds_write2_b32 v63, v22, v23 offset1:1
	ds_write2_b32 v64, v24, v25 offset1:1
	ds_write2_b32 v65, v26, v27 offset1:1
	ds_write2_b32 v66, v28, v29 offset1:1
	ds_write2_b32 v67, v30, v31 offset1:1
	s_waitcnt lgkmcnt(0)
	ds_read2_b32 v[4:5], v61 offset0:33 offset1:41
	ds_read2_b32 v[6:7], v61 offset1:8
	ds_read2_b32 v[8:9], v61 offset0:66 offset1:74
	ds_read2_b32 v[10:11], v61 offset0:99 offset1:107
	ds_read2_b32 v[12:13], v61 offset0:132 offset1:140
	ds_read2_b32 v[14:15], v61 offset0:165 offset1:173
	ds_read2_b32 v[16:17], v61 offset0:198 offset1:206
	ds_read2_b32 v[18:19], v61 offset0:231 offset1:239
	v_mad_i64_i32 v[20:21], s[2:3], v68, s28, v[52:53]
	s_waitcnt lgkmcnt(6)
	v_cvt_pk_bf16_f32 v0, v6, v4
	s_waitcnt lgkmcnt(4)
	v_cvt_pk_bf16_f32 v1, v8, v10
	s_waitcnt lgkmcnt(2)
	v_cvt_pk_bf16_f32 v2, v12, v14
	s_waitcnt lgkmcnt(0)
	v_cvt_pk_bf16_f32 v3, v16, v18
	global_store_dwordx4 v[20:21], v[0:3], off sc1
	v_add_u32_e32 v4, s8, v51
	s_nop 0
	v_cvt_pk_bf16_f32 v0, v7, v5
	v_cvt_pk_bf16_f32 v1, v9, v11
	v_cvt_pk_bf16_f32 v2, v13, v15
	v_cvt_pk_bf16_f32 v3, v17, v19
	ds_read2_b32 v[6:7], v61 offset0:49 offset1:57
	ds_read2_b32 v[8:9], v61 offset0:16 offset1:24
	ds_read2_b32 v[10:11], v61 offset0:82 offset1:90
	ds_read2_b32 v[12:13], v61 offset0:115 offset1:123
	ds_read2_b32 v[14:15], v61 offset0:148 offset1:156
	ds_read2_b32 v[16:17], v61 offset0:181 offset1:189
	ds_read2_b32 v[18:19], v61 offset0:214 offset1:222
	ds_read2_b32 v[20:21], v61 offset0:247 offset1:255
	v_mad_i64_i32 v[4:5], s[2:3], v4, s28, v[52:53]
	global_store_dwordx4 v[4:5], v[0:3], off sc1
	v_add_u32_e32 v4, s8, v55
	v_mad_i64_i32 v[4:5], s[2:3], v4, s28, v[52:53]
	s_waitcnt lgkmcnt(6)
	v_cvt_pk_bf16_f32 v0, v8, v6
	s_waitcnt lgkmcnt(4)
	v_cvt_pk_bf16_f32 v1, v10, v12
	s_waitcnt lgkmcnt(2)
	v_cvt_pk_bf16_f32 v2, v14, v16
	s_waitcnt lgkmcnt(0)
	v_cvt_pk_bf16_f32 v3, v18, v20
	global_store_dwordx4 v[4:5], v[0:3], off sc1
	v_add_u32_e32 v4, s8, v59
	v_mad_i64_i32 v[4:5], s[2:3], v4, s28, v[52:53]
	v_cvt_pk_bf16_f32 v0, v9, v7
	v_cvt_pk_bf16_f32 v1, v11, v13
	v_cvt_pk_bf16_f32 v2, v15, v17
	v_cvt_pk_bf16_f32 v3, v19, v21
	global_store_dwordx4 v[4:5], v[0:3], off sc1
	s_waitcnt lgkmcnt(0)

; __device__ __forceinline__ unsigned pk_bf16(float lo, float hi) { typedef __bf16 b2_t __attribute__((ext_vector_type(2))); f32x2 v = {lo, hi}; b2_t b = __builtin_convertvector(v, b2_t); return __builtin_bit_cast(unsigned, b); }
; #define LAS __attribute__((address_space(3)))
; __device__ __forceinline__ void transpose_tile(const float* W, const float* gain, int K, int N, int k0, int n0, bf16* WT, int drow0, LAS float* scr, int lane) {
;     f32x4 v[8]; float gv[8];
;     const int r0 = lane >> 3, c4 = lane & 7;
; #pragma unroll
;     for (int i = 0; i < 8; ++i) { v[i] = *(const f32x4*)(W + (size_t)(k0 + r0 + 8 * i) * N + n0 + 4 * c4); gv[i] = gain ? gain[k0 + r0 + 8 * i] : 1.0f; }
; #pragma unroll
;     for (int i = 0; i < 8; ++i) { LAS float* d = scr + (r0 + 8 * i) * 33 + 4 * c4; d[0] = v[i][0] * gv[i]; d[1] = v[i][1] * gv[i]; d[2] = v[i][2] * gv[i]; d[3] = v[i][3] * gv[i]; }
;     asm volatile("s_waitcnt lgkmcnt(0)" ::: "memory");
;     const int c = lane & 7;
; #pragma unroll
;     for (int j = 0; j < 4; ++j) { const int n = (lane >> 3) + 8 * j; const LAS float* s = scr + (8 * c) * 33 + n;
;         v4u o; o.x = pk_bf16(s[0 * 33], s[1 * 33]); o.y = pk_bf16(s[2 * 33], s[3 * 33]); o.z = pk_bf16(s[4 * 33], s[5 * 33]); o.w = pk_bf16(s[6 * 33], s[7 * 33]);
;         *(v4u*)(WT + (size_t)(drow0 + n) * K + k0 + 8 * c) = o; }
;     asm volatile("s_waitcnt lgkmcnt(0)" ::: "memory");
; }
; template <bool SWIGLU> __device__ __forceinline__ void transpose_item(const float* W, const float* gain, int K, int N, bf16* WT, LAS float* scr, int item, int lane) {
;     const int nblk = N / 32, kb = item / nblk, nb = item % nblk, n0 = 32 * nb;
;     int drow0 = n0;
;     if (SWIGLU) { const int up = n0 >= FF, f = up ? n0 - FF : n0; drow0 = 256 * (f >> 7) + (up ? 128 : 0) + (f & 127); }
;     transpose_tile(W, gain, K, N, 64 * kb, n0, WT, drow0, scr, lane);
; }
.LBB0_210:
	s_and_b64 vcc, exec, s[2:3]
	s_cbranch_vccz .LBB0_212
	s_mov_b32 s2, 8
	s_ashr_i32 s3, s2, 31
	s_lshl_b64 s[2:3], s[2:3], 3
	s_add_u32 s2, s0, s2
	s_addc_u32 s3, s1, s3
	s_load_dwordx2 s[2:3], s[2:3], 0x0
	s_lshl_b32 s6, s14, 5
	s_and_b32 s8, s6, 0x3e0
	s_and_b32 s6, s18, 0x1ffc0
	s_lshl_b32 s9, s8, 2
	v_add_u32_e32 v0, s6, v45
	s_waitcnt lgkmcnt(0)
	s_add_u32 s2, s2, s9
	s_addc_u32 s3, s3, 0
	v_ashrrev_i32_e32 v1, 31, v0
	v_lshl_add_u64 v[2:3], s[2:3], 0, v[32:33]
	v_lshlrev_b64 v[0:1], 12, v[0:1]
	v_lshl_add_u64 v[28:29], v[2:3], 0, v[0:1]
	v_add_co_u32_e32 v4, vcc, s21, v28
	v_add_u32_e32 v44, v47, v49
	s_nop 0
	v_addc_co_u32_e32 v5, vcc, 0, v29, vcc
	v_add_co_u32_e32 v8, vcc, s22, v28
	global_load_dwordx4 v[0:3], v[28:29], off
	s_nop 0
	global_load_dwordx4 v[4:7], v[4:5], off
	v_addc_co_u32_e32 v9, vcc, 0, v29, vcc
	v_add_co_u32_e32 v12, vcc, s23, v28
	v_add_u32_e32 v46, 0x420, v44
	s_nop 0
	v_addc_co_u32_e32 v13, vcc, 0, v29, vcc
	v_add_co_u32_e32 v16, vcc, s24, v28
	global_load_dwordx4 v[8:11], v[8:9], off
	s_nop 0
	global_load_dwordx4 v[12:15], v[12:13], off
	v_addc_co_u32_e32 v17, vcc, 0, v29, vcc
	v_add_co_u32_e32 v20, vcc, s25, v28
	v_add_u32_e32 v48, 0x428, v44
	s_nop 0
	v_addc_co_u32_e32 v21, vcc, 0, v29, vcc
	global_load_dwordx4 v[16:19], v[16:17], off
	s_nop 0
	global_load_dwordx4 v[20:23], v[20:21], off
	v_add_co_u32_e32 v24, vcc, s26, v28
	v_add_u32_e32 v50, 0x840, v44
	s_nop 0
	v_addc_co_u32_e32 v25, vcc, 0, v29, vcc
	global_load_dwordx4 v[24:27], v[24:25], off
	v_add_co_u32_e32 v28, vcc, s27, v28
	v_add_u32_e32 v54, 0x848, v44
	s_nop 0
	v_addc_co_u32_e32 v29, vcc, 0, v29, vcc
	global_load_dwordx4 v[28:31], v[28:29], off
	v_add_u32_e32 v58, 0xc60, v44
	v_add_u32_e32 v60, 0xc68, v44
	v_add_u32_e32 v62, 0x1080, v44
	v_add_u32_e32 v63, 0x1088, v44
	v_add_u32_e32 v64, 0x14a0, v44
	v_add_u32_e32 v65, 0x14a8, v44
	v_add_u32_e32 v66, 0x18c0, v44
	v_add_u32_e32 v67, 0x18c8, v44
	v_add_u32_e32 v68, 0x1ce0, v44
	v_add_u32_e32 v69, 0x1ce8, v44
	v_add_u32_e32 v52, s8, v45
	v_ashrrev_i32_e32 v53, 31, v52
	s_lshl_b32 s6, s6, 1
	v_lshlrev_b64 v[52:53], 11, v[52:53]
	v_lshl_add_u64 v[56:57], v[36:37], 0, s[6:7]
	s_waitcnt vmcnt(0)
	ds_write2_b32 v44, v0, v1 offset1:1
	ds_write2_b32 v44, v2, v3 offset0:2 offset1:3
	ds_write2_b32 v46, v4, v5 offset1:1
	ds_write2_b32 v48, v6, v7 offset1:1
	ds_write2_b32 v50, v8, v9 offset1:1
	ds_write2_b32 v54, v10, v11 offset1:1
	ds_write2_b32 v58, v12, v13 offset1:1
	ds_write2_b32 v60, v14, v15 offset1:1
	ds_write2_b32 v62, v16, v17 offset1:1
	ds_write2_b32 v63, v18, v19 offset1:1
	ds_write2_b32 v64, v20, v21 offset1:1
	ds_write2_b32 v65, v22, v23 offset1:1
	ds_write2_b32 v66, v24, v25 offset1:1
	ds_write2_b32 v67, v26, v27 offset1:1
	ds_write2_b32 v68, v28, v29 offset1:1
	ds_write2_b32 v69, v30, v31 offset1:1
	s_waitcnt lgkmcnt(0)
	ds_read2_b32 v[4:5], v61 offset0:33 offset1:41
	ds_read2_b32 v[6:7], v61 offset1:8
	ds_read2_b32 v[8:9], v61 offset0:66 offset1:74
	ds_read2_b32 v[10:11], v61 offset0:99 offset1:107
	ds_read2_b32 v[12:13], v61 offset0:132 offset1:140
	ds_read2_b32 v[14:15], v61 offset0:165 offset1:173
	ds_read2_b32 v[16:17], v61 offset0:198 offset1:206
	ds_read2_b32 v[18:19], v61 offset0:231 offset1:239
	v_lshl_add_u64 v[20:21], v[56:57], 0, v[52:53]
	s_waitcnt lgkmcnt(6)
	v_cvt_pk_bf16_f32 v0, v6, v4
	s_waitcnt lgkmcnt(4)
	v_cvt_pk_bf16_f32 v1, v8, v10
	s_waitcnt lgkmcnt(2)
	v_cvt_pk_bf16_f32 v2, v12, v14
	s_waitcnt lgkmcnt(0)
	v_cvt_pk_bf16_f32 v3, v16, v18
	v_add_u32_e32 v4, s8, v51
	global_store_dwordx4 v[20:21], v[0:3], off sc1
	s_nop 1
	v_cvt_pk_bf16_f32 v0, v7, v5
	v_ashrrev_i32_e32 v5, 31, v4
	v_cvt_pk_bf16_f32 v1, v9, v11
	v_cvt_pk_bf16_f32 v2, v13, v15
	v_cvt_pk_bf16_f32 v3, v17, v19
	v_lshlrev_b64 v[4:5], 11, v[4:5]
	ds_read2_b32 v[6:7], v61 offset0:49 offset1:57
	ds_read2_b32 v[8:9], v61 offset0:16 offset1:24
	ds_read2_b32 v[10:11], v61 offset0:82 offset1:90
	ds_read2_b32 v[12:13], v61 offset0:115 offset1:123
	ds_read2_b32 v[14:15], v61 offset0:148 offset1:156
	ds_read2_b32 v[16:17], v61 offset0:181 offset1:189
	ds_read2_b32 v[18:19], v61 offset0:214 offset1:222
	ds_read2_b32 v[20:21], v61 offset0:247 offset1:255
	v_lshl_add_u64 v[4:5], v[56:57], 0, v[4:5]
	global_store_dwordx4 v[4:5], v[0:3], off sc1
	v_add_u32_e32 v4, s8, v55
	v_ashrrev_i32_e32 v5, 31, v4
	v_lshlrev_b64 v[4:5], 11, v[4:5]
	s_waitcnt lgkmcnt(6)
	v_cvt_pk_bf16_f32 v0, v8, v6
	s_waitcnt lgkmcnt(4)
	v_cvt_pk_bf16_f32 v1, v10, v12
	s_waitcnt lgkmcnt(2)
	v_cvt_pk_bf16_f32 v2, v14, v16
	s_waitcnt lgkmcnt(0)
	v_cvt_pk_bf16_f32 v3, v18, v20
	v_lshl_add_u64 v[4:5], v[56:57], 0, v[4:5]
	global_store_dwordx4 v[4:5], v[0:3], off sc1
	v_add_u32_e32 v4, s8, v59
	v_ashrrev_i32_e32 v5, 31, v4
	v_lshlrev_b64 v[4:5], 11, v[4:5]
	v_cvt_pk_bf16_f32 v0, v9, v7
	v_cvt_pk_bf16_f32 v1, v11, v13
	v_cvt_pk_bf16_f32 v2, v15, v17
	v_cvt_pk_bf16_f32 v3, v19, v21
	v_lshl_add_u64 v[4:5], v[56:57], 0, v[4:5]
	global_store_dwordx4 v[4:5], v[0:3], off sc1
	s_waitcnt lgkmcnt(0)

; __device__ __forceinline__ unsigned pk_bf16(float lo, float hi) { typedef __bf16 b2_t __attribute__((ext_vector_type(2))); f32x2 v = {lo, hi}; b2_t b = __builtin_convertvector(v, b2_t); return __builtin_bit_cast(unsigned, b); }
; #define LAS __attribute__((address_space(3)))
; __device__ __forceinline__ void transpose_tile(const float* W, const float* gain, int K, int N, int k0, int n0, bf16* WT, int drow0, LAS float* scr, int lane) {
;     f32x4 v[8]; float gv[8];
;     const int r0 = lane >> 3, c4 = lane & 7;
; #pragma unroll
;     for (int i = 0; i < 8; ++i) { v[i] = *(const f32x4*)(W + (size_t)(k0 + r0 + 8 * i) * N + n0 + 4 * c4); gv[i] = gain ? gain[k0 + r0 + 8 * i] : 1.0f; }
; #pragma unroll
;     for (int i = 0; i < 8; ++i) { LAS float* d = scr + (r0 + 8 * i) * 33 + 4 * c4; d[0] = v[i][0] * gv[i]; d[1] = v[i][1] * gv[i]; d[2] = v[i][2] * gv[i]; d[3] = v[i][3] * gv[i]; }
;     asm volatile("s_waitcnt lgkmcnt(0)" ::: "memory");
;     const int c = lane & 7;
; #pragma unroll
;     for (int j = 0; j < 4; ++j) { const int n = (lane >> 3) + 8 * j; const LAS float* s = scr + (8 * c) * 33 + n;
;         v4u o; o.x = pk_bf16(s[0 * 33], s[1 * 33]); o.y = pk_bf16(s[2 * 33], s[3 * 33]); o.z = pk_bf16(s[4 * 33], s[5 * 33]); o.w = pk_bf16(s[6 * 33], s[7 * 33]);
;         *(v4u*)(WT + (size_t)(drow0 + n) * K + k0 + 8 * c) = o; }
;     asm volatile("s_waitcnt lgkmcnt(0)" ::: "memory");
; }
; template <bool SWIGLU> __device__ __forceinline__ void transpose_item(const float* W, const float* gain, int K, int N, bf16* WT, LAS float* scr, int item, int lane) {
;     const int nblk = N / 32, kb = item / nblk, nb = item % nblk, n0 = 32 * nb;
;     int drow0 = n0;
;     if (SWIGLU) { const int up = n0 >= FF, f = up ? n0 - FF : n0; drow0 = 256 * (f >> 7) + (up ? 128 : 0) + (f & 127); }
;     transpose_tile(W, gain, K, N, 64 * kb, n0, WT, drow0, scr, lane);
; }
.LBB0_232:
	s_andn2_b64 vcc, exec, s[2:3]
	s_cbranch_vccnz .LBB0_234
	s_mov_b32 s2, 3
	s_ashr_i32 s3, s2, 31
	s_lshl_b64 s[2:3], s[2:3], 3
	s_add_u32 s2, s0, s2
	s_addc_u32 s3, s1, s3
	s_load_dwordx2 s[2:3], s[2:3], 0x0
	s_lshl_b32 s6, s14, 5
	s_and_b32 s8, s6, 0x3e0
	s_add_i32 s6, s18, 0x1700
	s_and_b32 s6, s6, 0x1ffc0
	s_lshl_b32 s9, s8, 2
	v_add_u32_e32 v0, s6, v45
	s_waitcnt lgkmcnt(0)
	s_add_u32 s2, s2, s9
	s_addc_u32 s3, s3, 0
	v_ashrrev_i32_e32 v1, 31, v0
	v_lshl_add_u64 v[2:3], s[2:3], 0, v[32:33]
	v_lshlrev_b64 v[0:1], 12, v[0:1]
	v_lshl_add_u64 v[28:29], v[2:3], 0, v[0:1]
	v_add_co_u32_e32 v4, vcc, s21, v28
	v_add_u32_e32 v44, v47, v49
	s_nop 0
	v_addc_co_u32_e32 v5, vcc, 0, v29, vcc
	v_add_co_u32_e32 v8, vcc, s22, v28
	global_load_dwordx4 v[0:3], v[28:29], off
	s_nop 0
	global_load_dwordx4 v[4:7], v[4:5], off
	v_addc_co_u32_e32 v9, vcc, 0, v29, vcc
	v_add_co_u32_e32 v12, vcc, s23, v28
	v_add_u32_e32 v46, 0x420, v44
	s_nop 0
	v_addc_co_u32_e32 v13, vcc, 0, v29, vcc
	v_add_co_u32_e32 v16, vcc, s24, v28
	global_load_dwordx4 v[8:11], v[8:9], off
	s_nop 0
	global_load_dwordx4 v[12:15], v[12:13], off
	v_addc_co_u32_e32 v17, vcc, 0, v29, vcc
	v_add_co_u32_e32 v20, vcc, s25, v28
	v_add_u32_e32 v48, 0x428, v44
	s_nop 0
	v_addc_co_u32_e32 v21, vcc, 0, v29, vcc
	global_load_dwordx4 v[16:19], v[16:17], off
	s_nop 0
	global_load_dwordx4 v[20:23], v[20:21], off
	v_add_co_u32_e32 v24, vcc, s26, v28
	v_add_u32_e32 v50, 0x840, v44
	s_nop 0
	v_addc_co_u32_e32 v25, vcc, 0, v29, vcc
	global_load_dwordx4 v[24:27], v[24:25], off
	v_add_co_u32_e32 v28, vcc, s27, v28
	v_add_u32_e32 v54, 0x848, v44
	s_nop 0
	v_addc_co_u32_e32 v29, vcc, 0, v29, vcc
	global_load_dwordx4 v[28:31], v[28:29], off
	v_add_u32_e32 v56, 0xc60, v44
	v_add_u32_e32 v57, 0xc68, v44
	v_add_u32_e32 v58, 0x1080, v44
	v_add_u32_e32 v60, 0x1088, v44
	v_add_u32_e32 v62, 0x14a0, v44
	v_add_u32_e32 v63, 0x14a8, v44
	v_add_u32_e32 v64, 0x18c0, v44
	v_add_u32_e32 v65, 0x18c8, v44
	v_add_u32_e32 v66, 0x1ce0, v44
	v_add_u32_e32 v67, 0x1ce8, v44
	s_lshl_b32 s6, s6, 1
	v_add_u32_e32 v68, s8, v45
	v_lshl_add_u64 v[52:53], v[40:41], 0, s[6:7]
	s_waitcnt vmcnt(0)
	ds_write2_b32 v44, v0, v1 offset1:1
	ds_write2_b32 v44, v2, v3 offset0:2 offset1:3
	ds_write2_b32 v46, v4, v5 offset1:1
	ds_write2_b32 v48, v6, v7 offset1:1
	ds_write2_b32 v50, v8, v9 offset1:1
	ds_write2_b32 v54, v10, v11 offset1:1
	ds_write2_b32 v56, v12, v13 offset1:1
	ds_write2_b32 v57, v14, v15 offset1:1
	ds_write2_b32 v58, v16, v17 offset1:1
	ds_write2_b32 v60, v18, v19 offset1:1
	ds_write2_b32 v62, v20, v21 offset1:1
	ds_write2_b32 v63, v22, v23 offset1:1
	ds_write2_b32 v64, v24, v25 offset1:1
	ds_write2_b32 v65, v26, v27 offset1:1
	ds_write2_b32 v66, v28, v29 offset1:1
	ds_write2_b32 v67, v30, v31 offset1:1
	s_waitcnt lgkmcnt(0)
	ds_read2_b32 v[4:5], v61 offset0:33 offset1:41
	ds_read2_b32 v[6:7], v61 offset1:8
	ds_read2_b32 v[8:9], v61 offset0:66 offset1:74
	ds_read2_b32 v[10:11], v61 offset0:99 offset1:107
	ds_read2_b32 v[12:13], v61 offset0:132 offset1:140
	ds_read2_b32 v[14:15], v61 offset0:165 offset1:173
	ds_read2_b32 v[16:17], v61 offset0:198 offset1:206
	ds_read2_b32 v[18:19], v61 offset0:231 offset1:239
	v_mad_i64_i32 v[20:21], s[2:3], v68, s29, v[52:53]
	s_waitcnt lgkmcnt(6)
	v_cvt_pk_bf16_f32 v0, v6, v4
	s_waitcnt lgkmcnt(4)
	v_cvt_pk_bf16_f32 v1, v8, v10
	s_waitcnt lgkmcnt(2)
	v_cvt_pk_bf16_f32 v2, v12, v14
	s_waitcnt lgkmcnt(0)
	v_cvt_pk_bf16_f32 v3, v16, v18
	global_store_dwordx4 v[20:21], v[0:3], off sc1
	v_add_u32_e32 v4, s8, v51
	s_nop 0
	v_cvt_pk_bf16_f32 v0, v7, v5
	v_cvt_pk_bf16_f32 v1, v9, v11
	v_cvt_pk_bf16_f32 v2, v13, v15
	v_cvt_pk_bf16_f32 v3, v17, v19
	ds_read2_b32 v[6:7], v61 offset0:49 offset1:57
	ds_read2_b32 v[8:9], v61 offset0:16 offset1:24
	ds_read2_b32 v[10:11], v61 offset0:82 offset1:90
	ds_read2_b32 v[12:13], v61 offset0:115 offset1:123
	ds_read2_b32 v[14:15], v61 offset0:148 offset1:156
	ds_read2_b32 v[16:17], v61 offset0:181 offset1:189
	ds_read2_b32 v[18:19], v61 offset0:214 offset1:222
	ds_read2_b32 v[20:21], v61 offset0:247 offset1:255
	v_mad_i64_i32 v[4:5], s[2:3], v4, s29, v[52:53]
	global_store_dwordx4 v[4:5], v[0:3], off sc1
	v_add_u32_e32 v4, s8, v55
	v_mad_i64_i32 v[4:5], s[2:3], v4, s29, v[52:53]
	s_waitcnt lgkmcnt(6)
	v_cvt_pk_bf16_f32 v0, v8, v6
	s_waitcnt lgkmcnt(4)
	v_cvt_pk_bf16_f32 v1, v10, v12
	s_waitcnt lgkmcnt(2)
	v_cvt_pk_bf16_f32 v2, v14, v16
	s_waitcnt lgkmcnt(0)
	v_cvt_pk_bf16_f32 v3, v18, v20
	global_store_dwordx4 v[4:5], v[0:3], off sc1
	v_add_u32_e32 v4, s8, v59
	v_mad_i64_i32 v[4:5], s[2:3], v4, s29, v[52:53]
	v_cvt_pk_bf16_f32 v0, v9, v7
	v_cvt_pk_bf16_f32 v1, v11, v13
	v_cvt_pk_bf16_f32 v2, v15, v17
	v_cvt_pk_bf16_f32 v3, v19, v21
	global_store_dwordx4 v[4:5], v[0:3], off sc1
	s_waitcnt lgkmcnt(0)

; __device__ __forceinline__ int lane_id_() { int l; asm volatile("v_mbcnt_lo_u32_b32 %0, -1, 0\n\tv_mbcnt_hi_u32_b32 %0, -1, %0" : "=v"(l)); return l; }
; __device__ __forceinline__ unsigned xb_ld(unsigned* p)              { return __hip_atomic_load(p, __ATOMIC_RELAXED, __HIP_MEMORY_SCOPE_AGENT); }
; __device__ __forceinline__ unsigned xb_add(unsigned* p, unsigned v) { return __hip_atomic_fetch_add(p, v, __ATOMIC_RELAXED, __HIP_MEMORY_SCOPE_AGENT); }
; #define XB_SPIN(cond, bar) do { unsigned _sp = 0; while (cond) { __builtin_amdgcn_s_sleep(1); \
;     if ((++_sp & 255u) == 0u) { if (xb_ld(&(bar)[XB_TMO])) break; if (_sp > XB_SPIN_CAP) { atomicAdd(&(bar)[XB_TMO], 1u); break; } } } } while (0)
; __device__ __forceinline__ void xcd_barrier(const XcdBarrier& b, int wave_s) {
;     asm volatile("s_waitcnt vmcnt(0)" ::: "memory");
;     __syncthreads();
;     if (wave_s == 0 && lane_id_() == 0) {
;         unsigned* bar = b.bar;
;         __builtin_amdgcn_s_waitcnt(0);
;         unsigned nloc = b.st[0], nx = b.st[1];
;         if (nloc == 0u) { xcd_barrier_complete(bar, b.x, nloc, nx); b.st[0] = nloc; b.st[1] = nx; }
;         const unsigned old = xb_add(&bar[XB_XSUB(b.x)], 1u);
;         const unsigned gen = old / nloc;
;         if (old + 1u == (gen + 1u) * nloc) {
;             __builtin_amdgcn_fence(__ATOMIC_RELEASE, "agent");
;             asm volatile("s_waitcnt vmcnt(0)" ::: "memory");
;             const unsigned og = xb_add(&bar[XB_TOP], 1u);
;             const unsigned tg = og / nx;
;             if (og + 1u == (tg + 1u) * nx) xb_add(&bar[XB_TOPGEN], 1u);
;             else XB_SPIN(xb_ld(&bar[XB_TOPGEN]) == tg, bar);
;             __builtin_amdgcn_fence(__ATOMIC_ACQUIRE, "agent");
;             xb_add(&bar[XB_XGEN(b.x)], 1u);
.LBB0_252:
	s_waitcnt vmcnt(0)
	v_cndmask_b32_e64 v0, 0, 1, s[4:5]
	v_cmp_ne_u32_e64 s[2:3], 1, v0
	s_andn2_b64 vcc, exec, s[4:5]
	s_waitcnt vmcnt(0)
	s_barrier
	s_cbranch_vccnz .LBB0_306
	v_mbcnt_lo_u32_b32 v0, -1, 0
	v_mbcnt_hi_u32_b32 v0, -1, v0
	s_nop 0
	v_cmp_eq_u32_e32 vcc, 0, v0
	s_and_saveexec_b64 s[4:5], vcc
	s_cbranch_execz .LBB0_305
	s_cmp_eq_u32 s101, 1
	s_cbranch_scc0 .Lglob_S2
	s_and_b32 s98, s33, 7
	s_lshl_b32 s99, s98, 2
	s_addk_i32 s99, 0x4800
	v_mov_b32_e32 v3, s99
	s_lshl_b32 s98, s98, 8
	s_addk_i32 s98, 0x4000
	v_mov_b32_e32 v0, s98
	v_mov_b32_e32 v1, 1
	global_atomic_add v2, v0, v1, s[44:45] sc0
	buffer_inv sc1
	s_waitcnt vmcnt(1)
	v_readfirstlane_b32 s98, v2
	s_nop 3
	s_add_u32 s99, s98, 1
	s_and_b32 s99, s99, 31
	s_lshr_b32 s98, s98, 5
	s_cmp_eq_u32 s99, 0
	s_cbranch_scc0 .Llw_S2
	global_atomic_add v3, v1, s[44:45]

; __device__ __forceinline__ unsigned xb_ld(unsigned* p)              { return __hip_atomic_load(p, __ATOMIC_RELAXED, __HIP_MEMORY_SCOPE_AGENT); }
; __device__ __forceinline__ unsigned xb_add(unsigned* p, unsigned v) { return __hip_atomic_fetch_add(p, v, __ATOMIC_RELAXED, __HIP_MEMORY_SCOPE_AGENT); }
; #define XB_SPIN(cond, bar) do { unsigned _sp = 0; while (cond) { __builtin_amdgcn_s_sleep(1); \
;     if ((++_sp & 255u) == 0u) { if (xb_ld(&(bar)[XB_TMO])) break; if (_sp > XB_SPIN_CAP) { atomicAdd(&(bar)[XB_TMO], 1u); break; } } } } while (0)
; __device__ __forceinline__ void xcd_barrier(const XcdBarrier& b, int wave_s) {
;     ...
;             else XB_SPIN(xb_ld(&bar[XB_TOPGEN]) == tg, bar);
;             __builtin_amdgcn_fence(__ATOMIC_ACQUIRE, "agent");
;             xb_add(&bar[XB_XGEN(b.x)], 1u);
;             asm volatile("s_waitcnt vmcnt(0)" ::: "memory");
;         } else {
;             XB_SPIN(xb_ld(&bar[XB_XGEN(b.x)]) == gen, bar);
.Lls_S2:
	global_load_dword v2, v0, s[44:45] sc1
	s_waitcnt vmcnt(0)
	v_cmp_gt_u32_e32 vcc, s98, v2
	s_nop 3
	s_cmp_eq_u64 vcc, 0
	s_cbranch_scc1 .Lrd_S2
	s_add_u32 s99, s99, 1
	s_cmp_lt_u32 s99, 0x4000
	s_cbranch_scc1 .Lls_S2

; __device__ __forceinline__ unsigned xb_ld(unsigned* p)              { return __hip_atomic_load(p, __ATOMIC_RELAXED, __HIP_MEMORY_SCOPE_AGENT); }
; __device__ __forceinline__ unsigned xb_add(unsigned* p, unsigned v) { return __hip_atomic_fetch_add(p, v, __ATOMIC_RELAXED, __HIP_MEMORY_SCOPE_AGENT); }
; #define XB_SPIN(cond, bar) do { unsigned _sp = 0; while (cond) { __builtin_amdgcn_s_sleep(1); \
;     if ((++_sp & 255u) == 0u) { if (xb_ld(&(bar)[XB_TMO])) break; if (_sp > XB_SPIN_CAP) { atomicAdd(&(bar)[XB_TMO], 1u); break; } } } } while (0)
; __device__ __forceinline__ void xcd_barrier(const XcdBarrier& b, int wave_s) {
;     ...
;             else XB_SPIN(xb_ld(&bar[XB_TOPGEN]) == tg, bar);
;             __builtin_amdgcn_fence(__ATOMIC_ACQUIRE, "agent");
;             xb_add(&bar[XB_XGEN(b.x)], 1u);
;             asm volatile("s_waitcnt vmcnt(0)" ::: "memory");
;         } else {
;             XB_SPIN(xb_ld(&bar[XB_XGEN(b.x)]) == gen, bar);
.Lls_S4:
	global_load_dword v2, v3, s[44:45] sc1
	s_waitcnt vmcnt(0)
	v_readfirstlane_b32 s100, v2
	s_nop 3
	s_cmp_lg_u32 s100, s98
	s_cbranch_scc1 .Lla_S4
	s_add_u32 s99, s99, 1
	s_cmp_lt_u32 s99, 0x4000
	s_cbranch_scc1 .Lls_S4

; #define PG8_LAS __attribute__((address_space(3)))
; __device__ __forceinline__ unsigned pk_bf16(float lo, float hi) { typedef __bf16 b2_t __attribute__((ext_vector_type(2))); f32x2 v = {lo, hi}; b2_t b = __builtin_convertvector(v, b2_t); return __builtin_bit_cast(unsigned, b); }
;     __device__ __forceinline__ void operator()(const f32x4 (&acc)[2][2][4][2], const Unit& u, int wr, int wc, int fr, int fq, PG8_LAS unsigned char* lds, int wid) const {
;         const int row0 = u.pm * BM + wr * 64 + fr, col0 = u.pn * HALF + wc * 32 + 8 * fq;
; #pragma unroll
;         for (int ai = 0; ai < 2; ++ai)
; #pragma unroll
;             for (int m = 0; m < 4; ++m) {
;                 bf16_t* p = H + (size_t)(row0 + ai * HALF + m * 16) * ldh + col0;
;                 const float rstd = __builtin_amdgcn_rsqf(*(const PG8_LAS float*)(lds + PRE_SLOT + wid * 512 + (m & 1) * 256 + (fr + 16 * ((ai * 4 + m) >> 1)) * 4) * (1.0f / 1024.0f) + 1e-6f);
;                 const float c1 = -1.44269504089f * rstd, r2 = rstd * rstd;
;                 f32x2 hh[4];
; #pragma unroll
;                 for (int q = 0; q < 4; ++q) {
;                     const f32x2 ag = {acc[ai][0][m][q >> 1][2 * (q & 1)], acc[ai][0][m][q >> 1][2 * (q & 1) + 1]};
;                     const f32x2 au = {acc[ai][1][m][q >> 1][2 * (q & 1)], acc[ai][1][m][q >> 1][2 * (q & 1) + 1]};
;                     const f32x2 t = ag * c1;
;                     f32x2 e; e.x = __builtin_amdgcn_exp2f(t.x); e.y = __builtin_amdgcn_exp2f(t.y);
;                     const f32x2 d = e + 1.0f;
;                     f32x2 r; r.x = __builtin_amdgcn_rcpf(d.x); r.y = __builtin_amdgcn_rcpf(d.y);
;                     hh[q] = (ag * au) * (r * r2);
;                 }
;                 u32x4 w; w.x = pk_bf16(hh[0].x, hh[0].y); w.y = pk_bf16(hh[1].x, hh[1].y); w.z = pk_bf16(hh[2].x, hh[2].y); w.w = pk_bf16(hh[3].x, hh[3].y);
;                 *(u32x4*)p = w;
.LBB0_915:
	v_add_u32_e32 v159, s71, v145
	ds_read2_b32 v[140:141], v159 offset1:16
	v_lshl_or_b32 v142, s29, 7, v147
	v_lshl_add_u32 v0, s28, 8, v144
	v_ashrrev_i32_e32 v143, 31, v142
	s_andn2_b64 vcc, exec, s[8:9]
	s_waitcnt lgkmcnt(0)
	v_fmamk_f32 v2, v140, 0x3a800000, v148
	v_rsq_f32_e32 v158, v2
	v_mov_b64_e32 v[2:3], s[50:51]
	v_mad_i64_i32 v[156:157], s[6:7], v0, s88, v[2:3]
	v_mul_f32_e32 v140, 0xbfb8aa3b, v158
	v_pk_mul_f32 v[154:155], v[124:125], v[140:141] op_sel_hi:[1,0]
	v_pk_mul_f32 v[160:161], v[126:127], v[140:141] op_sel_hi:[1,0]
	v_exp_f32_e32 v154, v154
	v_exp_f32_e32 v155, v155
	v_exp_f32_e32 v160, v160
	v_exp_f32_e32 v161, v161
	v_mul_f32_e32 v158, v158, v158
	v_pk_add_f32 v[154:155], v[154:155], 1.0 op_sel_hi:[1,0]
	v_pk_mul_f32 v[126:127], v[126:127], v[130:131]
	v_rcp_f32_e32 v154, v154
	v_rcp_f32_e32 v155, v155
	v_pk_add_f32 v[130:131], v[160:161], 1.0 op_sel_hi:[1,0]
	v_pk_mul_f32 v[124:125], v[124:125], v[128:129]
	v_rcp_f32_e32 v130, v130
	v_pk_mul_f32 v[128:129], v[158:159], v[154:155] op_sel_hi:[0,1]
	v_rcp_f32_e32 v131, v131
	v_pk_mul_f32 v[154:155], v[116:117], v[140:141] op_sel_hi:[1,0]
	v_pk_mul_f32 v[124:125], v[124:125], v[128:129]
	v_exp_f32_e32 v154, v154
	v_exp_f32_e32 v155, v155
	v_pk_mul_f32 v[128:129], v[158:159], v[130:131] op_sel_hi:[0,1]
	v_pk_mul_f32 v[126:127], v[126:127], v[128:129]
	v_pk_mul_f32 v[130:131], v[118:119], v[140:141] op_sel_hi:[1,0]
	v_pk_add_f32 v[128:129], v[154:155], 1.0 op_sel_hi:[1,0]
	v_exp_f32_e32 v130, v130
	v_exp_f32_e32 v131, v131
	v_rcp_f32_e32 v128, v128
	v_rcp_f32_e32 v129, v129
	v_pk_mul_f32 v[118:119], v[118:119], v[122:123]
	v_pk_add_f32 v[122:123], v[130:131], 1.0 op_sel_hi:[1,0]
	v_pk_mul_f32 v[116:117], v[116:117], v[120:121]
	v_pk_mul_f32 v[120:121], v[158:159], v[128:129] op_sel_hi:[0,1]
	ds_read2_b32 v[128:129], v159 offset0:64 offset1:80
	v_rcp_f32_e32 v122, v122
	v_rcp_f32_e32 v123, v123
	v_pk_mul_f32 v[120:121], v[116:117], v[120:121]
	s_mov_b64 s[8:9], -1
	v_cvt_pk_bf16_f32 v120, v120, v121
	v_pk_mul_f32 v[116:117], v[158:159], v[122:123] op_sel_hi:[0,1]
	s_waitcnt lgkmcnt(0)
	v_fmamk_f32 v121, v128, 0x3a800000, v148
	v_pk_mul_f32 v[122:123], v[118:119], v[116:117]
	v_cvt_pk_bf16_f32 v118, v124, v125
	v_rsq_f32_e32 v124, v121
	v_lshlrev_b64 v[116:117], 1, v[142:143]
	v_lshl_add_u64 v[130:131], v[156:157], 0, v[116:117]
	v_cvt_pk_bf16_f32 v119, v126, v127
	v_cvt_pk_bf16_f32 v121, v122, v123
	global_store_dwordx4 v[130:131], v[118:121], off sc1
	s_nop 1
	v_or_b32_e32 v119, 16, v0
	v_mul_f32_e32 v118, 0xbfb8aa3b, v124
	v_pk_mul_f32 v[120:121], v[108:109], v[118:119] op_sel_hi:[1,0]
	v_pk_mul_f32 v[126:127], v[110:111], v[118:119] op_sel_hi:[1,0]
	v_exp_f32_e32 v120, v120
	v_exp_f32_e32 v121, v121
	v_exp_f32_e32 v126, v126
	v_exp_f32_e32 v127, v127
	v_pk_mul_f32 v[110:111], v[110:111], v[114:115]
	v_pk_add_f32 v[120:121], v[120:121], 1.0 op_sel_hi:[1,0]
	v_mul_f32_e32 v124, v124, v124
	v_rcp_f32_e32 v120, v120
	v_rcp_f32_e32 v121, v121
	v_pk_add_f32 v[114:115], v[126:127], 1.0 op_sel_hi:[1,0]
	v_pk_mul_f32 v[108:109], v[108:109], v[112:113]
	v_rcp_f32_e32 v114, v114
	v_rcp_f32_e32 v115, v115
	v_pk_mul_f32 v[112:113], v[124:125], v[120:121] op_sel_hi:[0,1]
	v_pk_mul_f32 v[120:121], v[100:101], v[118:119] op_sel_hi:[1,0]
	v_pk_mul_f32 v[108:109], v[108:109], v[112:113]
	v_exp_f32_e32 v120, v120
	v_exp_f32_e32 v121, v121
	v_pk_mul_f32 v[112:113], v[124:125], v[114:115] op_sel_hi:[0,1]
	v_pk_mul_f32 v[114:115], v[102:103], v[118:119] op_sel_hi:[1,0]
	v_pk_mul_f32 v[110:111], v[110:111], v[112:113]
	v_exp_f32_e32 v114, v114
	v_exp_f32_e32 v115, v115
	v_pk_add_f32 v[112:113], v[120:121], 1.0 op_sel_hi:[1,0]
	v_pk_mul_f32 v[102:103], v[102:103], v[106:107]
	v_rcp_f32_e32 v112, v112
	v_rcp_f32_e32 v113, v113
	v_pk_add_f32 v[106:107], v[114:115], 1.0 op_sel_hi:[1,0]
	v_pk_mul_f32 v[100:101], v[100:101], v[104:105]
	v_rcp_f32_e32 v106, v106
	v_rcp_f32_e32 v107, v107
	v_pk_mul_f32 v[104:105], v[124:125], v[112:113] op_sel_hi:[0,1]
	v_pk_mul_f32 v[104:105], v[100:101], v[104:105]
	v_mad_i64_i32 v[122:123], s[6:7], v119, s88, v[2:3]
	v_pk_mul_f32 v[100:101], v[124:125], v[106:107] op_sel_hi:[0,1]
	v_pk_mul_f32 v[106:107], v[102:103], v[100:101]
	v_fmamk_f32 v103, v141, 0x3a800000, v148
	v_cvt_pk_bf16_f32 v100, v108, v109
	v_rsq_f32_e32 v108, v103
	v_lshl_add_u64 v[112:113], v[122:123], 0, v[116:117]
	v_cvt_pk_bf16_f32 v101, v110, v111
	v_cvt_pk_bf16_f32 v102, v104, v105
	v_cvt_pk_bf16_f32 v103, v106, v107
	global_store_dwordx4 v[112:113], v[100:103], off sc1
	v_mul_f32_e32 v106, v108, v108
	s_nop 0
	v_or_b32_e32 v101, 32, v0
	v_mul_f32_e32 v100, 0xbfb8aa3b, v108
	v_pk_mul_f32 v[102:103], v[92:93], v[100:101] op_sel_hi:[1,0]
	v_pk_mul_f32 v[108:109], v[94:95], v[100:101] op_sel_hi:[1,0]
	v_exp_f32_e32 v102, v102
	v_exp_f32_e32 v103, v103
	v_exp_f32_e32 v108, v108
	v_exp_f32_e32 v109, v109
	v_pk_mul_f32 v[94:95], v[94:95], v[98:99]
	v_pk_add_f32 v[102:103], v[102:103], 1.0 op_sel_hi:[1,0]
	v_pk_mul_f32 v[92:93], v[92:93], v[96:97]
	v_rcp_f32_e32 v102, v102
	v_rcp_f32_e32 v103, v103
	v_pk_add_f32 v[98:99], v[108:109], 1.0 op_sel_hi:[1,0]
	v_mad_i64_i32 v[104:105], s[6:7], v101, s88, v[2:3]
	v_rcp_f32_e32 v98, v98
	v_rcp_f32_e32 v99, v99
	v_pk_mul_f32 v[96:97], v[106:107], v[102:103] op_sel_hi:[0,1]
	v_pk_mul_f32 v[102:103], v[84:85], v[100:101] op_sel_hi:[1,0]
	v_pk_mul_f32 v[92:93], v[92:93], v[96:97]
	v_exp_f32_e32 v102, v102
	v_exp_f32_e32 v103, v103
	v_pk_mul_f32 v[96:97], v[106:107], v[98:99] op_sel_hi:[0,1]
	v_pk_mul_f32 v[98:99], v[86:87], v[100:101] op_sel_hi:[1,0]
	v_pk_mul_f32 v[94:95], v[94:95], v[96:97]
	v_exp_f32_e32 v98, v98
	v_exp_f32_e32 v99, v99
; #define PG8_LAS __attribute__((address_space(3)))
; __device__ __forceinline__ unsigned pk_bf16(float lo, float hi) { typedef __bf16 b2_t __attribute__((ext_vector_type(2))); f32x2 v = {lo, hi}; b2_t b = __builtin_convertvector(v, b2_t); return __builtin_bit_cast(unsigned, b); }
;     __device__ __forceinline__ void operator()(const f32x4 (&acc)[2][2][4][2], const Unit& u, int wr, int wc, int fr, int fq, PG8_LAS unsigned char* lds, int wid) const {
;         const int row0 = u.pm * BM + wr * 64 + fr, col0 = u.pn * HALF + wc * 32 + 8 * fq;
; #pragma unroll
;         for (int ai = 0; ai < 2; ++ai)
; #pragma unroll
;             for (int m = 0; m < 4; ++m) {
;                 bf16_t* p = H + (size_t)(row0 + ai * HALF + m * 16) * ldh + col0;
;                 const float rstd = __builtin_amdgcn_rsqf(*(const PG8_LAS float*)(lds + PRE_SLOT + wid * 512 + (m & 1) * 256 + (fr + 16 * ((ai * 4 + m) >> 1)) * 4) * (1.0f / 1024.0f) + 1e-6f);
;                 const float c1 = -1.44269504089f * rstd, r2 = rstd * rstd;
;                 f32x2 hh[4];
; #pragma unroll
;                 for (int q = 0; q < 4; ++q) {
;                     const f32x2 ag = {acc[ai][0][m][q >> 1][2 * (q & 1)], acc[ai][0][m][q >> 1][2 * (q & 1) + 1]};
;                     const f32x2 au = {acc[ai][1][m][q >> 1][2 * (q & 1)], acc[ai][1][m][q >> 1][2 * (q & 1) + 1]};
;                     const f32x2 t = ag * c1;
;                     f32x2 e; e.x = __builtin_amdgcn_exp2f(t.x); e.y = __builtin_amdgcn_exp2f(t.y);
;                     const f32x2 d = e + 1.0f;
;                     f32x2 r; r.x = __builtin_amdgcn_rcpf(d.x); r.y = __builtin_amdgcn_rcpf(d.y);
;                     hh[q] = (ag * au) * (r * r2);
;                 }
;                 u32x4 w; w.x = pk_bf16(hh[0].x, hh[0].y); w.y = pk_bf16(hh[1].x, hh[1].y); w.z = pk_bf16(hh[2].x, hh[2].y); w.w = pk_bf16(hh[3].x, hh[3].y);
;                 *(u32x4*)p = w;
	v_pk_add_f32 v[96:97], v[102:103], 1.0 op_sel_hi:[1,0]
	v_pk_mul_f32 v[86:87], v[86:87], v[90:91]
	v_rcp_f32_e32 v96, v96
	v_rcp_f32_e32 v97, v97
	v_pk_add_f32 v[90:91], v[98:99], 1.0 op_sel_hi:[1,0]
	v_pk_mul_f32 v[84:85], v[84:85], v[88:89]
	v_rcp_f32_e32 v90, v90
	v_rcp_f32_e32 v91, v91
	v_pk_mul_f32 v[88:89], v[106:107], v[96:97] op_sel_hi:[0,1]
	v_pk_mul_f32 v[88:89], v[84:85], v[88:89]
	v_lshl_add_u64 v[96:97], v[104:105], 0, v[116:117]
	v_pk_mul_f32 v[84:85], v[106:107], v[90:91] op_sel_hi:[0,1]
	v_pk_mul_f32 v[90:91], v[86:87], v[84:85]
	v_fmamk_f32 v87, v129, 0x3a800000, v148
	v_cvt_pk_bf16_f32 v84, v92, v93
	v_rsq_f32_e32 v92, v87
	v_cvt_pk_bf16_f32 v85, v94, v95
	v_cvt_pk_bf16_f32 v86, v88, v89
	v_cvt_pk_bf16_f32 v87, v90, v91
	global_store_dwordx4 v[96:97], v[84:87], off sc1
	v_mul_f32_e32 v90, v92, v92
	s_nop 0
	v_or_b32_e32 v85, 48, v0
	v_mul_f32_e32 v84, 0xbfb8aa3b, v92
	v_pk_mul_f32 v[86:87], v[76:77], v[84:85] op_sel_hi:[1,0]
	v_pk_mul_f32 v[92:93], v[78:79], v[84:85] op_sel_hi:[1,0]
	v_exp_f32_e32 v86, v86
	v_exp_f32_e32 v87, v87
	v_exp_f32_e32 v92, v92
	v_exp_f32_e32 v93, v93
	v_pk_mul_f32 v[78:79], v[78:79], v[82:83]
	v_pk_add_f32 v[86:87], v[86:87], 1.0 op_sel_hi:[1,0]
	v_pk_mul_f32 v[76:77], v[76:77], v[80:81]
	v_rcp_f32_e32 v86, v86
	v_rcp_f32_e32 v87, v87
	v_pk_add_f32 v[82:83], v[92:93], 1.0 op_sel_hi:[1,0]
	v_mad_i64_i32 v[88:89], s[6:7], v85, s88, v[2:3]
	v_pk_mul_f32 v[80:81], v[90:91], v[86:87] op_sel_hi:[0,1]
	v_rcp_f32_e32 v82, v82
	v_rcp_f32_e32 v83, v83
	v_pk_mul_f32 v[86:87], v[60:61], v[84:85] op_sel_hi:[1,0]
	v_pk_mul_f32 v[76:77], v[76:77], v[80:81]
	v_exp_f32_e32 v86, v86
	v_exp_f32_e32 v87, v87
	v_pk_mul_f32 v[80:81], v[90:91], v[82:83] op_sel_hi:[0,1]
	v_pk_mul_f32 v[82:83], v[62:63], v[84:85] op_sel_hi:[1,0]
	v_pk_mul_f32 v[78:79], v[78:79], v[80:81]
	v_pk_add_f32 v[80:81], v[86:87], 1.0 op_sel_hi:[1,0]
	v_exp_f32_e32 v82, v82
	v_exp_f32_e32 v83, v83
	v_rcp_f32_e32 v80, v80
	v_rcp_f32_e32 v81, v81
	v_pk_mul_f32 v[62:63], v[62:63], v[70:71]
	v_pk_add_f32 v[70:71], v[82:83], 1.0 op_sel_hi:[1,0]
	v_pk_mul_f32 v[60:61], v[60:61], v[68:69]
	v_rcp_f32_e32 v70, v70
	v_rcp_f32_e32 v71, v71
	v_pk_mul_f32 v[68:69], v[90:91], v[80:81] op_sel_hi:[0,1]
	ds_read2_b32 v[80:81], v159 offset0:32 offset1:48
	v_pk_mul_f32 v[68:69], v[60:61], v[68:69]
	v_pk_mul_f32 v[60:61], v[90:91], v[70:71] op_sel_hi:[0,1]
	v_pk_mul_f32 v[70:71], v[62:63], v[60:61]
	v_cvt_pk_bf16_f32 v60, v76, v77
	s_waitcnt lgkmcnt(0)
	v_fmamk_f32 v63, v80, 0x3a800000, v148
	v_rsq_f32_e32 v76, v63
	v_lshl_add_u64 v[82:83], v[88:89], 0, v[116:117]
	v_cvt_pk_bf16_f32 v61, v78, v79
	v_cvt_pk_bf16_f32 v62, v68, v69
	v_cvt_pk_bf16_f32 v63, v70, v71
	global_store_dwordx4 v[82:83], v[60:63], off sc1
	v_mul_f32_e32 v70, v76, v76
	s_nop 0
	v_add_u32_e32 v61, 0x80, v0
	v_mul_f32_e32 v60, 0xbfb8aa3b, v76
	v_pk_mul_f32 v[62:63], v[64:65], v[60:61] op_sel_hi:[1,0]
	v_pk_mul_f32 v[76:77], v[66:67], v[60:61] op_sel_hi:[1,0]
	v_exp_f32_e32 v62, v62
	v_exp_f32_e32 v63, v63
	v_exp_f32_e32 v76, v76
	v_exp_f32_e32 v77, v77
	v_pk_mul_f32 v[64:65], v[64:65], v[72:73]
	v_pk_add_f32 v[62:63], v[62:63], 1.0 op_sel_hi:[1,0]
	v_pk_mul_f32 v[66:67], v[66:67], v[74:75]
	v_rcp_f32_e32 v62, v62
	v_rcp_f32_e32 v63, v63
	v_pk_add_f32 v[72:73], v[76:77], 1.0 op_sel_hi:[1,0]
	v_pk_mul_f32 v[74:75], v[52:53], v[60:61] op_sel_hi:[1,0]
	v_rcp_f32_e32 v72, v72
	v_rcp_f32_e32 v73, v73
	v_mad_i64_i32 v[68:69], s[6:7], v61, s88, v[2:3]
	v_exp_f32_e32 v74, v74
	v_exp_f32_e32 v75, v75
	v_pk_mul_f32 v[60:61], v[54:55], v[60:61] op_sel_hi:[1,0]
	v_pk_mul_f32 v[62:63], v[70:71], v[62:63] op_sel_hi:[0,1]
	v_exp_f32_e32 v60, v60
	v_exp_f32_e32 v61, v61
	v_pk_mul_f32 v[62:63], v[64:65], v[62:63]
	v_pk_mul_f32 v[64:65], v[70:71], v[72:73] op_sel_hi:[0,1]
	v_pk_mul_f32 v[64:65], v[66:67], v[64:65]
	v_pk_add_f32 v[66:67], v[74:75], 1.0 op_sel_hi:[1,0]
	v_pk_mul_f32 v[54:55], v[54:55], v[58:59]
	v_rcp_f32_e32 v66, v66
	v_rcp_f32_e32 v67, v67
	v_pk_add_f32 v[58:59], v[60:61], 1.0 op_sel_hi:[1,0]
	ds_read2_b32 v[60:61], v159 offset0:96 offset1:112
	v_rcp_f32_e32 v58, v58
	v_rcp_f32_e32 v59, v59
	v_pk_mul_f32 v[52:53], v[52:53], v[56:57]
	v_pk_mul_f32 v[56:57], v[70:71], v[66:67] op_sel_hi:[0,1]
	v_pk_mul_f32 v[56:57], v[52:53], v[56:57]
	v_pk_mul_f32 v[52:53], v[70:71], v[58:59] op_sel_hi:[0,1]
	v_pk_mul_f32 v[58:59], v[54:55], v[52:53]
	s_waitcnt lgkmcnt(0)
; #define PG8_LAS __attribute__((address_space(3)))
; #define PG8_BAR __builtin_amdgcn_s_barrier()
;     __device__ __forceinline__ void operator()(const f32x4 (&acc)[2][2][4][2], const Unit& u, int wr, int wc, int fr, int fq, PG8_LAS unsigned char* lds, int wid) const {
;         const int row0 = u.pm * BM + wr * 64 + fr, col0 = u.pn * HALF + wc * 32 + 8 * fq;
; #pragma unroll
;         for (int ai = 0; ai < 2; ++ai)
; #pragma unroll
;             for (int m = 0; m < 4; ++m) {
;                 bf16_t* p = H + (size_t)(row0 + ai * HALF + m * 16) * ldh + col0;
;                 const float rstd = __builtin_amdgcn_rsqf(*(const PG8_LAS float*)(lds + PRE_SLOT + wid * 512 + (m & 1) * 256 + (fr + 16 * ((ai * 4 + m) >> 1)) * 4) * (1.0f / 1024.0f) + 1e-6f);
;                 const float c1 = -1.44269504089f * rstd, r2 = rstd * rstd;
;                 f32x2 hh[4];
; #pragma unroll
;                 for (int q = 0; q < 4; ++q) {
;                     const f32x2 ag = {acc[ai][0][m][q >> 1][2 * (q & 1)], acc[ai][0][m][q >> 1][2 * (q & 1) + 1]};
;                     const f32x2 au = {acc[ai][1][m][q >> 1][2 * (q & 1)], acc[ai][1][m][q >> 1][2 * (q & 1) + 1]};
;                     const f32x2 t = ag * c1;
;                     f32x2 e; e.x = __builtin_amdgcn_exp2f(t.x); e.y = __builtin_amdgcn_exp2f(t.y);
;                     const f32x2 d = e + 1.0f;
;                     f32x2 r; r.x = __builtin_amdgcn_rcpf(d.x); r.y = __builtin_amdgcn_rcpf(d.y);
;                     hh[q] = (ag * au) * (r * r2);
;                 }
;                 u32x4 w; w.x = pk_bf16(hh[0].x, hh[0].y); w.y = pk_bf16(hh[1].x, hh[1].y); w.z = pk_bf16(hh[2].x, hh[2].y); w.w = pk_bf16(hh[3].x, hh[3].y);
;                 *(u32x4*)p = w;
; template <class Epi, class Sched, bool ALIGN_EPI = false, bool SP2 = false>
; __device__ __forceinline__ void gemm_phase(PG8_LAS unsigned char* lds, const Gemm g, const Sched& S, const Epi& E, int wave_s) {
;     ...
;         if (!has_next) break;
; #pragma unroll
;         for (int a = 0; a < 2; ++a)
; #pragma unroll
;             for (int b = 0; b < 2; ++b)
; #pragma unroll
;                 for (int m = 0; m < 4; ++m)
; #pragma unroll
;                     for (int n = 0; n < 2; ++n) acc[a][b][m][n] = (f32x4){0.f, 0.f, 0.f, 0.f};
;         cur = nxt; cA = nA; cB = nB; ++ui;
;         if constexpr (ALIGN_EPI) { if (wr == 1) PG8_BAR; }
	v_fmamk_f32 v55, v60, 0x3a800000, v148
	v_rsq_f32_e32 v60, v55
	v_lshl_add_u64 v[66:67], v[68:69], 0, v[116:117]
	v_cvt_pk_bf16_f32 v52, v62, v63
	v_cvt_pk_bf16_f32 v53, v64, v65
	v_cvt_pk_bf16_f32 v54, v56, v57
	v_cvt_pk_bf16_f32 v55, v58, v59
	global_store_dwordx4 v[66:67], v[52:55], off sc1
	v_mul_f32_e32 v58, v60, v60
	s_nop 0
	v_add_u32_e32 v53, 0x90, v0
	v_mul_f32_e32 v52, 0xbfb8aa3b, v60
	v_pk_mul_f32 v[54:55], v[44:45], v[52:53] op_sel_hi:[1,0]
	v_pk_mul_f32 v[62:63], v[46:47], v[52:53] op_sel_hi:[1,0]
	v_exp_f32_e32 v54, v54
	v_exp_f32_e32 v55, v55
	v_exp_f32_e32 v62, v62
	v_exp_f32_e32 v63, v63
	v_pk_mul_f32 v[46:47], v[46:47], v[50:51]
	v_pk_add_f32 v[54:55], v[54:55], 1.0 op_sel_hi:[1,0]
	v_pk_mul_f32 v[44:45], v[44:45], v[48:49]
	v_rcp_f32_e32 v54, v54
	v_rcp_f32_e32 v55, v55
	v_pk_add_f32 v[50:51], v[62:63], 1.0 op_sel_hi:[1,0]
	v_mad_i64_i32 v[56:57], s[6:7], v53, s88, v[2:3]
	v_rcp_f32_e32 v50, v50
	v_rcp_f32_e32 v51, v51
	v_pk_mul_f32 v[48:49], v[58:59], v[54:55] op_sel_hi:[0,1]
	v_pk_mul_f32 v[54:55], v[36:37], v[52:53] op_sel_hi:[1,0]
	v_pk_mul_f32 v[44:45], v[44:45], v[48:49]
	v_exp_f32_e32 v54, v54
	v_exp_f32_e32 v55, v55
	v_pk_mul_f32 v[48:49], v[58:59], v[50:51] op_sel_hi:[0,1]
	v_pk_mul_f32 v[50:51], v[38:39], v[52:53] op_sel_hi:[1,0]
	v_pk_mul_f32 v[46:47], v[46:47], v[48:49]
	v_exp_f32_e32 v50, v50
	v_exp_f32_e32 v51, v51
	v_pk_add_f32 v[48:49], v[54:55], 1.0 op_sel_hi:[1,0]
	v_pk_mul_f32 v[38:39], v[38:39], v[42:43]
	v_rcp_f32_e32 v48, v48
	v_rcp_f32_e32 v49, v49
	v_pk_add_f32 v[42:43], v[50:51], 1.0 op_sel_hi:[1,0]
	v_pk_mul_f32 v[36:37], v[36:37], v[40:41]
	v_rcp_f32_e32 v42, v42
	v_rcp_f32_e32 v43, v43
	v_pk_mul_f32 v[40:41], v[58:59], v[48:49] op_sel_hi:[0,1]
	v_pk_mul_f32 v[40:41], v[36:37], v[40:41]
	v_lshl_add_u64 v[48:49], v[56:57], 0, v[116:117]
	v_pk_mul_f32 v[36:37], v[58:59], v[42:43] op_sel_hi:[0,1]
	v_pk_mul_f32 v[42:43], v[38:39], v[36:37]
	v_fmamk_f32 v39, v81, 0x3a800000, v148
	v_cvt_pk_bf16_f32 v36, v44, v45
	v_rsq_f32_e32 v44, v39
	v_cvt_pk_bf16_f32 v37, v46, v47
	v_cvt_pk_bf16_f32 v38, v40, v41
	v_cvt_pk_bf16_f32 v39, v42, v43
	global_store_dwordx4 v[48:49], v[36:39], off sc1
	v_mul_f32_e32 v42, v44, v44
	s_nop 0
	v_add_u32_e32 v37, 0xa0, v0
	v_mul_f32_e32 v36, 0xbfb8aa3b, v44
	v_pk_mul_f32 v[38:39], v[28:29], v[36:37] op_sel_hi:[1,0]
	v_pk_mul_f32 v[44:45], v[30:31], v[36:37] op_sel_hi:[1,0]
	v_exp_f32_e32 v38, v38
	v_exp_f32_e32 v39, v39
	v_exp_f32_e32 v44, v44
	v_exp_f32_e32 v45, v45
	v_pk_mul_f32 v[30:31], v[30:31], v[34:35]
	v_pk_add_f32 v[38:39], v[38:39], 1.0 op_sel_hi:[1,0]
	v_pk_mul_f32 v[28:29], v[28:29], v[32:33]
	v_rcp_f32_e32 v38, v38
	v_rcp_f32_e32 v39, v39
	v_pk_add_f32 v[34:35], v[44:45], 1.0 op_sel_hi:[1,0]
	v_mad_i64_i32 v[40:41], s[6:7], v37, s88, v[2:3]
	v_rcp_f32_e32 v34, v34
	v_rcp_f32_e32 v35, v35
	v_pk_mul_f32 v[32:33], v[42:43], v[38:39] op_sel_hi:[0,1]
	v_pk_mul_f32 v[38:39], v[20:21], v[36:37] op_sel_hi:[1,0]
	v_pk_mul_f32 v[28:29], v[28:29], v[32:33]
	v_exp_f32_e32 v38, v38
	v_exp_f32_e32 v39, v39
	v_pk_mul_f32 v[32:33], v[42:43], v[34:35] op_sel_hi:[0,1]
	v_pk_mul_f32 v[34:35], v[22:23], v[36:37] op_sel_hi:[1,0]
	v_pk_mul_f32 v[30:31], v[30:31], v[32:33]
	v_exp_f32_e32 v34, v34
	v_exp_f32_e32 v35, v35
	v_pk_add_f32 v[32:33], v[38:39], 1.0 op_sel_hi:[1,0]
	v_pk_mul_f32 v[22:23], v[22:23], v[26:27]
	v_rcp_f32_e32 v32, v32
	v_rcp_f32_e32 v33, v33
	v_pk_add_f32 v[26:27], v[34:35], 1.0 op_sel_hi:[1,0]
	v_pk_mul_f32 v[20:21], v[20:21], v[24:25]
	v_rcp_f32_e32 v26, v26
	v_rcp_f32_e32 v27, v27
	v_pk_mul_f32 v[24:25], v[42:43], v[32:33] op_sel_hi:[0,1]
	v_pk_mul_f32 v[24:25], v[20:21], v[24:25]
	v_lshl_add_u64 v[32:33], v[40:41], 0, v[116:117]
	v_pk_mul_f32 v[20:21], v[42:43], v[26:27] op_sel_hi:[0,1]
	v_pk_mul_f32 v[26:27], v[22:23], v[20:21]
	v_fmamk_f32 v23, v61, 0x3a800000, v148
	v_cvt_pk_bf16_f32 v22, v24, v25
	v_rsq_f32_e32 v24, v23
	v_cvt_pk_bf16_f32 v20, v28, v29
	v_cvt_pk_bf16_f32 v21, v30, v31
	v_cvt_pk_bf16_f32 v23, v26, v27
	global_store_dwordx4 v[32:33], v[20:23], off sc1
	s_nop 1
	v_add_u32_e32 v22, 0xb0, v0
	v_mul_f32_e32 v0, 0xbfb8aa3b, v24
	v_pk_mul_f32 v[20:21], v[12:13], v[0:1] op_sel_hi:[1,0]
	v_mad_i64_i32 v[2:3], s[6:7], v22, s88, v[2:3]
	v_exp_f32_e32 v20, v20
	v_exp_f32_e32 v21, v21
	v_mul_f32_e32 v22, v24, v24
	v_pk_mul_f32 v[24:25], v[14:15], v[0:1] op_sel_hi:[1,0]
	v_pk_mul_f32 v[14:15], v[14:15], v[18:19]
	v_exp_f32_e32 v24, v24
	v_exp_f32_e32 v25, v25
	v_pk_add_f32 v[20:21], v[20:21], 1.0 op_sel_hi:[1,0]
	v_pk_mul_f32 v[12:13], v[12:13], v[16:17]
	v_rcp_f32_e32 v20, v20
	v_rcp_f32_e32 v21, v21
	v_pk_add_f32 v[18:19], v[24:25], 1.0 op_sel_hi:[1,0]
	v_pk_mul_f32 v[16:17], v[22:23], v[20:21] op_sel_hi:[0,1]
	v_rcp_f32_e32 v18, v18
	v_rcp_f32_e32 v19, v19
	v_pk_mul_f32 v[20:21], v[4:5], v[0:1] op_sel_hi:[1,0]
	v_pk_mul_f32 v[12:13], v[12:13], v[16:17]
	v_exp_f32_e32 v20, v20
	v_exp_f32_e32 v21, v21
	v_pk_mul_f32 v[16:17], v[22:23], v[18:19] op_sel_hi:[0,1]
	v_pk_mul_f32 v[18:19], v[6:7], v[0:1] op_sel_hi:[1,0]
	v_pk_mul_f32 v[14:15], v[14:15], v[16:17]
	v_exp_f32_e32 v18, v18
	v_exp_f32_e32 v19, v19
	v_pk_add_f32 v[16:17], v[20:21], 1.0 op_sel_hi:[1,0]
	v_pk_mul_f32 v[6:7], v[6:7], v[10:11]
	v_rcp_f32_e32 v16, v16
	v_rcp_f32_e32 v17, v17
	v_pk_add_f32 v[10:11], v[18:19], 1.0 op_sel_hi:[1,0]
	v_pk_mul_f32 v[4:5], v[4:5], v[8:9]
	v_rcp_f32_e32 v10, v10
	v_rcp_f32_e32 v11, v11
	v_pk_mul_f32 v[8:9], v[22:23], v[16:17] op_sel_hi:[0,1]
	v_pk_mul_f32 v[4:5], v[4:5], v[8:9]
	v_pk_mul_f32 v[8:9], v[22:23], v[10:11] op_sel_hi:[0,1]
	v_pk_mul_f32 v[6:7], v[6:7], v[8:9]
	v_lshl_add_u64 v[8:9], v[2:3], 0, v[116:117]
	v_cvt_pk_bf16_f32 v2, v12, v13
	v_cvt_pk_bf16_f32 v3, v14, v15
	v_cvt_pk_bf16_f32 v4, v4, v5
	v_cvt_pk_bf16_f32 v5, v6, v7
	global_store_dwordx4 v[8:9], v[2:5], off sc1
	s_cbranch_vccnz .LBB0_908
	s_andn2_b64 vcc, exec, s[12:13]
	s_cbranch_vccnz .LBB0_907
	s_barrier
	s_branch .LBB0_907

; __device__ __forceinline__ unsigned pk_bf16(float lo, float hi) { typedef __bf16 b2_t __attribute__((ext_vector_type(2))); f32x2 v = {lo, hi}; b2_t b = __builtin_convertvector(v, b2_t); return __builtin_bit_cast(unsigned, b); }
; #define LAS __attribute__((address_space(3)))
; __device__ __forceinline__ void transpose_tile(const float* W, const float* gain, int K, int N, int k0, int n0, bf16* WT, int drow0, LAS float* scr, int lane) {
;     f32x4 v[8]; float gv[8];
;     const int r0 = lane >> 3, c4 = lane & 7;
; #pragma unroll
;     for (int i = 0; i < 8; ++i) { v[i] = *(const f32x4*)(W + (size_t)(k0 + r0 + 8 * i) * N + n0 + 4 * c4); gv[i] = gain ? gain[k0 + r0 + 8 * i] : 1.0f; }
; #pragma unroll
;     for (int i = 0; i < 8; ++i) { LAS float* d = scr + (r0 + 8 * i) * 33 + 4 * c4; d[0] = v[i][0] * gv[i]; d[1] = v[i][1] * gv[i]; d[2] = v[i][2] * gv[i]; d[3] = v[i][3] * gv[i]; }
;     asm volatile("s_waitcnt lgkmcnt(0)" ::: "memory");
;     const int c = lane & 7;
; #pragma unroll
;     for (int j = 0; j < 4; ++j) { const int n = (lane >> 3) + 8 * j; const LAS float* s = scr + (8 * c) * 33 + n;
;         v4u o; o.x = pk_bf16(s[0 * 33], s[1 * 33]); o.y = pk_bf16(s[2 * 33], s[3 * 33]); o.z = pk_bf16(s[4 * 33], s[5 * 33]); o.w = pk_bf16(s[6 * 33], s[7 * 33]);
;         *(v4u*)(WT + (size_t)(drow0 + n) * K + k0 + 8 * c) = o; }
;     asm volatile("s_waitcnt lgkmcnt(0)" ::: "memory");
; }
; template <bool SWIGLU> __device__ __forceinline__ void transpose_item(const float* W, const float* gain, int K, int N, bf16* WT, LAS float* scr, int item, int lane) {
;     const int nblk = N / 32, kb = item / nblk, nb = item % nblk, n0 = 32 * nb;
;     int drow0 = n0;
;     if (SWIGLU) { const int up = n0 >= FF, f = up ? n0 - FF : n0; drow0 = 256 * (f >> 7) + (up ? 128 : 0) + (f & 127); }
;     transpose_tile(W, gain, K, N, 64 * kb, n0, WT, drow0, scr, lane);
; }
.LBB0_921:
	s_waitcnt vmcnt(0)
	v_pk_mul_f32 v[0:1], v[0:1], v[52:53] op_sel_hi:[1,0]
	ds_write2_b32 v65, v0, v1 offset1:1
	v_pk_mul_f32 v[0:1], v[2:3], v[52:53] op_sel_hi:[1,0]
	ds_write2_b32 v65, v0, v1 offset0:2 offset1:3
	v_pk_mul_f32 v[0:1], v[4:5], v[50:51] op_sel_hi:[1,0]
	ds_write2_b32 v67, v0, v1 offset1:1
	v_pk_mul_f32 v[0:1], v[6:7], v[50:51] op_sel_hi:[1,0]
	ds_write2_b32 v68, v0, v1 offset1:1
	v_pk_mul_f32 v[0:1], v[8:9], v[56:57] op_sel_hi:[1,0]
	ds_write2_b32 v69, v0, v1 offset1:1
	v_pk_mul_f32 v[0:1], v[10:11], v[56:57] op_sel_hi:[1,0]
	ds_write2_b32 v70, v0, v1 offset1:1
	v_pk_mul_f32 v[0:1], v[12:13], v[54:55] op_sel_hi:[1,0]
	ds_write2_b32 v71, v0, v1 offset1:1
	v_pk_mul_f32 v[0:1], v[14:15], v[54:55] op_sel_hi:[1,0]
	ds_write2_b32 v72, v0, v1 offset1:1
	v_pk_mul_f32 v[0:1], v[16:17], v[62:63] op_sel_hi:[1,0]
	ds_write2_b32 v73, v0, v1 offset1:1
	v_pk_mul_f32 v[0:1], v[18:19], v[62:63] op_sel_hi:[1,0]
	ds_write2_b32 v74, v0, v1 offset1:1
	v_pk_mul_f32 v[0:1], v[20:21], v[58:59] op_sel_hi:[1,0]
	ds_write2_b32 v75, v0, v1 offset1:1
	v_pk_mul_f32 v[0:1], v[22:23], v[58:59] op_sel_hi:[1,0]
	ds_write2_b32 v76, v0, v1 offset1:1
	v_pk_mul_f32 v[0:1], v[24:25], v[66:67] op_sel_hi:[1,0]
	s_mulk_i32 s6, 0xff50
	ds_write2_b32 v77, v0, v1 offset1:1
	v_pk_mul_f32 v[0:1], v[26:27], v[66:67] op_sel_hi:[1,0]
	s_add_i32 s6, s22, s6
	s_add_i32 s7, s18, 0xfffff500
	ds_write2_b32 v78, v0, v1 offset1:1
	v_pk_mul_f32 v[0:1], v[28:29], v[64:65] op_sel_hi:[1,0]
	s_cmpk_gt_i32 s6, 0x57
	ds_write2_b32 v79, v0, v1 offset1:1
	v_pk_mul_f32 v[0:1], v[30:31], v[64:65] op_sel_hi:[1,0]
	s_cselect_b32 s6, s7, s18
	ds_write2_b32 v80, v0, v1 offset1:1
	s_cselect_b32 s7, 0x80, 0
	s_lshl_b32 s8, s6, 1
	s_and_b32 s6, s6, 0x60
	s_waitcnt lgkmcnt(0)
	s_and_b32 s8, s8, 0xffffff00
	s_or_b32 s6, s6, s7
	ds_read2_b32 v[4:5], v63 offset0:33 offset1:41
	ds_read2_b32 v[6:7], v63 offset1:8
	ds_read2_b32 v[8:9], v63 offset0:66 offset1:74
	ds_read2_b32 v[10:11], v63 offset0:99 offset1:107
	ds_read2_b32 v[12:13], v63 offset0:132 offset1:140
	ds_read2_b32 v[14:15], v63 offset0:165 offset1:173
	ds_read2_b32 v[16:17], v63 offset0:198 offset1:206
	ds_read2_b32 v[18:19], v63 offset0:231 offset1:239
	s_or_b32 s6, s6, s8
	v_add_u32_e32 v22, s6, v51
	s_ashr_i32 s13, s12, 31
	v_ashrrev_i32_e32 v23, 31, v22
	v_lshl_add_u64 v[20:21], s[12:13], 1, v[48:49]
	v_lshlrev_b64 v[22:23], 11, v[22:23]
	s_waitcnt lgkmcnt(6)
	v_cvt_pk_bf16_f32 v0, v6, v4
	s_waitcnt lgkmcnt(4)
	v_cvt_pk_bf16_f32 v1, v8, v10
	s_waitcnt lgkmcnt(2)
	v_cvt_pk_bf16_f32 v2, v12, v14
	s_waitcnt lgkmcnt(0)
	v_cvt_pk_bf16_f32 v3, v16, v18
	v_lshl_add_u64 v[22:23], v[20:21], 0, v[22:23]
	v_add_u32_e32 v4, s6, v53
	global_store_dwordx4 v[22:23], v[0:3], off sc1
	s_nop 1
	v_cvt_pk_bf16_f32 v0, v7, v5
	v_ashrrev_i32_e32 v5, 31, v4
	v_cvt_pk_bf16_f32 v1, v9, v11
	v_cvt_pk_bf16_f32 v2, v13, v15
	v_cvt_pk_bf16_f32 v3, v17, v19
	v_lshlrev_b64 v[4:5], 11, v[4:5]
	ds_read2_b32 v[6:7], v63 offset0:49 offset1:57
	ds_read2_b32 v[8:9], v63 offset0:16 offset1:24
	ds_read2_b32 v[10:11], v63 offset0:82 offset1:90
	ds_read2_b32 v[12:13], v63 offset0:115 offset1:123
	ds_read2_b32 v[14:15], v63 offset0:148 offset1:156
	ds_read2_b32 v[16:17], v63 offset0:181 offset1:189
	ds_read2_b32 v[18:19], v63 offset0:214 offset1:222
	ds_read2_b32 v[22:23], v63 offset0:247 offset1:255
	v_lshl_add_u64 v[4:5], v[20:21], 0, v[4:5]
	global_store_dwordx4 v[4:5], v[0:3], off sc1
	v_add_u32_e32 v4, s6, v55
	v_ashrrev_i32_e32 v5, 31, v4
	v_lshlrev_b64 v[4:5], 11, v[4:5]
	s_waitcnt lgkmcnt(6)
	v_cvt_pk_bf16_f32 v0, v8, v6
	s_waitcnt lgkmcnt(4)
	v_cvt_pk_bf16_f32 v1, v10, v12
	s_waitcnt lgkmcnt(2)
	v_cvt_pk_bf16_f32 v2, v14, v16
	s_waitcnt lgkmcnt(0)
	v_cvt_pk_bf16_f32 v3, v18, v22
	v_lshl_add_u64 v[4:5], v[20:21], 0, v[4:5]
	global_store_dwordx4 v[4:5], v[0:3], off sc1
	v_add_u32_e32 v4, s6, v59
	v_ashrrev_i32_e32 v5, 31, v4
	v_lshlrev_b64 v[4:5], 11, v[4:5]
	v_cvt_pk_bf16_f32 v0, v9, v7
	v_cvt_pk_bf16_f32 v1, v11, v13
	v_cvt_pk_bf16_f32 v2, v15, v17
	v_cvt_pk_bf16_f32 v3, v19, v23
	v_lshl_add_u64 v[4:5], v[20:21], 0, v[4:5]
	global_store_dwordx4 v[4:5], v[0:3], off sc1
	s_waitcnt lgkmcnt(0)

; __device__ __forceinline__ unsigned pk_bf16(float lo, float hi) { typedef __bf16 b2_t __attribute__((ext_vector_type(2))); f32x2 v = {lo, hi}; b2_t b = __builtin_convertvector(v, b2_t); return __builtin_bit_cast(unsigned, b); }
; #define LAS __attribute__((address_space(3)))
; __device__ __forceinline__ void transpose_tile(const float* W, const float* gain, int K, int N, int k0, int n0, bf16* WT, int drow0, LAS float* scr, int lane) {
;     f32x4 v[8]; float gv[8];
;     const int r0 = lane >> 3, c4 = lane & 7;
; #pragma unroll
;     for (int i = 0; i < 8; ++i) { v[i] = *(const f32x4*)(W + (size_t)(k0 + r0 + 8 * i) * N + n0 + 4 * c4); gv[i] = gain ? gain[k0 + r0 + 8 * i] : 1.0f; }
; #pragma unroll
;     for (int i = 0; i < 8; ++i) { LAS float* d = scr + (r0 + 8 * i) * 33 + 4 * c4; d[0] = v[i][0] * gv[i]; d[1] = v[i][1] * gv[i]; d[2] = v[i][2] * gv[i]; d[3] = v[i][3] * gv[i]; }
;     asm volatile("s_waitcnt lgkmcnt(0)" ::: "memory");
;     const int c = lane & 7;
; #pragma unroll
;     for (int j = 0; j < 4; ++j) { const int n = (lane >> 3) + 8 * j; const LAS float* s = scr + (8 * c) * 33 + n;
;         v4u o; o.x = pk_bf16(s[0 * 33], s[1 * 33]); o.y = pk_bf16(s[2 * 33], s[3 * 33]); o.z = pk_bf16(s[4 * 33], s[5 * 33]); o.w = pk_bf16(s[6 * 33], s[7 * 33]);
;         *(v4u*)(WT + (size_t)(drow0 + n) * K + k0 + 8 * c) = o; }
;     asm volatile("s_waitcnt lgkmcnt(0)" ::: "memory");
; }
.LBB0_923:
	s_cmpk_gt_i32 s22, 0xaff
	s_mov_b64 s[8:9], -1
	s_cbranch_scc0 .LBB0_997
	s_cmpk_gt_u32 s22, 0x107f
	s_cbranch_scc0 .LBB0_994
	s_cmpk_gt_u32 s22, 0x167f
	s_cbranch_scc0 .LBB0_975
	s_cmpk_gt_u32 s22, 0x187f
	s_cbranch_scc0 .LBB0_972
	s_cmpk_gt_u32 s22, 0x237f
	s_cbranch_scc0 .LBB0_953
	s_cmpk_gt_u32 s22, 0x28ff
	s_cbranch_scc0 .LBB0_950
	s_cmpk_gt_u32 s22, 0x33ff
	s_cbranch_scc0 .LBB0_931
	s_mov_b32 s6, 14
	s_ashr_i32 s7, s6, 31
	s_lshl_b64 s[6:7], s[6:7], 3
	s_add_u32 s6, s0, s6
	s_addc_u32 s7, s1, s7
	s_load_dwordx2 s[6:7], s[6:7], 0x0
	s_lshl_b32 s8, s22, 5
	s_and_b32 s8, s8, 0x3e0
	s_and_b32 s9, s25, 0x1ffc0
	s_lshl_b32 s10, s8, 2
	v_add_u32_e32 v0, s9, v51
	s_waitcnt lgkmcnt(0)
	s_add_u32 s6, s6, s10
	s_addc_u32 s7, s7, 0
	v_ashrrev_i32_e32 v1, 31, v0
	v_lshl_add_u64 v[2:3], s[6:7], 0, v[32:33]
	v_lshlrev_b64 v[0:1], 12, v[0:1]
	v_lshl_add_u64 v[28:29], v[2:3], 0, v[0:1]
	v_add_co_u32_e32 v4, vcc, s27, v28
	s_lshl_b32 s10, s9, 1
	s_nop 0
	v_addc_co_u32_e32 v5, vcc, 0, v29, vcc
	v_add_co_u32_e32 v8, vcc, s28, v28
	global_load_dwordx4 v[0:3], v[28:29], off
	s_nop 0
	global_load_dwordx4 v[4:7], v[4:5], off
	v_addc_co_u32_e32 v9, vcc, 0, v29, vcc
	v_add_co_u32_e32 v12, vcc, s29, v28
	v_add_u32_e32 v50, s8, v51
	s_nop 0
	v_addc_co_u32_e32 v13, vcc, 0, v29, vcc
	v_add_co_u32_e32 v16, vcc, s30, v28
	global_load_dwordx4 v[8:11], v[8:9], off
	s_nop 0
	global_load_dwordx4 v[12:15], v[12:13], off
	v_addc_co_u32_e32 v17, vcc, 0, v29, vcc
	v_add_co_u32_e32 v20, vcc, s31, v28
	v_lshl_add_u64 v[56:57], v[34:35], 0, s[10:11]
	s_nop 0
	v_addc_co_u32_e32 v21, vcc, 0, v29, vcc
	global_load_dwordx4 v[16:19], v[16:17], off
	s_nop 0
	global_load_dwordx4 v[20:23], v[20:21], off
	v_add_co_u32_e32 v24, vcc, s34, v28
	v_add_u32_e32 v52, s8, v53
	s_nop 0
	v_addc_co_u32_e32 v25, vcc, 0, v29, vcc
	global_load_dwordx4 v[24:27], v[24:25], off
	v_add_co_u32_e32 v28, vcc, s35, v28
	v_mad_i64_i32 v[60:61], s[6:7], v50, s36, v[56:57]
	s_nop 0
	v_addc_co_u32_e32 v29, vcc, 0, v29, vcc
	global_load_dwordx4 v[28:31], v[28:29], off
	v_mad_i64_i32 v[82:83], s[6:7], v52, s36, v[56:57]
	s_waitcnt vmcnt(0)
	ds_write2_b32 v65, v0, v1 offset1:1
	ds_write2_b32 v65, v2, v3 offset0:2 offset1:3
	ds_write2_b32 v67, v4, v5 offset1:1
	ds_write2_b32 v68, v6, v7 offset1:1
	ds_write2_b32 v69, v8, v9 offset1:1
	ds_write2_b32 v70, v10, v11 offset1:1
	ds_write2_b32 v71, v12, v13 offset1:1
	ds_write2_b32 v72, v14, v15 offset1:1
	ds_write2_b32 v73, v16, v17 offset1:1
	ds_write2_b32 v74, v18, v19 offset1:1
	ds_write2_b32 v75, v20, v21 offset1:1
	ds_write2_b32 v76, v22, v23 offset1:1
	ds_write2_b32 v77, v24, v25 offset1:1
	ds_write2_b32 v78, v26, v27 offset1:1
	ds_write2_b32 v79, v28, v29 offset1:1
	ds_write2_b32 v80, v30, v31 offset1:1
	s_waitcnt lgkmcnt(0)
	ds_read2_b32 v[4:5], v63 offset0:33 offset1:41
	ds_read2_b32 v[6:7], v63 offset1:8
	ds_read2_b32 v[8:9], v63 offset0:66 offset1:74
	ds_read2_b32 v[10:11], v63 offset0:99 offset1:107
	ds_read2_b32 v[12:13], v63 offset0:132 offset1:140
	ds_read2_b32 v[14:15], v63 offset0:165 offset1:173
	ds_read2_b32 v[16:17], v63 offset0:198 offset1:206
	ds_read2_b32 v[18:19], v63 offset0:231 offset1:239
	ds_read2_b32 v[20:21], v63 offset0:49 offset1:57
	ds_read2_b32 v[22:23], v63 offset0:16 offset1:24
	ds_read2_b32 v[24:25], v63 offset0:82 offset1:90
	ds_read2_b32 v[26:27], v63 offset0:115 offset1:123
	ds_read2_b32 v[28:29], v63 offset0:148 offset1:156
	ds_read2_b32 v[30:31], v63 offset0:181 offset1:189
	ds_read2_b32 v[84:85], v63 offset0:214 offset1:222
	ds_read2_b32 v[86:87], v63 offset0:247 offset1:255
	s_waitcnt lgkmcnt(14)
	v_cvt_pk_bf16_f32 v0, v6, v4
	s_waitcnt lgkmcnt(12)
	v_cvt_pk_bf16_f32 v1, v8, v10
	s_waitcnt lgkmcnt(10)
	v_cvt_pk_bf16_f32 v2, v12, v14
	s_waitcnt lgkmcnt(8)
	v_cvt_pk_bf16_f32 v3, v16, v18
	v_cvt_pk_bf16_f32 v4, v7, v5
	v_cvt_pk_bf16_f32 v5, v9, v11
	v_cvt_pk_bf16_f32 v6, v13, v15
	v_cvt_pk_bf16_f32 v7, v17, v19
	global_store_dwordx4 v[60:61], v[0:3], off sc1
	global_store_dwordx4 v[82:83], v[4:7], off sc1
	s_waitcnt lgkmcnt(6)
	v_cvt_pk_bf16_f32 v0, v22, v20
	v_add_u32_e32 v4, s8, v55
	s_waitcnt lgkmcnt(4)
	v_cvt_pk_bf16_f32 v1, v24, v26
	s_waitcnt lgkmcnt(2)
	v_cvt_pk_bf16_f32 v2, v28, v30
	s_waitcnt lgkmcnt(0)
	v_cvt_pk_bf16_f32 v3, v84, v86
	v_mad_i64_i32 v[4:5], s[6:7], v4, s36, v[56:57]
	global_store_dwordx4 v[4:5], v[0:3], off sc1
	v_add_u32_e32 v4, s8, v59
	v_mad_i64_i32 v[4:5], s[6:7], v4, s36, v[56:57]
	v_cvt_pk_bf16_f32 v0, v23, v21
	v_cvt_pk_bf16_f32 v1, v25, v27
	v_cvt_pk_bf16_f32 v2, v29, v31
	v_cvt_pk_bf16_f32 v3, v85, v87
	global_store_dwordx4 v[4:5], v[0:3], off sc1
	s_waitcnt lgkmcnt(0)
	s_mov_b64 s[8:9], 0

; __device__ __forceinline__ unsigned pk_bf16(float lo, float hi) { typedef __bf16 b2_t __attribute__((ext_vector_type(2))); f32x2 v = {lo, hi}; b2_t b = __builtin_convertvector(v, b2_t); return __builtin_bit_cast(unsigned, b); }
; #define LAS __attribute__((address_space(3)))
; __device__ __forceinline__ void transpose_tile(const float* W, const float* gain, int K, int N, int k0, int n0, bf16* WT, int drow0, LAS float* scr, int lane) {
;     f32x4 v[8]; float gv[8];
;     const int r0 = lane >> 3, c4 = lane & 7;
; #pragma unroll
;     for (int i = 0; i < 8; ++i) { v[i] = *(const f32x4*)(W + (size_t)(k0 + r0 + 8 * i) * N + n0 + 4 * c4); gv[i] = gain ? gain[k0 + r0 + 8 * i] : 1.0f; }
; #pragma unroll
;     for (int i = 0; i < 8; ++i) { LAS float* d = scr + (r0 + 8 * i) * 33 + 4 * c4; d[0] = v[i][0] * gv[i]; d[1] = v[i][1] * gv[i]; d[2] = v[i][2] * gv[i]; d[3] = v[i][3] * gv[i]; }
;     asm volatile("s_waitcnt lgkmcnt(0)" ::: "memory");
;     const int c = lane & 7;
; #pragma unroll
;     for (int j = 0; j < 4; ++j) { const int n = (lane >> 3) + 8 * j; const LAS float* s = scr + (8 * c) * 33 + n;
;         v4u o; o.x = pk_bf16(s[0 * 33], s[1 * 33]); o.y = pk_bf16(s[2 * 33], s[3 * 33]); o.z = pk_bf16(s[4 * 33], s[5 * 33]); o.w = pk_bf16(s[6 * 33], s[7 * 33]);
;         *(v4u*)(WT + (size_t)(drow0 + n) * K + k0 + 8 * c) = o; }
;     asm volatile("s_waitcnt lgkmcnt(0)" ::: "memory");
; }
; template <bool SWIGLU> __device__ __forceinline__ void transpose_item(const float* W, const float* gain, int K, int N, bf16* WT, LAS float* scr, int item, int lane) {
;     const int nblk = N / 32, kb = item / nblk, nb = item % nblk, n0 = 32 * nb;
;     int drow0 = n0;
;     if (SWIGLU) { const int up = n0 >= FF, f = up ? n0 - FF : n0; drow0 = 256 * (f >> 7) + (up ? 128 : 0) + (f & 127); }
;     transpose_tile(W, gain, K, N, 64 * kb, n0, WT, drow0, scr, lane);
; }
.LBB0_948:
	s_waitcnt vmcnt(0)
	v_pk_mul_f32 v[0:1], v[0:1], v[52:53] op_sel_hi:[1,0]
	ds_write2_b32 v65, v0, v1 offset1:1
	v_pk_mul_f32 v[0:1], v[2:3], v[52:53] op_sel_hi:[1,0]
	ds_write2_b32 v65, v0, v1 offset0:2 offset1:3
	v_pk_mul_f32 v[0:1], v[4:5], v[50:51] op_sel_hi:[1,0]
	ds_write2_b32 v67, v0, v1 offset1:1
	v_pk_mul_f32 v[0:1], v[6:7], v[50:51] op_sel_hi:[1,0]
	ds_write2_b32 v68, v0, v1 offset1:1
	v_pk_mul_f32 v[0:1], v[8:9], v[56:57] op_sel_hi:[1,0]
	ds_write2_b32 v69, v0, v1 offset1:1
	v_pk_mul_f32 v[0:1], v[10:11], v[56:57] op_sel_hi:[1,0]
	ds_write2_b32 v70, v0, v1 offset1:1
	v_pk_mul_f32 v[0:1], v[12:13], v[54:55] op_sel_hi:[1,0]
	ds_write2_b32 v71, v0, v1 offset1:1
	v_pk_mul_f32 v[0:1], v[14:15], v[54:55] op_sel_hi:[1,0]
	ds_write2_b32 v72, v0, v1 offset1:1
	v_pk_mul_f32 v[0:1], v[16:17], v[62:63] op_sel_hi:[1,0]
	ds_write2_b32 v73, v0, v1 offset1:1
	v_pk_mul_f32 v[0:1], v[18:19], v[62:63] op_sel_hi:[1,0]
	ds_write2_b32 v74, v0, v1 offset1:1
	v_pk_mul_f32 v[0:1], v[20:21], v[58:59] op_sel_hi:[1,0]
	ds_write2_b32 v75, v0, v1 offset1:1
	v_pk_mul_f32 v[0:1], v[22:23], v[58:59] op_sel_hi:[1,0]
	s_lshl_b32 s8, s7, 5
	ds_write2_b32 v76, v0, v1 offset1:1
	v_pk_mul_f32 v[0:1], v[24:25], v[66:67] op_sel_hi:[1,0]
	s_and_b32 s8, 0xffff, s8
	ds_write2_b32 v77, v0, v1 offset1:1
	v_pk_mul_f32 v[0:1], v[26:27], v[66:67] op_sel_hi:[1,0]
	s_and_b32 s7, 0xffff, s7
	s_add_i32 s9, s8, 0xfffff500
	ds_write2_b32 v78, v0, v1 offset1:1
	v_pk_mul_f32 v[0:1], v[28:29], v[64:65] op_sel_hi:[1,0]
	s_cmpk_gt_u32 s7, 0x57
	ds_write2_b32 v79, v0, v1 offset1:1
	v_pk_mul_f32 v[0:1], v[30:31], v[64:65] op_sel_hi:[1,0]
	s_cselect_b32 s7, s9, s8
	ds_write2_b32 v80, v0, v1 offset1:1
	s_cselect_b32 s8, 0x80, 0
	s_lshl_b32 s9, s7, 1
	s_and_b32 s7, s7, 0x60
	s_waitcnt lgkmcnt(0)
	s_and_b32 s9, s9, 0xffffff00
	s_or_b32 s7, s7, s8
	ds_read2_b32 v[4:5], v63 offset0:33 offset1:41
	ds_read2_b32 v[6:7], v63 offset1:8
	ds_read2_b32 v[8:9], v63 offset0:66 offset1:74
	ds_read2_b32 v[10:11], v63 offset0:99 offset1:107
	ds_read2_b32 v[12:13], v63 offset0:132 offset1:140
	ds_read2_b32 v[14:15], v63 offset0:165 offset1:173
	ds_read2_b32 v[16:17], v63 offset0:198 offset1:206
	ds_read2_b32 v[18:19], v63 offset0:231 offset1:239
	s_or_b32 s7, s7, s9
	s_and_b32 s6, 0xffff, s6
	v_add_u32_e32 v22, s7, v51
	s_lshl_b32 s10, s6, 1
	v_ashrrev_i32_e32 v23, 31, v22
	v_lshl_add_u64 v[20:21], v[36:37], 0, s[10:11]
	v_lshlrev_b64 v[22:23], 11, v[22:23]
	s_waitcnt lgkmcnt(6)
	v_cvt_pk_bf16_f32 v0, v6, v4
	s_waitcnt lgkmcnt(4)
	v_cvt_pk_bf16_f32 v1, v8, v10
	s_waitcnt lgkmcnt(2)
	v_cvt_pk_bf16_f32 v2, v12, v14
	s_waitcnt lgkmcnt(0)
	v_cvt_pk_bf16_f32 v3, v16, v18
	v_lshl_add_u64 v[22:23], v[20:21], 0, v[22:23]
	v_add_u32_e32 v4, s7, v53
	global_store_dwordx4 v[22:23], v[0:3], off sc1
	s_nop 1
	v_cvt_pk_bf16_f32 v0, v7, v5
	v_ashrrev_i32_e32 v5, 31, v4
	v_cvt_pk_bf16_f32 v1, v9, v11
	v_cvt_pk_bf16_f32 v2, v13, v15
	v_cvt_pk_bf16_f32 v3, v17, v19
	v_lshlrev_b64 v[4:5], 11, v[4:5]
	ds_read2_b32 v[6:7], v63 offset0:49 offset1:57
	ds_read2_b32 v[8:9], v63 offset0:16 offset1:24
	ds_read2_b32 v[10:11], v63 offset0:82 offset1:90
	ds_read2_b32 v[12:13], v63 offset0:115 offset1:123
	ds_read2_b32 v[14:15], v63 offset0:148 offset1:156
	ds_read2_b32 v[16:17], v63 offset0:181 offset1:189
	ds_read2_b32 v[18:19], v63 offset0:214 offset1:222
	ds_read2_b32 v[22:23], v63 offset0:247 offset1:255
	v_lshl_add_u64 v[4:5], v[20:21], 0, v[4:5]
	global_store_dwordx4 v[4:5], v[0:3], off sc1
	v_add_u32_e32 v4, s7, v55
	v_ashrrev_i32_e32 v5, 31, v4
	v_lshlrev_b64 v[4:5], 11, v[4:5]
	s_waitcnt lgkmcnt(6)
	v_cvt_pk_bf16_f32 v0, v8, v6
	s_waitcnt lgkmcnt(4)
	v_cvt_pk_bf16_f32 v1, v10, v12
	s_waitcnt lgkmcnt(2)
	v_cvt_pk_bf16_f32 v2, v14, v16
	s_waitcnt lgkmcnt(0)
	v_cvt_pk_bf16_f32 v3, v18, v22
	v_lshl_add_u64 v[4:5], v[20:21], 0, v[4:5]
	global_store_dwordx4 v[4:5], v[0:3], off sc1
	v_add_u32_e32 v4, s7, v59
	v_ashrrev_i32_e32 v5, 31, v4
	v_lshlrev_b64 v[4:5], 11, v[4:5]
	v_cvt_pk_bf16_f32 v0, v9, v7
	v_cvt_pk_bf16_f32 v1, v11, v13
	v_cvt_pk_bf16_f32 v2, v15, v17
	v_cvt_pk_bf16_f32 v3, v19, v23
	v_lshl_add_u64 v[4:5], v[20:21], 0, v[4:5]
	global_store_dwordx4 v[4:5], v[0:3], off sc1
	s_waitcnt lgkmcnt(0)

; __device__ __forceinline__ unsigned pk_bf16(float lo, float hi) { typedef __bf16 b2_t __attribute__((ext_vector_type(2))); f32x2 v = {lo, hi}; b2_t b = __builtin_convertvector(v, b2_t); return __builtin_bit_cast(unsigned, b); }
; #define LAS __attribute__((address_space(3)))
; __device__ __forceinline__ void transpose_tile(const float* W, const float* gain, int K, int N, int k0, int n0, bf16* WT, int drow0, LAS float* scr, int lane) {
;     f32x4 v[8]; float gv[8];
;     const int r0 = lane >> 3, c4 = lane & 7;
; #pragma unroll
;     for (int i = 0; i < 8; ++i) { v[i] = *(const f32x4*)(W + (size_t)(k0 + r0 + 8 * i) * N + n0 + 4 * c4); gv[i] = gain ? gain[k0 + r0 + 8 * i] : 1.0f; }
; #pragma unroll
;     for (int i = 0; i < 8; ++i) { LAS float* d = scr + (r0 + 8 * i) * 33 + 4 * c4; d[0] = v[i][0] * gv[i]; d[1] = v[i][1] * gv[i]; d[2] = v[i][2] * gv[i]; d[3] = v[i][3] * gv[i]; }
;     asm volatile("s_waitcnt lgkmcnt(0)" ::: "memory");
;     const int c = lane & 7;
; #pragma unroll
;     for (int j = 0; j < 4; ++j) { const int n = (lane >> 3) + 8 * j; const LAS float* s = scr + (8 * c) * 33 + n;
;         v4u o; o.x = pk_bf16(s[0 * 33], s[1 * 33]); o.y = pk_bf16(s[2 * 33], s[3 * 33]); o.z = pk_bf16(s[4 * 33], s[5 * 33]); o.w = pk_bf16(s[6 * 33], s[7 * 33]);
;         *(v4u*)(WT + (size_t)(drow0 + n) * K + k0 + 8 * c) = o; }
;     asm volatile("s_waitcnt lgkmcnt(0)" ::: "memory");
; }
.LBB0_950:
	s_andn2_b64 vcc, exec, s[8:9]
	s_cbranch_vccnz .LBB0_952
	s_mov_b32 s6, 11
	s_ashr_i32 s7, s6, 31
	s_lshl_b64 s[6:7], s[6:7], 3
	s_add_u32 s6, s0, s6
	s_addc_u32 s7, s1, s7
	s_load_dwordx2 s[6:7], s[6:7], 0x0
	s_lshl_b32 s8, s22, 5
	s_and_b32 s8, s8, 0x3e0
	s_add_i32 s9, s25, 0x2100
	s_and_b32 s9, s9, 0x1ffc0
	s_lshl_b32 s10, s8, 2
	v_add_u32_e32 v0, s9, v51
	s_waitcnt lgkmcnt(0)
	s_add_u32 s6, s6, s10
	s_addc_u32 s7, s7, 0
	v_ashrrev_i32_e32 v1, 31, v0
	v_lshl_add_u64 v[2:3], s[6:7], 0, v[32:33]
	v_lshlrev_b64 v[0:1], 12, v[0:1]
	v_lshl_add_u64 v[28:29], v[2:3], 0, v[0:1]
	v_add_co_u32_e32 v4, vcc, s27, v28
	s_lshl_b32 s10, s9, 1
	s_nop 0
	v_addc_co_u32_e32 v5, vcc, 0, v29, vcc
	v_add_co_u32_e32 v8, vcc, s28, v28
	global_load_dwordx4 v[0:3], v[28:29], off
	s_nop 0
	global_load_dwordx4 v[4:7], v[4:5], off
	v_addc_co_u32_e32 v9, vcc, 0, v29, vcc
	v_add_co_u32_e32 v12, vcc, s29, v28
	v_add_u32_e32 v50, s8, v51
	s_nop 0
	v_addc_co_u32_e32 v13, vcc, 0, v29, vcc
	v_add_co_u32_e32 v16, vcc, s30, v28
	global_load_dwordx4 v[8:11], v[8:9], off
	s_nop 0
	global_load_dwordx4 v[12:15], v[12:13], off
	v_addc_co_u32_e32 v17, vcc, 0, v29, vcc
	v_add_co_u32_e32 v20, vcc, s31, v28
	v_lshl_add_u64 v[56:57], v[38:39], 0, s[10:11]
	s_nop 0
	v_addc_co_u32_e32 v21, vcc, 0, v29, vcc
	global_load_dwordx4 v[16:19], v[16:17], off
	s_nop 0
	global_load_dwordx4 v[20:23], v[20:21], off
	v_add_co_u32_e32 v24, vcc, s34, v28
	v_add_u32_e32 v52, s8, v53
	s_nop 0
	v_addc_co_u32_e32 v25, vcc, 0, v29, vcc
	global_load_dwordx4 v[24:27], v[24:25], off
	v_add_co_u32_e32 v28, vcc, s35, v28
	v_mad_i64_i32 v[60:61], s[6:7], v50, s36, v[56:57]
	s_nop 0
	v_addc_co_u32_e32 v29, vcc, 0, v29, vcc
	global_load_dwordx4 v[28:31], v[28:29], off
	v_mad_i64_i32 v[82:83], s[6:7], v52, s36, v[56:57]
	s_waitcnt vmcnt(0)
	ds_write2_b32 v65, v0, v1 offset1:1
	ds_write2_b32 v65, v2, v3 offset0:2 offset1:3
	ds_write2_b32 v67, v4, v5 offset1:1
	ds_write2_b32 v68, v6, v7 offset1:1
	ds_write2_b32 v69, v8, v9 offset1:1
	ds_write2_b32 v70, v10, v11 offset1:1
	ds_write2_b32 v71, v12, v13 offset1:1
	ds_write2_b32 v72, v14, v15 offset1:1
	ds_write2_b32 v73, v16, v17 offset1:1
	ds_write2_b32 v74, v18, v19 offset1:1
	ds_write2_b32 v75, v20, v21 offset1:1
	ds_write2_b32 v76, v22, v23 offset1:1
	ds_write2_b32 v77, v24, v25 offset1:1
	ds_write2_b32 v78, v26, v27 offset1:1
	ds_write2_b32 v79, v28, v29 offset1:1
	ds_write2_b32 v80, v30, v31 offset1:1
	s_waitcnt lgkmcnt(0)
	ds_read2_b32 v[4:5], v63 offset0:33 offset1:41
	ds_read2_b32 v[6:7], v63 offset1:8
	ds_read2_b32 v[8:9], v63 offset0:66 offset1:74
	ds_read2_b32 v[10:11], v63 offset0:99 offset1:107
	ds_read2_b32 v[12:13], v63 offset0:132 offset1:140
	ds_read2_b32 v[14:15], v63 offset0:165 offset1:173
	ds_read2_b32 v[16:17], v63 offset0:198 offset1:206
	ds_read2_b32 v[18:19], v63 offset0:231 offset1:239
	ds_read2_b32 v[20:21], v63 offset0:49 offset1:57
	ds_read2_b32 v[22:23], v63 offset0:16 offset1:24
	ds_read2_b32 v[24:25], v63 offset0:82 offset1:90
	ds_read2_b32 v[26:27], v63 offset0:115 offset1:123
	ds_read2_b32 v[28:29], v63 offset0:148 offset1:156
	ds_read2_b32 v[30:31], v63 offset0:181 offset1:189
	ds_read2_b32 v[84:85], v63 offset0:214 offset1:222
	ds_read2_b32 v[86:87], v63 offset0:247 offset1:255
	s_waitcnt lgkmcnt(14)
	v_cvt_pk_bf16_f32 v0, v6, v4
	s_waitcnt lgkmcnt(12)
	v_cvt_pk_bf16_f32 v1, v8, v10
	s_waitcnt lgkmcnt(10)
	v_cvt_pk_bf16_f32 v2, v12, v14
	s_waitcnt lgkmcnt(8)
	v_cvt_pk_bf16_f32 v3, v16, v18
	v_cvt_pk_bf16_f32 v4, v7, v5
	v_cvt_pk_bf16_f32 v5, v9, v11
	v_cvt_pk_bf16_f32 v6, v13, v15
	v_cvt_pk_bf16_f32 v7, v17, v19
	global_store_dwordx4 v[60:61], v[0:3], off sc1
	global_store_dwordx4 v[82:83], v[4:7], off sc1
	s_waitcnt lgkmcnt(6)
	v_cvt_pk_bf16_f32 v0, v22, v20
	v_add_u32_e32 v4, s8, v55
	s_waitcnt lgkmcnt(4)
	v_cvt_pk_bf16_f32 v1, v24, v26
	s_waitcnt lgkmcnt(2)
	v_cvt_pk_bf16_f32 v2, v28, v30
	s_waitcnt lgkmcnt(0)
	v_cvt_pk_bf16_f32 v3, v84, v86
	v_mad_i64_i32 v[4:5], s[6:7], v4, s36, v[56:57]
	global_store_dwordx4 v[4:5], v[0:3], off sc1
	v_add_u32_e32 v4, s8, v59
	v_mad_i64_i32 v[4:5], s[6:7], v4, s36, v[56:57]
	v_cvt_pk_bf16_f32 v0, v23, v21
	v_cvt_pk_bf16_f32 v1, v25, v27
	v_cvt_pk_bf16_f32 v2, v29, v31
	v_cvt_pk_bf16_f32 v3, v85, v87
	global_store_dwordx4 v[4:5], v[0:3], off sc1
	s_waitcnt lgkmcnt(0)

; __device__ __forceinline__ unsigned pk_bf16(float lo, float hi) { typedef __bf16 b2_t __attribute__((ext_vector_type(2))); f32x2 v = {lo, hi}; b2_t b = __builtin_convertvector(v, b2_t); return __builtin_bit_cast(unsigned, b); }
; #define LAS __attribute__((address_space(3)))
; __device__ __forceinline__ void transpose_tile(const float* W, const float* gain, int K, int N, int k0, int n0, bf16* WT, int drow0, LAS float* scr, int lane) {
;     f32x4 v[8]; float gv[8];
;     const int r0 = lane >> 3, c4 = lane & 7;
; #pragma unroll
;     for (int i = 0; i < 8; ++i) { v[i] = *(const f32x4*)(W + (size_t)(k0 + r0 + 8 * i) * N + n0 + 4 * c4); gv[i] = gain ? gain[k0 + r0 + 8 * i] : 1.0f; }
; #pragma unroll
;     for (int i = 0; i < 8; ++i) { LAS float* d = scr + (r0 + 8 * i) * 33 + 4 * c4; d[0] = v[i][0] * gv[i]; d[1] = v[i][1] * gv[i]; d[2] = v[i][2] * gv[i]; d[3] = v[i][3] * gv[i]; }
;     asm volatile("s_waitcnt lgkmcnt(0)" ::: "memory");
;     const int c = lane & 7;
; #pragma unroll
;     for (int j = 0; j < 4; ++j) { const int n = (lane >> 3) + 8 * j; const LAS float* s = scr + (8 * c) * 33 + n;
;         v4u o; o.x = pk_bf16(s[0 * 33], s[1 * 33]); o.y = pk_bf16(s[2 * 33], s[3 * 33]); o.z = pk_bf16(s[4 * 33], s[5 * 33]); o.w = pk_bf16(s[6 * 33], s[7 * 33]);
;         *(v4u*)(WT + (size_t)(drow0 + n) * K + k0 + 8 * c) = o; }
;     asm volatile("s_waitcnt lgkmcnt(0)" ::: "memory");
; }
; template <bool SWIGLU> __device__ __forceinline__ void transpose_item(const float* W, const float* gain, int K, int N, bf16* WT, LAS float* scr, int item, int lane) {
;     const int nblk = N / 32, kb = item / nblk, nb = item % nblk, n0 = 32 * nb;
;     int drow0 = n0;
;     if (SWIGLU) { const int up = n0 >= FF, f = up ? n0 - FF : n0; drow0 = 256 * (f >> 7) + (up ? 128 : 0) + (f & 127); }
;     transpose_tile(W, gain, K, N, 64 * kb, n0, WT, drow0, scr, lane);
; }
.LBB0_970:
	s_waitcnt vmcnt(0)
	v_pk_mul_f32 v[0:1], v[0:1], v[52:53] op_sel_hi:[1,0]
	ds_write2_b32 v65, v0, v1 offset1:1
	v_pk_mul_f32 v[0:1], v[2:3], v[52:53] op_sel_hi:[1,0]
	ds_write2_b32 v65, v0, v1 offset0:2 offset1:3
	v_pk_mul_f32 v[0:1], v[4:5], v[50:51] op_sel_hi:[1,0]
	ds_write2_b32 v67, v0, v1 offset1:1
	v_pk_mul_f32 v[0:1], v[6:7], v[50:51] op_sel_hi:[1,0]
	ds_write2_b32 v68, v0, v1 offset1:1
	v_pk_mul_f32 v[0:1], v[8:9], v[56:57] op_sel_hi:[1,0]
	ds_write2_b32 v69, v0, v1 offset1:1
	v_pk_mul_f32 v[0:1], v[10:11], v[56:57] op_sel_hi:[1,0]
	ds_write2_b32 v70, v0, v1 offset1:1
	v_pk_mul_f32 v[0:1], v[12:13], v[54:55] op_sel_hi:[1,0]
	ds_write2_b32 v71, v0, v1 offset1:1
	v_pk_mul_f32 v[0:1], v[14:15], v[54:55] op_sel_hi:[1,0]
	ds_write2_b32 v72, v0, v1 offset1:1
	v_pk_mul_f32 v[0:1], v[16:17], v[62:63] op_sel_hi:[1,0]
	ds_write2_b32 v73, v0, v1 offset1:1
	v_pk_mul_f32 v[0:1], v[18:19], v[62:63] op_sel_hi:[1,0]
	ds_write2_b32 v74, v0, v1 offset1:1
	v_pk_mul_f32 v[0:1], v[20:21], v[58:59] op_sel_hi:[1,0]
	ds_write2_b32 v75, v0, v1 offset1:1
	v_pk_mul_f32 v[0:1], v[22:23], v[58:59] op_sel_hi:[1,0]
	s_lshl_b32 s8, s7, 5
	ds_write2_b32 v76, v0, v1 offset1:1
	v_pk_mul_f32 v[0:1], v[24:25], v[66:67] op_sel_hi:[1,0]
	s_and_b32 s8, 0xffff, s8
	ds_write2_b32 v77, v0, v1 offset1:1
	v_pk_mul_f32 v[0:1], v[26:27], v[66:67] op_sel_hi:[1,0]
	s_and_b32 s7, 0xffff, s7
	s_add_i32 s9, s8, 0xfffff500
	ds_write2_b32 v78, v0, v1 offset1:1
	v_pk_mul_f32 v[0:1], v[28:29], v[64:65] op_sel_hi:[1,0]
	s_cmpk_gt_u32 s7, 0x57
	ds_write2_b32 v79, v0, v1 offset1:1
	v_pk_mul_f32 v[0:1], v[30:31], v[64:65] op_sel_hi:[1,0]
	s_cselect_b32 s7, s9, s8
	ds_write2_b32 v80, v0, v1 offset1:1
	s_cselect_b32 s8, 0x80, 0
	s_lshl_b32 s9, s7, 1
	s_and_b32 s7, s7, 0x60
	s_waitcnt lgkmcnt(0)
	s_and_b32 s9, s9, 0xffffff00
	s_or_b32 s7, s7, s8
	ds_read2_b32 v[4:5], v63 offset0:33 offset1:41
	ds_read2_b32 v[6:7], v63 offset1:8
	ds_read2_b32 v[8:9], v63 offset0:66 offset1:74
	ds_read2_b32 v[10:11], v63 offset0:99 offset1:107
	ds_read2_b32 v[12:13], v63 offset0:132 offset1:140
	ds_read2_b32 v[14:15], v63 offset0:165 offset1:173
	ds_read2_b32 v[16:17], v63 offset0:198 offset1:206
	ds_read2_b32 v[18:19], v63 offset0:231 offset1:239
	s_or_b32 s7, s7, s9
	s_and_b32 s6, 0xffff, s6
	v_add_u32_e32 v22, s7, v51
	s_lshl_b32 s10, s6, 1
	v_ashrrev_i32_e32 v23, 31, v22
	v_lshl_add_u64 v[20:21], v[40:41], 0, s[10:11]
	v_lshlrev_b64 v[22:23], 11, v[22:23]
	s_waitcnt lgkmcnt(6)
	v_cvt_pk_bf16_f32 v0, v6, v4
	s_waitcnt lgkmcnt(4)
	v_cvt_pk_bf16_f32 v1, v8, v10
	s_waitcnt lgkmcnt(2)
	v_cvt_pk_bf16_f32 v2, v12, v14
	s_waitcnt lgkmcnt(0)
	v_cvt_pk_bf16_f32 v3, v16, v18
	v_lshl_add_u64 v[22:23], v[20:21], 0, v[22:23]
	v_add_u32_e32 v4, s7, v53
	global_store_dwordx4 v[22:23], v[0:3], off sc1
	s_nop 1
	v_cvt_pk_bf16_f32 v0, v7, v5
	v_ashrrev_i32_e32 v5, 31, v4
	v_cvt_pk_bf16_f32 v1, v9, v11
	v_cvt_pk_bf16_f32 v2, v13, v15
	v_cvt_pk_bf16_f32 v3, v17, v19
	v_lshlrev_b64 v[4:5], 11, v[4:5]
	ds_read2_b32 v[6:7], v63 offset0:49 offset1:57
	ds_read2_b32 v[8:9], v63 offset0:16 offset1:24
	ds_read2_b32 v[10:11], v63 offset0:82 offset1:90
	ds_read2_b32 v[12:13], v63 offset0:115 offset1:123
	ds_read2_b32 v[14:15], v63 offset0:148 offset1:156
	ds_read2_b32 v[16:17], v63 offset0:181 offset1:189
	ds_read2_b32 v[18:19], v63 offset0:214 offset1:222
	ds_read2_b32 v[22:23], v63 offset0:247 offset1:255
	v_lshl_add_u64 v[4:5], v[20:21], 0, v[4:5]
	global_store_dwordx4 v[4:5], v[0:3], off sc1
	v_add_u32_e32 v4, s7, v55
	v_ashrrev_i32_e32 v5, 31, v4
	v_lshlrev_b64 v[4:5], 11, v[4:5]
	s_waitcnt lgkmcnt(6)
	v_cvt_pk_bf16_f32 v0, v8, v6
	s_waitcnt lgkmcnt(4)
	v_cvt_pk_bf16_f32 v1, v10, v12
	s_waitcnt lgkmcnt(2)
	v_cvt_pk_bf16_f32 v2, v14, v16
	s_waitcnt lgkmcnt(0)
	v_cvt_pk_bf16_f32 v3, v18, v22
	v_lshl_add_u64 v[4:5], v[20:21], 0, v[4:5]
	global_store_dwordx4 v[4:5], v[0:3], off sc1
	v_add_u32_e32 v4, s7, v59
	v_ashrrev_i32_e32 v5, 31, v4
	v_lshlrev_b64 v[4:5], 11, v[4:5]
	v_cvt_pk_bf16_f32 v0, v9, v7
	v_cvt_pk_bf16_f32 v1, v11, v13
	v_cvt_pk_bf16_f32 v2, v15, v17
	v_cvt_pk_bf16_f32 v3, v19, v23
	v_lshl_add_u64 v[4:5], v[20:21], 0, v[4:5]
	global_store_dwordx4 v[4:5], v[0:3], off sc1
	s_waitcnt lgkmcnt(0)

; __device__ __forceinline__ unsigned pk_bf16(float lo, float hi) { typedef __bf16 b2_t __attribute__((ext_vector_type(2))); f32x2 v = {lo, hi}; b2_t b = __builtin_convertvector(v, b2_t); return __builtin_bit_cast(unsigned, b); }
; #define LAS __attribute__((address_space(3)))
; __device__ __forceinline__ void transpose_tile(const float* W, const float* gain, int K, int N, int k0, int n0, bf16* WT, int drow0, LAS float* scr, int lane) {
;     f32x4 v[8]; float gv[8];
;     const int r0 = lane >> 3, c4 = lane & 7;
; #pragma unroll
;     for (int i = 0; i < 8; ++i) { v[i] = *(const f32x4*)(W + (size_t)(k0 + r0 + 8 * i) * N + n0 + 4 * c4); gv[i] = gain ? gain[k0 + r0 + 8 * i] : 1.0f; }
; #pragma unroll
;     for (int i = 0; i < 8; ++i) { LAS float* d = scr + (r0 + 8 * i) * 33 + 4 * c4; d[0] = v[i][0] * gv[i]; d[1] = v[i][1] * gv[i]; d[2] = v[i][2] * gv[i]; d[3] = v[i][3] * gv[i]; }
;     asm volatile("s_waitcnt lgkmcnt(0)" ::: "memory");
;     const int c = lane & 7;
; #pragma unroll
;     for (int j = 0; j < 4; ++j) { const int n = (lane >> 3) + 8 * j; const LAS float* s = scr + (8 * c) * 33 + n;
;         v4u o; o.x = pk_bf16(s[0 * 33], s[1 * 33]); o.y = pk_bf16(s[2 * 33], s[3 * 33]); o.z = pk_bf16(s[4 * 33], s[5 * 33]); o.w = pk_bf16(s[6 * 33], s[7 * 33]);
;         *(v4u*)(WT + (size_t)(drow0 + n) * K + k0 + 8 * c) = o; }
;     asm volatile("s_waitcnt lgkmcnt(0)" ::: "memory");
; }
.LBB0_972:
	s_andn2_b64 vcc, exec, s[8:9]
	s_cbranch_vccnz .LBB0_974
	s_mov_b32 s6, 8
	s_ashr_i32 s7, s6, 31
	s_lshl_b64 s[6:7], s[6:7], 3
	s_add_u32 s6, s0, s6
	s_addc_u32 s7, s1, s7
	s_load_dwordx2 s[6:7], s[6:7], 0x0
	s_lshl_b32 s8, s22, 5
	s_and_b32 s8, s8, 0x3e0
	s_add_i32 s9, s25, 0x3b00
	s_and_b32 s9, s9, 0x1ffc0
	s_lshl_b32 s10, s8, 2
	v_add_u32_e32 v0, s9, v51
	s_waitcnt lgkmcnt(0)
	s_add_u32 s6, s6, s10
	s_addc_u32 s7, s7, 0
	v_ashrrev_i32_e32 v1, 31, v0
	v_lshl_add_u64 v[2:3], s[6:7], 0, v[32:33]
	v_lshlrev_b64 v[0:1], 12, v[0:1]
	v_lshl_add_u64 v[28:29], v[2:3], 0, v[0:1]
	v_add_co_u32_e32 v4, vcc, s27, v28
	v_add_u32_e32 v56, s8, v51
	s_nop 0
	v_addc_co_u32_e32 v5, vcc, 0, v29, vcc
	v_add_co_u32_e32 v8, vcc, s28, v28
	global_load_dwordx4 v[0:3], v[28:29], off
	s_nop 0
	global_load_dwordx4 v[4:7], v[4:5], off
	v_addc_co_u32_e32 v9, vcc, 0, v29, vcc
	v_add_co_u32_e32 v12, vcc, s29, v28
	v_ashrrev_i32_e32 v57, 31, v56
	s_nop 0
	v_addc_co_u32_e32 v13, vcc, 0, v29, vcc
	v_add_co_u32_e32 v16, vcc, s30, v28
	global_load_dwordx4 v[8:11], v[8:9], off
	s_nop 0
	global_load_dwordx4 v[12:15], v[12:13], off
	v_addc_co_u32_e32 v17, vcc, 0, v29, vcc
	v_add_co_u32_e32 v20, vcc, s31, v28
	s_lshl_b32 s10, s9, 1
	s_nop 0
	v_addc_co_u32_e32 v21, vcc, 0, v29, vcc
	global_load_dwordx4 v[16:19], v[16:17], off
	s_nop 0
	global_load_dwordx4 v[20:23], v[20:21], off
	v_add_co_u32_e32 v24, vcc, s34, v28
	v_lshlrev_b64 v[56:57], 11, v[56:57]
	s_nop 0
	v_addc_co_u32_e32 v25, vcc, 0, v29, vcc
	global_load_dwordx4 v[24:27], v[24:25], off
	v_add_co_u32_e32 v28, vcc, s35, v28
	v_lshl_add_u64 v[82:83], v[42:43], 0, s[10:11]
	s_nop 0
	v_addc_co_u32_e32 v29, vcc, 0, v29, vcc
	global_load_dwordx4 v[28:31], v[28:29], off
	v_add_u32_e32 v60, s8, v53
	v_lshl_add_u64 v[56:57], v[82:83], 0, v[56:57]
	v_ashrrev_i32_e32 v61, 31, v60
	v_lshlrev_b64 v[60:61], 11, v[60:61]
	v_lshl_add_u64 v[60:61], v[82:83], 0, v[60:61]
	s_waitcnt vmcnt(0)
	ds_write2_b32 v65, v0, v1 offset1:1
	ds_write2_b32 v65, v2, v3 offset0:2 offset1:3
	ds_write2_b32 v67, v4, v5 offset1:1
	ds_write2_b32 v68, v6, v7 offset1:1
	ds_write2_b32 v69, v8, v9 offset1:1
	ds_write2_b32 v70, v10, v11 offset1:1
	ds_write2_b32 v71, v12, v13 offset1:1
	ds_write2_b32 v72, v14, v15 offset1:1
	ds_write2_b32 v73, v16, v17 offset1:1
	ds_write2_b32 v74, v18, v19 offset1:1
	ds_write2_b32 v75, v20, v21 offset1:1
	ds_write2_b32 v76, v22, v23 offset1:1
	ds_write2_b32 v77, v24, v25 offset1:1
	ds_write2_b32 v78, v26, v27 offset1:1
	ds_write2_b32 v79, v28, v29 offset1:1
	ds_write2_b32 v80, v30, v31 offset1:1
	s_waitcnt lgkmcnt(0)
	ds_read2_b32 v[4:5], v63 offset0:33 offset1:41
	ds_read2_b32 v[6:7], v63 offset1:8
	ds_read2_b32 v[8:9], v63 offset0:66 offset1:74
	ds_read2_b32 v[10:11], v63 offset0:99 offset1:107
	ds_read2_b32 v[12:13], v63 offset0:132 offset1:140
	ds_read2_b32 v[14:15], v63 offset0:165 offset1:173
	ds_read2_b32 v[16:17], v63 offset0:198 offset1:206
	ds_read2_b32 v[18:19], v63 offset0:231 offset1:239
	ds_read2_b32 v[20:21], v63 offset0:49 offset1:57
	ds_read2_b32 v[22:23], v63 offset0:16 offset1:24
	ds_read2_b32 v[24:25], v63 offset0:82 offset1:90
	ds_read2_b32 v[26:27], v63 offset0:115 offset1:123
	ds_read2_b32 v[28:29], v63 offset0:148 offset1:156
	ds_read2_b32 v[30:31], v63 offset0:181 offset1:189
	s_waitcnt lgkmcnt(12)
	v_cvt_pk_bf16_f32 v0, v6, v4
	s_waitcnt lgkmcnt(10)
	v_cvt_pk_bf16_f32 v1, v8, v10
	s_waitcnt lgkmcnt(8)
	v_cvt_pk_bf16_f32 v2, v12, v14
	s_waitcnt lgkmcnt(6)
	v_cvt_pk_bf16_f32 v3, v16, v18
	global_store_dwordx4 v[56:57], v[0:3], off sc1
	v_cvt_pk_bf16_f32 v4, v7, v5
	v_cvt_pk_bf16_f32 v5, v9, v11
	ds_read2_b32 v[8:9], v63 offset0:214 offset1:222
	ds_read2_b32 v[10:11], v63 offset0:247 offset1:255
	v_cvt_pk_bf16_f32 v6, v13, v15
	v_cvt_pk_bf16_f32 v7, v17, v19
	global_store_dwordx4 v[60:61], v[4:7], off sc1
	s_waitcnt lgkmcnt(6)
	v_cvt_pk_bf16_f32 v0, v22, v20
	s_waitcnt lgkmcnt(4)
	v_cvt_pk_bf16_f32 v1, v24, v26
	v_add_u32_e32 v4, s8, v55
	v_ashrrev_i32_e32 v5, 31, v4
	v_lshlrev_b64 v[4:5], 11, v[4:5]
	s_waitcnt lgkmcnt(2)
	v_cvt_pk_bf16_f32 v2, v28, v30
	s_waitcnt lgkmcnt(0)
	v_cvt_pk_bf16_f32 v3, v8, v10
	v_lshl_add_u64 v[4:5], v[82:83], 0, v[4:5]
	global_store_dwordx4 v[4:5], v[0:3], off sc1
	v_add_u32_e32 v4, s8, v59
	v_ashrrev_i32_e32 v5, 31, v4
	v_lshlrev_b64 v[4:5], 11, v[4:5]
	v_cvt_pk_bf16_f32 v0, v23, v21
	v_cvt_pk_bf16_f32 v1, v25, v27
	v_cvt_pk_bf16_f32 v2, v29, v31
	v_cvt_pk_bf16_f32 v3, v9, v11
	v_lshl_add_u64 v[4:5], v[82:83], 0, v[4:5]
	global_store_dwordx4 v[4:5], v[0:3], off sc1
	s_waitcnt lgkmcnt(0)

; __device__ __forceinline__ unsigned pk_bf16(float lo, float hi) { typedef __bf16 b2_t __attribute__((ext_vector_type(2))); f32x2 v = {lo, hi}; b2_t b = __builtin_convertvector(v, b2_t); return __builtin_bit_cast(unsigned, b); }
; #define LAS __attribute__((address_space(3)))
; __device__ __forceinline__ void transpose_tile(const float* W, const float* gain, int K, int N, int k0, int n0, bf16* WT, int drow0, LAS float* scr, int lane) {
;     f32x4 v[8]; float gv[8];
;     const int r0 = lane >> 3, c4 = lane & 7;
; #pragma unroll
;     for (int i = 0; i < 8; ++i) { v[i] = *(const f32x4*)(W + (size_t)(k0 + r0 + 8 * i) * N + n0 + 4 * c4); gv[i] = gain ? gain[k0 + r0 + 8 * i] : 1.0f; }
; #pragma unroll
;     for (int i = 0; i < 8; ++i) { LAS float* d = scr + (r0 + 8 * i) * 33 + 4 * c4; d[0] = v[i][0] * gv[i]; d[1] = v[i][1] * gv[i]; d[2] = v[i][2] * gv[i]; d[3] = v[i][3] * gv[i]; }
;     asm volatile("s_waitcnt lgkmcnt(0)" ::: "memory");
;     const int c = lane & 7;
; #pragma unroll
;     for (int j = 0; j < 4; ++j) { const int n = (lane >> 3) + 8 * j; const LAS float* s = scr + (8 * c) * 33 + n;
;         v4u o; o.x = pk_bf16(s[0 * 33], s[1 * 33]); o.y = pk_bf16(s[2 * 33], s[3 * 33]); o.z = pk_bf16(s[4 * 33], s[5 * 33]); o.w = pk_bf16(s[6 * 33], s[7 * 33]);
;         *(v4u*)(WT + (size_t)(drow0 + n) * K + k0 + 8 * c) = o; }
;     asm volatile("s_waitcnt lgkmcnt(0)" ::: "memory");
; }
; template <bool SWIGLU> __device__ __forceinline__ void transpose_item(const float* W, const float* gain, int K, int N, bf16* WT, LAS float* scr, int item, int lane) {
;     const int nblk = N / 32, kb = item / nblk, nb = item % nblk, n0 = 32 * nb;
;     int drow0 = n0;
;     if (SWIGLU) { const int up = n0 >= FF, f = up ? n0 - FF : n0; drow0 = 256 * (f >> 7) + (up ? 128 : 0) + (f & 127); }
;     transpose_tile(W, gain, K, N, 64 * kb, n0, WT, drow0, scr, lane);
; }
.LBB0_992:
	s_waitcnt vmcnt(0)
	v_pk_mul_f32 v[0:1], v[0:1], v[52:53] op_sel_hi:[1,0]
	ds_write2_b32 v65, v0, v1 offset1:1
	v_pk_mul_f32 v[0:1], v[2:3], v[52:53] op_sel_hi:[1,0]
	ds_write2_b32 v65, v0, v1 offset0:2 offset1:3
	v_pk_mul_f32 v[0:1], v[4:5], v[50:51] op_sel_hi:[1,0]
	ds_write2_b32 v67, v0, v1 offset1:1
	v_pk_mul_f32 v[0:1], v[6:7], v[50:51] op_sel_hi:[1,0]
	ds_write2_b32 v68, v0, v1 offset1:1
	v_pk_mul_f32 v[0:1], v[8:9], v[58:59] op_sel_hi:[1,0]
	ds_write2_b32 v69, v0, v1 offset1:1
	v_pk_mul_f32 v[0:1], v[10:11], v[58:59] op_sel_hi:[1,0]
	ds_write2_b32 v70, v0, v1 offset1:1
	v_pk_mul_f32 v[0:1], v[12:13], v[54:55] op_sel_hi:[1,0]
	ds_write2_b32 v71, v0, v1 offset1:1
	v_pk_mul_f32 v[0:1], v[14:15], v[54:55] op_sel_hi:[1,0]
	ds_write2_b32 v72, v0, v1 offset1:1
	v_pk_mul_f32 v[0:1], v[16:17], v[62:63] op_sel_hi:[1,0]
	ds_write2_b32 v73, v0, v1 offset1:1
	v_pk_mul_f32 v[0:1], v[18:19], v[62:63] op_sel_hi:[1,0]
	ds_write2_b32 v74, v0, v1 offset1:1
	v_pk_mul_f32 v[0:1], v[20:21], v[60:61] op_sel_hi:[1,0]
	ds_write2_b32 v75, v0, v1 offset1:1
	v_pk_mul_f32 v[0:1], v[22:23], v[60:61] op_sel_hi:[1,0]
	ds_write2_b32 v76, v0, v1 offset1:1
	v_pk_mul_f32 v[0:1], v[24:25], v[66:67] op_sel_hi:[1,0]
	ds_write2_b32 v77, v0, v1 offset1:1
	v_pk_mul_f32 v[0:1], v[26:27], v[66:67] op_sel_hi:[1,0]
	ds_write2_b32 v78, v0, v1 offset1:1
	v_pk_mul_f32 v[0:1], v[28:29], v[64:65] op_sel_hi:[1,0]
	ds_write2_b32 v79, v0, v1 offset1:1
	v_pk_mul_f32 v[0:1], v[30:31], v[64:65] op_sel_hi:[1,0]
	ds_write2_b32 v80, v0, v1 offset1:1
	s_waitcnt lgkmcnt(0)
	s_lshl_b32 s7, s7, 5
	ds_read2_b32 v[4:5], v63 offset0:33 offset1:41
	ds_read2_b32 v[6:7], v63 offset1:8
	ds_read2_b32 v[8:9], v63 offset0:66 offset1:74
	ds_read2_b32 v[10:11], v63 offset0:99 offset1:107
	ds_read2_b32 v[12:13], v63 offset0:132 offset1:140
	ds_read2_b32 v[14:15], v63 offset0:165 offset1:173
	ds_read2_b32 v[16:17], v63 offset0:198 offset1:206
	ds_read2_b32 v[18:19], v63 offset0:231 offset1:239
	s_and_b32 s7, 0xffff, s7
	s_and_b32 s6, 0xffff, s6
	v_add_u32_e32 v22, s7, v51
	s_lshl_b32 s10, s6, 1
	v_ashrrev_i32_e32 v23, 31, v22
	v_lshl_add_u64 v[20:21], v[44:45], 0, s[10:11]
	v_lshlrev_b64 v[22:23], 11, v[22:23]
	s_waitcnt lgkmcnt(6)
	v_cvt_pk_bf16_f32 v0, v6, v4
	s_waitcnt lgkmcnt(4)
	v_cvt_pk_bf16_f32 v1, v8, v10
	s_waitcnt lgkmcnt(2)
	v_cvt_pk_bf16_f32 v2, v12, v14
	s_waitcnt lgkmcnt(0)
	v_cvt_pk_bf16_f32 v3, v16, v18
	v_lshl_add_u64 v[22:23], v[20:21], 0, v[22:23]
	v_add_u32_e32 v4, s7, v53
	global_store_dwordx4 v[22:23], v[0:3], off sc1
	s_nop 1
	v_cvt_pk_bf16_f32 v0, v7, v5
	v_ashrrev_i32_e32 v5, 31, v4
	v_cvt_pk_bf16_f32 v1, v9, v11
	v_cvt_pk_bf16_f32 v2, v13, v15
	v_cvt_pk_bf16_f32 v3, v17, v19
	v_lshlrev_b64 v[4:5], 11, v[4:5]
	ds_read2_b32 v[6:7], v63 offset0:49 offset1:57
	ds_read2_b32 v[8:9], v63 offset0:16 offset1:24
	ds_read2_b32 v[10:11], v63 offset0:82 offset1:90
	ds_read2_b32 v[12:13], v63 offset0:115 offset1:123
	ds_read2_b32 v[14:15], v63 offset0:148 offset1:156
	ds_read2_b32 v[16:17], v63 offset0:181 offset1:189
	ds_read2_b32 v[18:19], v63 offset0:214 offset1:222
	ds_read2_b32 v[22:23], v63 offset0:247 offset1:255
	v_lshl_add_u64 v[4:5], v[20:21], 0, v[4:5]
	global_store_dwordx4 v[4:5], v[0:3], off sc1
	v_add_u32_e32 v4, s7, v55
	v_ashrrev_i32_e32 v5, 31, v4
	v_lshlrev_b64 v[4:5], 11, v[4:5]
	s_waitcnt lgkmcnt(6)
	v_cvt_pk_bf16_f32 v0, v8, v6
	s_waitcnt lgkmcnt(4)
	v_cvt_pk_bf16_f32 v1, v10, v12
	s_waitcnt lgkmcnt(2)
	v_cvt_pk_bf16_f32 v2, v14, v16
	s_waitcnt lgkmcnt(0)
	v_cvt_pk_bf16_f32 v3, v18, v22
	v_lshl_add_u64 v[4:5], v[20:21], 0, v[4:5]
	global_store_dwordx4 v[4:5], v[0:3], off sc1
	v_add_u32_e32 v4, s7, v59
	v_ashrrev_i32_e32 v5, 31, v4
	v_lshlrev_b64 v[4:5], 11, v[4:5]
	v_cvt_pk_bf16_f32 v0, v9, v7
	v_cvt_pk_bf16_f32 v1, v11, v13
	v_cvt_pk_bf16_f32 v2, v15, v17
	v_cvt_pk_bf16_f32 v3, v19, v23
	v_lshl_add_u64 v[4:5], v[20:21], 0, v[4:5]
	global_store_dwordx4 v[4:5], v[0:3], off sc1
	s_waitcnt lgkmcnt(0)

; __device__ __forceinline__ unsigned pk_bf16(float lo, float hi) { typedef __bf16 b2_t __attribute__((ext_vector_type(2))); f32x2 v = {lo, hi}; b2_t b = __builtin_convertvector(v, b2_t); return __builtin_bit_cast(unsigned, b); }
; #define LAS __attribute__((address_space(3)))
; __device__ __forceinline__ void transpose_tile(const float* W, const float* gain, int K, int N, int k0, int n0, bf16* WT, int drow0, LAS float* scr, int lane) {
;     f32x4 v[8]; float gv[8];
;     const int r0 = lane >> 3, c4 = lane & 7;
; #pragma unroll
;     for (int i = 0; i < 8; ++i) { v[i] = *(const f32x4*)(W + (size_t)(k0 + r0 + 8 * i) * N + n0 + 4 * c4); gv[i] = gain ? gain[k0 + r0 + 8 * i] : 1.0f; }
; #pragma unroll
;     for (int i = 0; i < 8; ++i) { LAS float* d = scr + (r0 + 8 * i) * 33 + 4 * c4; d[0] = v[i][0] * gv[i]; d[1] = v[i][1] * gv[i]; d[2] = v[i][2] * gv[i]; d[3] = v[i][3] * gv[i]; }
;     asm volatile("s_waitcnt lgkmcnt(0)" ::: "memory");
;     const int c = lane & 7;
; #pragma unroll
;     for (int j = 0; j < 4; ++j) { const int n = (lane >> 3) + 8 * j; const LAS float* s = scr + (8 * c) * 33 + n;
;         v4u o; o.x = pk_bf16(s[0 * 33], s[1 * 33]); o.y = pk_bf16(s[2 * 33], s[3 * 33]); o.z = pk_bf16(s[4 * 33], s[5 * 33]); o.w = pk_bf16(s[6 * 33], s[7 * 33]);
;         *(v4u*)(WT + (size_t)(drow0 + n) * K + k0 + 8 * c) = o; }
;     asm volatile("s_waitcnt lgkmcnt(0)" ::: "memory");
; }
.LBB0_994:
	s_andn2_b64 vcc, exec, s[8:9]
	s_cbranch_vccnz .LBB0_996
	s_mov_b32 s6, 3
	s_ashr_i32 s7, s6, 31
	s_lshl_b64 s[6:7], s[6:7], 3
	s_add_u32 s6, s0, s6
	s_addc_u32 s7, s1, s7
	s_load_dwordx2 s[6:7], s[6:7], 0x0
	s_lshl_b32 s8, s22, 5
	s_and_b32 s8, s8, 0x3e0
	s_add_i32 s9, s25, 0x5200
	s_and_b32 s9, s9, 0x1ffc0
	s_lshl_b32 s10, s8, 2
	v_add_u32_e32 v0, s9, v51
	s_waitcnt lgkmcnt(0)
	s_add_u32 s6, s6, s10
	s_addc_u32 s7, s7, 0
	v_ashrrev_i32_e32 v1, 31, v0
	v_lshl_add_u64 v[2:3], s[6:7], 0, v[32:33]
	v_lshlrev_b64 v[0:1], 12, v[0:1]
	v_lshl_add_u64 v[28:29], v[2:3], 0, v[0:1]
	v_add_co_u32_e32 v4, vcc, s27, v28
	s_lshl_b32 s10, s9, 1
	s_nop 0
	v_addc_co_u32_e32 v5, vcc, 0, v29, vcc
	v_add_co_u32_e32 v8, vcc, s28, v28
	global_load_dwordx4 v[0:3], v[28:29], off
	s_nop 0
	global_load_dwordx4 v[4:7], v[4:5], off
	v_addc_co_u32_e32 v9, vcc, 0, v29, vcc
	v_add_co_u32_e32 v12, vcc, s29, v28
	v_add_u32_e32 v50, s8, v51
	s_nop 0
	v_addc_co_u32_e32 v13, vcc, 0, v29, vcc
	v_add_co_u32_e32 v16, vcc, s30, v28
	global_load_dwordx4 v[8:11], v[8:9], off
	s_nop 0
	global_load_dwordx4 v[12:15], v[12:13], off
	v_addc_co_u32_e32 v17, vcc, 0, v29, vcc
	v_add_co_u32_e32 v20, vcc, s31, v28
	v_lshl_add_u64 v[56:57], v[46:47], 0, s[10:11]
	s_nop 0
	v_addc_co_u32_e32 v21, vcc, 0, v29, vcc
	global_load_dwordx4 v[16:19], v[16:17], off
	s_nop 0
	global_load_dwordx4 v[20:23], v[20:21], off
	v_add_co_u32_e32 v24, vcc, s34, v28
	v_add_u32_e32 v52, s8, v53
	s_nop 0
	v_addc_co_u32_e32 v25, vcc, 0, v29, vcc
	global_load_dwordx4 v[24:27], v[24:25], off
	v_add_co_u32_e32 v28, vcc, s35, v28
	v_mad_i64_i32 v[60:61], s[6:7], v50, s36, v[56:57]
	s_nop 0
	v_addc_co_u32_e32 v29, vcc, 0, v29, vcc
	global_load_dwordx4 v[28:31], v[28:29], off
	v_mad_i64_i32 v[82:83], s[6:7], v52, s36, v[56:57]
	s_waitcnt vmcnt(0)
	ds_write2_b32 v65, v0, v1 offset1:1
	ds_write2_b32 v65, v2, v3 offset0:2 offset1:3
	ds_write2_b32 v67, v4, v5 offset1:1
	ds_write2_b32 v68, v6, v7 offset1:1
	ds_write2_b32 v69, v8, v9 offset1:1
	ds_write2_b32 v70, v10, v11 offset1:1
	ds_write2_b32 v71, v12, v13 offset1:1
	ds_write2_b32 v72, v14, v15 offset1:1
	ds_write2_b32 v73, v16, v17 offset1:1
	ds_write2_b32 v74, v18, v19 offset1:1
	ds_write2_b32 v75, v20, v21 offset1:1
	ds_write2_b32 v76, v22, v23 offset1:1
	ds_write2_b32 v77, v24, v25 offset1:1
	ds_write2_b32 v78, v26, v27 offset1:1
	ds_write2_b32 v79, v28, v29 offset1:1
	ds_write2_b32 v80, v30, v31 offset1:1
	s_waitcnt lgkmcnt(0)
	ds_read2_b32 v[4:5], v63 offset0:33 offset1:41
	ds_read2_b32 v[6:7], v63 offset1:8
	ds_read2_b32 v[8:9], v63 offset0:66 offset1:74
	ds_read2_b32 v[10:11], v63 offset0:99 offset1:107
	ds_read2_b32 v[12:13], v63 offset0:132 offset1:140
	ds_read2_b32 v[14:15], v63 offset0:165 offset1:173
	ds_read2_b32 v[16:17], v63 offset0:198 offset1:206
	ds_read2_b32 v[18:19], v63 offset0:231 offset1:239
	ds_read2_b32 v[20:21], v63 offset0:49 offset1:57
	ds_read2_b32 v[22:23], v63 offset0:16 offset1:24
	ds_read2_b32 v[24:25], v63 offset0:82 offset1:90
	ds_read2_b32 v[26:27], v63 offset0:115 offset1:123
	ds_read2_b32 v[28:29], v63 offset0:148 offset1:156
	ds_read2_b32 v[30:31], v63 offset0:181 offset1:189
	ds_read2_b32 v[84:85], v63 offset0:214 offset1:222
	ds_read2_b32 v[86:87], v63 offset0:247 offset1:255
	s_waitcnt lgkmcnt(14)
	v_cvt_pk_bf16_f32 v0, v6, v4
	s_waitcnt lgkmcnt(12)
	v_cvt_pk_bf16_f32 v1, v8, v10
	s_waitcnt lgkmcnt(10)
	v_cvt_pk_bf16_f32 v2, v12, v14
	s_waitcnt lgkmcnt(8)
	v_cvt_pk_bf16_f32 v3, v16, v18
	v_cvt_pk_bf16_f32 v4, v7, v5
	v_cvt_pk_bf16_f32 v5, v9, v11
	v_cvt_pk_bf16_f32 v6, v13, v15
	v_cvt_pk_bf16_f32 v7, v17, v19
	global_store_dwordx4 v[60:61], v[0:3], off sc1
	global_store_dwordx4 v[82:83], v[4:7], off sc1
	s_waitcnt lgkmcnt(6)
	v_cvt_pk_bf16_f32 v0, v22, v20
	v_add_u32_e32 v4, s8, v55
	s_waitcnt lgkmcnt(4)
	v_cvt_pk_bf16_f32 v1, v24, v26
	s_waitcnt lgkmcnt(2)
	v_cvt_pk_bf16_f32 v2, v28, v30
	s_waitcnt lgkmcnt(0)
	v_cvt_pk_bf16_f32 v3, v84, v86
	v_mad_i64_i32 v[4:5], s[6:7], v4, s36, v[56:57]
	global_store_dwordx4 v[4:5], v[0:3], off sc1
	v_add_u32_e32 v4, s8, v59
	v_mad_i64_i32 v[4:5], s[6:7], v4, s36, v[56:57]
	v_cvt_pk_bf16_f32 v0, v23, v21
	v_cvt_pk_bf16_f32 v1, v25, v27
	v_cvt_pk_bf16_f32 v2, v29, v31
	v_cvt_pk_bf16_f32 v3, v85, v87
	global_store_dwordx4 v[4:5], v[0:3], off sc1
	s_waitcnt lgkmcnt(0)

; __device__ __forceinline__ unsigned pk_bf16(float lo, float hi) { typedef __bf16 b2_t __attribute__((ext_vector_type(2))); f32x2 v = {lo, hi}; b2_t b = __builtin_convertvector(v, b2_t); return __builtin_bit_cast(unsigned, b); }
; #define LAS __attribute__((address_space(3)))
; __device__ __forceinline__ void transpose_tile(const float* W, const float* gain, int K, int N, int k0, int n0, bf16* WT, int drow0, LAS float* scr, int lane) {
;     f32x4 v[8]; float gv[8];
;     const int r0 = lane >> 3, c4 = lane & 7;
; #pragma unroll
;     for (int i = 0; i < 8; ++i) { v[i] = *(const f32x4*)(W + (size_t)(k0 + r0 + 8 * i) * N + n0 + 4 * c4); gv[i] = gain ? gain[k0 + r0 + 8 * i] : 1.0f; }
; #pragma unroll
;     for (int i = 0; i < 8; ++i) { LAS float* d = scr + (r0 + 8 * i) * 33 + 4 * c4; d[0] = v[i][0] * gv[i]; d[1] = v[i][1] * gv[i]; d[2] = v[i][2] * gv[i]; d[3] = v[i][3] * gv[i]; }
;     asm volatile("s_waitcnt lgkmcnt(0)" ::: "memory");
;     const int c = lane & 7;
; #pragma unroll
;     for (int j = 0; j < 4; ++j) { const int n = (lane >> 3) + 8 * j; const LAS float* s = scr + (8 * c) * 33 + n;
;         v4u o; o.x = pk_bf16(s[0 * 33], s[1 * 33]); o.y = pk_bf16(s[2 * 33], s[3 * 33]); o.z = pk_bf16(s[4 * 33], s[5 * 33]); o.w = pk_bf16(s[6 * 33], s[7 * 33]);
;         *(v4u*)(WT + (size_t)(drow0 + n) * K + k0 + 8 * c) = o; }
;     asm volatile("s_waitcnt lgkmcnt(0)" ::: "memory");
; }
.LBB0_1020:
	s_cmpk_gt_i32 s22, 0xaff
	s_mov_b64 s[8:9], -1
	s_cbranch_scc0 .LBB0_1094
	s_cmpk_gt_u32 s22, 0x107f
	s_cbranch_scc0 .LBB0_1091
	s_cmpk_gt_u32 s22, 0x167f
	s_cbranch_scc0 .LBB0_1072
	s_cmpk_gt_u32 s22, 0x187f
	s_cbranch_scc0 .LBB0_1069
	s_cmpk_gt_u32 s22, 0x237f
	s_cbranch_scc0 .LBB0_1050
	s_cmpk_gt_u32 s22, 0x28ff
	s_cbranch_scc0 .LBB0_1047
	s_cmpk_gt_u32 s22, 0x33ff
	s_cbranch_scc0 .LBB0_1028
	s_mov_b32 s6, 14
	s_ashr_i32 s7, s6, 31
	s_lshl_b64 s[6:7], s[6:7], 3
	s_add_u32 s6, s0, s6
	s_addc_u32 s7, s1, s7
	s_load_dwordx2 s[6:7], s[6:7], 0x0
	s_lshl_b32 s8, s22, 5
	s_and_b32 s8, s8, 0x3e0
	s_and_b32 s9, s26, 0x1ffc0
	s_lshl_b32 s10, s8, 2
	v_add_u32_e32 v0, s9, v51
	s_waitcnt lgkmcnt(0)
	s_add_u32 s6, s6, s10
	s_addc_u32 s7, s7, 0
	v_ashrrev_i32_e32 v1, 31, v0
	v_lshl_add_u64 v[2:3], s[6:7], 0, v[32:33]
	v_lshlrev_b64 v[0:1], 12, v[0:1]
	v_lshl_add_u64 v[28:29], v[2:3], 0, v[0:1]
	v_add_co_u32_e32 v4, vcc, s28, v28
	s_lshl_b32 s10, s9, 1
	s_nop 0
	v_addc_co_u32_e32 v5, vcc, 0, v29, vcc
	v_add_co_u32_e32 v8, vcc, s29, v28
	global_load_dwordx4 v[0:3], v[28:29], off
	s_nop 0
	global_load_dwordx4 v[4:7], v[4:5], off
	v_addc_co_u32_e32 v9, vcc, 0, v29, vcc
	v_add_co_u32_e32 v12, vcc, s30, v28
	v_add_u32_e32 v50, s8, v51
	s_nop 0
	v_addc_co_u32_e32 v13, vcc, 0, v29, vcc
	v_add_co_u32_e32 v16, vcc, s31, v28
	global_load_dwordx4 v[8:11], v[8:9], off
	s_nop 0
	global_load_dwordx4 v[12:15], v[12:13], off
	v_addc_co_u32_e32 v17, vcc, 0, v29, vcc
	v_add_co_u32_e32 v20, vcc, s34, v28
	v_lshl_add_u64 v[56:57], v[34:35], 0, s[10:11]
	s_nop 0
	v_addc_co_u32_e32 v21, vcc, 0, v29, vcc
	global_load_dwordx4 v[16:19], v[16:17], off
	s_nop 0
	global_load_dwordx4 v[20:23], v[20:21], off
	v_add_co_u32_e32 v24, vcc, s35, v28
	v_add_u32_e32 v52, s8, v53
	s_nop 0
	v_addc_co_u32_e32 v25, vcc, 0, v29, vcc
	global_load_dwordx4 v[24:27], v[24:25], off
	v_add_co_u32_e32 v28, vcc, s36, v28
	v_mad_i64_i32 v[60:61], s[6:7], v50, s37, v[56:57]
	s_nop 0
	v_addc_co_u32_e32 v29, vcc, 0, v29, vcc
	global_load_dwordx4 v[28:31], v[28:29], off
	v_mad_i64_i32 v[82:83], s[6:7], v52, s37, v[56:57]
	s_waitcnt vmcnt(0)
	ds_write2_b32 v65, v0, v1 offset1:1
	ds_write2_b32 v65, v2, v3 offset0:2 offset1:3
	ds_write2_b32 v67, v4, v5 offset1:1
	ds_write2_b32 v68, v6, v7 offset1:1
	ds_write2_b32 v69, v8, v9 offset1:1
	ds_write2_b32 v70, v10, v11 offset1:1
	ds_write2_b32 v71, v12, v13 offset1:1
	ds_write2_b32 v72, v14, v15 offset1:1
	ds_write2_b32 v73, v16, v17 offset1:1
	ds_write2_b32 v74, v18, v19 offset1:1
	ds_write2_b32 v75, v20, v21 offset1:1
	ds_write2_b32 v76, v22, v23 offset1:1
	ds_write2_b32 v77, v24, v25 offset1:1
	ds_write2_b32 v78, v26, v27 offset1:1
	ds_write2_b32 v79, v28, v29 offset1:1
	ds_write2_b32 v80, v30, v31 offset1:1
	s_waitcnt lgkmcnt(0)
	ds_read2_b32 v[4:5], v63 offset0:33 offset1:41
	ds_read2_b32 v[6:7], v63 offset1:8
	ds_read2_b32 v[8:9], v63 offset0:66 offset1:74
	ds_read2_b32 v[10:11], v63 offset0:99 offset1:107
	ds_read2_b32 v[12:13], v63 offset0:132 offset1:140
	ds_read2_b32 v[14:15], v63 offset0:165 offset1:173
	ds_read2_b32 v[16:17], v63 offset0:198 offset1:206
	ds_read2_b32 v[18:19], v63 offset0:231 offset1:239
	ds_read2_b32 v[20:21], v63 offset0:49 offset1:57
	ds_read2_b32 v[22:23], v63 offset0:16 offset1:24
	ds_read2_b32 v[24:25], v63 offset0:82 offset1:90
	ds_read2_b32 v[26:27], v63 offset0:115 offset1:123
	ds_read2_b32 v[28:29], v63 offset0:148 offset1:156
	ds_read2_b32 v[30:31], v63 offset0:181 offset1:189
	ds_read2_b32 v[84:85], v63 offset0:214 offset1:222
	ds_read2_b32 v[86:87], v63 offset0:247 offset1:255
	s_waitcnt lgkmcnt(14)
	v_cvt_pk_bf16_f32 v0, v6, v4
	s_waitcnt lgkmcnt(12)
	v_cvt_pk_bf16_f32 v1, v8, v10
	s_waitcnt lgkmcnt(10)
	v_cvt_pk_bf16_f32 v2, v12, v14
	s_waitcnt lgkmcnt(8)
	v_cvt_pk_bf16_f32 v3, v16, v18
	v_cvt_pk_bf16_f32 v4, v7, v5
	v_cvt_pk_bf16_f32 v5, v9, v11
	v_cvt_pk_bf16_f32 v6, v13, v15
	v_cvt_pk_bf16_f32 v7, v17, v19
	global_store_dwordx4 v[60:61], v[0:3], off sc1
	global_store_dwordx4 v[82:83], v[4:7], off sc1
	s_waitcnt lgkmcnt(6)
	v_cvt_pk_bf16_f32 v0, v22, v20
	v_add_u32_e32 v4, s8, v55
	s_waitcnt lgkmcnt(4)
	v_cvt_pk_bf16_f32 v1, v24, v26
	s_waitcnt lgkmcnt(2)
	v_cvt_pk_bf16_f32 v2, v28, v30
	s_waitcnt lgkmcnt(0)
	v_cvt_pk_bf16_f32 v3, v84, v86
	v_mad_i64_i32 v[4:5], s[6:7], v4, s37, v[56:57]
	global_store_dwordx4 v[4:5], v[0:3], off sc1
	v_add_u32_e32 v4, s8, v59
	v_mad_i64_i32 v[4:5], s[6:7], v4, s37, v[56:57]
	v_cvt_pk_bf16_f32 v0, v23, v21
	v_cvt_pk_bf16_f32 v1, v25, v27
	v_cvt_pk_bf16_f32 v2, v29, v31
	v_cvt_pk_bf16_f32 v3, v85, v87
	global_store_dwordx4 v[4:5], v[0:3], off sc1
	s_waitcnt lgkmcnt(0)
	s_mov_b64 s[8:9], 0

; __device__ __forceinline__ unsigned pk_bf16(float lo, float hi) { typedef __bf16 b2_t __attribute__((ext_vector_type(2))); f32x2 v = {lo, hi}; b2_t b = __builtin_convertvector(v, b2_t); return __builtin_bit_cast(unsigned, b); }
; #define LAS __attribute__((address_space(3)))
; __device__ __forceinline__ void transpose_tile(const float* W, const float* gain, int K, int N, int k0, int n0, bf16* WT, int drow0, LAS float* scr, int lane) {
;     f32x4 v[8]; float gv[8];
;     const int r0 = lane >> 3, c4 = lane & 7;
; #pragma unroll
;     for (int i = 0; i < 8; ++i) { v[i] = *(const f32x4*)(W + (size_t)(k0 + r0 + 8 * i) * N + n0 + 4 * c4); gv[i] = gain ? gain[k0 + r0 + 8 * i] : 1.0f; }
; #pragma unroll
;     for (int i = 0; i < 8; ++i) { LAS float* d = scr + (r0 + 8 * i) * 33 + 4 * c4; d[0] = v[i][0] * gv[i]; d[1] = v[i][1] * gv[i]; d[2] = v[i][2] * gv[i]; d[3] = v[i][3] * gv[i]; }
;     asm volatile("s_waitcnt lgkmcnt(0)" ::: "memory");
;     const int c = lane & 7;
; #pragma unroll
;     for (int j = 0; j < 4; ++j) { const int n = (lane >> 3) + 8 * j; const LAS float* s = scr + (8 * c) * 33 + n;
;         v4u o; o.x = pk_bf16(s[0 * 33], s[1 * 33]); o.y = pk_bf16(s[2 * 33], s[3 * 33]); o.z = pk_bf16(s[4 * 33], s[5 * 33]); o.w = pk_bf16(s[6 * 33], s[7 * 33]);
;         *(v4u*)(WT + (size_t)(drow0 + n) * K + k0 + 8 * c) = o; }
;     asm volatile("s_waitcnt lgkmcnt(0)" ::: "memory");
; }
.LBB0_1047:
	s_andn2_b64 vcc, exec, s[8:9]
	s_cbranch_vccnz .LBB0_1049
	s_mov_b32 s6, 11
	s_ashr_i32 s7, s6, 31
	s_lshl_b64 s[6:7], s[6:7], 3
	s_add_u32 s6, s0, s6
	s_addc_u32 s7, s1, s7
	s_load_dwordx2 s[6:7], s[6:7], 0x0
	s_lshl_b32 s8, s22, 5
	s_and_b32 s8, s8, 0x3e0
	s_add_i32 s9, s26, 0x2100
	s_and_b32 s9, s9, 0x1ffc0
	s_lshl_b32 s10, s8, 2
	v_add_u32_e32 v0, s9, v51
	s_waitcnt lgkmcnt(0)
	s_add_u32 s6, s6, s10
	s_addc_u32 s7, s7, 0
	v_ashrrev_i32_e32 v1, 31, v0
	v_lshl_add_u64 v[2:3], s[6:7], 0, v[32:33]
	v_lshlrev_b64 v[0:1], 12, v[0:1]
	v_lshl_add_u64 v[28:29], v[2:3], 0, v[0:1]
	v_add_co_u32_e32 v4, vcc, s28, v28
	s_lshl_b32 s10, s9, 1
	s_nop 0
	v_addc_co_u32_e32 v5, vcc, 0, v29, vcc
	v_add_co_u32_e32 v8, vcc, s29, v28
	global_load_dwordx4 v[0:3], v[28:29], off
	s_nop 0
	global_load_dwordx4 v[4:7], v[4:5], off
	v_addc_co_u32_e32 v9, vcc, 0, v29, vcc
	v_add_co_u32_e32 v12, vcc, s30, v28
	v_add_u32_e32 v50, s8, v51
	s_nop 0
	v_addc_co_u32_e32 v13, vcc, 0, v29, vcc
	v_add_co_u32_e32 v16, vcc, s31, v28
	global_load_dwordx4 v[8:11], v[8:9], off
	s_nop 0
	global_load_dwordx4 v[12:15], v[12:13], off
	v_addc_co_u32_e32 v17, vcc, 0, v29, vcc
	v_add_co_u32_e32 v20, vcc, s34, v28
	v_lshl_add_u64 v[56:57], v[38:39], 0, s[10:11]
	s_nop 0
	v_addc_co_u32_e32 v21, vcc, 0, v29, vcc
	global_load_dwordx4 v[16:19], v[16:17], off
	s_nop 0
	global_load_dwordx4 v[20:23], v[20:21], off
	v_add_co_u32_e32 v24, vcc, s35, v28
	v_add_u32_e32 v52, s8, v53
	s_nop 0
	v_addc_co_u32_e32 v25, vcc, 0, v29, vcc
	global_load_dwordx4 v[24:27], v[24:25], off
	v_add_co_u32_e32 v28, vcc, s36, v28
	v_mad_i64_i32 v[60:61], s[6:7], v50, s37, v[56:57]
	s_nop 0
	v_addc_co_u32_e32 v29, vcc, 0, v29, vcc
	global_load_dwordx4 v[28:31], v[28:29], off
	v_mad_i64_i32 v[82:83], s[6:7], v52, s37, v[56:57]
	s_waitcnt vmcnt(0)
	ds_write2_b32 v65, v0, v1 offset1:1
	ds_write2_b32 v65, v2, v3 offset0:2 offset1:3
	ds_write2_b32 v67, v4, v5 offset1:1
	ds_write2_b32 v68, v6, v7 offset1:1
	ds_write2_b32 v69, v8, v9 offset1:1
	ds_write2_b32 v70, v10, v11 offset1:1
	ds_write2_b32 v71, v12, v13 offset1:1
	ds_write2_b32 v72, v14, v15 offset1:1
	ds_write2_b32 v73, v16, v17 offset1:1
	ds_write2_b32 v74, v18, v19 offset1:1
	ds_write2_b32 v75, v20, v21 offset1:1
	ds_write2_b32 v76, v22, v23 offset1:1
	ds_write2_b32 v77, v24, v25 offset1:1
	ds_write2_b32 v78, v26, v27 offset1:1
	ds_write2_b32 v79, v28, v29 offset1:1
	ds_write2_b32 v80, v30, v31 offset1:1
	s_waitcnt lgkmcnt(0)
	ds_read2_b32 v[4:5], v63 offset0:33 offset1:41
	ds_read2_b32 v[6:7], v63 offset1:8
	ds_read2_b32 v[8:9], v63 offset0:66 offset1:74
	ds_read2_b32 v[10:11], v63 offset0:99 offset1:107
	ds_read2_b32 v[12:13], v63 offset0:132 offset1:140
	ds_read2_b32 v[14:15], v63 offset0:165 offset1:173
	ds_read2_b32 v[16:17], v63 offset0:198 offset1:206
	ds_read2_b32 v[18:19], v63 offset0:231 offset1:239
	ds_read2_b32 v[20:21], v63 offset0:49 offset1:57
	ds_read2_b32 v[22:23], v63 offset0:16 offset1:24
	ds_read2_b32 v[24:25], v63 offset0:82 offset1:90
	ds_read2_b32 v[26:27], v63 offset0:115 offset1:123
	ds_read2_b32 v[28:29], v63 offset0:148 offset1:156
	ds_read2_b32 v[30:31], v63 offset0:181 offset1:189
	ds_read2_b32 v[84:85], v63 offset0:214 offset1:222
	ds_read2_b32 v[86:87], v63 offset0:247 offset1:255
	s_waitcnt lgkmcnt(14)
	v_cvt_pk_bf16_f32 v0, v6, v4
	s_waitcnt lgkmcnt(12)
	v_cvt_pk_bf16_f32 v1, v8, v10
	s_waitcnt lgkmcnt(10)
	v_cvt_pk_bf16_f32 v2, v12, v14
	s_waitcnt lgkmcnt(8)
	v_cvt_pk_bf16_f32 v3, v16, v18
	v_cvt_pk_bf16_f32 v4, v7, v5
	v_cvt_pk_bf16_f32 v5, v9, v11
	v_cvt_pk_bf16_f32 v6, v13, v15
	v_cvt_pk_bf16_f32 v7, v17, v19
	global_store_dwordx4 v[60:61], v[0:3], off sc1
	global_store_dwordx4 v[82:83], v[4:7], off sc1
	s_waitcnt lgkmcnt(6)
	v_cvt_pk_bf16_f32 v0, v22, v20
	v_add_u32_e32 v4, s8, v55
	s_waitcnt lgkmcnt(4)
	v_cvt_pk_bf16_f32 v1, v24, v26
	s_waitcnt lgkmcnt(2)
	v_cvt_pk_bf16_f32 v2, v28, v30
	s_waitcnt lgkmcnt(0)
	v_cvt_pk_bf16_f32 v3, v84, v86
	v_mad_i64_i32 v[4:5], s[6:7], v4, s37, v[56:57]
	global_store_dwordx4 v[4:5], v[0:3], off sc1
	v_add_u32_e32 v4, s8, v59
	v_mad_i64_i32 v[4:5], s[6:7], v4, s37, v[56:57]
	v_cvt_pk_bf16_f32 v0, v23, v21
	v_cvt_pk_bf16_f32 v1, v25, v27
	v_cvt_pk_bf16_f32 v2, v29, v31
	v_cvt_pk_bf16_f32 v3, v85, v87
	global_store_dwordx4 v[4:5], v[0:3], off sc1
	s_waitcnt lgkmcnt(0)

; __device__ __forceinline__ unsigned pk_bf16(float lo, float hi) { typedef __bf16 b2_t __attribute__((ext_vector_type(2))); f32x2 v = {lo, hi}; b2_t b = __builtin_convertvector(v, b2_t); return __builtin_bit_cast(unsigned, b); }
; #define LAS __attribute__((address_space(3)))
; __device__ __forceinline__ void transpose_tile(const float* W, const float* gain, int K, int N, int k0, int n0, bf16* WT, int drow0, LAS float* scr, int lane) {
;     f32x4 v[8]; float gv[8];
;     const int r0 = lane >> 3, c4 = lane & 7;
; #pragma unroll
;     for (int i = 0; i < 8; ++i) { v[i] = *(const f32x4*)(W + (size_t)(k0 + r0 + 8 * i) * N + n0 + 4 * c4); gv[i] = gain ? gain[k0 + r0 + 8 * i] : 1.0f; }
; #pragma unroll
;     for (int i = 0; i < 8; ++i) { LAS float* d = scr + (r0 + 8 * i) * 33 + 4 * c4; d[0] = v[i][0] * gv[i]; d[1] = v[i][1] * gv[i]; d[2] = v[i][2] * gv[i]; d[3] = v[i][3] * gv[i]; }
;     asm volatile("s_waitcnt lgkmcnt(0)" ::: "memory");
;     const int c = lane & 7;
; #pragma unroll
;     for (int j = 0; j < 4; ++j) { const int n = (lane >> 3) + 8 * j; const LAS float* s = scr + (8 * c) * 33 + n;
;         v4u o; o.x = pk_bf16(s[0 * 33], s[1 * 33]); o.y = pk_bf16(s[2 * 33], s[3 * 33]); o.z = pk_bf16(s[4 * 33], s[5 * 33]); o.w = pk_bf16(s[6 * 33], s[7 * 33]);
;         *(v4u*)(WT + (size_t)(drow0 + n) * K + k0 + 8 * c) = o; }
;     asm volatile("s_waitcnt lgkmcnt(0)" ::: "memory");
; }
.LBB0_1069:
	s_andn2_b64 vcc, exec, s[8:9]
	s_cbranch_vccnz .LBB0_1071
	s_mov_b32 s6, 8
	s_ashr_i32 s7, s6, 31
	s_lshl_b64 s[6:7], s[6:7], 3
	s_add_u32 s6, s0, s6
	s_addc_u32 s7, s1, s7
	s_load_dwordx2 s[6:7], s[6:7], 0x0
	s_lshl_b32 s8, s22, 5
	s_and_b32 s8, s8, 0x3e0
	s_add_i32 s9, s26, 0x3b00
	s_and_b32 s9, s9, 0x1ffc0
	s_lshl_b32 s10, s8, 2
	v_add_u32_e32 v0, s9, v51
	s_waitcnt lgkmcnt(0)
	s_add_u32 s6, s6, s10
	s_addc_u32 s7, s7, 0
	v_ashrrev_i32_e32 v1, 31, v0
	v_lshl_add_u64 v[2:3], s[6:7], 0, v[32:33]
	v_lshlrev_b64 v[0:1], 12, v[0:1]
	v_lshl_add_u64 v[28:29], v[2:3], 0, v[0:1]
	v_add_co_u32_e32 v4, vcc, s28, v28
	v_add_u32_e32 v56, s8, v51
	s_nop 0
	v_addc_co_u32_e32 v5, vcc, 0, v29, vcc
	v_add_co_u32_e32 v8, vcc, s29, v28
	global_load_dwordx4 v[0:3], v[28:29], off
	s_nop 0
	global_load_dwordx4 v[4:7], v[4:5], off
	v_addc_co_u32_e32 v9, vcc, 0, v29, vcc
	v_add_co_u32_e32 v12, vcc, s30, v28
	v_ashrrev_i32_e32 v57, 31, v56
	s_nop 0
	v_addc_co_u32_e32 v13, vcc, 0, v29, vcc
	v_add_co_u32_e32 v16, vcc, s31, v28
	global_load_dwordx4 v[8:11], v[8:9], off
	s_nop 0
	global_load_dwordx4 v[12:15], v[12:13], off
	v_addc_co_u32_e32 v17, vcc, 0, v29, vcc
	v_add_co_u32_e32 v20, vcc, s34, v28
	s_lshl_b32 s10, s9, 1
	s_nop 0
	v_addc_co_u32_e32 v21, vcc, 0, v29, vcc
	global_load_dwordx4 v[16:19], v[16:17], off
	s_nop 0
	global_load_dwordx4 v[20:23], v[20:21], off
	v_add_co_u32_e32 v24, vcc, s35, v28
	v_lshlrev_b64 v[56:57], 11, v[56:57]
	s_nop 0
	v_addc_co_u32_e32 v25, vcc, 0, v29, vcc
	global_load_dwordx4 v[24:27], v[24:25], off
	v_add_co_u32_e32 v28, vcc, s36, v28
	v_lshl_add_u64 v[82:83], v[42:43], 0, s[10:11]
	s_nop 0
	v_addc_co_u32_e32 v29, vcc, 0, v29, vcc
	global_load_dwordx4 v[28:31], v[28:29], off
	v_add_u32_e32 v60, s8, v53
	v_lshl_add_u64 v[56:57], v[82:83], 0, v[56:57]
	v_ashrrev_i32_e32 v61, 31, v60
	v_lshlrev_b64 v[60:61], 11, v[60:61]
	v_lshl_add_u64 v[60:61], v[82:83], 0, v[60:61]
	s_waitcnt vmcnt(0)
	ds_write2_b32 v65, v0, v1 offset1:1
	ds_write2_b32 v65, v2, v3 offset0:2 offset1:3
	ds_write2_b32 v67, v4, v5 offset1:1
	ds_write2_b32 v68, v6, v7 offset1:1
	ds_write2_b32 v69, v8, v9 offset1:1
	ds_write2_b32 v70, v10, v11 offset1:1
	ds_write2_b32 v71, v12, v13 offset1:1
	ds_write2_b32 v72, v14, v15 offset1:1
	ds_write2_b32 v73, v16, v17 offset1:1
	ds_write2_b32 v74, v18, v19 offset1:1
	ds_write2_b32 v75, v20, v21 offset1:1
	ds_write2_b32 v76, v22, v23 offset1:1
	ds_write2_b32 v77, v24, v25 offset1:1
	ds_write2_b32 v78, v26, v27 offset1:1
	ds_write2_b32 v79, v28, v29 offset1:1
	ds_write2_b32 v80, v30, v31 offset1:1
	s_waitcnt lgkmcnt(0)
	ds_read2_b32 v[4:5], v63 offset0:33 offset1:41
	ds_read2_b32 v[6:7], v63 offset1:8
	ds_read2_b32 v[8:9], v63 offset0:66 offset1:74
	ds_read2_b32 v[10:11], v63 offset0:99 offset1:107
	ds_read2_b32 v[12:13], v63 offset0:132 offset1:140
	ds_read2_b32 v[14:15], v63 offset0:165 offset1:173
	ds_read2_b32 v[16:17], v63 offset0:198 offset1:206
	ds_read2_b32 v[18:19], v63 offset0:231 offset1:239
	ds_read2_b32 v[20:21], v63 offset0:49 offset1:57
	ds_read2_b32 v[22:23], v63 offset0:16 offset1:24
	ds_read2_b32 v[24:25], v63 offset0:82 offset1:90
	ds_read2_b32 v[26:27], v63 offset0:115 offset1:123
	ds_read2_b32 v[28:29], v63 offset0:148 offset1:156
	ds_read2_b32 v[30:31], v63 offset0:181 offset1:189
	s_waitcnt lgkmcnt(12)
	v_cvt_pk_bf16_f32 v0, v6, v4
	s_waitcnt lgkmcnt(10)
	v_cvt_pk_bf16_f32 v1, v8, v10
	s_waitcnt lgkmcnt(8)
	v_cvt_pk_bf16_f32 v2, v12, v14
	s_waitcnt lgkmcnt(6)
	v_cvt_pk_bf16_f32 v3, v16, v18
	global_store_dwordx4 v[56:57], v[0:3], off sc1
	v_cvt_pk_bf16_f32 v4, v7, v5
	v_cvt_pk_bf16_f32 v5, v9, v11
	ds_read2_b32 v[8:9], v63 offset0:214 offset1:222
	ds_read2_b32 v[10:11], v63 offset0:247 offset1:255
	v_cvt_pk_bf16_f32 v6, v13, v15
	v_cvt_pk_bf16_f32 v7, v17, v19
	global_store_dwordx4 v[60:61], v[4:7], off sc1
	s_waitcnt lgkmcnt(6)
	v_cvt_pk_bf16_f32 v0, v22, v20
	s_waitcnt lgkmcnt(4)
	v_cvt_pk_bf16_f32 v1, v24, v26
	v_add_u32_e32 v4, s8, v55
	v_ashrrev_i32_e32 v5, 31, v4
	v_lshlrev_b64 v[4:5], 11, v[4:5]
	s_waitcnt lgkmcnt(2)
	v_cvt_pk_bf16_f32 v2, v28, v30
	s_waitcnt lgkmcnt(0)
	v_cvt_pk_bf16_f32 v3, v8, v10
	v_lshl_add_u64 v[4:5], v[82:83], 0, v[4:5]
	global_store_dwordx4 v[4:5], v[0:3], off sc1
	v_add_u32_e32 v4, s8, v59
	v_ashrrev_i32_e32 v5, 31, v4
	v_lshlrev_b64 v[4:5], 11, v[4:5]
	v_cvt_pk_bf16_f32 v0, v23, v21
	v_cvt_pk_bf16_f32 v1, v25, v27
	v_cvt_pk_bf16_f32 v2, v29, v31
	v_cvt_pk_bf16_f32 v3, v9, v11
	v_lshl_add_u64 v[4:5], v[82:83], 0, v[4:5]
	global_store_dwordx4 v[4:5], v[0:3], off sc1
	s_waitcnt lgkmcnt(0)

; __device__ __forceinline__ unsigned pk_bf16(float lo, float hi) { typedef __bf16 b2_t __attribute__((ext_vector_type(2))); f32x2 v = {lo, hi}; b2_t b = __builtin_convertvector(v, b2_t); return __builtin_bit_cast(unsigned, b); }
; #define LAS __attribute__((address_space(3)))
; __device__ __forceinline__ void transpose_tile(const float* W, const float* gain, int K, int N, int k0, int n0, bf16* WT, int drow0, LAS float* scr, int lane) {
;     f32x4 v[8]; float gv[8];
;     const int r0 = lane >> 3, c4 = lane & 7;
; #pragma unroll
;     for (int i = 0; i < 8; ++i) { v[i] = *(const f32x4*)(W + (size_t)(k0 + r0 + 8 * i) * N + n0 + 4 * c4); gv[i] = gain ? gain[k0 + r0 + 8 * i] : 1.0f; }
; #pragma unroll
;     for (int i = 0; i < 8; ++i) { LAS float* d = scr + (r0 + 8 * i) * 33 + 4 * c4; d[0] = v[i][0] * gv[i]; d[1] = v[i][1] * gv[i]; d[2] = v[i][2] * gv[i]; d[3] = v[i][3] * gv[i]; }
;     asm volatile("s_waitcnt lgkmcnt(0)" ::: "memory");
;     const int c = lane & 7;
; #pragma unroll
;     for (int j = 0; j < 4; ++j) { const int n = (lane >> 3) + 8 * j; const LAS float* s = scr + (8 * c) * 33 + n;
;         v4u o; o.x = pk_bf16(s[0 * 33], s[1 * 33]); o.y = pk_bf16(s[2 * 33], s[3 * 33]); o.z = pk_bf16(s[4 * 33], s[5 * 33]); o.w = pk_bf16(s[6 * 33], s[7 * 33]);
;         *(v4u*)(WT + (size_t)(drow0 + n) * K + k0 + 8 * c) = o; }
;     asm volatile("s_waitcnt lgkmcnt(0)" ::: "memory");
; }
.LBB0_1091:
	s_andn2_b64 vcc, exec, s[8:9]
	s_cbranch_vccnz .LBB0_1093
	s_mov_b32 s6, 3
	s_ashr_i32 s7, s6, 31
	s_lshl_b64 s[6:7], s[6:7], 3
	s_add_u32 s6, s0, s6
	s_addc_u32 s7, s1, s7
	s_load_dwordx2 s[6:7], s[6:7], 0x0
	s_lshl_b32 s8, s22, 5
	s_and_b32 s8, s8, 0x3e0
	s_add_i32 s9, s26, 0x5200
	s_and_b32 s9, s9, 0x1ffc0
	s_lshl_b32 s10, s8, 2
	v_add_u32_e32 v0, s9, v51
	s_waitcnt lgkmcnt(0)
	s_add_u32 s6, s6, s10
	s_addc_u32 s7, s7, 0
	v_ashrrev_i32_e32 v1, 31, v0
	v_lshl_add_u64 v[2:3], s[6:7], 0, v[32:33]
	v_lshlrev_b64 v[0:1], 12, v[0:1]
	v_lshl_add_u64 v[28:29], v[2:3], 0, v[0:1]
	v_add_co_u32_e32 v4, vcc, s28, v28
	s_lshl_b32 s10, s9, 1
	s_nop 0
	v_addc_co_u32_e32 v5, vcc, 0, v29, vcc
	v_add_co_u32_e32 v8, vcc, s29, v28
	global_load_dwordx4 v[0:3], v[28:29], off
	s_nop 0
	global_load_dwordx4 v[4:7], v[4:5], off
	v_addc_co_u32_e32 v9, vcc, 0, v29, vcc
	v_add_co_u32_e32 v12, vcc, s30, v28
	v_add_u32_e32 v50, s8, v51
	s_nop 0
	v_addc_co_u32_e32 v13, vcc, 0, v29, vcc
	v_add_co_u32_e32 v16, vcc, s31, v28
	global_load_dwordx4 v[8:11], v[8:9], off
	s_nop 0
	global_load_dwordx4 v[12:15], v[12:13], off
	v_addc_co_u32_e32 v17, vcc, 0, v29, vcc
	v_add_co_u32_e32 v20, vcc, s34, v28
	v_lshl_add_u64 v[56:57], v[46:47], 0, s[10:11]
	s_nop 0
	v_addc_co_u32_e32 v21, vcc, 0, v29, vcc
	global_load_dwordx4 v[16:19], v[16:17], off
	s_nop 0
	global_load_dwordx4 v[20:23], v[20:21], off
	v_add_co_u32_e32 v24, vcc, s35, v28
	v_add_u32_e32 v52, s8, v53
	s_nop 0
	v_addc_co_u32_e32 v25, vcc, 0, v29, vcc
	global_load_dwordx4 v[24:27], v[24:25], off
	v_add_co_u32_e32 v28, vcc, s36, v28
	v_mad_i64_i32 v[60:61], s[6:7], v50, s37, v[56:57]
	s_nop 0
	v_addc_co_u32_e32 v29, vcc, 0, v29, vcc
	global_load_dwordx4 v[28:31], v[28:29], off
	v_mad_i64_i32 v[82:83], s[6:7], v52, s37, v[56:57]
	s_waitcnt vmcnt(0)
	ds_write2_b32 v65, v0, v1 offset1:1
	ds_write2_b32 v65, v2, v3 offset0:2 offset1:3
	ds_write2_b32 v67, v4, v5 offset1:1
	ds_write2_b32 v68, v6, v7 offset1:1
	ds_write2_b32 v69, v8, v9 offset1:1
	ds_write2_b32 v70, v10, v11 offset1:1
	ds_write2_b32 v71, v12, v13 offset1:1
	ds_write2_b32 v72, v14, v15 offset1:1
	ds_write2_b32 v73, v16, v17 offset1:1
	ds_write2_b32 v74, v18, v19 offset1:1
	ds_write2_b32 v75, v20, v21 offset1:1
	ds_write2_b32 v76, v22, v23 offset1:1
	ds_write2_b32 v77, v24, v25 offset1:1
	ds_write2_b32 v78, v26, v27 offset1:1
	ds_write2_b32 v79, v28, v29 offset1:1
	ds_write2_b32 v80, v30, v31 offset1:1
	s_waitcnt lgkmcnt(0)
	ds_read2_b32 v[4:5], v63 offset0:33 offset1:41
	ds_read2_b32 v[6:7], v63 offset1:8
	ds_read2_b32 v[8:9], v63 offset0:66 offset1:74
	ds_read2_b32 v[10:11], v63 offset0:99 offset1:107
	ds_read2_b32 v[12:13], v63 offset0:132 offset1:140
	ds_read2_b32 v[14:15], v63 offset0:165 offset1:173
	ds_read2_b32 v[16:17], v63 offset0:198 offset1:206
	ds_read2_b32 v[18:19], v63 offset0:231 offset1:239
	ds_read2_b32 v[20:21], v63 offset0:49 offset1:57
	ds_read2_b32 v[22:23], v63 offset0:16 offset1:24
	ds_read2_b32 v[24:25], v63 offset0:82 offset1:90
	ds_read2_b32 v[26:27], v63 offset0:115 offset1:123
	ds_read2_b32 v[28:29], v63 offset0:148 offset1:156
	ds_read2_b32 v[30:31], v63 offset0:181 offset1:189
	ds_read2_b32 v[84:85], v63 offset0:214 offset1:222
	ds_read2_b32 v[86:87], v63 offset0:247 offset1:255
	s_waitcnt lgkmcnt(14)
	v_cvt_pk_bf16_f32 v0, v6, v4
	s_waitcnt lgkmcnt(12)
	v_cvt_pk_bf16_f32 v1, v8, v10
	s_waitcnt lgkmcnt(10)
	v_cvt_pk_bf16_f32 v2, v12, v14
	s_waitcnt lgkmcnt(8)
	v_cvt_pk_bf16_f32 v3, v16, v18
	v_cvt_pk_bf16_f32 v4, v7, v5
	v_cvt_pk_bf16_f32 v5, v9, v11
	v_cvt_pk_bf16_f32 v6, v13, v15
	v_cvt_pk_bf16_f32 v7, v17, v19
	global_store_dwordx4 v[60:61], v[0:3], off sc1
	global_store_dwordx4 v[82:83], v[4:7], off sc1
	s_waitcnt lgkmcnt(6)
	v_cvt_pk_bf16_f32 v0, v22, v20
	v_add_u32_e32 v4, s8, v55
	s_waitcnt lgkmcnt(4)
	v_cvt_pk_bf16_f32 v1, v24, v26
	s_waitcnt lgkmcnt(2)
	v_cvt_pk_bf16_f32 v2, v28, v30
	s_waitcnt lgkmcnt(0)
	v_cvt_pk_bf16_f32 v3, v84, v86
	v_mad_i64_i32 v[4:5], s[6:7], v4, s37, v[56:57]
	global_store_dwordx4 v[4:5], v[0:3], off sc1
	v_add_u32_e32 v4, s8, v59
	v_mad_i64_i32 v[4:5], s[6:7], v4, s37, v[56:57]
	v_cvt_pk_bf16_f32 v0, v23, v21
	v_cvt_pk_bf16_f32 v1, v25, v27
	v_cvt_pk_bf16_f32 v2, v29, v31
	v_cvt_pk_bf16_f32 v3, v85, v87
	global_store_dwordx4 v[4:5], v[0:3], off sc1
	s_waitcnt lgkmcnt(0)

; __device__ __forceinline__ int lane_id_() { int l; asm volatile("v_mbcnt_lo_u32_b32 %0, -1, 0\n\tv_mbcnt_hi_u32_b32 %0, -1, %0" : "=v"(l)); return l; }
; __device__ __forceinline__ unsigned xb_ld(unsigned* p)              { return __hip_atomic_load(p, __ATOMIC_RELAXED, __HIP_MEMORY_SCOPE_AGENT); }
; __device__ __forceinline__ unsigned xb_add(unsigned* p, unsigned v) { return __hip_atomic_fetch_add(p, v, __ATOMIC_RELAXED, __HIP_MEMORY_SCOPE_AGENT); }
; #define XB_SPIN(cond, bar) do { unsigned _sp = 0; while (cond) { __builtin_amdgcn_s_sleep(1); \
;     if ((++_sp & 255u) == 0u) { if (xb_ld(&(bar)[XB_TMO])) break; if (_sp > XB_SPIN_CAP) { atomicAdd(&(bar)[XB_TMO], 1u); break; } } } } while (0)
; __device__ __forceinline__ void transpose_tile(const float* W, const float* gain, int K, int N, int k0, int n0, bf16* WT, int drow0, LAS float* scr, int lane) {
;     ...
;     for (int i = 0; i < 8; ++i) { v[i] = *(const f32x4*)(W + (size_t)(k0 + r0 + 8 * i) * N + n0 + 4 * c4); gv[i] = gain ? gain[k0 + r0 + 8 * i] : 1.0f; }
; __device__ __forceinline__ void xcd_barrier(const XcdBarrier& b, int wave_s) {
;     asm volatile("s_waitcnt vmcnt(0)" ::: "memory");
;     __syncthreads();
;     if (wave_s == 0 && lane_id_() == 0) {
;         unsigned* bar = b.bar;
;         __builtin_amdgcn_s_waitcnt(0);
;         unsigned nloc = b.st[0], nx = b.st[1];
;         if (nloc == 0u) { xcd_barrier_complete(bar, b.x, nloc, nx); b.st[0] = nloc; b.st[1] = nx; }
;         const unsigned old = xb_add(&bar[XB_XSUB(b.x)], 1u);
;         const unsigned gen = old / nloc;
;         if (old + 1u == (gen + 1u) * nloc) {
;             __builtin_amdgcn_fence(__ATOMIC_RELEASE, "agent");
;             asm volatile("s_waitcnt vmcnt(0)" ::: "memory");
;             const unsigned og = xb_add(&bar[XB_TOP], 1u);
;             const unsigned tg = og / nx;
;             if (og + 1u == (tg + 1u) * nx) xb_add(&bar[XB_TOPGEN], 1u);
;             else XB_SPIN(xb_ld(&bar[XB_TOPGEN]) == tg, bar);
;             __builtin_amdgcn_fence(__ATOMIC_ACQUIRE, "agent");
;             xb_add(&bar[XB_XGEN(b.x)], 1u);
.LBB0_1109:
	v_add_u32_e32 v28, 56, v28
	v_mad_i64_i32 v[28:29], s[20:21], v28, s38, v[30:31]
	global_load_dwordx4 v[28:31], v[28:29], off
	s_and_b64 vcc, exec, s[8:9]
	s_cbranch_vccnz .LBB0_1018
	global_load_dword v64, v[60:61], off offset:224
	s_branch .LBB0_1018
.LBB0_1111:
	s_waitcnt vmcnt(0)
	s_and_b64 vcc, exec, s[2:3]
	s_waitcnt vmcnt(0)
	s_barrier
	s_cbranch_vccnz .LBB0_1165
	v_mbcnt_lo_u32_b32 v0, -1, 0
	v_mbcnt_hi_u32_b32 v0, -1, v0
	s_nop 0
	v_cmp_eq_u32_e32 vcc, 0, v0
	s_and_saveexec_b64 s[8:9], vcc
	s_cbranch_execz .LBB0_1164
	s_cmp_eq_u32 s101, 1
	s_cbranch_scc0 .Lglob_S7
	s_and_b32 s98, s33, 7
	s_lshl_b32 s99, s98, 2
	s_addk_i32 s99, 0x4800
	v_mov_b32_e32 v3, s99
	s_lshl_b32 s98, s98, 8
	s_addk_i32 s98, 0x4000
	v_mov_b32_e32 v0, s98
	v_mov_b32_e32 v1, 1
	global_atomic_add v2, v0, v1, s[44:45] sc0
	buffer_inv sc1
	s_waitcnt vmcnt(1)
	v_readfirstlane_b32 s98, v2
	s_nop 3
	s_add_u32 s99, s98, 1
	s_and_b32 s99, s99, 31
	s_lshr_b32 s98, s98, 5
	s_cmp_eq_u32 s99, 0
	s_cbranch_scc0 .Llw_S7
	global_atomic_add v3, v1, s[44:45]
.Llw_S7:
	s_add_u32 s98, s98, 1
	s_mov_b64 exec, 0xff
	v_mbcnt_lo_u32_b32 v0, -1, 0
	v_lshlrev_b32_e32 v0, 2, v0
	v_add_u32_e32 v0, 0x4800, v0
	s_mov_b32 s99, 0

; #define PG8_LAS __attribute__((address_space(3)))
; __device__ __forceinline__ unsigned pk_bf16(float lo, float hi) { typedef __bf16 b2_t __attribute__((ext_vector_type(2))); f32x2 v = {lo, hi}; b2_t b = __builtin_convertvector(v, b2_t); return __builtin_bit_cast(unsigned, b); }
;     __device__ __forceinline__ void operator()(const f32x4 (&acc)[2][2][4][2], const Unit& u, int wr, int wc, int fr, int fq, PG8_LAS unsigned char* lds, int wid) const {
;         const int row0 = u.pm * BM + wr * 64 + fr, col0 = u.pn * HALF + wc * 32 + 8 * fq;
; #pragma unroll
;         for (int ai = 0; ai < 2; ++ai)
; #pragma unroll
;             for (int m = 0; m < 4; ++m) {
;                 bf16_t* p = H + (size_t)(row0 + ai * HALF + m * 16) * ldh + col0;
;                 const float rstd = __builtin_amdgcn_rsqf(*(const PG8_LAS float*)(lds + PRE_SLOT + wid * 512 + (m & 1) * 256 + (fr + 16 * ((ai * 4 + m) >> 1)) * 4) * (1.0f / 1024.0f) + 1e-6f);
;                 const float c1 = -1.44269504089f * rstd, r2 = rstd * rstd;
;                 f32x2 hh[4];
; #pragma unroll
;                 for (int q = 0; q < 4; ++q) {
;                     const f32x2 ag = {acc[ai][0][m][q >> 1][2 * (q & 1)], acc[ai][0][m][q >> 1][2 * (q & 1) + 1]};
;                     const f32x2 au = {acc[ai][1][m][q >> 1][2 * (q & 1)], acc[ai][1][m][q >> 1][2 * (q & 1) + 1]};
;                     const f32x2 t = ag * c1;
;                     f32x2 e; e.x = __builtin_amdgcn_exp2f(t.x); e.y = __builtin_amdgcn_exp2f(t.y);
;                     const f32x2 d = e + 1.0f;
;                     f32x2 r; r.x = __builtin_amdgcn_rcpf(d.x); r.y = __builtin_amdgcn_rcpf(d.y);
;                     hh[q] = (ag * au) * (r * r2);
;                 }
;                 u32x4 w; w.x = pk_bf16(hh[0].x, hh[0].y); w.y = pk_bf16(hh[1].x, hh[1].y); w.z = pk_bf16(hh[2].x, hh[2].y); w.w = pk_bf16(hh[3].x, hh[3].y);
;                 *(u32x4*)p = w;
.LBB0_1281:
	v_add_u32_e32 v163, s76, v145
	ds_read2_b32 v[154:155], v163 offset1:16
	v_lshl_or_b32 v156, s35, 7, v147
	v_lshl_add_u32 v0, s34, 8, v144
	v_ashrrev_i32_e32 v157, 31, v156
	s_andn2_b64 vcc, exec, s[8:9]
	s_waitcnt lgkmcnt(0)
	v_fmamk_f32 v2, v154, 0x3a800000, v148
	v_rsq_f32_e32 v162, v2
	v_mov_b64_e32 v[2:3], s[50:51]
	v_mad_i64_i32 v[160:161], s[6:7], v0, s92, v[2:3]
	v_mul_f32_e32 v154, 0xbfb8aa3b, v162
	v_pk_mul_f32 v[158:159], v[124:125], v[154:155] op_sel_hi:[1,0]
	v_pk_mul_f32 v[164:165], v[126:127], v[154:155] op_sel_hi:[1,0]
	v_exp_f32_e32 v158, v158
	v_exp_f32_e32 v159, v159
	v_exp_f32_e32 v164, v164
	v_exp_f32_e32 v165, v165
	v_mul_f32_e32 v162, v162, v162
	v_pk_add_f32 v[158:159], v[158:159], 1.0 op_sel_hi:[1,0]
	v_pk_mul_f32 v[126:127], v[126:127], v[130:131]
	v_rcp_f32_e32 v158, v158
	v_rcp_f32_e32 v159, v159
	v_pk_add_f32 v[130:131], v[164:165], 1.0 op_sel_hi:[1,0]
	v_pk_mul_f32 v[124:125], v[124:125], v[128:129]
	v_rcp_f32_e32 v130, v130
	v_pk_mul_f32 v[128:129], v[162:163], v[158:159] op_sel_hi:[0,1]
	v_rcp_f32_e32 v131, v131
	v_pk_mul_f32 v[158:159], v[116:117], v[154:155] op_sel_hi:[1,0]
	v_pk_mul_f32 v[124:125], v[124:125], v[128:129]
	v_exp_f32_e32 v158, v158
	v_exp_f32_e32 v159, v159
	v_pk_mul_f32 v[128:129], v[162:163], v[130:131] op_sel_hi:[0,1]
	v_pk_mul_f32 v[126:127], v[126:127], v[128:129]
	v_pk_mul_f32 v[130:131], v[118:119], v[154:155] op_sel_hi:[1,0]
	v_pk_add_f32 v[128:129], v[158:159], 1.0 op_sel_hi:[1,0]
	v_exp_f32_e32 v130, v130
	v_exp_f32_e32 v131, v131
	v_rcp_f32_e32 v128, v128
	v_rcp_f32_e32 v129, v129
	v_pk_mul_f32 v[118:119], v[118:119], v[122:123]
	v_pk_add_f32 v[122:123], v[130:131], 1.0 op_sel_hi:[1,0]
	v_pk_mul_f32 v[116:117], v[116:117], v[120:121]
	v_pk_mul_f32 v[120:121], v[162:163], v[128:129] op_sel_hi:[0,1]
	ds_read2_b32 v[128:129], v163 offset0:64 offset1:80
	v_rcp_f32_e32 v122, v122
	v_rcp_f32_e32 v123, v123
	v_pk_mul_f32 v[120:121], v[116:117], v[120:121]
	s_mov_b64 s[8:9], -1
	v_cvt_pk_bf16_f32 v120, v120, v121
	v_pk_mul_f32 v[116:117], v[162:163], v[122:123] op_sel_hi:[0,1]
	s_waitcnt lgkmcnt(0)
	v_fmamk_f32 v121, v128, 0x3a800000, v148
	v_pk_mul_f32 v[122:123], v[118:119], v[116:117]
	v_cvt_pk_bf16_f32 v118, v124, v125
	v_rsq_f32_e32 v124, v121
	v_lshlrev_b64 v[116:117], 1, v[156:157]
	v_lshl_add_u64 v[130:131], v[160:161], 0, v[116:117]
	v_cvt_pk_bf16_f32 v119, v126, v127
	v_cvt_pk_bf16_f32 v121, v122, v123
	global_store_dwordx4 v[130:131], v[118:121], off sc1
	s_nop 1
	v_or_b32_e32 v119, 16, v0
	v_mul_f32_e32 v118, 0xbfb8aa3b, v124
	v_pk_mul_f32 v[120:121], v[108:109], v[118:119] op_sel_hi:[1,0]
	v_pk_mul_f32 v[126:127], v[110:111], v[118:119] op_sel_hi:[1,0]
	v_exp_f32_e32 v120, v120
	v_exp_f32_e32 v121, v121
	v_exp_f32_e32 v126, v126
	v_exp_f32_e32 v127, v127
	v_pk_mul_f32 v[110:111], v[110:111], v[114:115]
	v_pk_add_f32 v[120:121], v[120:121], 1.0 op_sel_hi:[1,0]
	v_mul_f32_e32 v124, v124, v124
	v_rcp_f32_e32 v120, v120
	v_rcp_f32_e32 v121, v121
	v_pk_add_f32 v[114:115], v[126:127], 1.0 op_sel_hi:[1,0]
	v_pk_mul_f32 v[108:109], v[108:109], v[112:113]
	v_rcp_f32_e32 v114, v114
	v_rcp_f32_e32 v115, v115
	v_pk_mul_f32 v[112:113], v[124:125], v[120:121] op_sel_hi:[0,1]
	v_pk_mul_f32 v[120:121], v[100:101], v[118:119] op_sel_hi:[1,0]
	v_pk_mul_f32 v[108:109], v[108:109], v[112:113]
	v_exp_f32_e32 v120, v120
	v_exp_f32_e32 v121, v121
	v_pk_mul_f32 v[112:113], v[124:125], v[114:115] op_sel_hi:[0,1]
	v_pk_mul_f32 v[114:115], v[102:103], v[118:119] op_sel_hi:[1,0]
	v_pk_mul_f32 v[110:111], v[110:111], v[112:113]
	v_exp_f32_e32 v114, v114
	v_exp_f32_e32 v115, v115
	v_pk_add_f32 v[112:113], v[120:121], 1.0 op_sel_hi:[1,0]
	v_pk_mul_f32 v[102:103], v[102:103], v[106:107]
	v_rcp_f32_e32 v112, v112
	v_rcp_f32_e32 v113, v113
	v_pk_add_f32 v[106:107], v[114:115], 1.0 op_sel_hi:[1,0]
	v_pk_mul_f32 v[100:101], v[100:101], v[104:105]
	v_rcp_f32_e32 v106, v106
	v_rcp_f32_e32 v107, v107
	v_pk_mul_f32 v[104:105], v[124:125], v[112:113] op_sel_hi:[0,1]
	v_pk_mul_f32 v[104:105], v[100:101], v[104:105]
	v_mad_i64_i32 v[122:123], s[6:7], v119, s92, v[2:3]
	v_pk_mul_f32 v[100:101], v[124:125], v[106:107] op_sel_hi:[0,1]
	v_pk_mul_f32 v[106:107], v[102:103], v[100:101]
	v_fmamk_f32 v103, v155, 0x3a800000, v148
	v_cvt_pk_bf16_f32 v100, v108, v109
	v_rsq_f32_e32 v108, v103
	v_lshl_add_u64 v[112:113], v[122:123], 0, v[116:117]
	v_cvt_pk_bf16_f32 v101, v110, v111
	v_cvt_pk_bf16_f32 v102, v104, v105
	v_cvt_pk_bf16_f32 v103, v106, v107
	global_store_dwordx4 v[112:113], v[100:103], off sc1
	v_mul_f32_e32 v106, v108, v108
	s_nop 0
	v_or_b32_e32 v101, 32, v0
	v_mul_f32_e32 v100, 0xbfb8aa3b, v108
	v_pk_mul_f32 v[102:103], v[92:93], v[100:101] op_sel_hi:[1,0]
	v_pk_mul_f32 v[108:109], v[94:95], v[100:101] op_sel_hi:[1,0]
	v_exp_f32_e32 v102, v102
	v_exp_f32_e32 v103, v103
	v_exp_f32_e32 v108, v108
	v_exp_f32_e32 v109, v109
	v_pk_mul_f32 v[94:95], v[94:95], v[98:99]
	v_pk_add_f32 v[102:103], v[102:103], 1.0 op_sel_hi:[1,0]
	v_pk_mul_f32 v[92:93], v[92:93], v[96:97]
	v_rcp_f32_e32 v102, v102
	v_rcp_f32_e32 v103, v103
	v_pk_add_f32 v[98:99], v[108:109], 1.0 op_sel_hi:[1,0]
	v_mad_i64_i32 v[104:105], s[6:7], v101, s92, v[2:3]
	v_rcp_f32_e32 v98, v98
	v_rcp_f32_e32 v99, v99
	v_pk_mul_f32 v[96:97], v[106:107], v[102:103] op_sel_hi:[0,1]
	v_pk_mul_f32 v[102:103], v[84:85], v[100:101] op_sel_hi:[1,0]
	v_pk_mul_f32 v[92:93], v[92:93], v[96:97]
	v_exp_f32_e32 v102, v102
	v_exp_f32_e32 v103, v103
	v_pk_mul_f32 v[96:97], v[106:107], v[98:99] op_sel_hi:[0,1]
	v_pk_mul_f32 v[98:99], v[86:87], v[100:101] op_sel_hi:[1,0]
	v_pk_mul_f32 v[94:95], v[94:95], v[96:97]
	v_exp_f32_e32 v98, v98
	v_exp_f32_e32 v99, v99
; #define PG8_LAS __attribute__((address_space(3)))
; __device__ __forceinline__ unsigned pk_bf16(float lo, float hi) { typedef __bf16 b2_t __attribute__((ext_vector_type(2))); f32x2 v = {lo, hi}; b2_t b = __builtin_convertvector(v, b2_t); return __builtin_bit_cast(unsigned, b); }
;     __device__ __forceinline__ void operator()(const f32x4 (&acc)[2][2][4][2], const Unit& u, int wr, int wc, int fr, int fq, PG8_LAS unsigned char* lds, int wid) const {
;     ...
;             for (int m = 0; m < 4; ++m) {
;                 bf16_t* p = H + (size_t)(row0 + ai * HALF + m * 16) * ldh + col0;
;                 const float rstd = __builtin_amdgcn_rsqf(*(const PG8_LAS float*)(lds + PRE_SLOT + wid * 512 + (m & 1) * 256 + (fr + 16 * ((ai * 4 + m) >> 1)) * 4) * (1.0f / 1024.0f) + 1e-6f);
;                 const float c1 = -1.44269504089f * rstd, r2 = rstd * rstd;
;                 f32x2 hh[4];
; #pragma unroll
;                 for (int q = 0; q < 4; ++q) {
;                     const f32x2 ag = {acc[ai][0][m][q >> 1][2 * (q & 1)], acc[ai][0][m][q >> 1][2 * (q & 1) + 1]};
;                     const f32x2 au = {acc[ai][1][m][q >> 1][2 * (q & 1)], acc[ai][1][m][q >> 1][2 * (q & 1) + 1]};
;                     const f32x2 t = ag * c1;
;                     f32x2 e; e.x = __builtin_amdgcn_exp2f(t.x); e.y = __builtin_amdgcn_exp2f(t.y);
;                     const f32x2 d = e + 1.0f;
;                     f32x2 r; r.x = __builtin_amdgcn_rcpf(d.x); r.y = __builtin_amdgcn_rcpf(d.y);
;                     hh[q] = (ag * au) * (r * r2);
;                 }
;                 u32x4 w; w.x = pk_bf16(hh[0].x, hh[0].y); w.y = pk_bf16(hh[1].x, hh[1].y); w.z = pk_bf16(hh[2].x, hh[2].y); w.w = pk_bf16(hh[3].x, hh[3].y);
;                 *(u32x4*)p = w;
	v_pk_add_f32 v[96:97], v[102:103], 1.0 op_sel_hi:[1,0]
	v_pk_mul_f32 v[86:87], v[86:87], v[90:91]
	v_rcp_f32_e32 v96, v96
	v_rcp_f32_e32 v97, v97
	v_pk_add_f32 v[90:91], v[98:99], 1.0 op_sel_hi:[1,0]
	v_pk_mul_f32 v[84:85], v[84:85], v[88:89]
	v_rcp_f32_e32 v90, v90
	v_rcp_f32_e32 v91, v91
	v_pk_mul_f32 v[88:89], v[106:107], v[96:97] op_sel_hi:[0,1]
	v_pk_mul_f32 v[88:89], v[84:85], v[88:89]
	v_lshl_add_u64 v[96:97], v[104:105], 0, v[116:117]
	v_pk_mul_f32 v[84:85], v[106:107], v[90:91] op_sel_hi:[0,1]
	v_pk_mul_f32 v[90:91], v[86:87], v[84:85]
	v_fmamk_f32 v87, v129, 0x3a800000, v148
	v_cvt_pk_bf16_f32 v84, v92, v93
	v_rsq_f32_e32 v92, v87
	v_cvt_pk_bf16_f32 v85, v94, v95
	v_cvt_pk_bf16_f32 v86, v88, v89
	v_cvt_pk_bf16_f32 v87, v90, v91
	global_store_dwordx4 v[96:97], v[84:87], off sc1
	v_mul_f32_e32 v90, v92, v92
	s_nop 0
	v_or_b32_e32 v85, 48, v0
	v_mul_f32_e32 v84, 0xbfb8aa3b, v92
	v_pk_mul_f32 v[86:87], v[76:77], v[84:85] op_sel_hi:[1,0]
	v_pk_mul_f32 v[92:93], v[78:79], v[84:85] op_sel_hi:[1,0]
	v_exp_f32_e32 v86, v86
	v_exp_f32_e32 v87, v87
	v_exp_f32_e32 v92, v92
	v_exp_f32_e32 v93, v93
	v_pk_mul_f32 v[78:79], v[78:79], v[82:83]
	v_pk_add_f32 v[86:87], v[86:87], 1.0 op_sel_hi:[1,0]
	v_pk_mul_f32 v[76:77], v[76:77], v[80:81]
	v_rcp_f32_e32 v86, v86
	v_rcp_f32_e32 v87, v87
	v_pk_add_f32 v[82:83], v[92:93], 1.0 op_sel_hi:[1,0]
	v_mad_i64_i32 v[88:89], s[6:7], v85, s92, v[2:3]
	v_pk_mul_f32 v[80:81], v[90:91], v[86:87] op_sel_hi:[0,1]
	v_rcp_f32_e32 v82, v82
	v_rcp_f32_e32 v83, v83
	v_pk_mul_f32 v[86:87], v[60:61], v[84:85] op_sel_hi:[1,0]
	v_pk_mul_f32 v[76:77], v[76:77], v[80:81]
	v_exp_f32_e32 v86, v86
	v_exp_f32_e32 v87, v87
	v_pk_mul_f32 v[80:81], v[90:91], v[82:83] op_sel_hi:[0,1]
	v_pk_mul_f32 v[82:83], v[62:63], v[84:85] op_sel_hi:[1,0]
	v_pk_mul_f32 v[78:79], v[78:79], v[80:81]
	v_pk_add_f32 v[80:81], v[86:87], 1.0 op_sel_hi:[1,0]
	v_exp_f32_e32 v82, v82
	v_exp_f32_e32 v83, v83
	v_rcp_f32_e32 v80, v80
	v_rcp_f32_e32 v81, v81
	v_pk_mul_f32 v[62:63], v[62:63], v[70:71]
	v_pk_add_f32 v[70:71], v[82:83], 1.0 op_sel_hi:[1,0]
	v_pk_mul_f32 v[60:61], v[60:61], v[68:69]
	v_rcp_f32_e32 v70, v70
	v_rcp_f32_e32 v71, v71
	v_pk_mul_f32 v[68:69], v[90:91], v[80:81] op_sel_hi:[0,1]
	ds_read2_b32 v[80:81], v163 offset0:32 offset1:48
	v_pk_mul_f32 v[68:69], v[60:61], v[68:69]
	v_pk_mul_f32 v[60:61], v[90:91], v[70:71] op_sel_hi:[0,1]
	v_pk_mul_f32 v[70:71], v[62:63], v[60:61]
	v_cvt_pk_bf16_f32 v60, v76, v77
	s_waitcnt lgkmcnt(0)
	v_fmamk_f32 v63, v80, 0x3a800000, v148
	v_rsq_f32_e32 v76, v63
	v_lshl_add_u64 v[82:83], v[88:89], 0, v[116:117]
	v_cvt_pk_bf16_f32 v61, v78, v79
	v_cvt_pk_bf16_f32 v62, v68, v69
	v_cvt_pk_bf16_f32 v63, v70, v71
	global_store_dwordx4 v[82:83], v[60:63], off sc1
	v_mul_f32_e32 v70, v76, v76
	s_nop 0
	v_add_u32_e32 v61, 0x80, v0
	v_mul_f32_e32 v60, 0xbfb8aa3b, v76
	v_pk_mul_f32 v[62:63], v[64:65], v[60:61] op_sel_hi:[1,0]
	v_pk_mul_f32 v[76:77], v[66:67], v[60:61] op_sel_hi:[1,0]
	v_exp_f32_e32 v62, v62
	v_exp_f32_e32 v63, v63
	v_exp_f32_e32 v76, v76
	v_exp_f32_e32 v77, v77
	v_pk_mul_f32 v[64:65], v[64:65], v[72:73]
	v_pk_add_f32 v[62:63], v[62:63], 1.0 op_sel_hi:[1,0]
	v_pk_mul_f32 v[66:67], v[66:67], v[74:75]
	v_rcp_f32_e32 v62, v62
	v_rcp_f32_e32 v63, v63
	v_pk_add_f32 v[72:73], v[76:77], 1.0 op_sel_hi:[1,0]
	v_pk_mul_f32 v[74:75], v[52:53], v[60:61] op_sel_hi:[1,0]
	v_rcp_f32_e32 v72, v72
	v_rcp_f32_e32 v73, v73
	v_mad_i64_i32 v[68:69], s[6:7], v61, s92, v[2:3]
	v_exp_f32_e32 v74, v74
	v_exp_f32_e32 v75, v75
	v_pk_mul_f32 v[60:61], v[54:55], v[60:61] op_sel_hi:[1,0]
	v_pk_mul_f32 v[62:63], v[70:71], v[62:63] op_sel_hi:[0,1]
	v_exp_f32_e32 v60, v60
	v_exp_f32_e32 v61, v61
	v_pk_mul_f32 v[62:63], v[64:65], v[62:63]
	v_pk_mul_f32 v[64:65], v[70:71], v[72:73] op_sel_hi:[0,1]
	v_pk_mul_f32 v[64:65], v[66:67], v[64:65]
	v_pk_add_f32 v[66:67], v[74:75], 1.0 op_sel_hi:[1,0]
	v_pk_mul_f32 v[54:55], v[54:55], v[58:59]
	v_rcp_f32_e32 v66, v66
	v_rcp_f32_e32 v67, v67
	v_pk_add_f32 v[58:59], v[60:61], 1.0 op_sel_hi:[1,0]
	ds_read2_b32 v[60:61], v163 offset0:96 offset1:112
	v_rcp_f32_e32 v58, v58
	v_rcp_f32_e32 v59, v59
	v_pk_mul_f32 v[52:53], v[52:53], v[56:57]
	v_pk_mul_f32 v[56:57], v[70:71], v[66:67] op_sel_hi:[0,1]
	v_pk_mul_f32 v[56:57], v[52:53], v[56:57]
	v_pk_mul_f32 v[52:53], v[70:71], v[58:59] op_sel_hi:[0,1]
	v_pk_mul_f32 v[58:59], v[54:55], v[52:53]
	s_waitcnt lgkmcnt(0)
; #define PG8_LAS __attribute__((address_space(3)))
; #define PG8_BAR __builtin_amdgcn_s_barrier()
;     __device__ __forceinline__ void operator()(const f32x4 (&acc)[2][2][4][2], const Unit& u, int wr, int wc, int fr, int fq, PG8_LAS unsigned char* lds, int wid) const {
;     ...
;             for (int m = 0; m < 4; ++m) {
;                 bf16_t* p = H + (size_t)(row0 + ai * HALF + m * 16) * ldh + col0;
;                 const float rstd = __builtin_amdgcn_rsqf(*(const PG8_LAS float*)(lds + PRE_SLOT + wid * 512 + (m & 1) * 256 + (fr + 16 * ((ai * 4 + m) >> 1)) * 4) * (1.0f / 1024.0f) + 1e-6f);
;                 const float c1 = -1.44269504089f * rstd, r2 = rstd * rstd;
;                 f32x2 hh[4];
; #pragma unroll
;                 for (int q = 0; q < 4; ++q) {
;                     const f32x2 ag = {acc[ai][0][m][q >> 1][2 * (q & 1)], acc[ai][0][m][q >> 1][2 * (q & 1) + 1]};
;                     const f32x2 au = {acc[ai][1][m][q >> 1][2 * (q & 1)], acc[ai][1][m][q >> 1][2 * (q & 1) + 1]};
;                     const f32x2 t = ag * c1;
;                     f32x2 e; e.x = __builtin_amdgcn_exp2f(t.x); e.y = __builtin_amdgcn_exp2f(t.y);
;                     const f32x2 d = e + 1.0f;
;                     f32x2 r; r.x = __builtin_amdgcn_rcpf(d.x); r.y = __builtin_amdgcn_rcpf(d.y);
;                     hh[q] = (ag * au) * (r * r2);
;                 }
;                 u32x4 w; w.x = pk_bf16(hh[0].x, hh[0].y); w.y = pk_bf16(hh[1].x, hh[1].y); w.z = pk_bf16(hh[2].x, hh[2].y); w.w = pk_bf16(hh[3].x, hh[3].y);
;                 *(u32x4*)p = w;
; template <class Epi, class Sched, bool ALIGN_EPI = false, bool SP2 = false>
; __device__ __forceinline__ void gemm_phase(PG8_LAS unsigned char* lds, const Gemm g, const Sched& S, const Epi& E, int wave_s) {
;     ...
;         if constexpr (!Epi::AFTER_DRAIN) { E(acc, cur, wr, wc, fr, fq, lds, wid); S.done(cur); }
;         if (!has_next) break;
; #pragma unroll
;         for (int a = 0; a < 2; ++a)
; #pragma unroll
;             for (int b = 0; b < 2; ++b)
; #pragma unroll
;                 for (int m = 0; m < 4; ++m)
; #pragma unroll
;                     for (int n = 0; n < 2; ++n) acc[a][b][m][n] = (f32x4){0.f, 0.f, 0.f, 0.f};
;         cur = nxt; cA = nA; cB = nB; ++ui;
;         if constexpr (ALIGN_EPI) { if (wr == 1) PG8_BAR; }
	v_fmamk_f32 v55, v60, 0x3a800000, v148
	v_rsq_f32_e32 v60, v55
	v_lshl_add_u64 v[66:67], v[68:69], 0, v[116:117]
	v_cvt_pk_bf16_f32 v52, v62, v63
	v_cvt_pk_bf16_f32 v53, v64, v65
	v_cvt_pk_bf16_f32 v54, v56, v57
	v_cvt_pk_bf16_f32 v55, v58, v59
	global_store_dwordx4 v[66:67], v[52:55], off sc1
	v_mul_f32_e32 v58, v60, v60
	s_nop 0
	v_add_u32_e32 v53, 0x90, v0
	v_mul_f32_e32 v52, 0xbfb8aa3b, v60
	v_pk_mul_f32 v[54:55], v[44:45], v[52:53] op_sel_hi:[1,0]
	v_pk_mul_f32 v[62:63], v[46:47], v[52:53] op_sel_hi:[1,0]
	v_exp_f32_e32 v54, v54
	v_exp_f32_e32 v55, v55
	v_exp_f32_e32 v62, v62
	v_exp_f32_e32 v63, v63
	v_pk_mul_f32 v[46:47], v[46:47], v[50:51]
	v_pk_add_f32 v[54:55], v[54:55], 1.0 op_sel_hi:[1,0]
	v_pk_mul_f32 v[44:45], v[44:45], v[48:49]
	v_rcp_f32_e32 v54, v54
	v_rcp_f32_e32 v55, v55
	v_pk_add_f32 v[50:51], v[62:63], 1.0 op_sel_hi:[1,0]
	v_mad_i64_i32 v[56:57], s[6:7], v53, s92, v[2:3]
	v_rcp_f32_e32 v50, v50
	v_rcp_f32_e32 v51, v51
	v_pk_mul_f32 v[48:49], v[58:59], v[54:55] op_sel_hi:[0,1]
	v_pk_mul_f32 v[54:55], v[36:37], v[52:53] op_sel_hi:[1,0]
	v_pk_mul_f32 v[44:45], v[44:45], v[48:49]
	v_exp_f32_e32 v54, v54
	v_exp_f32_e32 v55, v55
	v_pk_mul_f32 v[48:49], v[58:59], v[50:51] op_sel_hi:[0,1]
	v_pk_mul_f32 v[50:51], v[38:39], v[52:53] op_sel_hi:[1,0]
	v_pk_mul_f32 v[46:47], v[46:47], v[48:49]
	v_exp_f32_e32 v50, v50
	v_exp_f32_e32 v51, v51
	v_pk_add_f32 v[48:49], v[54:55], 1.0 op_sel_hi:[1,0]
	v_pk_mul_f32 v[38:39], v[38:39], v[42:43]
	v_rcp_f32_e32 v48, v48
	v_rcp_f32_e32 v49, v49
	v_pk_add_f32 v[42:43], v[50:51], 1.0 op_sel_hi:[1,0]
	v_pk_mul_f32 v[36:37], v[36:37], v[40:41]
	v_rcp_f32_e32 v42, v42
	v_rcp_f32_e32 v43, v43
	v_pk_mul_f32 v[40:41], v[58:59], v[48:49] op_sel_hi:[0,1]
	v_pk_mul_f32 v[40:41], v[36:37], v[40:41]
	v_lshl_add_u64 v[48:49], v[56:57], 0, v[116:117]
	v_pk_mul_f32 v[36:37], v[58:59], v[42:43] op_sel_hi:[0,1]
	v_pk_mul_f32 v[42:43], v[38:39], v[36:37]
	v_fmamk_f32 v39, v81, 0x3a800000, v148
	v_cvt_pk_bf16_f32 v36, v44, v45
	v_rsq_f32_e32 v44, v39
	v_cvt_pk_bf16_f32 v37, v46, v47
	v_cvt_pk_bf16_f32 v38, v40, v41
	v_cvt_pk_bf16_f32 v39, v42, v43
	global_store_dwordx4 v[48:49], v[36:39], off sc1
	v_mul_f32_e32 v42, v44, v44
	s_nop 0
	v_add_u32_e32 v37, 0xa0, v0
	v_mul_f32_e32 v36, 0xbfb8aa3b, v44
	v_pk_mul_f32 v[38:39], v[28:29], v[36:37] op_sel_hi:[1,0]
	v_pk_mul_f32 v[44:45], v[30:31], v[36:37] op_sel_hi:[1,0]
	v_exp_f32_e32 v38, v38
	v_exp_f32_e32 v39, v39
	v_exp_f32_e32 v44, v44
	v_exp_f32_e32 v45, v45
	v_pk_mul_f32 v[30:31], v[30:31], v[34:35]
	v_pk_add_f32 v[38:39], v[38:39], 1.0 op_sel_hi:[1,0]
	v_pk_mul_f32 v[28:29], v[28:29], v[32:33]
	v_rcp_f32_e32 v38, v38
	v_rcp_f32_e32 v39, v39
	v_pk_add_f32 v[34:35], v[44:45], 1.0 op_sel_hi:[1,0]
	v_mad_i64_i32 v[40:41], s[6:7], v37, s92, v[2:3]
	v_rcp_f32_e32 v34, v34
	v_rcp_f32_e32 v35, v35
	v_pk_mul_f32 v[32:33], v[42:43], v[38:39] op_sel_hi:[0,1]
	v_pk_mul_f32 v[38:39], v[20:21], v[36:37] op_sel_hi:[1,0]
	v_pk_mul_f32 v[28:29], v[28:29], v[32:33]
	v_exp_f32_e32 v38, v38
	v_exp_f32_e32 v39, v39
	v_pk_mul_f32 v[32:33], v[42:43], v[34:35] op_sel_hi:[0,1]
	v_pk_mul_f32 v[34:35], v[22:23], v[36:37] op_sel_hi:[1,0]
	v_pk_mul_f32 v[30:31], v[30:31], v[32:33]
	v_exp_f32_e32 v34, v34
	v_exp_f32_e32 v35, v35
	v_pk_add_f32 v[32:33], v[38:39], 1.0 op_sel_hi:[1,0]
	v_pk_mul_f32 v[22:23], v[22:23], v[26:27]
	v_rcp_f32_e32 v32, v32
	v_rcp_f32_e32 v33, v33
	v_pk_add_f32 v[26:27], v[34:35], 1.0 op_sel_hi:[1,0]
	v_pk_mul_f32 v[20:21], v[20:21], v[24:25]
	v_rcp_f32_e32 v26, v26
	v_rcp_f32_e32 v27, v27
	v_pk_mul_f32 v[24:25], v[42:43], v[32:33] op_sel_hi:[0,1]
	v_pk_mul_f32 v[24:25], v[20:21], v[24:25]
	v_lshl_add_u64 v[32:33], v[40:41], 0, v[116:117]
	v_pk_mul_f32 v[20:21], v[42:43], v[26:27] op_sel_hi:[0,1]
	v_pk_mul_f32 v[26:27], v[22:23], v[20:21]
	v_fmamk_f32 v23, v61, 0x3a800000, v148
	v_cvt_pk_bf16_f32 v22, v24, v25
	v_rsq_f32_e32 v24, v23
	v_cvt_pk_bf16_f32 v20, v28, v29
	v_cvt_pk_bf16_f32 v21, v30, v31
	v_cvt_pk_bf16_f32 v23, v26, v27
	global_store_dwordx4 v[32:33], v[20:23], off sc1
	s_nop 1
	v_add_u32_e32 v22, 0xb0, v0
	v_mul_f32_e32 v0, 0xbfb8aa3b, v24
	v_pk_mul_f32 v[20:21], v[12:13], v[0:1] op_sel_hi:[1,0]
	v_mad_i64_i32 v[2:3], s[6:7], v22, s92, v[2:3]
	v_exp_f32_e32 v20, v20
	v_exp_f32_e32 v21, v21
	v_mul_f32_e32 v22, v24, v24
	v_pk_mul_f32 v[24:25], v[14:15], v[0:1] op_sel_hi:[1,0]
	v_pk_mul_f32 v[14:15], v[14:15], v[18:19]
	v_exp_f32_e32 v24, v24
	v_exp_f32_e32 v25, v25
	v_pk_add_f32 v[20:21], v[20:21], 1.0 op_sel_hi:[1,0]
	v_pk_mul_f32 v[12:13], v[12:13], v[16:17]
	v_rcp_f32_e32 v20, v20
	v_rcp_f32_e32 v21, v21
	v_pk_add_f32 v[18:19], v[24:25], 1.0 op_sel_hi:[1,0]
	v_pk_mul_f32 v[16:17], v[22:23], v[20:21] op_sel_hi:[0,1]
	v_rcp_f32_e32 v18, v18
	v_rcp_f32_e32 v19, v19
	v_pk_mul_f32 v[20:21], v[4:5], v[0:1] op_sel_hi:[1,0]
	v_pk_mul_f32 v[12:13], v[12:13], v[16:17]
	v_exp_f32_e32 v20, v20
	v_exp_f32_e32 v21, v21
	v_pk_mul_f32 v[16:17], v[22:23], v[18:19] op_sel_hi:[0,1]
	v_pk_mul_f32 v[18:19], v[6:7], v[0:1] op_sel_hi:[1,0]
	v_pk_mul_f32 v[14:15], v[14:15], v[16:17]
	v_exp_f32_e32 v18, v18
	v_exp_f32_e32 v19, v19
	v_pk_add_f32 v[16:17], v[20:21], 1.0 op_sel_hi:[1,0]
	v_pk_mul_f32 v[6:7], v[6:7], v[10:11]
	v_rcp_f32_e32 v16, v16
	v_rcp_f32_e32 v17, v17
	v_pk_add_f32 v[10:11], v[18:19], 1.0 op_sel_hi:[1,0]
	v_pk_mul_f32 v[4:5], v[4:5], v[8:9]
	v_rcp_f32_e32 v10, v10
	v_rcp_f32_e32 v11, v11
	v_pk_mul_f32 v[8:9], v[22:23], v[16:17] op_sel_hi:[0,1]
	v_pk_mul_f32 v[4:5], v[4:5], v[8:9]
	v_pk_mul_f32 v[8:9], v[22:23], v[10:11] op_sel_hi:[0,1]
	v_pk_mul_f32 v[6:7], v[6:7], v[8:9]
	v_lshl_add_u64 v[8:9], v[2:3], 0, v[116:117]
	v_cvt_pk_bf16_f32 v2, v12, v13
	v_cvt_pk_bf16_f32 v3, v14, v15
	v_cvt_pk_bf16_f32 v4, v4, v5
	v_cvt_pk_bf16_f32 v5, v6, v7
	global_store_dwordx4 v[8:9], v[2:5], off sc1
	s_cbranch_vccnz .LBB0_1274
	s_andn2_b64 vcc, exec, s[20:21]
	s_cbranch_vccnz .LBB0_1273
	s_barrier
	s_branch .LBB0_1273

; __device__ __forceinline__ unsigned pk_bf16(float lo, float hi) { typedef __bf16 b2_t __attribute__((ext_vector_type(2))); f32x2 v = {lo, hi}; b2_t b = __builtin_convertvector(v, b2_t); return __builtin_bit_cast(unsigned, b); }
; #define LAS __attribute__((address_space(3)))
; __device__ __forceinline__ void transpose_tile(const float* W, const float* gain, int K, int N, int k0, int n0, bf16* WT, int drow0, LAS float* scr, int lane) {
;     f32x4 v[8]; float gv[8];
;     const int r0 = lane >> 3, c4 = lane & 7;
; #pragma unroll
;     for (int i = 0; i < 8; ++i) { v[i] = *(const f32x4*)(W + (size_t)(k0 + r0 + 8 * i) * N + n0 + 4 * c4); gv[i] = gain ? gain[k0 + r0 + 8 * i] : 1.0f; }
; #pragma unroll
;     for (int i = 0; i < 8; ++i) { LAS float* d = scr + (r0 + 8 * i) * 33 + 4 * c4; d[0] = v[i][0] * gv[i]; d[1] = v[i][1] * gv[i]; d[2] = v[i][2] * gv[i]; d[3] = v[i][3] * gv[i]; }
;     asm volatile("s_waitcnt lgkmcnt(0)" ::: "memory");
;     const int c = lane & 7;
; #pragma unroll
;     for (int j = 0; j < 4; ++j) { const int n = (lane >> 3) + 8 * j; const LAS float* s = scr + (8 * c) * 33 + n;
;         v4u o; o.x = pk_bf16(s[0 * 33], s[1 * 33]); o.y = pk_bf16(s[2 * 33], s[3 * 33]); o.z = pk_bf16(s[4 * 33], s[5 * 33]); o.w = pk_bf16(s[6 * 33], s[7 * 33]);
;         *(v4u*)(WT + (size_t)(drow0 + n) * K + k0 + 8 * c) = o; }
;     asm volatile("s_waitcnt lgkmcnt(0)" ::: "memory");
; }
; template <bool SWIGLU> __device__ __forceinline__ void transpose_item(const float* W, const float* gain, int K, int N, bf16* WT, LAS float* scr, int item, int lane) {
;     const int nblk = N / 32, kb = item / nblk, nb = item % nblk, n0 = 32 * nb;
;     int drow0 = n0;
;     if (SWIGLU) { const int up = n0 >= FF, f = up ? n0 - FF : n0; drow0 = 256 * (f >> 7) + (up ? 128 : 0) + (f & 127); }
.LBB0_1287:
	s_waitcnt vmcnt(0)
	v_pk_mul_f32 v[0:1], v[0:1], v[88:89] op_sel_hi:[1,0]
	v_add_u32_e32 v33, v35, v89
	ds_write2_b32 v33, v0, v1 offset1:1
	v_pk_mul_f32 v[0:1], v[2:3], v[88:89] op_sel_hi:[1,0]
	ds_write2_b32 v33, v0, v1 offset0:2 offset1:3
	v_pk_mul_f32 v[0:1], v[4:5], v[36:37] op_sel_hi:[1,0]
	v_add_u32_e32 v2, 0x420, v33
	ds_write2_b32 v2, v0, v1 offset1:1
	v_pk_mul_f32 v[0:1], v[6:7], v[36:37] op_sel_hi:[1,0]
	v_add_u32_e32 v2, 0x428, v33
	ds_write2_b32 v2, v0, v1 offset1:1
	v_pk_mul_f32 v[0:1], v[8:9], v[94:95] op_sel_hi:[1,0]
	v_add_u32_e32 v2, 0x840, v33
	ds_write2_b32 v2, v0, v1 offset1:1
	v_pk_mul_f32 v[0:1], v[10:11], v[94:95] op_sel_hi:[1,0]
	v_add_u32_e32 v2, 0x848, v33
	ds_write2_b32 v2, v0, v1 offset1:1
	v_pk_mul_f32 v[0:1], v[12:13], v[90:91] op_sel_hi:[1,0]
	v_add_u32_e32 v2, 0xc60, v33
	ds_write2_b32 v2, v0, v1 offset1:1
	v_pk_mul_f32 v[0:1], v[14:15], v[90:91] op_sel_hi:[1,0]
	v_add_u32_e32 v2, 0xc68, v33
	ds_write2_b32 v2, v0, v1 offset1:1
	v_pk_mul_f32 v[0:1], v[16:17], v[100:101] op_sel_hi:[1,0]
	v_add_u32_e32 v2, 0x1080, v33
	ds_write2_b32 v2, v0, v1 offset1:1
	v_pk_mul_f32 v[0:1], v[18:19], v[100:101] op_sel_hi:[1,0]
	v_add_u32_e32 v2, 0x1088, v33
	ds_write2_b32 v2, v0, v1 offset1:1
	v_pk_mul_f32 v[0:1], v[20:21], v[92:93] op_sel_hi:[1,0]
	v_add_u32_e32 v2, 0x14a0, v33
	ds_write2_b32 v2, v0, v1 offset1:1
	v_pk_mul_f32 v[0:1], v[22:23], v[92:93] op_sel_hi:[1,0]
	v_add_u32_e32 v2, 0x14a8, v33
	ds_write2_b32 v2, v0, v1 offset1:1
	v_pk_mul_f32 v[0:1], v[24:25], v[102:103] op_sel_hi:[1,0]
	v_add_u32_e32 v2, 0x18c0, v33
	s_mulk_i32 s6, 0xff50
	ds_write2_b32 v2, v0, v1 offset1:1
	v_pk_mul_f32 v[0:1], v[26:27], v[102:103] op_sel_hi:[1,0]
	v_add_u32_e32 v2, 0x18c8, v33
	s_add_i32 s6, s26, s6
	s_add_i32 s7, s22, 0xfffff500
	ds_write2_b32 v2, v0, v1 offset1:1
	v_pk_mul_f32 v[0:1], v[28:29], v[96:97] op_sel_hi:[1,0]
	v_add_u32_e32 v2, 0x1ce0, v33
	s_cmpk_gt_i32 s6, 0x57
	ds_write2_b32 v2, v0, v1 offset1:1
	v_pk_mul_f32 v[0:1], v[30:31], v[96:97] op_sel_hi:[1,0]
	v_add_u32_e32 v2, 0x1ce8, v33
	s_cselect_b32 s6, s7, s22
	ds_write2_b32 v2, v0, v1 offset1:1
	s_cselect_b32 s7, 0x80, 0
	s_lshl_b32 s8, s6, 1
	s_and_b32 s6, s6, 0x60
	s_waitcnt lgkmcnt(0)
	s_and_b32 s8, s8, 0xffffff00
	s_or_b32 s6, s6, s7
	ds_read2_b32 v[4:5], v93 offset0:33 offset1:41
	ds_read2_b32 v[6:7], v93 offset1:8
	ds_read2_b32 v[8:9], v93 offset0:66 offset1:74
	ds_read2_b32 v[10:11], v93 offset0:99 offset1:107
	ds_read2_b32 v[12:13], v93 offset0:132 offset1:140
	ds_read2_b32 v[14:15], v93 offset0:165 offset1:173
	ds_read2_b32 v[16:17], v93 offset0:198 offset1:206
	ds_read2_b32 v[18:19], v93 offset0:231 offset1:239
	s_or_b32 s6, s6, s8
	v_add_u32_e32 v22, s6, v32
	s_ashr_i32 s21, s20, 31
	v_ashrrev_i32_e32 v23, 31, v22
	v_lshl_add_u64 v[20:21], s[20:21], 1, v[86:87]
	v_lshlrev_b64 v[22:23], 11, v[22:23]
	s_waitcnt lgkmcnt(6)
	v_cvt_pk_bf16_f32 v0, v6, v4
	s_waitcnt lgkmcnt(4)
	v_cvt_pk_bf16_f32 v1, v8, v10
	s_waitcnt lgkmcnt(2)
	v_cvt_pk_bf16_f32 v2, v12, v14
	s_waitcnt lgkmcnt(0)
	v_cvt_pk_bf16_f32 v3, v16, v18
	v_lshl_add_u64 v[22:23], v[20:21], 0, v[22:23]
	v_add_u32_e32 v4, s6, v38
	global_store_dwordx4 v[22:23], v[0:3], off sc1
	s_nop 1
	v_cvt_pk_bf16_f32 v0, v7, v5
	v_ashrrev_i32_e32 v5, 31, v4
	v_cvt_pk_bf16_f32 v1, v9, v11
	v_cvt_pk_bf16_f32 v2, v13, v15
	v_cvt_pk_bf16_f32 v3, v17, v19
	v_lshlrev_b64 v[4:5], 11, v[4:5]
	ds_read2_b32 v[6:7], v93 offset0:49 offset1:57
	ds_read2_b32 v[8:9], v93 offset0:16 offset1:24
	ds_read2_b32 v[10:11], v93 offset0:82 offset1:90
	ds_read2_b32 v[12:13], v93 offset0:115 offset1:123
	ds_read2_b32 v[14:15], v93 offset0:148 offset1:156
	ds_read2_b32 v[16:17], v93 offset0:181 offset1:189
	ds_read2_b32 v[18:19], v93 offset0:214 offset1:222
	ds_read2_b32 v[22:23], v93 offset0:247 offset1:255
	v_lshl_add_u64 v[4:5], v[20:21], 0, v[4:5]
	global_store_dwordx4 v[4:5], v[0:3], off sc1
	v_add_u32_e32 v4, s6, v40
	v_ashrrev_i32_e32 v5, 31, v4
	v_lshlrev_b64 v[4:5], 11, v[4:5]
	s_waitcnt lgkmcnt(6)
	v_cvt_pk_bf16_f32 v0, v8, v6
	s_waitcnt lgkmcnt(4)
	v_cvt_pk_bf16_f32 v1, v10, v12
	s_waitcnt lgkmcnt(2)
	v_cvt_pk_bf16_f32 v2, v14, v16
	s_waitcnt lgkmcnt(0)
	v_cvt_pk_bf16_f32 v3, v18, v22
	v_lshl_add_u64 v[4:5], v[20:21], 0, v[4:5]
	global_store_dwordx4 v[4:5], v[0:3], off sc1
	v_add_u32_e32 v4, s6, v42
	v_ashrrev_i32_e32 v5, 31, v4
	v_lshlrev_b64 v[4:5], 11, v[4:5]
	v_cvt_pk_bf16_f32 v0, v9, v7
	v_cvt_pk_bf16_f32 v1, v11, v13
	v_cvt_pk_bf16_f32 v2, v15, v17
	v_cvt_pk_bf16_f32 v3, v19, v23
	v_lshl_add_u64 v[4:5], v[20:21], 0, v[4:5]
	global_store_dwordx4 v[4:5], v[0:3], off sc1
	s_waitcnt lgkmcnt(0)

; __device__ __forceinline__ unsigned pk_bf16(float lo, float hi) { typedef __bf16 b2_t __attribute__((ext_vector_type(2))); f32x2 v = {lo, hi}; b2_t b = __builtin_convertvector(v, b2_t); return __builtin_bit_cast(unsigned, b); }
; #define LAS __attribute__((address_space(3)))
; __device__ __forceinline__ void transpose_tile(const float* W, const float* gain, int K, int N, int k0, int n0, bf16* WT, int drow0, LAS float* scr, int lane) {
;     f32x4 v[8]; float gv[8];
;     const int r0 = lane >> 3, c4 = lane & 7;
; #pragma unroll
;     for (int i = 0; i < 8; ++i) { v[i] = *(const f32x4*)(W + (size_t)(k0 + r0 + 8 * i) * N + n0 + 4 * c4); gv[i] = gain ? gain[k0 + r0 + 8 * i] : 1.0f; }
; #pragma unroll
;     for (int i = 0; i < 8; ++i) { LAS float* d = scr + (r0 + 8 * i) * 33 + 4 * c4; d[0] = v[i][0] * gv[i]; d[1] = v[i][1] * gv[i]; d[2] = v[i][2] * gv[i]; d[3] = v[i][3] * gv[i]; }
;     asm volatile("s_waitcnt lgkmcnt(0)" ::: "memory");
;     const int c = lane & 7;
; #pragma unroll
;     for (int j = 0; j < 4; ++j) { const int n = (lane >> 3) + 8 * j; const LAS float* s = scr + (8 * c) * 33 + n;
;         v4u o; o.x = pk_bf16(s[0 * 33], s[1 * 33]); o.y = pk_bf16(s[2 * 33], s[3 * 33]); o.z = pk_bf16(s[4 * 33], s[5 * 33]); o.w = pk_bf16(s[6 * 33], s[7 * 33]);
;         *(v4u*)(WT + (size_t)(drow0 + n) * K + k0 + 8 * c) = o; }
;     asm volatile("s_waitcnt lgkmcnt(0)" ::: "memory");
; }
.LBB0_1289:
	s_cmpk_gt_i32 s26, 0xaff
	s_mov_b64 s[8:9], -1
	s_cbranch_scc0 .LBB0_1419
	s_cmpk_gt_u32 s26, 0x107f
	s_cbranch_scc0 .LBB0_1416
	s_cmpk_gt_u32 s26, 0x167f
	s_cbranch_scc0 .LBB0_1397
	s_cmpk_gt_u32 s26, 0x187f
	s_cbranch_scc0 .LBB0_1394
	s_cmpk_gt_u32 s26, 0x237f
	s_cbranch_scc0 .LBB0_1375
	s_cmpk_gt_u32 s26, 0x28ff
	s_cbranch_scc0 .LBB0_1372
	s_cmpk_gt_u32 s26, 0x33ff
	s_cbranch_scc0 .LBB0_1353
	s_cmpk_gt_u32 s26, 0x397f
	s_cbranch_scc0 .LBB0_1350
	s_cmpk_gt_u32 s26, 0x3d7f
	s_cbranch_scc0 .LBB0_1331
	s_cmpk_gt_u32 s26, 0x3f7f
	s_cbranch_scc0 .LBB0_1328
	s_cmpk_gt_u32 s26, 0x3f9f
	s_cbranch_scc0 .LBB0_1325
	s_cmpk_gt_u32 s26, 0x3fbf
	s_cbranch_scc0 .LBB0_1322
	s_cmpk_gt_u32 s26, 0x4abf
	s_cbranch_scc0 .LBB0_1303
	s_mov_b32 s6, 27
	s_ashr_i32 s7, s6, 31
	s_lshl_b64 s[6:7], s[6:7], 3
	s_add_u32 s6, s0, s6
	s_addc_u32 s7, s1, s7
	s_load_dwordx2 s[6:7], s[6:7], 0x0
	s_lshl_b32 s8, s26, 5
	s_and_b32 s8, s8, 0x3e0
	s_and_b32 s9, s29, 0x1ffc0
	s_lshl_b32 s12, s8, 2
	v_add_u32_e32 v0, s9, v32
	s_waitcnt lgkmcnt(0)
	s_add_u32 s6, s6, s12
	s_addc_u32 s7, s7, 0
	v_lshlrev_b32_e32 v36, 2, v34
	v_ashrrev_i32_e32 v1, 31, v0
	v_lshl_add_u64 v[2:3], s[6:7], 0, v[36:37]
	v_lshlrev_b64 v[0:1], 12, v[0:1]
	v_lshl_add_u64 v[28:29], v[2:3], 0, v[0:1]
	v_add_co_u32_e32 v4, vcc, s31, v28
	v_add_u32_e32 v33, v35, v89
	s_nop 0
	v_addc_co_u32_e32 v5, vcc, 0, v29, vcc
	v_add_co_u32_e32 v8, vcc, s34, v28
	global_load_dwordx4 v[0:3], v[28:29], off
	s_nop 0
	global_load_dwordx4 v[4:7], v[4:5], off
	v_addc_co_u32_e32 v9, vcc, 0, v29, vcc
	v_add_co_u32_e32 v12, vcc, s35, v28
	v_add_u32_e32 v36, 0x420, v33
	s_nop 0
	v_addc_co_u32_e32 v13, vcc, 0, v29, vcc
	v_add_co_u32_e32 v16, vcc, s36, v28
	global_load_dwordx4 v[8:11], v[8:9], off
	s_nop 0
	global_load_dwordx4 v[12:15], v[12:13], off
	v_addc_co_u32_e32 v17, vcc, 0, v29, vcc
	v_add_co_u32_e32 v20, vcc, s37, v28
	v_add_u32_e32 v39, 0x428, v33
	s_nop 0
	v_addc_co_u32_e32 v21, vcc, 0, v29, vcc
	global_load_dwordx4 v[16:19], v[16:17], off
	s_nop 0
	global_load_dwordx4 v[20:23], v[20:21], off
	v_add_co_u32_e32 v24, vcc, s38, v28
	v_add_u32_e32 v41, 0x840, v33
	s_nop 0
	v_addc_co_u32_e32 v25, vcc, 0, v29, vcc
	global_load_dwordx4 v[24:27], v[24:25], off
	v_add_co_u32_e32 v28, vcc, s39, v28
	v_add_u32_e32 v43, 0x848, v33
	s_nop 0
	v_addc_co_u32_e32 v29, vcc, 0, v29, vcc
	global_load_dwordx4 v[28:31], v[28:29], off
	v_add_u32_e32 v88, 0xc60, v33
	v_add_u32_e32 v92, 0xc68, v33
	v_add_u32_e32 v94, 0x1080, v33
	v_add_u32_e32 v95, 0x1088, v33
	v_add_u32_e32 v96, 0x14a0, v33
	v_add_u32_e32 v97, 0x14a8, v33
	v_add_u32_e32 v98, 0x18c0, v33
	v_add_u32_e32 v99, 0x18c8, v33
	v_add_u32_e32 v100, 0x1ce0, v33
	v_add_u32_e32 v101, 0x1ce8, v33
	s_lshl_b32 s12, s9, 1
	v_add_u32_e32 v102, s8, v32
	v_lshl_add_u64 v[90:91], v[44:45], 0, s[12:13]
	s_waitcnt vmcnt(0)
	ds_write2_b32 v33, v0, v1 offset1:1
	ds_write2_b32 v33, v2, v3 offset0:2 offset1:3
	ds_write2_b32 v36, v4, v5 offset1:1
	ds_write2_b32 v39, v6, v7 offset1:1
	ds_write2_b32 v41, v8, v9 offset1:1
	ds_write2_b32 v43, v10, v11 offset1:1
	ds_write2_b32 v88, v12, v13 offset1:1
	ds_write2_b32 v92, v14, v15 offset1:1
	ds_write2_b32 v94, v16, v17 offset1:1
	ds_write2_b32 v95, v18, v19 offset1:1
	ds_write2_b32 v96, v20, v21 offset1:1
	ds_write2_b32 v97, v22, v23 offset1:1
	ds_write2_b32 v98, v24, v25 offset1:1
	ds_write2_b32 v99, v26, v27 offset1:1
	ds_write2_b32 v100, v28, v29 offset1:1
	ds_write2_b32 v101, v30, v31 offset1:1
	s_waitcnt lgkmcnt(0)
	ds_read2_b32 v[4:5], v93 offset0:33 offset1:41
	ds_read2_b32 v[6:7], v93 offset1:8
	ds_read2_b32 v[8:9], v93 offset0:66 offset1:74
	ds_read2_b32 v[10:11], v93 offset0:99 offset1:107
	ds_read2_b32 v[12:13], v93 offset0:132 offset1:140
	ds_read2_b32 v[14:15], v93 offset0:165 offset1:173
	ds_read2_b32 v[16:17], v93 offset0:198 offset1:206
	ds_read2_b32 v[18:19], v93 offset0:231 offset1:239
	v_mad_i64_i32 v[20:21], s[6:7], v102, s40, v[90:91]
	s_waitcnt lgkmcnt(6)
	v_cvt_pk_bf16_f32 v0, v6, v4
	s_waitcnt lgkmcnt(4)
	v_cvt_pk_bf16_f32 v1, v8, v10
	s_waitcnt lgkmcnt(2)
	v_cvt_pk_bf16_f32 v2, v12, v14
	s_waitcnt lgkmcnt(0)
	v_cvt_pk_bf16_f32 v3, v16, v18
	global_store_dwordx4 v[20:21], v[0:3], off sc1
	v_add_u32_e32 v4, s8, v38
	s_nop 0
	v_cvt_pk_bf16_f32 v0, v7, v5
	v_cvt_pk_bf16_f32 v1, v9, v11
	v_cvt_pk_bf16_f32 v2, v13, v15
	v_cvt_pk_bf16_f32 v3, v17, v19
	ds_read2_b32 v[6:7], v93 offset0:49 offset1:57
	ds_read2_b32 v[8:9], v93 offset0:16 offset1:24
	ds_read2_b32 v[10:11], v93 offset0:82 offset1:90
	ds_read2_b32 v[12:13], v93 offset0:115 offset1:123
	ds_read2_b32 v[14:15], v93 offset0:148 offset1:156
	ds_read2_b32 v[16:17], v93 offset0:181 offset1:189
	ds_read2_b32 v[18:19], v93 offset0:214 offset1:222
	ds_read2_b32 v[20:21], v93 offset0:247 offset1:255
	v_mad_i64_i32 v[4:5], s[6:7], v4, s40, v[90:91]
	global_store_dwordx4 v[4:5], v[0:3], off sc1
	v_add_u32_e32 v4, s8, v40
	v_mad_i64_i32 v[4:5], s[6:7], v4, s40, v[90:91]
	s_waitcnt lgkmcnt(6)
	v_cvt_pk_bf16_f32 v0, v8, v6
	s_waitcnt lgkmcnt(4)
	v_cvt_pk_bf16_f32 v1, v10, v12
	s_waitcnt lgkmcnt(2)
	v_cvt_pk_bf16_f32 v2, v14, v16
	s_waitcnt lgkmcnt(0)
	v_cvt_pk_bf16_f32 v3, v18, v20
	global_store_dwordx4 v[4:5], v[0:3], off sc1
	v_add_u32_e32 v4, s8, v42
	v_mad_i64_i32 v[4:5], s[6:7], v4, s40, v[90:91]
	v_cvt_pk_bf16_f32 v0, v9, v7
	v_cvt_pk_bf16_f32 v1, v11, v13
	v_cvt_pk_bf16_f32 v2, v15, v17
	v_cvt_pk_bf16_f32 v3, v19, v21
	global_store_dwordx4 v[4:5], v[0:3], off sc1
	s_waitcnt lgkmcnt(0)
	s_mov_b64 s[8:9], 0

; __device__ __forceinline__ unsigned pk_bf16(float lo, float hi) { typedef __bf16 b2_t __attribute__((ext_vector_type(2))); f32x2 v = {lo, hi}; b2_t b = __builtin_convertvector(v, b2_t); return __builtin_bit_cast(unsigned, b); }
; #define LAS __attribute__((address_space(3)))
; __device__ __forceinline__ void transpose_tile(const float* W, const float* gain, int K, int N, int k0, int n0, bf16* WT, int drow0, LAS float* scr, int lane) {
;     f32x4 v[8]; float gv[8];
;     const int r0 = lane >> 3, c4 = lane & 7;
; #pragma unroll
;     for (int i = 0; i < 8; ++i) { v[i] = *(const f32x4*)(W + (size_t)(k0 + r0 + 8 * i) * N + n0 + 4 * c4); gv[i] = gain ? gain[k0 + r0 + 8 * i] : 1.0f; }
; #pragma unroll
;     for (int i = 0; i < 8; ++i) { LAS float* d = scr + (r0 + 8 * i) * 33 + 4 * c4; d[0] = v[i][0] * gv[i]; d[1] = v[i][1] * gv[i]; d[2] = v[i][2] * gv[i]; d[3] = v[i][3] * gv[i]; }
;     asm volatile("s_waitcnt lgkmcnt(0)" ::: "memory");
;     const int c = lane & 7;
; #pragma unroll
;     for (int j = 0; j < 4; ++j) { const int n = (lane >> 3) + 8 * j; const LAS float* s = scr + (8 * c) * 33 + n;
;         v4u o; o.x = pk_bf16(s[0 * 33], s[1 * 33]); o.y = pk_bf16(s[2 * 33], s[3 * 33]); o.z = pk_bf16(s[4 * 33], s[5 * 33]); o.w = pk_bf16(s[6 * 33], s[7 * 33]);
;         *(v4u*)(WT + (size_t)(drow0 + n) * K + k0 + 8 * c) = o; }
;     asm volatile("s_waitcnt lgkmcnt(0)" ::: "memory");
; }
; template <bool SWIGLU> __device__ __forceinline__ void transpose_item(const float* W, const float* gain, int K, int N, bf16* WT, LAS float* scr, int item, int lane) {
;     const int nblk = N / 32, kb = item / nblk, nb = item % nblk, n0 = 32 * nb;
;     int drow0 = n0;
;     if (SWIGLU) { const int up = n0 >= FF, f = up ? n0 - FF : n0; drow0 = 256 * (f >> 7) + (up ? 128 : 0) + (f & 127); }
.LBB0_1320:
	s_waitcnt vmcnt(0)
	v_pk_mul_f32 v[0:1], v[0:1], v[88:89] op_sel_hi:[1,0]
	v_add_u32_e32 v33, v35, v89
	ds_write2_b32 v33, v0, v1 offset1:1
	v_pk_mul_f32 v[0:1], v[2:3], v[88:89] op_sel_hi:[1,0]
	ds_write2_b32 v33, v0, v1 offset0:2 offset1:3
	v_pk_mul_f32 v[0:1], v[4:5], v[36:37] op_sel_hi:[1,0]
	v_add_u32_e32 v2, 0x420, v33
	ds_write2_b32 v2, v0, v1 offset1:1
	v_pk_mul_f32 v[0:1], v[6:7], v[36:37] op_sel_hi:[1,0]
	v_add_u32_e32 v2, 0x428, v33
	ds_write2_b32 v2, v0, v1 offset1:1
	v_pk_mul_f32 v[0:1], v[8:9], v[94:95] op_sel_hi:[1,0]
	v_add_u32_e32 v2, 0x840, v33
	ds_write2_b32 v2, v0, v1 offset1:1
	v_pk_mul_f32 v[0:1], v[10:11], v[94:95] op_sel_hi:[1,0]
	v_add_u32_e32 v2, 0x848, v33
	ds_write2_b32 v2, v0, v1 offset1:1
	v_pk_mul_f32 v[0:1], v[12:13], v[90:91] op_sel_hi:[1,0]
	v_add_u32_e32 v2, 0xc60, v33
	ds_write2_b32 v2, v0, v1 offset1:1
	v_pk_mul_f32 v[0:1], v[14:15], v[90:91] op_sel_hi:[1,0]
	v_add_u32_e32 v2, 0xc68, v33
	ds_write2_b32 v2, v0, v1 offset1:1
	v_pk_mul_f32 v[0:1], v[16:17], v[100:101] op_sel_hi:[1,0]
	v_add_u32_e32 v2, 0x1080, v33
	ds_write2_b32 v2, v0, v1 offset1:1
	v_pk_mul_f32 v[0:1], v[18:19], v[100:101] op_sel_hi:[1,0]
	v_add_u32_e32 v2, 0x1088, v33
	ds_write2_b32 v2, v0, v1 offset1:1
	v_pk_mul_f32 v[0:1], v[20:21], v[92:93] op_sel_hi:[1,0]
	v_add_u32_e32 v2, 0x14a0, v33
	ds_write2_b32 v2, v0, v1 offset1:1
	v_pk_mul_f32 v[0:1], v[22:23], v[92:93] op_sel_hi:[1,0]
	v_add_u32_e32 v2, 0x14a8, v33
	ds_write2_b32 v2, v0, v1 offset1:1
	v_pk_mul_f32 v[0:1], v[24:25], v[102:103] op_sel_hi:[1,0]
	v_add_u32_e32 v2, 0x18c0, v33
	s_and_b32 s8, 0xffff, s8
	ds_write2_b32 v2, v0, v1 offset1:1
	v_pk_mul_f32 v[0:1], v[26:27], v[102:103] op_sel_hi:[1,0]
	v_add_u32_e32 v2, 0x18c8, v33
	s_and_b32 s7, 0xffff, s7
	s_add_i32 s9, s8, 0xfffff500
	ds_write2_b32 v2, v0, v1 offset1:1
	v_pk_mul_f32 v[0:1], v[28:29], v[96:97] op_sel_hi:[1,0]
	v_add_u32_e32 v2, 0x1ce0, v33
	s_cmpk_gt_u32 s7, 0x57
	ds_write2_b32 v2, v0, v1 offset1:1
	v_pk_mul_f32 v[0:1], v[30:31], v[96:97] op_sel_hi:[1,0]
	v_add_u32_e32 v2, 0x1ce8, v33
	s_cselect_b32 s7, s9, s8
	ds_write2_b32 v2, v0, v1 offset1:1
	s_cselect_b32 s8, 0x80, 0
	s_lshl_b32 s9, s7, 1
	s_and_b32 s7, s7, 0x60
	s_waitcnt lgkmcnt(0)
	s_and_b32 s9, s9, 0xffffff00
	s_or_b32 s7, s7, s8
	ds_read2_b32 v[4:5], v93 offset0:33 offset1:41
	ds_read2_b32 v[6:7], v93 offset1:8
	ds_read2_b32 v[8:9], v93 offset0:66 offset1:74
	ds_read2_b32 v[10:11], v93 offset0:99 offset1:107
	ds_read2_b32 v[12:13], v93 offset0:132 offset1:140
	ds_read2_b32 v[14:15], v93 offset0:165 offset1:173
	ds_read2_b32 v[16:17], v93 offset0:198 offset1:206
	ds_read2_b32 v[18:19], v93 offset0:231 offset1:239
	s_or_b32 s7, s7, s9
	s_and_b32 s6, 0xffff, s6
	v_add_u32_e32 v22, s7, v32
	s_lshl_b32 s12, s6, 1
	v_ashrrev_i32_e32 v23, 31, v22
	v_lshl_add_u64 v[20:21], v[46:47], 0, s[12:13]
	v_lshlrev_b64 v[22:23], 11, v[22:23]
	s_waitcnt lgkmcnt(6)
	v_cvt_pk_bf16_f32 v0, v6, v4
	s_waitcnt lgkmcnt(4)
	v_cvt_pk_bf16_f32 v1, v8, v10
	s_waitcnt lgkmcnt(2)
	v_cvt_pk_bf16_f32 v2, v12, v14
	s_waitcnt lgkmcnt(0)
	v_cvt_pk_bf16_f32 v3, v16, v18
	v_lshl_add_u64 v[22:23], v[20:21], 0, v[22:23]
	v_add_u32_e32 v4, s7, v38
	global_store_dwordx4 v[22:23], v[0:3], off sc1
	s_nop 1
	v_cvt_pk_bf16_f32 v0, v7, v5
	v_ashrrev_i32_e32 v5, 31, v4
	v_cvt_pk_bf16_f32 v1, v9, v11
	v_cvt_pk_bf16_f32 v2, v13, v15
	v_cvt_pk_bf16_f32 v3, v17, v19
	v_lshlrev_b64 v[4:5], 11, v[4:5]
	ds_read2_b32 v[6:7], v93 offset0:49 offset1:57
	ds_read2_b32 v[8:9], v93 offset0:16 offset1:24
	ds_read2_b32 v[10:11], v93 offset0:82 offset1:90
	ds_read2_b32 v[12:13], v93 offset0:115 offset1:123
	ds_read2_b32 v[14:15], v93 offset0:148 offset1:156
	ds_read2_b32 v[16:17], v93 offset0:181 offset1:189
	ds_read2_b32 v[18:19], v93 offset0:214 offset1:222
	ds_read2_b32 v[22:23], v93 offset0:247 offset1:255
	v_lshl_add_u64 v[4:5], v[20:21], 0, v[4:5]
	global_store_dwordx4 v[4:5], v[0:3], off sc1
	v_add_u32_e32 v4, s7, v40
	v_ashrrev_i32_e32 v5, 31, v4
	v_lshlrev_b64 v[4:5], 11, v[4:5]
	s_waitcnt lgkmcnt(6)
	v_cvt_pk_bf16_f32 v0, v8, v6
	s_waitcnt lgkmcnt(4)
	v_cvt_pk_bf16_f32 v1, v10, v12
	s_waitcnt lgkmcnt(2)
	v_cvt_pk_bf16_f32 v2, v14, v16
	s_waitcnt lgkmcnt(0)
	v_cvt_pk_bf16_f32 v3, v18, v22
	v_lshl_add_u64 v[4:5], v[20:21], 0, v[4:5]
	global_store_dwordx4 v[4:5], v[0:3], off sc1
	v_add_u32_e32 v4, s7, v42
	v_ashrrev_i32_e32 v5, 31, v4
	v_lshlrev_b64 v[4:5], 11, v[4:5]
	v_cvt_pk_bf16_f32 v0, v9, v7
	v_cvt_pk_bf16_f32 v1, v11, v13
	v_cvt_pk_bf16_f32 v2, v15, v17
	v_cvt_pk_bf16_f32 v3, v19, v23
	v_lshl_add_u64 v[4:5], v[20:21], 0, v[4:5]
	global_store_dwordx4 v[4:5], v[0:3], off sc1
	s_waitcnt lgkmcnt(0)

; __device__ __forceinline__ unsigned pk_bf16(float lo, float hi) { typedef __bf16 b2_t __attribute__((ext_vector_type(2))); f32x2 v = {lo, hi}; b2_t b = __builtin_convertvector(v, b2_t); return __builtin_bit_cast(unsigned, b); }
; #define LAS __attribute__((address_space(3)))
; __device__ __forceinline__ void transpose_tile(const float* W, const float* gain, int K, int N, int k0, int n0, bf16* WT, int drow0, LAS float* scr, int lane) {
;     f32x4 v[8]; float gv[8];
;     const int r0 = lane >> 3, c4 = lane & 7;
; #pragma unroll
;     for (int i = 0; i < 8; ++i) { v[i] = *(const f32x4*)(W + (size_t)(k0 + r0 + 8 * i) * N + n0 + 4 * c4); gv[i] = gain ? gain[k0 + r0 + 8 * i] : 1.0f; }
; #pragma unroll
;     for (int i = 0; i < 8; ++i) { LAS float* d = scr + (r0 + 8 * i) * 33 + 4 * c4; d[0] = v[i][0] * gv[i]; d[1] = v[i][1] * gv[i]; d[2] = v[i][2] * gv[i]; d[3] = v[i][3] * gv[i]; }
;     asm volatile("s_waitcnt lgkmcnt(0)" ::: "memory");
;     const int c = lane & 7;
; #pragma unroll
;     for (int j = 0; j < 4; ++j) { const int n = (lane >> 3) + 8 * j; const LAS float* s = scr + (8 * c) * 33 + n;
;         v4u o; o.x = pk_bf16(s[0 * 33], s[1 * 33]); o.y = pk_bf16(s[2 * 33], s[3 * 33]); o.z = pk_bf16(s[4 * 33], s[5 * 33]); o.w = pk_bf16(s[6 * 33], s[7 * 33]);
;         *(v4u*)(WT + (size_t)(drow0 + n) * K + k0 + 8 * c) = o; }
;     asm volatile("s_waitcnt lgkmcnt(0)" ::: "memory");
; }
.LBB0_1322:
	s_andn2_b64 vcc, exec, s[8:9]
	s_cbranch_vccnz .LBB0_1324
	s_mov_b32 s6, 21
	s_ashr_i32 s7, s6, 31
	s_add_i32 s8, s26, 0xffffc060
	s_lshl_b64 s[6:7], s[6:7], 3
	s_add_u32 s6, s0, s6
	s_addc_u32 s7, s1, s7
	s_load_dwordx2 s[6:7], s[6:7], 0x0
	s_lshr_b32 s12, s8, 1
	s_lshl_b64 s[8:9], s[12:13], 14
	v_lshlrev_b32_e32 v36, 2, v34
	v_add_u32_e32 v33, v35, v89
	s_waitcnt lgkmcnt(0)
	s_add_u32 s6, s6, s8
	s_addc_u32 s7, s7, s9
	s_lshl_b32 s8, s26, 5
	s_and_b32 s8, s8, 32
	s_lshl_b32 s9, s8, 2
	s_add_u32 s6, s6, s9
	s_addc_u32 s7, s7, 0
	v_lshl_add_u64 v[28:29], s[6:7], 0, v[36:37]
	v_lshl_add_u64 v[0:1], v[28:29], 0, v[48:49]
	global_load_dwordx4 v[0:3], v[0:1], off
	v_lshl_add_u64 v[4:5], v[28:29], 0, v[50:51]
	global_load_dwordx4 v[4:7], v[4:5], off
	v_lshl_add_u64 v[8:9], v[28:29], 0, v[52:53]
	global_load_dwordx4 v[8:11], v[8:9], off
	v_lshl_add_u64 v[12:13], v[28:29], 0, v[54:55]
	global_load_dwordx4 v[12:15], v[12:13], off
	v_lshl_add_u64 v[16:17], v[28:29], 0, v[56:57]
	global_load_dwordx4 v[16:19], v[16:17], off
	v_lshl_add_u64 v[20:21], v[28:29], 0, v[58:59]
	global_load_dwordx4 v[20:23], v[20:21], off
	v_lshl_add_u64 v[24:25], v[28:29], 0, v[60:61]
	global_load_dwordx4 v[24:27], v[24:25], off
	v_lshl_add_u64 v[28:29], v[28:29], 0, v[62:63]
	global_load_dwordx4 v[28:31], v[28:29], off
	v_add_u32_e32 v36, 0x420, v33
	v_add_u32_e32 v39, 0x428, v33
	v_add_u32_e32 v41, 0x840, v33
	v_add_u32_e32 v43, 0x848, v33
	v_add_u32_e32 v88, 0xc60, v33
	v_add_u32_e32 v92, 0xc68, v33
	v_add_u32_e32 v97, 0x1080, v33
	v_add_u32_e32 v100, 0x1088, v33
	v_add_u32_e32 v101, 0x14a0, v33
	v_add_u32_e32 v102, 0x14a8, v33
	v_add_u32_e32 v103, 0x18c0, v33
	v_add_u32_e32 v104, 0x18c8, v33
	v_add_u32_e32 v105, 0x1ce0, v33
	v_add_u32_e32 v106, 0x1ce8, v33
	v_add_u32_e32 v90, s8, v32
	v_add_u32_e32 v94, s8, v38
	v_ashrrev_i32_e32 v91, 31, v90
	s_lshl_b64 s[6:7], s[12:13], 13
	v_ashrrev_i32_e32 v95, 31, v94
	v_lshlrev_b64 v[90:91], 7, v[90:91]
	v_lshl_add_u64 v[98:99], v[64:65], 0, s[6:7]
	v_add_u32_e32 v96, s8, v40
	v_lshlrev_b64 v[94:95], 7, v[94:95]
	v_lshl_add_u64 v[90:91], v[98:99], 0, v[90:91]
	v_lshl_add_u64 v[94:95], v[98:99], 0, v[94:95]
	s_waitcnt vmcnt(0)
	ds_write2_b32 v33, v0, v1 offset1:1
	ds_write2_b32 v33, v2, v3 offset0:2 offset1:3
	ds_write2_b32 v36, v4, v5 offset1:1
	ds_write2_b32 v39, v6, v7 offset1:1
	ds_write2_b32 v41, v8, v9 offset1:1
	ds_write2_b32 v43, v10, v11 offset1:1
	ds_write2_b32 v88, v12, v13 offset1:1
	ds_write2_b32 v92, v14, v15 offset1:1
	ds_write2_b32 v97, v16, v17 offset1:1
	ds_write2_b32 v100, v18, v19 offset1:1
	ds_write2_b32 v101, v20, v21 offset1:1
	ds_write2_b32 v102, v22, v23 offset1:1
	ds_write2_b32 v103, v24, v25 offset1:1
	ds_write2_b32 v104, v26, v27 offset1:1
	ds_write2_b32 v105, v28, v29 offset1:1
	ds_write2_b32 v106, v30, v31 offset1:1
	s_waitcnt lgkmcnt(0)
	ds_read2_b32 v[4:5], v93 offset0:33 offset1:41
	ds_read2_b32 v[6:7], v93 offset1:8
	ds_read2_b32 v[8:9], v93 offset0:66 offset1:74
	ds_read2_b32 v[10:11], v93 offset0:99 offset1:107
	ds_read2_b32 v[12:13], v93 offset0:132 offset1:140
	ds_read2_b32 v[14:15], v93 offset0:165 offset1:173
	ds_read2_b32 v[16:17], v93 offset0:198 offset1:206
	ds_read2_b32 v[18:19], v93 offset0:231 offset1:239
	ds_read2_b32 v[20:21], v93 offset0:49 offset1:57
	ds_read2_b32 v[22:23], v93 offset0:16 offset1:24
	ds_read2_b32 v[24:25], v93 offset0:82 offset1:90
	ds_read2_b32 v[26:27], v93 offset0:115 offset1:123
	ds_read2_b32 v[28:29], v93 offset0:148 offset1:156
	ds_read2_b32 v[30:31], v93 offset0:181 offset1:189
	ds_read2_b32 v[100:101], v93 offset0:214 offset1:222
	ds_read2_b32 v[102:103], v93 offset0:247 offset1:255
	s_waitcnt lgkmcnt(14)
	v_cvt_pk_bf16_f32 v0, v6, v4
	s_waitcnt lgkmcnt(12)
	v_cvt_pk_bf16_f32 v1, v8, v10
	s_waitcnt lgkmcnt(10)
	v_cvt_pk_bf16_f32 v2, v12, v14
	s_waitcnt lgkmcnt(8)
	v_cvt_pk_bf16_f32 v3, v16, v18
	v_cvt_pk_bf16_f32 v4, v7, v5
	v_cvt_pk_bf16_f32 v5, v9, v11
	v_cvt_pk_bf16_f32 v6, v13, v15
	v_cvt_pk_bf16_f32 v7, v17, v19
	global_store_dwordx4 v[90:91], v[0:3], off sc1
	global_store_dwordx4 v[94:95], v[4:7], off sc1
	v_ashrrev_i32_e32 v97, 31, v96
	v_lshlrev_b64 v[0:1], 7, v[96:97]
	v_add_u32_e32 v4, s8, v42
	v_ashrrev_i32_e32 v5, 31, v4
	s_waitcnt lgkmcnt(6)
	v_cvt_pk_bf16_f32 v8, v22, v20
	s_waitcnt lgkmcnt(4)
	v_cvt_pk_bf16_f32 v9, v24, v26
	s_waitcnt lgkmcnt(2)
	v_cvt_pk_bf16_f32 v10, v28, v30
	s_waitcnt lgkmcnt(0)
	v_cvt_pk_bf16_f32 v11, v100, v102
	v_lshl_add_u64 v[0:1], v[98:99], 0, v[0:1]
	v_lshlrev_b64 v[4:5], 7, v[4:5]
	global_store_dwordx4 v[0:1], v[8:11], off sc1
	v_cvt_pk_bf16_f32 v0, v23, v21
	v_cvt_pk_bf16_f32 v1, v25, v27
	v_cvt_pk_bf16_f32 v2, v29, v31
	v_cvt_pk_bf16_f32 v3, v101, v103
	v_lshl_add_u64 v[4:5], v[98:99], 0, v[4:5]
	global_store_dwordx4 v[4:5], v[0:3], off sc1
	s_waitcnt lgkmcnt(0)

; __device__ __forceinline__ unsigned pk_bf16(float lo, float hi) { typedef __bf16 b2_t __attribute__((ext_vector_type(2))); f32x2 v = {lo, hi}; b2_t b = __builtin_convertvector(v, b2_t); return __builtin_bit_cast(unsigned, b); }
; #define LAS __attribute__((address_space(3)))
; __device__ __forceinline__ void transpose_tile(const float* W, const float* gain, int K, int N, int k0, int n0, bf16* WT, int drow0, LAS float* scr, int lane) {
;     f32x4 v[8]; float gv[8];
;     const int r0 = lane >> 3, c4 = lane & 7;
; #pragma unroll
;     for (int i = 0; i < 8; ++i) { v[i] = *(const f32x4*)(W + (size_t)(k0 + r0 + 8 * i) * N + n0 + 4 * c4); gv[i] = gain ? gain[k0 + r0 + 8 * i] : 1.0f; }
; #pragma unroll
;     for (int i = 0; i < 8; ++i) { LAS float* d = scr + (r0 + 8 * i) * 33 + 4 * c4; d[0] = v[i][0] * gv[i]; d[1] = v[i][1] * gv[i]; d[2] = v[i][2] * gv[i]; d[3] = v[i][3] * gv[i]; }
;     asm volatile("s_waitcnt lgkmcnt(0)" ::: "memory");
;     const int c = lane & 7;
; #pragma unroll
;     for (int j = 0; j < 4; ++j) { const int n = (lane >> 3) + 8 * j; const LAS float* s = scr + (8 * c) * 33 + n;
;         v4u o; o.x = pk_bf16(s[0 * 33], s[1 * 33]); o.y = pk_bf16(s[2 * 33], s[3 * 33]); o.z = pk_bf16(s[4 * 33], s[5 * 33]); o.w = pk_bf16(s[6 * 33], s[7 * 33]);
;         *(v4u*)(WT + (size_t)(drow0 + n) * K + k0 + 8 * c) = o; }
;     asm volatile("s_waitcnt lgkmcnt(0)" ::: "memory");
; }
.LBB0_1325:
	s_andn2_b64 vcc, exec, s[8:9]
	s_cbranch_vccnz .LBB0_1327
	s_mov_b32 s6, 19
	s_ashr_i32 s7, s6, 31
	s_add_i32 s8, s26, 0xffffc080
	s_lshl_b64 s[6:7], s[6:7], 3
	s_add_u32 s6, s0, s6
	s_addc_u32 s7, s1, s7
	s_load_dwordx2 s[6:7], s[6:7], 0x0
	s_lshr_b32 s12, s8, 1
	s_lshl_b64 s[8:9], s[12:13], 14
	v_lshlrev_b32_e32 v36, 2, v34
	v_add_u32_e32 v33, v35, v89
	s_waitcnt lgkmcnt(0)
	s_add_u32 s6, s6, s8
	s_addc_u32 s7, s7, s9
	s_lshl_b32 s8, s26, 5
	s_and_b32 s8, s8, 32
	s_lshl_b32 s9, s8, 2
	s_add_u32 s6, s6, s9
	s_addc_u32 s7, s7, 0
	v_lshl_add_u64 v[28:29], s[6:7], 0, v[36:37]
	v_lshl_add_u64 v[0:1], v[28:29], 0, v[48:49]
	global_load_dwordx4 v[0:3], v[0:1], off
	v_lshl_add_u64 v[4:5], v[28:29], 0, v[50:51]
	global_load_dwordx4 v[4:7], v[4:5], off
	v_lshl_add_u64 v[8:9], v[28:29], 0, v[52:53]
	global_load_dwordx4 v[8:11], v[8:9], off
	v_lshl_add_u64 v[12:13], v[28:29], 0, v[54:55]
	global_load_dwordx4 v[12:15], v[12:13], off
	v_lshl_add_u64 v[16:17], v[28:29], 0, v[56:57]
	global_load_dwordx4 v[16:19], v[16:17], off
	v_lshl_add_u64 v[20:21], v[28:29], 0, v[58:59]
	global_load_dwordx4 v[20:23], v[20:21], off
	v_lshl_add_u64 v[24:25], v[28:29], 0, v[60:61]
	global_load_dwordx4 v[24:27], v[24:25], off
	v_lshl_add_u64 v[28:29], v[28:29], 0, v[62:63]
	global_load_dwordx4 v[28:31], v[28:29], off
	v_add_u32_e32 v36, 0x420, v33
	v_add_u32_e32 v39, 0x428, v33
	v_add_u32_e32 v41, 0x840, v33
	v_add_u32_e32 v43, 0x848, v33
	v_add_u32_e32 v88, 0xc60, v33
	v_add_u32_e32 v92, 0xc68, v33
	v_add_u32_e32 v97, 0x1080, v33
	v_add_u32_e32 v100, 0x1088, v33
	v_add_u32_e32 v101, 0x14a0, v33
	v_add_u32_e32 v102, 0x14a8, v33
	v_add_u32_e32 v103, 0x18c0, v33
	v_add_u32_e32 v104, 0x18c8, v33
	v_add_u32_e32 v105, 0x1ce0, v33
	v_add_u32_e32 v106, 0x1ce8, v33
	v_add_u32_e32 v90, s8, v32
	v_add_u32_e32 v94, s8, v38
	v_ashrrev_i32_e32 v91, 31, v90
	s_lshl_b64 s[6:7], s[12:13], 13
	v_ashrrev_i32_e32 v95, 31, v94
	v_lshlrev_b64 v[90:91], 7, v[90:91]
	v_lshl_add_u64 v[98:99], v[66:67], 0, s[6:7]
	v_add_u32_e32 v96, s8, v40
	v_lshlrev_b64 v[94:95], 7, v[94:95]
	v_lshl_add_u64 v[90:91], v[98:99], 0, v[90:91]
	v_lshl_add_u64 v[94:95], v[98:99], 0, v[94:95]
	s_waitcnt vmcnt(0)
	ds_write2_b32 v33, v0, v1 offset1:1
	ds_write2_b32 v33, v2, v3 offset0:2 offset1:3
	ds_write2_b32 v36, v4, v5 offset1:1
	ds_write2_b32 v39, v6, v7 offset1:1
	ds_write2_b32 v41, v8, v9 offset1:1
	ds_write2_b32 v43, v10, v11 offset1:1
	ds_write2_b32 v88, v12, v13 offset1:1
	ds_write2_b32 v92, v14, v15 offset1:1
	ds_write2_b32 v97, v16, v17 offset1:1
	ds_write2_b32 v100, v18, v19 offset1:1
	ds_write2_b32 v101, v20, v21 offset1:1
	ds_write2_b32 v102, v22, v23 offset1:1
	ds_write2_b32 v103, v24, v25 offset1:1
	ds_write2_b32 v104, v26, v27 offset1:1
	ds_write2_b32 v105, v28, v29 offset1:1
	ds_write2_b32 v106, v30, v31 offset1:1
	s_waitcnt lgkmcnt(0)
	ds_read2_b32 v[4:5], v93 offset0:33 offset1:41
	ds_read2_b32 v[6:7], v93 offset1:8
	ds_read2_b32 v[8:9], v93 offset0:66 offset1:74
	ds_read2_b32 v[10:11], v93 offset0:99 offset1:107
	ds_read2_b32 v[12:13], v93 offset0:132 offset1:140
	ds_read2_b32 v[14:15], v93 offset0:165 offset1:173
	ds_read2_b32 v[16:17], v93 offset0:198 offset1:206
	ds_read2_b32 v[18:19], v93 offset0:231 offset1:239
	ds_read2_b32 v[20:21], v93 offset0:49 offset1:57
	ds_read2_b32 v[22:23], v93 offset0:16 offset1:24
	ds_read2_b32 v[24:25], v93 offset0:82 offset1:90
	ds_read2_b32 v[26:27], v93 offset0:115 offset1:123
	ds_read2_b32 v[28:29], v93 offset0:148 offset1:156
	ds_read2_b32 v[30:31], v93 offset0:181 offset1:189
	ds_read2_b32 v[100:101], v93 offset0:214 offset1:222
	ds_read2_b32 v[102:103], v93 offset0:247 offset1:255
	s_waitcnt lgkmcnt(14)
	v_cvt_pk_bf16_f32 v0, v6, v4
	s_waitcnt lgkmcnt(12)
	v_cvt_pk_bf16_f32 v1, v8, v10
	s_waitcnt lgkmcnt(10)
	v_cvt_pk_bf16_f32 v2, v12, v14
	s_waitcnt lgkmcnt(8)
	v_cvt_pk_bf16_f32 v3, v16, v18
	v_cvt_pk_bf16_f32 v4, v7, v5
	v_cvt_pk_bf16_f32 v5, v9, v11
	v_cvt_pk_bf16_f32 v6, v13, v15
	v_cvt_pk_bf16_f32 v7, v17, v19
	global_store_dwordx4 v[90:91], v[0:3], off sc1
	global_store_dwordx4 v[94:95], v[4:7], off sc1
	v_ashrrev_i32_e32 v97, 31, v96
	v_lshlrev_b64 v[0:1], 7, v[96:97]
	v_add_u32_e32 v4, s8, v42
	v_ashrrev_i32_e32 v5, 31, v4
	s_waitcnt lgkmcnt(6)
	v_cvt_pk_bf16_f32 v8, v22, v20
	s_waitcnt lgkmcnt(4)
	v_cvt_pk_bf16_f32 v9, v24, v26
	s_waitcnt lgkmcnt(2)
	v_cvt_pk_bf16_f32 v10, v28, v30
	s_waitcnt lgkmcnt(0)
	v_cvt_pk_bf16_f32 v11, v100, v102
	v_lshl_add_u64 v[0:1], v[98:99], 0, v[0:1]
	v_lshlrev_b64 v[4:5], 7, v[4:5]
	global_store_dwordx4 v[0:1], v[8:11], off sc1
	v_cvt_pk_bf16_f32 v0, v23, v21
	v_cvt_pk_bf16_f32 v1, v25, v27
	v_cvt_pk_bf16_f32 v2, v29, v31
	v_cvt_pk_bf16_f32 v3, v101, v103
	v_lshl_add_u64 v[4:5], v[98:99], 0, v[4:5]
	global_store_dwordx4 v[4:5], v[0:3], off sc1
	s_waitcnt lgkmcnt(0)

; __device__ __forceinline__ unsigned pk_bf16(float lo, float hi) { typedef __bf16 b2_t __attribute__((ext_vector_type(2))); f32x2 v = {lo, hi}; b2_t b = __builtin_convertvector(v, b2_t); return __builtin_bit_cast(unsigned, b); }
; #define LAS __attribute__((address_space(3)))
; __device__ __forceinline__ void transpose_tile(const float* W, const float* gain, int K, int N, int k0, int n0, bf16* WT, int drow0, LAS float* scr, int lane) {
;     f32x4 v[8]; float gv[8];
;     const int r0 = lane >> 3, c4 = lane & 7;
; #pragma unroll
;     for (int i = 0; i < 8; ++i) { v[i] = *(const f32x4*)(W + (size_t)(k0 + r0 + 8 * i) * N + n0 + 4 * c4); gv[i] = gain ? gain[k0 + r0 + 8 * i] : 1.0f; }
; #pragma unroll
;     for (int i = 0; i < 8; ++i) { LAS float* d = scr + (r0 + 8 * i) * 33 + 4 * c4; d[0] = v[i][0] * gv[i]; d[1] = v[i][1] * gv[i]; d[2] = v[i][2] * gv[i]; d[3] = v[i][3] * gv[i]; }
;     asm volatile("s_waitcnt lgkmcnt(0)" ::: "memory");
;     const int c = lane & 7;
; #pragma unroll
;     for (int j = 0; j < 4; ++j) { const int n = (lane >> 3) + 8 * j; const LAS float* s = scr + (8 * c) * 33 + n;
;         v4u o; o.x = pk_bf16(s[0 * 33], s[1 * 33]); o.y = pk_bf16(s[2 * 33], s[3 * 33]); o.z = pk_bf16(s[4 * 33], s[5 * 33]); o.w = pk_bf16(s[6 * 33], s[7 * 33]);
;         *(v4u*)(WT + (size_t)(drow0 + n) * K + k0 + 8 * c) = o; }
;     asm volatile("s_waitcnt lgkmcnt(0)" ::: "memory");
; }
.LBB0_1328:
	s_andn2_b64 vcc, exec, s[8:9]
	s_cbranch_vccnz .LBB0_1330
	s_mov_b32 s6, 24
	s_ashr_i32 s7, s6, 31
	s_lshl_b64 s[6:7], s[6:7], 3
	s_add_u32 s6, s0, s6
	s_addc_u32 s7, s1, s7
	s_load_dwordx2 s[6:7], s[6:7], 0x0
	s_lshl_b32 s8, s26, 5
	s_and_b32 s8, s8, 0x3e0
	s_add_i32 s9, s29, 0x1a80
	s_and_b32 s9, s9, 0x1ffc0
	s_lshl_b32 s12, s8, 2
	v_add_u32_e32 v0, s9, v32
	s_waitcnt lgkmcnt(0)
	s_add_u32 s6, s6, s12
	s_addc_u32 s7, s7, 0
	v_lshlrev_b32_e32 v36, 2, v34
	v_ashrrev_i32_e32 v1, 31, v0
	v_lshl_add_u64 v[2:3], s[6:7], 0, v[36:37]
	v_lshlrev_b64 v[0:1], 12, v[0:1]
	v_lshl_add_u64 v[28:29], v[2:3], 0, v[0:1]
	v_add_co_u32_e32 v4, vcc, s31, v28
	v_add_u32_e32 v33, v35, v89
	s_nop 0
	v_addc_co_u32_e32 v5, vcc, 0, v29, vcc
	v_add_co_u32_e32 v8, vcc, s34, v28
	global_load_dwordx4 v[0:3], v[28:29], off
	s_nop 0
	global_load_dwordx4 v[4:7], v[4:5], off
	v_addc_co_u32_e32 v9, vcc, 0, v29, vcc
	v_add_co_u32_e32 v12, vcc, s35, v28
	v_add_u32_e32 v36, 0x420, v33
	s_nop 0
	v_addc_co_u32_e32 v13, vcc, 0, v29, vcc
	v_add_co_u32_e32 v16, vcc, s36, v28
	global_load_dwordx4 v[8:11], v[8:9], off
	s_nop 0
	global_load_dwordx4 v[12:15], v[12:13], off
	v_addc_co_u32_e32 v17, vcc, 0, v29, vcc
	v_add_co_u32_e32 v20, vcc, s37, v28
	v_add_u32_e32 v39, 0x428, v33
	s_nop 0
	v_addc_co_u32_e32 v21, vcc, 0, v29, vcc
	global_load_dwordx4 v[16:19], v[16:17], off
	s_nop 0
	global_load_dwordx4 v[20:23], v[20:21], off
	v_add_co_u32_e32 v24, vcc, s38, v28
	v_add_u32_e32 v41, 0x840, v33
	s_nop 0
	v_addc_co_u32_e32 v25, vcc, 0, v29, vcc
	global_load_dwordx4 v[24:27], v[24:25], off
	v_add_co_u32_e32 v28, vcc, s39, v28
	v_add_u32_e32 v43, 0x848, v33
	s_nop 0
	v_addc_co_u32_e32 v29, vcc, 0, v29, vcc
	global_load_dwordx4 v[28:31], v[28:29], off
	v_add_u32_e32 v88, 0xc60, v33
	v_add_u32_e32 v92, 0xc68, v33
	v_add_u32_e32 v94, 0x1080, v33
	v_add_u32_e32 v95, 0x1088, v33
	v_add_u32_e32 v96, 0x14a0, v33
	v_add_u32_e32 v97, 0x14a8, v33
	v_add_u32_e32 v98, 0x18c0, v33
	v_add_u32_e32 v99, 0x18c8, v33
	v_add_u32_e32 v100, 0x1ce0, v33
	v_add_u32_e32 v101, 0x1ce8, v33
	v_add_u32_e32 v90, s8, v32
	v_ashrrev_i32_e32 v91, 31, v90
	s_lshl_b32 s12, s9, 1
	s_waitcnt vmcnt(0)
	ds_write2_b32 v33, v0, v1 offset1:1
	ds_write2_b32 v33, v2, v3 offset0:2 offset1:3
	ds_write2_b32 v36, v4, v5 offset1:1
	ds_write2_b32 v39, v6, v7 offset1:1
	ds_write2_b32 v41, v8, v9 offset1:1
	ds_write2_b32 v43, v10, v11 offset1:1
	ds_write2_b32 v88, v12, v13 offset1:1
	ds_write2_b32 v92, v14, v15 offset1:1
	ds_write2_b32 v94, v16, v17 offset1:1
	ds_write2_b32 v95, v18, v19 offset1:1
	ds_write2_b32 v96, v20, v21 offset1:1
	ds_write2_b32 v97, v22, v23 offset1:1
	ds_write2_b32 v98, v24, v25 offset1:1
	ds_write2_b32 v99, v26, v27 offset1:1
	ds_write2_b32 v100, v28, v29 offset1:1
	ds_write2_b32 v101, v30, v31 offset1:1
	s_waitcnt lgkmcnt(0)
	ds_read2_b32 v[4:5], v93 offset0:33 offset1:41
	ds_read2_b32 v[6:7], v93 offset1:8
	ds_read2_b32 v[8:9], v93 offset0:66 offset1:74
	ds_read2_b32 v[10:11], v93 offset0:99 offset1:107
	ds_read2_b32 v[12:13], v93 offset0:132 offset1:140
	ds_read2_b32 v[14:15], v93 offset0:165 offset1:173
	ds_read2_b32 v[16:17], v93 offset0:198 offset1:206
	ds_read2_b32 v[18:19], v93 offset0:231 offset1:239
	v_lshl_add_u64 v[20:21], v[68:69], 0, s[12:13]
	v_lshlrev_b64 v[22:23], 11, v[90:91]
	s_waitcnt lgkmcnt(6)
	v_cvt_pk_bf16_f32 v0, v6, v4
	s_waitcnt lgkmcnt(4)
	v_cvt_pk_bf16_f32 v1, v8, v10
	s_waitcnt lgkmcnt(2)
	v_cvt_pk_bf16_f32 v2, v12, v14
	s_waitcnt lgkmcnt(0)
	v_cvt_pk_bf16_f32 v3, v16, v18
	v_lshl_add_u64 v[22:23], v[20:21], 0, v[22:23]
	v_add_u32_e32 v4, s8, v38
	global_store_dwordx4 v[22:23], v[0:3], off sc1
	s_nop 1
	v_cvt_pk_bf16_f32 v0, v7, v5
	v_ashrrev_i32_e32 v5, 31, v4
	v_cvt_pk_bf16_f32 v1, v9, v11
	v_cvt_pk_bf16_f32 v2, v13, v15
	v_cvt_pk_bf16_f32 v3, v17, v19
	v_lshlrev_b64 v[4:5], 11, v[4:5]
	ds_read2_b32 v[6:7], v93 offset0:49 offset1:57
	ds_read2_b32 v[8:9], v93 offset0:16 offset1:24
	ds_read2_b32 v[10:11], v93 offset0:82 offset1:90
	ds_read2_b32 v[12:13], v93 offset0:115 offset1:123
	ds_read2_b32 v[14:15], v93 offset0:148 offset1:156
	ds_read2_b32 v[16:17], v93 offset0:181 offset1:189
	ds_read2_b32 v[18:19], v93 offset0:214 offset1:222
	ds_read2_b32 v[22:23], v93 offset0:247 offset1:255
	v_lshl_add_u64 v[4:5], v[20:21], 0, v[4:5]
	global_store_dwordx4 v[4:5], v[0:3], off sc1
	v_add_u32_e32 v4, s8, v40
	v_ashrrev_i32_e32 v5, 31, v4
	v_lshlrev_b64 v[4:5], 11, v[4:5]
	s_waitcnt lgkmcnt(6)
	v_cvt_pk_bf16_f32 v0, v8, v6
	s_waitcnt lgkmcnt(4)
	v_cvt_pk_bf16_f32 v1, v10, v12
	s_waitcnt lgkmcnt(2)
	v_cvt_pk_bf16_f32 v2, v14, v16
	s_waitcnt lgkmcnt(0)
	v_cvt_pk_bf16_f32 v3, v18, v22
	v_lshl_add_u64 v[4:5], v[20:21], 0, v[4:5]
	global_store_dwordx4 v[4:5], v[0:3], off sc1
	v_add_u32_e32 v4, s8, v42
	v_ashrrev_i32_e32 v5, 31, v4
	v_lshlrev_b64 v[4:5], 11, v[4:5]
	v_cvt_pk_bf16_f32 v0, v9, v7
	v_cvt_pk_bf16_f32 v1, v11, v13
	v_cvt_pk_bf16_f32 v2, v15, v17
	v_cvt_pk_bf16_f32 v3, v19, v23
	v_lshl_add_u64 v[4:5], v[20:21], 0, v[4:5]
	global_store_dwordx4 v[4:5], v[0:3], off sc1
	s_waitcnt lgkmcnt(0)

; __device__ __forceinline__ unsigned pk_bf16(float lo, float hi) { typedef __bf16 b2_t __attribute__((ext_vector_type(2))); f32x2 v = {lo, hi}; b2_t b = __builtin_convertvector(v, b2_t); return __builtin_bit_cast(unsigned, b); }
; #define LAS __attribute__((address_space(3)))
; __device__ __forceinline__ void transpose_tile(const float* W, const float* gain, int K, int N, int k0, int n0, bf16* WT, int drow0, LAS float* scr, int lane) {
;     f32x4 v[8]; float gv[8];
;     const int r0 = lane >> 3, c4 = lane & 7;
; #pragma unroll
;     for (int i = 0; i < 8; ++i) { v[i] = *(const f32x4*)(W + (size_t)(k0 + r0 + 8 * i) * N + n0 + 4 * c4); gv[i] = gain ? gain[k0 + r0 + 8 * i] : 1.0f; }
; #pragma unroll
;     for (int i = 0; i < 8; ++i) { LAS float* d = scr + (r0 + 8 * i) * 33 + 4 * c4; d[0] = v[i][0] * gv[i]; d[1] = v[i][1] * gv[i]; d[2] = v[i][2] * gv[i]; d[3] = v[i][3] * gv[i]; }
;     asm volatile("s_waitcnt lgkmcnt(0)" ::: "memory");
;     const int c = lane & 7;
; #pragma unroll
;     for (int j = 0; j < 4; ++j) { const int n = (lane >> 3) + 8 * j; const LAS float* s = scr + (8 * c) * 33 + n;
;         v4u o; o.x = pk_bf16(s[0 * 33], s[1 * 33]); o.y = pk_bf16(s[2 * 33], s[3 * 33]); o.z = pk_bf16(s[4 * 33], s[5 * 33]); o.w = pk_bf16(s[6 * 33], s[7 * 33]);
;         *(v4u*)(WT + (size_t)(drow0 + n) * K + k0 + 8 * c) = o; }
;     asm volatile("s_waitcnt lgkmcnt(0)" ::: "memory");
; }
.LBB0_1348:
	s_waitcnt vmcnt(0)
	v_pk_mul_f32 v[0:1], v[0:1], v[88:89] op_sel_hi:[1,0]
	v_add_u32_e32 v33, v35, v89
	ds_write2_b32 v33, v0, v1 offset1:1
	v_pk_mul_f32 v[0:1], v[2:3], v[88:89] op_sel_hi:[1,0]
	ds_write2_b32 v33, v0, v1 offset0:2 offset1:3
	v_pk_mul_f32 v[0:1], v[4:5], v[36:37] op_sel_hi:[1,0]
	v_add_u32_e32 v2, 0x420, v33
	ds_write2_b32 v2, v0, v1 offset1:1
	v_pk_mul_f32 v[0:1], v[6:7], v[36:37] op_sel_hi:[1,0]
	v_add_u32_e32 v2, 0x428, v33
	ds_write2_b32 v2, v0, v1 offset1:1
	v_pk_mul_f32 v[0:1], v[8:9], v[94:95] op_sel_hi:[1,0]
	v_add_u32_e32 v2, 0x840, v33
	ds_write2_b32 v2, v0, v1 offset1:1
	v_pk_mul_f32 v[0:1], v[10:11], v[94:95] op_sel_hi:[1,0]
	v_add_u32_e32 v2, 0x848, v33
	ds_write2_b32 v2, v0, v1 offset1:1
	v_pk_mul_f32 v[0:1], v[12:13], v[92:93] op_sel_hi:[1,0]
	v_add_u32_e32 v2, 0xc60, v33
	ds_write2_b32 v2, v0, v1 offset1:1
	v_pk_mul_f32 v[0:1], v[14:15], v[92:93] op_sel_hi:[1,0]
	v_add_u32_e32 v2, 0xc68, v33
	ds_write2_b32 v2, v0, v1 offset1:1
	v_pk_mul_f32 v[0:1], v[16:17], v[98:99] op_sel_hi:[1,0]
	v_add_u32_e32 v2, 0x1080, v33
	ds_write2_b32 v2, v0, v1 offset1:1
	v_pk_mul_f32 v[0:1], v[18:19], v[98:99] op_sel_hi:[1,0]
	v_add_u32_e32 v2, 0x1088, v33
	ds_write2_b32 v2, v0, v1 offset1:1
	v_pk_mul_f32 v[0:1], v[20:21], v[96:97] op_sel_hi:[1,0]
	v_add_u32_e32 v2, 0x14a0, v33
	ds_write2_b32 v2, v0, v1 offset1:1
	v_pk_mul_f32 v[0:1], v[22:23], v[96:97] op_sel_hi:[1,0]
	v_add_u32_e32 v2, 0x14a8, v33
	ds_write2_b32 v2, v0, v1 offset1:1
	v_pk_mul_f32 v[0:1], v[24:25], v[102:103] op_sel_hi:[1,0]
	v_add_u32_e32 v2, 0x18c0, v33
	ds_write2_b32 v2, v0, v1 offset1:1
	v_pk_mul_f32 v[0:1], v[26:27], v[102:103] op_sel_hi:[1,0]
	v_add_u32_e32 v2, 0x18c8, v33
	ds_write2_b32 v2, v0, v1 offset1:1
	v_pk_mul_f32 v[0:1], v[28:29], v[100:101] op_sel_hi:[1,0]
	v_add_u32_e32 v2, 0x1ce0, v33
	ds_write2_b32 v2, v0, v1 offset1:1
	v_pk_mul_f32 v[0:1], v[30:31], v[100:101] op_sel_hi:[1,0]
	v_add_u32_e32 v2, 0x1ce8, v33
	ds_write2_b32 v2, v0, v1 offset1:1
	s_waitcnt lgkmcnt(0)
	ds_read2_b32 v[4:5], v93 offset0:33 offset1:41
	ds_read2_b32 v[6:7], v93 offset1:8
	ds_read2_b32 v[8:9], v93 offset0:66 offset1:74
	ds_read2_b32 v[10:11], v93 offset0:99 offset1:107
	ds_read2_b32 v[12:13], v93 offset0:132 offset1:140
	ds_read2_b32 v[14:15], v93 offset0:165 offset1:173
	ds_read2_b32 v[16:17], v93 offset0:198 offset1:206
	ds_read2_b32 v[18:19], v93 offset0:231 offset1:239
	s_and_b32 s7, 0xffff, s7
	v_add_u32_e32 v22, s7, v32
	s_lshl_b32 s12, s6, 1
	v_ashrrev_i32_e32 v23, 31, v22
	v_lshl_add_u64 v[20:21], v[70:71], 0, s[12:13]
	v_lshlrev_b64 v[22:23], 11, v[22:23]
	s_waitcnt lgkmcnt(6)
	v_cvt_pk_bf16_f32 v0, v6, v4
	s_waitcnt lgkmcnt(4)
	v_cvt_pk_bf16_f32 v1, v8, v10
	s_waitcnt lgkmcnt(2)
	v_cvt_pk_bf16_f32 v2, v12, v14
	s_waitcnt lgkmcnt(0)
	v_cvt_pk_bf16_f32 v3, v16, v18
	v_lshl_add_u64 v[22:23], v[20:21], 0, v[22:23]
	v_add_u32_e32 v4, s7, v38
	global_store_dwordx4 v[22:23], v[0:3], off sc1
	s_nop 1
	v_cvt_pk_bf16_f32 v0, v7, v5
	v_ashrrev_i32_e32 v5, 31, v4
	v_cvt_pk_bf16_f32 v1, v9, v11
	v_cvt_pk_bf16_f32 v2, v13, v15
	v_cvt_pk_bf16_f32 v3, v17, v19
	v_lshlrev_b64 v[4:5], 11, v[4:5]
	ds_read2_b32 v[6:7], v93 offset0:49 offset1:57
	ds_read2_b32 v[8:9], v93 offset0:16 offset1:24
	ds_read2_b32 v[10:11], v93 offset0:82 offset1:90
	ds_read2_b32 v[12:13], v93 offset0:115 offset1:123
	ds_read2_b32 v[14:15], v93 offset0:148 offset1:156
	ds_read2_b32 v[16:17], v93 offset0:181 offset1:189
	ds_read2_b32 v[18:19], v93 offset0:214 offset1:222
	ds_read2_b32 v[22:23], v93 offset0:247 offset1:255
	v_lshl_add_u64 v[4:5], v[20:21], 0, v[4:5]
	global_store_dwordx4 v[4:5], v[0:3], off sc1
	v_add_u32_e32 v4, s7, v40
	v_ashrrev_i32_e32 v5, 31, v4
	v_lshlrev_b64 v[4:5], 11, v[4:5]
	s_waitcnt lgkmcnt(6)
	v_cvt_pk_bf16_f32 v0, v8, v6
	s_waitcnt lgkmcnt(4)
	v_cvt_pk_bf16_f32 v1, v10, v12
	s_waitcnt lgkmcnt(2)
	v_cvt_pk_bf16_f32 v2, v14, v16
	s_waitcnt lgkmcnt(0)
	v_cvt_pk_bf16_f32 v3, v18, v22
	v_lshl_add_u64 v[4:5], v[20:21], 0, v[4:5]
	global_store_dwordx4 v[4:5], v[0:3], off sc1
	v_add_u32_e32 v4, s7, v42
	v_ashrrev_i32_e32 v5, 31, v4
	v_lshlrev_b64 v[4:5], 11, v[4:5]
	v_cvt_pk_bf16_f32 v0, v9, v7
	v_cvt_pk_bf16_f32 v1, v11, v13
	v_cvt_pk_bf16_f32 v2, v15, v17
	v_cvt_pk_bf16_f32 v3, v19, v23
	v_lshl_add_u64 v[4:5], v[20:21], 0, v[4:5]
	global_store_dwordx4 v[4:5], v[0:3], off sc1
	s_waitcnt lgkmcnt(0)

; __device__ __forceinline__ unsigned pk_bf16(float lo, float hi) { typedef __bf16 b2_t __attribute__((ext_vector_type(2))); f32x2 v = {lo, hi}; b2_t b = __builtin_convertvector(v, b2_t); return __builtin_bit_cast(unsigned, b); }
; #define LAS __attribute__((address_space(3)))
; __device__ __forceinline__ void transpose_tile(const float* W, const float* gain, int K, int N, int k0, int n0, bf16* WT, int drow0, LAS float* scr, int lane) {
;     f32x4 v[8]; float gv[8];
;     const int r0 = lane >> 3, c4 = lane & 7;
; #pragma unroll
;     for (int i = 0; i < 8; ++i) { v[i] = *(const f32x4*)(W + (size_t)(k0 + r0 + 8 * i) * N + n0 + 4 * c4); gv[i] = gain ? gain[k0 + r0 + 8 * i] : 1.0f; }
; #pragma unroll
;     for (int i = 0; i < 8; ++i) { LAS float* d = scr + (r0 + 8 * i) * 33 + 4 * c4; d[0] = v[i][0] * gv[i]; d[1] = v[i][1] * gv[i]; d[2] = v[i][2] * gv[i]; d[3] = v[i][3] * gv[i]; }
;     asm volatile("s_waitcnt lgkmcnt(0)" ::: "memory");
;     const int c = lane & 7;
; #pragma unroll
;     for (int j = 0; j < 4; ++j) { const int n = (lane >> 3) + 8 * j; const LAS float* s = scr + (8 * c) * 33 + n;
;         v4u o; o.x = pk_bf16(s[0 * 33], s[1 * 33]); o.y = pk_bf16(s[2 * 33], s[3 * 33]); o.z = pk_bf16(s[4 * 33], s[5 * 33]); o.w = pk_bf16(s[6 * 33], s[7 * 33]);
;         *(v4u*)(WT + (size_t)(drow0 + n) * K + k0 + 8 * c) = o; }
;     asm volatile("s_waitcnt lgkmcnt(0)" ::: "memory");
; }
.LBB0_1350:
	s_andn2_b64 vcc, exec, s[8:9]
	s_cbranch_vccnz .LBB0_1352
	s_mov_b32 s6, 14
	s_ashr_i32 s7, s6, 31
	s_lshl_b64 s[6:7], s[6:7], 3
	s_add_u32 s6, s0, s6
	s_addc_u32 s7, s1, s7
	s_load_dwordx2 s[6:7], s[6:7], 0x0
	s_lshl_b32 s8, s26, 5
	s_and_b32 s8, s8, 0x3e0
	s_add_i32 s9, s29, 0x2d80
	s_and_b32 s9, s9, 0x1ffc0
	s_lshl_b32 s12, s8, 2
	v_add_u32_e32 v0, s9, v32
	s_waitcnt lgkmcnt(0)
	s_add_u32 s6, s6, s12
	s_addc_u32 s7, s7, 0
	v_lshlrev_b32_e32 v36, 2, v34
	v_ashrrev_i32_e32 v1, 31, v0
	v_lshl_add_u64 v[2:3], s[6:7], 0, v[36:37]
	v_lshlrev_b64 v[0:1], 12, v[0:1]
	v_lshl_add_u64 v[28:29], v[2:3], 0, v[0:1]
	v_add_co_u32_e32 v4, vcc, s31, v28
	v_add_u32_e32 v33, v35, v89
	s_nop 0
	v_addc_co_u32_e32 v5, vcc, 0, v29, vcc
	v_add_co_u32_e32 v8, vcc, s34, v28
	global_load_dwordx4 v[0:3], v[28:29], off
	s_nop 0
	global_load_dwordx4 v[4:7], v[4:5], off
	v_addc_co_u32_e32 v9, vcc, 0, v29, vcc
	v_add_co_u32_e32 v12, vcc, s35, v28
	v_add_u32_e32 v36, 0x420, v33
	s_nop 0
	v_addc_co_u32_e32 v13, vcc, 0, v29, vcc
	v_add_co_u32_e32 v16, vcc, s36, v28
	global_load_dwordx4 v[8:11], v[8:9], off
	s_nop 0
	global_load_dwordx4 v[12:15], v[12:13], off
	v_addc_co_u32_e32 v17, vcc, 0, v29, vcc
	v_add_co_u32_e32 v20, vcc, s37, v28
	v_add_u32_e32 v39, 0x428, v33
	s_nop 0
	v_addc_co_u32_e32 v21, vcc, 0, v29, vcc
	global_load_dwordx4 v[16:19], v[16:17], off
	s_nop 0
	global_load_dwordx4 v[20:23], v[20:21], off
	v_add_co_u32_e32 v24, vcc, s38, v28
	v_add_u32_e32 v41, 0x840, v33
	s_nop 0
	v_addc_co_u32_e32 v25, vcc, 0, v29, vcc
	global_load_dwordx4 v[24:27], v[24:25], off
	v_add_co_u32_e32 v28, vcc, s39, v28
	v_add_u32_e32 v43, 0x848, v33
	s_nop 0
	v_addc_co_u32_e32 v29, vcc, 0, v29, vcc
	global_load_dwordx4 v[28:31], v[28:29], off
	v_add_u32_e32 v88, 0xc60, v33
	v_add_u32_e32 v90, 0xc68, v33
	v_add_u32_e32 v91, 0x1080, v33
	v_add_u32_e32 v92, 0x1088, v33
	v_add_u32_e32 v94, 0x14a0, v33
	v_add_u32_e32 v95, 0x14a8, v33
	v_add_u32_e32 v96, 0x18c0, v33
	v_add_u32_e32 v97, 0x18c8, v33
	v_add_u32_e32 v98, 0x1ce0, v33
	v_add_u32_e32 v99, 0x1ce8, v33
	s_lshl_b32 s12, s9, 1
	v_add_u32_e32 v100, s8, v32
	s_waitcnt vmcnt(0)
	ds_write2_b32 v33, v0, v1 offset1:1
	ds_write2_b32 v33, v2, v3 offset0:2 offset1:3
	ds_write2_b32 v36, v4, v5 offset1:1
	ds_write2_b32 v39, v6, v7 offset1:1
	ds_write2_b32 v41, v8, v9 offset1:1
	ds_write2_b32 v43, v10, v11 offset1:1
	ds_write2_b32 v88, v12, v13 offset1:1
	ds_write2_b32 v90, v14, v15 offset1:1
	ds_write2_b32 v91, v16, v17 offset1:1
	ds_write2_b32 v92, v18, v19 offset1:1
	ds_write2_b32 v94, v20, v21 offset1:1
	ds_write2_b32 v95, v22, v23 offset1:1
	ds_write2_b32 v96, v24, v25 offset1:1
	ds_write2_b32 v97, v26, v27 offset1:1
	ds_write2_b32 v98, v28, v29 offset1:1
	ds_write2_b32 v99, v30, v31 offset1:1
	s_waitcnt lgkmcnt(0)
	ds_read2_b32 v[4:5], v93 offset0:33 offset1:41
	ds_read2_b32 v[6:7], v93 offset1:8
	ds_read2_b32 v[8:9], v93 offset0:66 offset1:74
	ds_read2_b32 v[10:11], v93 offset0:99 offset1:107
	ds_read2_b32 v[12:13], v93 offset0:132 offset1:140
	ds_read2_b32 v[14:15], v93 offset0:165 offset1:173
	ds_read2_b32 v[16:17], v93 offset0:198 offset1:206
	ds_read2_b32 v[18:19], v93 offset0:231 offset1:239
	v_lshl_add_u64 v[20:21], v[72:73], 0, s[12:13]
	s_waitcnt lgkmcnt(6)
	v_cvt_pk_bf16_f32 v0, v6, v4
	s_waitcnt lgkmcnt(4)
	v_cvt_pk_bf16_f32 v1, v8, v10
	s_waitcnt lgkmcnt(2)
	v_cvt_pk_bf16_f32 v2, v12, v14
	s_waitcnt lgkmcnt(0)
	v_cvt_pk_bf16_f32 v3, v16, v18
	v_mad_i64_i32 v[22:23], s[6:7], v100, s40, v[20:21]
	global_store_dwordx4 v[22:23], v[0:3], off sc1
	v_add_u32_e32 v4, s8, v38
	s_nop 0
	v_cvt_pk_bf16_f32 v0, v7, v5
	v_cvt_pk_bf16_f32 v1, v9, v11
	v_cvt_pk_bf16_f32 v2, v13, v15
	v_cvt_pk_bf16_f32 v3, v17, v19
	ds_read2_b32 v[6:7], v93 offset0:49 offset1:57
	ds_read2_b32 v[8:9], v93 offset0:16 offset1:24
	ds_read2_b32 v[10:11], v93 offset0:82 offset1:90
	ds_read2_b32 v[12:13], v93 offset0:115 offset1:123
	ds_read2_b32 v[14:15], v93 offset0:148 offset1:156
	ds_read2_b32 v[16:17], v93 offset0:181 offset1:189
	ds_read2_b32 v[18:19], v93 offset0:214 offset1:222
	ds_read2_b32 v[22:23], v93 offset0:247 offset1:255
	v_mad_i64_i32 v[4:5], s[6:7], v4, s40, v[20:21]
	global_store_dwordx4 v[4:5], v[0:3], off sc1
	v_add_u32_e32 v4, s8, v40
	v_mad_i64_i32 v[4:5], s[6:7], v4, s40, v[20:21]
	s_waitcnt lgkmcnt(6)
	v_cvt_pk_bf16_f32 v0, v8, v6
	s_waitcnt lgkmcnt(4)
	v_cvt_pk_bf16_f32 v1, v10, v12
	s_waitcnt lgkmcnt(2)
	v_cvt_pk_bf16_f32 v2, v14, v16
	s_waitcnt lgkmcnt(0)
	v_cvt_pk_bf16_f32 v3, v18, v22
	global_store_dwordx4 v[4:5], v[0:3], off sc1
	v_add_u32_e32 v4, s8, v42
	v_mad_i64_i32 v[4:5], s[6:7], v4, s40, v[20:21]
	v_cvt_pk_bf16_f32 v0, v9, v7
	v_cvt_pk_bf16_f32 v1, v11, v13
	v_cvt_pk_bf16_f32 v2, v15, v17
	v_cvt_pk_bf16_f32 v3, v19, v23
	global_store_dwordx4 v[4:5], v[0:3], off sc1
	s_waitcnt lgkmcnt(0)

; __device__ __forceinline__ unsigned pk_bf16(float lo, float hi) { typedef __bf16 b2_t __attribute__((ext_vector_type(2))); f32x2 v = {lo, hi}; b2_t b = __builtin_convertvector(v, b2_t); return __builtin_bit_cast(unsigned, b); }
; #define LAS __attribute__((address_space(3)))
; __device__ __forceinline__ void transpose_tile(const float* W, const float* gain, int K, int N, int k0, int n0, bf16* WT, int drow0, LAS float* scr, int lane) {
;     f32x4 v[8]; float gv[8];
;     const int r0 = lane >> 3, c4 = lane & 7;
; #pragma unroll
;     for (int i = 0; i < 8; ++i) { v[i] = *(const f32x4*)(W + (size_t)(k0 + r0 + 8 * i) * N + n0 + 4 * c4); gv[i] = gain ? gain[k0 + r0 + 8 * i] : 1.0f; }
; #pragma unroll
;     for (int i = 0; i < 8; ++i) { LAS float* d = scr + (r0 + 8 * i) * 33 + 4 * c4; d[0] = v[i][0] * gv[i]; d[1] = v[i][1] * gv[i]; d[2] = v[i][2] * gv[i]; d[3] = v[i][3] * gv[i]; }
;     asm volatile("s_waitcnt lgkmcnt(0)" ::: "memory");
;     const int c = lane & 7;
; #pragma unroll
;     for (int j = 0; j < 4; ++j) { const int n = (lane >> 3) + 8 * j; const LAS float* s = scr + (8 * c) * 33 + n;
;         v4u o; o.x = pk_bf16(s[0 * 33], s[1 * 33]); o.y = pk_bf16(s[2 * 33], s[3 * 33]); o.z = pk_bf16(s[4 * 33], s[5 * 33]); o.w = pk_bf16(s[6 * 33], s[7 * 33]);
;         *(v4u*)(WT + (size_t)(drow0 + n) * K + k0 + 8 * c) = o; }
;     asm volatile("s_waitcnt lgkmcnt(0)" ::: "memory");
; }
; template <bool SWIGLU> __device__ __forceinline__ void transpose_item(const float* W, const float* gain, int K, int N, bf16* WT, LAS float* scr, int item, int lane) {
;     const int nblk = N / 32, kb = item / nblk, nb = item % nblk, n0 = 32 * nb;
;     int drow0 = n0;
;     if (SWIGLU) { const int up = n0 >= FF, f = up ? n0 - FF : n0; drow0 = 256 * (f >> 7) + (up ? 128 : 0) + (f & 127); }
.LBB0_1370:
	s_waitcnt vmcnt(0)
	v_pk_mul_f32 v[0:1], v[0:1], v[88:89] op_sel_hi:[1,0]
	v_add_u32_e32 v33, v35, v89
	ds_write2_b32 v33, v0, v1 offset1:1
	v_pk_mul_f32 v[0:1], v[2:3], v[88:89] op_sel_hi:[1,0]
	ds_write2_b32 v33, v0, v1 offset0:2 offset1:3
	v_pk_mul_f32 v[0:1], v[4:5], v[36:37] op_sel_hi:[1,0]
	v_add_u32_e32 v2, 0x420, v33
	ds_write2_b32 v2, v0, v1 offset1:1
	v_pk_mul_f32 v[0:1], v[6:7], v[36:37] op_sel_hi:[1,0]
	v_add_u32_e32 v2, 0x428, v33
	ds_write2_b32 v2, v0, v1 offset1:1
	v_pk_mul_f32 v[0:1], v[8:9], v[94:95] op_sel_hi:[1,0]
	v_add_u32_e32 v2, 0x840, v33
	ds_write2_b32 v2, v0, v1 offset1:1
	v_pk_mul_f32 v[0:1], v[10:11], v[94:95] op_sel_hi:[1,0]
	v_add_u32_e32 v2, 0x848, v33
	ds_write2_b32 v2, v0, v1 offset1:1
	v_pk_mul_f32 v[0:1], v[12:13], v[90:91] op_sel_hi:[1,0]
	v_add_u32_e32 v2, 0xc60, v33
	ds_write2_b32 v2, v0, v1 offset1:1
	v_pk_mul_f32 v[0:1], v[14:15], v[90:91] op_sel_hi:[1,0]
	v_add_u32_e32 v2, 0xc68, v33
	ds_write2_b32 v2, v0, v1 offset1:1
	v_pk_mul_f32 v[0:1], v[16:17], v[100:101] op_sel_hi:[1,0]
	v_add_u32_e32 v2, 0x1080, v33
	ds_write2_b32 v2, v0, v1 offset1:1
	v_pk_mul_f32 v[0:1], v[18:19], v[100:101] op_sel_hi:[1,0]
	v_add_u32_e32 v2, 0x1088, v33
	ds_write2_b32 v2, v0, v1 offset1:1
	v_pk_mul_f32 v[0:1], v[20:21], v[92:93] op_sel_hi:[1,0]
	v_add_u32_e32 v2, 0x14a0, v33
	ds_write2_b32 v2, v0, v1 offset1:1
	v_pk_mul_f32 v[0:1], v[22:23], v[92:93] op_sel_hi:[1,0]
	v_add_u32_e32 v2, 0x14a8, v33
	ds_write2_b32 v2, v0, v1 offset1:1
	v_pk_mul_f32 v[0:1], v[24:25], v[102:103] op_sel_hi:[1,0]
	v_add_u32_e32 v2, 0x18c0, v33
	s_and_b32 s8, 0xffff, s8
	ds_write2_b32 v2, v0, v1 offset1:1
	v_pk_mul_f32 v[0:1], v[26:27], v[102:103] op_sel_hi:[1,0]
	v_add_u32_e32 v2, 0x18c8, v33
	s_and_b32 s7, 0xffff, s7
	s_add_i32 s9, s8, 0xfffff500
	ds_write2_b32 v2, v0, v1 offset1:1
	v_pk_mul_f32 v[0:1], v[28:29], v[96:97] op_sel_hi:[1,0]
	v_add_u32_e32 v2, 0x1ce0, v33
	s_cmpk_gt_u32 s7, 0x57
	ds_write2_b32 v2, v0, v1 offset1:1
	v_pk_mul_f32 v[0:1], v[30:31], v[96:97] op_sel_hi:[1,0]
	v_add_u32_e32 v2, 0x1ce8, v33
	s_cselect_b32 s7, s9, s8
	ds_write2_b32 v2, v0, v1 offset1:1
	s_cselect_b32 s8, 0x80, 0
	s_lshl_b32 s9, s7, 1
	s_and_b32 s7, s7, 0x60
	s_waitcnt lgkmcnt(0)
	s_and_b32 s9, s9, 0xffffff00
	s_or_b32 s7, s7, s8
	ds_read2_b32 v[4:5], v93 offset0:33 offset1:41
	ds_read2_b32 v[6:7], v93 offset1:8
	ds_read2_b32 v[8:9], v93 offset0:66 offset1:74
	ds_read2_b32 v[10:11], v93 offset0:99 offset1:107
	ds_read2_b32 v[12:13], v93 offset0:132 offset1:140
	ds_read2_b32 v[14:15], v93 offset0:165 offset1:173
	ds_read2_b32 v[16:17], v93 offset0:198 offset1:206
	ds_read2_b32 v[18:19], v93 offset0:231 offset1:239
	s_or_b32 s7, s7, s9
	s_and_b32 s6, 0xffff, s6
	v_add_u32_e32 v22, s7, v32
	s_lshl_b32 s12, s6, 1
	v_ashrrev_i32_e32 v23, 31, v22
	v_lshl_add_u64 v[20:21], v[74:75], 0, s[12:13]
	v_lshlrev_b64 v[22:23], 11, v[22:23]
	s_waitcnt lgkmcnt(6)
	v_cvt_pk_bf16_f32 v0, v6, v4
	s_waitcnt lgkmcnt(4)
	v_cvt_pk_bf16_f32 v1, v8, v10
	s_waitcnt lgkmcnt(2)
	v_cvt_pk_bf16_f32 v2, v12, v14
	s_waitcnt lgkmcnt(0)
	v_cvt_pk_bf16_f32 v3, v16, v18
	v_lshl_add_u64 v[22:23], v[20:21], 0, v[22:23]
	v_add_u32_e32 v4, s7, v38
	global_store_dwordx4 v[22:23], v[0:3], off sc1
	s_nop 1
	v_cvt_pk_bf16_f32 v0, v7, v5
	v_ashrrev_i32_e32 v5, 31, v4
	v_cvt_pk_bf16_f32 v1, v9, v11
	v_cvt_pk_bf16_f32 v2, v13, v15
	v_cvt_pk_bf16_f32 v3, v17, v19
	v_lshlrev_b64 v[4:5], 11, v[4:5]
	ds_read2_b32 v[6:7], v93 offset0:49 offset1:57
	ds_read2_b32 v[8:9], v93 offset0:16 offset1:24
	ds_read2_b32 v[10:11], v93 offset0:82 offset1:90
	ds_read2_b32 v[12:13], v93 offset0:115 offset1:123
	ds_read2_b32 v[14:15], v93 offset0:148 offset1:156
	ds_read2_b32 v[16:17], v93 offset0:181 offset1:189
	ds_read2_b32 v[18:19], v93 offset0:214 offset1:222
	ds_read2_b32 v[22:23], v93 offset0:247 offset1:255
	v_lshl_add_u64 v[4:5], v[20:21], 0, v[4:5]
	global_store_dwordx4 v[4:5], v[0:3], off sc1
	v_add_u32_e32 v4, s7, v40
	v_ashrrev_i32_e32 v5, 31, v4
	v_lshlrev_b64 v[4:5], 11, v[4:5]
	s_waitcnt lgkmcnt(6)
	v_cvt_pk_bf16_f32 v0, v8, v6
	s_waitcnt lgkmcnt(4)
	v_cvt_pk_bf16_f32 v1, v10, v12
	s_waitcnt lgkmcnt(2)
	v_cvt_pk_bf16_f32 v2, v14, v16
	s_waitcnt lgkmcnt(0)
	v_cvt_pk_bf16_f32 v3, v18, v22
	v_lshl_add_u64 v[4:5], v[20:21], 0, v[4:5]
	global_store_dwordx4 v[4:5], v[0:3], off sc1
	v_add_u32_e32 v4, s7, v42
	v_ashrrev_i32_e32 v5, 31, v4
	v_lshlrev_b64 v[4:5], 11, v[4:5]
	v_cvt_pk_bf16_f32 v0, v9, v7
	v_cvt_pk_bf16_f32 v1, v11, v13
	v_cvt_pk_bf16_f32 v2, v15, v17
	v_cvt_pk_bf16_f32 v3, v19, v23
	v_lshl_add_u64 v[4:5], v[20:21], 0, v[4:5]
	global_store_dwordx4 v[4:5], v[0:3], off sc1
	s_waitcnt lgkmcnt(0)

; __device__ __forceinline__ unsigned pk_bf16(float lo, float hi) { typedef __bf16 b2_t __attribute__((ext_vector_type(2))); f32x2 v = {lo, hi}; b2_t b = __builtin_convertvector(v, b2_t); return __builtin_bit_cast(unsigned, b); }
; #define LAS __attribute__((address_space(3)))
; __device__ __forceinline__ void transpose_tile(const float* W, const float* gain, int K, int N, int k0, int n0, bf16* WT, int drow0, LAS float* scr, int lane) {
;     f32x4 v[8]; float gv[8];
;     const int r0 = lane >> 3, c4 = lane & 7;
; #pragma unroll
;     for (int i = 0; i < 8; ++i) { v[i] = *(const f32x4*)(W + (size_t)(k0 + r0 + 8 * i) * N + n0 + 4 * c4); gv[i] = gain ? gain[k0 + r0 + 8 * i] : 1.0f; }
; #pragma unroll
;     for (int i = 0; i < 8; ++i) { LAS float* d = scr + (r0 + 8 * i) * 33 + 4 * c4; d[0] = v[i][0] * gv[i]; d[1] = v[i][1] * gv[i]; d[2] = v[i][2] * gv[i]; d[3] = v[i][3] * gv[i]; }
;     asm volatile("s_waitcnt lgkmcnt(0)" ::: "memory");
;     const int c = lane & 7;
; #pragma unroll
;     for (int j = 0; j < 4; ++j) { const int n = (lane >> 3) + 8 * j; const LAS float* s = scr + (8 * c) * 33 + n;
;         v4u o; o.x = pk_bf16(s[0 * 33], s[1 * 33]); o.y = pk_bf16(s[2 * 33], s[3 * 33]); o.z = pk_bf16(s[4 * 33], s[5 * 33]); o.w = pk_bf16(s[6 * 33], s[7 * 33]);
;         *(v4u*)(WT + (size_t)(drow0 + n) * K + k0 + 8 * c) = o; }
;     asm volatile("s_waitcnt lgkmcnt(0)" ::: "memory");
; }
.LBB0_1372:
	s_andn2_b64 vcc, exec, s[8:9]
	s_cbranch_vccnz .LBB0_1374
	s_mov_b32 s6, 11
	s_ashr_i32 s7, s6, 31
	s_lshl_b64 s[6:7], s[6:7], 3
	s_add_u32 s6, s0, s6
	s_addc_u32 s7, s1, s7
	s_load_dwordx2 s[6:7], s[6:7], 0x0
	s_lshl_b32 s8, s26, 5
	s_and_b32 s8, s8, 0x3e0
	s_add_i32 s9, s29, 0x4e80
	s_and_b32 s9, s9, 0x1ffc0
	s_lshl_b32 s12, s8, 2
	v_add_u32_e32 v0, s9, v32
	s_waitcnt lgkmcnt(0)
	s_add_u32 s6, s6, s12
	s_addc_u32 s7, s7, 0
	v_lshlrev_b32_e32 v36, 2, v34
	v_ashrrev_i32_e32 v1, 31, v0
	v_lshl_add_u64 v[2:3], s[6:7], 0, v[36:37]
	v_lshlrev_b64 v[0:1], 12, v[0:1]
	v_lshl_add_u64 v[28:29], v[2:3], 0, v[0:1]
	v_add_co_u32_e32 v4, vcc, s31, v28
	v_add_u32_e32 v33, v35, v89
	s_nop 0
	v_addc_co_u32_e32 v5, vcc, 0, v29, vcc
	v_add_co_u32_e32 v8, vcc, s34, v28
	global_load_dwordx4 v[0:3], v[28:29], off
	s_nop 0
	global_load_dwordx4 v[4:7], v[4:5], off
	v_addc_co_u32_e32 v9, vcc, 0, v29, vcc
	v_add_co_u32_e32 v12, vcc, s35, v28
	v_add_u32_e32 v36, 0x420, v33
	s_nop 0
	v_addc_co_u32_e32 v13, vcc, 0, v29, vcc
	v_add_co_u32_e32 v16, vcc, s36, v28
	global_load_dwordx4 v[8:11], v[8:9], off
	s_nop 0
	global_load_dwordx4 v[12:15], v[12:13], off
	v_addc_co_u32_e32 v17, vcc, 0, v29, vcc
	v_add_co_u32_e32 v20, vcc, s37, v28
	v_add_u32_e32 v39, 0x428, v33
	s_nop 0
	v_addc_co_u32_e32 v21, vcc, 0, v29, vcc
	global_load_dwordx4 v[16:19], v[16:17], off
	s_nop 0
	global_load_dwordx4 v[20:23], v[20:21], off
	v_add_co_u32_e32 v24, vcc, s38, v28
	v_add_u32_e32 v41, 0x840, v33
	s_nop 0
	v_addc_co_u32_e32 v25, vcc, 0, v29, vcc
	global_load_dwordx4 v[24:27], v[24:25], off
	v_add_co_u32_e32 v28, vcc, s39, v28
	v_add_u32_e32 v43, 0x848, v33
	s_nop 0
	v_addc_co_u32_e32 v29, vcc, 0, v29, vcc
	global_load_dwordx4 v[28:31], v[28:29], off
	v_add_u32_e32 v88, 0xc60, v33
	v_add_u32_e32 v90, 0xc68, v33
	v_add_u32_e32 v91, 0x1080, v33
	v_add_u32_e32 v92, 0x1088, v33
	v_add_u32_e32 v94, 0x14a0, v33
	v_add_u32_e32 v95, 0x14a8, v33
	v_add_u32_e32 v96, 0x18c0, v33
	v_add_u32_e32 v97, 0x18c8, v33
	v_add_u32_e32 v98, 0x1ce0, v33
	v_add_u32_e32 v99, 0x1ce8, v33
	s_lshl_b32 s12, s9, 1
	v_add_u32_e32 v100, s8, v32
	s_waitcnt vmcnt(0)
	ds_write2_b32 v33, v0, v1 offset1:1
	ds_write2_b32 v33, v2, v3 offset0:2 offset1:3
	ds_write2_b32 v36, v4, v5 offset1:1
	ds_write2_b32 v39, v6, v7 offset1:1
	ds_write2_b32 v41, v8, v9 offset1:1
	ds_write2_b32 v43, v10, v11 offset1:1
	ds_write2_b32 v88, v12, v13 offset1:1
	ds_write2_b32 v90, v14, v15 offset1:1
	ds_write2_b32 v91, v16, v17 offset1:1
	ds_write2_b32 v92, v18, v19 offset1:1
	ds_write2_b32 v94, v20, v21 offset1:1
	ds_write2_b32 v95, v22, v23 offset1:1
	ds_write2_b32 v96, v24, v25 offset1:1
	ds_write2_b32 v97, v26, v27 offset1:1
	ds_write2_b32 v98, v28, v29 offset1:1
	ds_write2_b32 v99, v30, v31 offset1:1
	s_waitcnt lgkmcnt(0)
	ds_read2_b32 v[4:5], v93 offset0:33 offset1:41
	ds_read2_b32 v[6:7], v93 offset1:8
	ds_read2_b32 v[8:9], v93 offset0:66 offset1:74
	ds_read2_b32 v[10:11], v93 offset0:99 offset1:107
	ds_read2_b32 v[12:13], v93 offset0:132 offset1:140
	ds_read2_b32 v[14:15], v93 offset0:165 offset1:173
	ds_read2_b32 v[16:17], v93 offset0:198 offset1:206
	ds_read2_b32 v[18:19], v93 offset0:231 offset1:239
	v_lshl_add_u64 v[20:21], v[76:77], 0, s[12:13]
	s_waitcnt lgkmcnt(6)
	v_cvt_pk_bf16_f32 v0, v6, v4
	s_waitcnt lgkmcnt(4)
	v_cvt_pk_bf16_f32 v1, v8, v10
	s_waitcnt lgkmcnt(2)
	v_cvt_pk_bf16_f32 v2, v12, v14
	s_waitcnt lgkmcnt(0)
	v_cvt_pk_bf16_f32 v3, v16, v18
	v_mad_i64_i32 v[22:23], s[6:7], v100, s40, v[20:21]
	global_store_dwordx4 v[22:23], v[0:3], off sc1
	v_add_u32_e32 v4, s8, v38
	s_nop 0
	v_cvt_pk_bf16_f32 v0, v7, v5
	v_cvt_pk_bf16_f32 v1, v9, v11
	v_cvt_pk_bf16_f32 v2, v13, v15
	v_cvt_pk_bf16_f32 v3, v17, v19
	ds_read2_b32 v[6:7], v93 offset0:49 offset1:57
	ds_read2_b32 v[8:9], v93 offset0:16 offset1:24
	ds_read2_b32 v[10:11], v93 offset0:82 offset1:90
	ds_read2_b32 v[12:13], v93 offset0:115 offset1:123
	ds_read2_b32 v[14:15], v93 offset0:148 offset1:156
	ds_read2_b32 v[16:17], v93 offset0:181 offset1:189
	ds_read2_b32 v[18:19], v93 offset0:214 offset1:222
	ds_read2_b32 v[22:23], v93 offset0:247 offset1:255
	v_mad_i64_i32 v[4:5], s[6:7], v4, s40, v[20:21]
	global_store_dwordx4 v[4:5], v[0:3], off sc1
	v_add_u32_e32 v4, s8, v40
	v_mad_i64_i32 v[4:5], s[6:7], v4, s40, v[20:21]
	s_waitcnt lgkmcnt(6)
	v_cvt_pk_bf16_f32 v0, v8, v6
	s_waitcnt lgkmcnt(4)
	v_cvt_pk_bf16_f32 v1, v10, v12
	s_waitcnt lgkmcnt(2)
	v_cvt_pk_bf16_f32 v2, v14, v16
	s_waitcnt lgkmcnt(0)
	v_cvt_pk_bf16_f32 v3, v18, v22
	global_store_dwordx4 v[4:5], v[0:3], off sc1
	v_add_u32_e32 v4, s8, v42
	v_mad_i64_i32 v[4:5], s[6:7], v4, s40, v[20:21]
	v_cvt_pk_bf16_f32 v0, v9, v7
	v_cvt_pk_bf16_f32 v1, v11, v13
	v_cvt_pk_bf16_f32 v2, v15, v17
	v_cvt_pk_bf16_f32 v3, v19, v23
	global_store_dwordx4 v[4:5], v[0:3], off sc1
	s_waitcnt lgkmcnt(0)

; __device__ __forceinline__ unsigned pk_bf16(float lo, float hi) { typedef __bf16 b2_t __attribute__((ext_vector_type(2))); f32x2 v = {lo, hi}; b2_t b = __builtin_convertvector(v, b2_t); return __builtin_bit_cast(unsigned, b); }
; #define LAS __attribute__((address_space(3)))
; __device__ __forceinline__ void transpose_tile(const float* W, const float* gain, int K, int N, int k0, int n0, bf16* WT, int drow0, LAS float* scr, int lane) {
;     f32x4 v[8]; float gv[8];
;     const int r0 = lane >> 3, c4 = lane & 7;
; #pragma unroll
;     for (int i = 0; i < 8; ++i) { v[i] = *(const f32x4*)(W + (size_t)(k0 + r0 + 8 * i) * N + n0 + 4 * c4); gv[i] = gain ? gain[k0 + r0 + 8 * i] : 1.0f; }
; #pragma unroll
;     for (int i = 0; i < 8; ++i) { LAS float* d = scr + (r0 + 8 * i) * 33 + 4 * c4; d[0] = v[i][0] * gv[i]; d[1] = v[i][1] * gv[i]; d[2] = v[i][2] * gv[i]; d[3] = v[i][3] * gv[i]; }
;     asm volatile("s_waitcnt lgkmcnt(0)" ::: "memory");
;     const int c = lane & 7;
; #pragma unroll
;     for (int j = 0; j < 4; ++j) { const int n = (lane >> 3) + 8 * j; const LAS float* s = scr + (8 * c) * 33 + n;
;         v4u o; o.x = pk_bf16(s[0 * 33], s[1 * 33]); o.y = pk_bf16(s[2 * 33], s[3 * 33]); o.z = pk_bf16(s[4 * 33], s[5 * 33]); o.w = pk_bf16(s[6 * 33], s[7 * 33]);
;         *(v4u*)(WT + (size_t)(drow0 + n) * K + k0 + 8 * c) = o; }
;     asm volatile("s_waitcnt lgkmcnt(0)" ::: "memory");
; }
; template <bool SWIGLU> __device__ __forceinline__ void transpose_item(const float* W, const float* gain, int K, int N, bf16* WT, LAS float* scr, int item, int lane) {
;     const int nblk = N / 32, kb = item / nblk, nb = item % nblk, n0 = 32 * nb;
;     int drow0 = n0;
;     if (SWIGLU) { const int up = n0 >= FF, f = up ? n0 - FF : n0; drow0 = 256 * (f >> 7) + (up ? 128 : 0) + (f & 127); }
.LBB0_1392:
	s_waitcnt vmcnt(0)
	v_pk_mul_f32 v[0:1], v[0:1], v[88:89] op_sel_hi:[1,0]
	v_add_u32_e32 v33, v35, v89
	ds_write2_b32 v33, v0, v1 offset1:1
	v_pk_mul_f32 v[0:1], v[2:3], v[88:89] op_sel_hi:[1,0]
	ds_write2_b32 v33, v0, v1 offset0:2 offset1:3
	v_pk_mul_f32 v[0:1], v[4:5], v[36:37] op_sel_hi:[1,0]
	v_add_u32_e32 v2, 0x420, v33
	ds_write2_b32 v2, v0, v1 offset1:1
	v_pk_mul_f32 v[0:1], v[6:7], v[36:37] op_sel_hi:[1,0]
	v_add_u32_e32 v2, 0x428, v33
	ds_write2_b32 v2, v0, v1 offset1:1
	v_pk_mul_f32 v[0:1], v[8:9], v[94:95] op_sel_hi:[1,0]
	v_add_u32_e32 v2, 0x840, v33
	ds_write2_b32 v2, v0, v1 offset1:1
	v_pk_mul_f32 v[0:1], v[10:11], v[94:95] op_sel_hi:[1,0]
	v_add_u32_e32 v2, 0x848, v33
	ds_write2_b32 v2, v0, v1 offset1:1
	v_pk_mul_f32 v[0:1], v[12:13], v[90:91] op_sel_hi:[1,0]
	v_add_u32_e32 v2, 0xc60, v33
	ds_write2_b32 v2, v0, v1 offset1:1
	v_pk_mul_f32 v[0:1], v[14:15], v[90:91] op_sel_hi:[1,0]
	v_add_u32_e32 v2, 0xc68, v33
	ds_write2_b32 v2, v0, v1 offset1:1
	v_pk_mul_f32 v[0:1], v[16:17], v[100:101] op_sel_hi:[1,0]
	v_add_u32_e32 v2, 0x1080, v33
	ds_write2_b32 v2, v0, v1 offset1:1
	v_pk_mul_f32 v[0:1], v[18:19], v[100:101] op_sel_hi:[1,0]
	v_add_u32_e32 v2, 0x1088, v33
	ds_write2_b32 v2, v0, v1 offset1:1
	v_pk_mul_f32 v[0:1], v[20:21], v[92:93] op_sel_hi:[1,0]
	v_add_u32_e32 v2, 0x14a0, v33
	ds_write2_b32 v2, v0, v1 offset1:1
	v_pk_mul_f32 v[0:1], v[22:23], v[92:93] op_sel_hi:[1,0]
	v_add_u32_e32 v2, 0x14a8, v33
	ds_write2_b32 v2, v0, v1 offset1:1
	v_pk_mul_f32 v[0:1], v[24:25], v[102:103] op_sel_hi:[1,0]
	v_add_u32_e32 v2, 0x18c0, v33
	s_and_b32 s8, 0xffff, s8
	ds_write2_b32 v2, v0, v1 offset1:1
	v_pk_mul_f32 v[0:1], v[26:27], v[102:103] op_sel_hi:[1,0]
	v_add_u32_e32 v2, 0x18c8, v33
	s_and_b32 s7, 0xffff, s7
	s_add_i32 s9, s8, 0xfffff500
	ds_write2_b32 v2, v0, v1 offset1:1
	v_pk_mul_f32 v[0:1], v[28:29], v[96:97] op_sel_hi:[1,0]
	v_add_u32_e32 v2, 0x1ce0, v33
	s_cmpk_gt_u32 s7, 0x57
	ds_write2_b32 v2, v0, v1 offset1:1
	v_pk_mul_f32 v[0:1], v[30:31], v[96:97] op_sel_hi:[1,0]
	v_add_u32_e32 v2, 0x1ce8, v33
	s_cselect_b32 s7, s9, s8
	ds_write2_b32 v2, v0, v1 offset1:1
	s_cselect_b32 s8, 0x80, 0
	s_lshl_b32 s9, s7, 1
	s_and_b32 s7, s7, 0x60
	s_waitcnt lgkmcnt(0)
	s_and_b32 s9, s9, 0xffffff00
	s_or_b32 s7, s7, s8
	ds_read2_b32 v[4:5], v93 offset0:33 offset1:41
	ds_read2_b32 v[6:7], v93 offset1:8
	ds_read2_b32 v[8:9], v93 offset0:66 offset1:74
	ds_read2_b32 v[10:11], v93 offset0:99 offset1:107
	ds_read2_b32 v[12:13], v93 offset0:132 offset1:140
	ds_read2_b32 v[14:15], v93 offset0:165 offset1:173
	ds_read2_b32 v[16:17], v93 offset0:198 offset1:206
	ds_read2_b32 v[18:19], v93 offset0:231 offset1:239
	s_or_b32 s7, s7, s9
	s_and_b32 s6, 0xffff, s6
	v_add_u32_e32 v22, s7, v32
	s_lshl_b32 s12, s6, 1
	v_ashrrev_i32_e32 v23, 31, v22
	v_lshl_add_u64 v[20:21], v[78:79], 0, s[12:13]
	v_lshlrev_b64 v[22:23], 11, v[22:23]
	s_waitcnt lgkmcnt(6)
	v_cvt_pk_bf16_f32 v0, v6, v4
	s_waitcnt lgkmcnt(4)
	v_cvt_pk_bf16_f32 v1, v8, v10
	s_waitcnt lgkmcnt(2)
	v_cvt_pk_bf16_f32 v2, v12, v14
	s_waitcnt lgkmcnt(0)
	v_cvt_pk_bf16_f32 v3, v16, v18
	v_lshl_add_u64 v[22:23], v[20:21], 0, v[22:23]
	v_add_u32_e32 v4, s7, v38
	global_store_dwordx4 v[22:23], v[0:3], off sc1
	s_nop 1
	v_cvt_pk_bf16_f32 v0, v7, v5
	v_ashrrev_i32_e32 v5, 31, v4
	v_cvt_pk_bf16_f32 v1, v9, v11
	v_cvt_pk_bf16_f32 v2, v13, v15
	v_cvt_pk_bf16_f32 v3, v17, v19
	v_lshlrev_b64 v[4:5], 11, v[4:5]
	ds_read2_b32 v[6:7], v93 offset0:49 offset1:57
	ds_read2_b32 v[8:9], v93 offset0:16 offset1:24
	ds_read2_b32 v[10:11], v93 offset0:82 offset1:90
	ds_read2_b32 v[12:13], v93 offset0:115 offset1:123
	ds_read2_b32 v[14:15], v93 offset0:148 offset1:156
	ds_read2_b32 v[16:17], v93 offset0:181 offset1:189
	ds_read2_b32 v[18:19], v93 offset0:214 offset1:222
	ds_read2_b32 v[22:23], v93 offset0:247 offset1:255
	v_lshl_add_u64 v[4:5], v[20:21], 0, v[4:5]
	global_store_dwordx4 v[4:5], v[0:3], off sc1
	v_add_u32_e32 v4, s7, v40
	v_ashrrev_i32_e32 v5, 31, v4
	v_lshlrev_b64 v[4:5], 11, v[4:5]
	s_waitcnt lgkmcnt(6)
	v_cvt_pk_bf16_f32 v0, v8, v6
	s_waitcnt lgkmcnt(4)
	v_cvt_pk_bf16_f32 v1, v10, v12
	s_waitcnt lgkmcnt(2)
	v_cvt_pk_bf16_f32 v2, v14, v16
	s_waitcnt lgkmcnt(0)
	v_cvt_pk_bf16_f32 v3, v18, v22
	v_lshl_add_u64 v[4:5], v[20:21], 0, v[4:5]
	global_store_dwordx4 v[4:5], v[0:3], off sc1
	v_add_u32_e32 v4, s7, v42
	v_ashrrev_i32_e32 v5, 31, v4
	v_lshlrev_b64 v[4:5], 11, v[4:5]
	v_cvt_pk_bf16_f32 v0, v9, v7
	v_cvt_pk_bf16_f32 v1, v11, v13
	v_cvt_pk_bf16_f32 v2, v15, v17
	v_cvt_pk_bf16_f32 v3, v19, v23
	v_lshl_add_u64 v[4:5], v[20:21], 0, v[4:5]
	global_store_dwordx4 v[4:5], v[0:3], off sc1
	s_waitcnt lgkmcnt(0)

; __device__ __forceinline__ unsigned pk_bf16(float lo, float hi) { typedef __bf16 b2_t __attribute__((ext_vector_type(2))); f32x2 v = {lo, hi}; b2_t b = __builtin_convertvector(v, b2_t); return __builtin_bit_cast(unsigned, b); }
; #define LAS __attribute__((address_space(3)))
; __device__ __forceinline__ void transpose_tile(const float* W, const float* gain, int K, int N, int k0, int n0, bf16* WT, int drow0, LAS float* scr, int lane) {
;     f32x4 v[8]; float gv[8];
;     const int r0 = lane >> 3, c4 = lane & 7;
; #pragma unroll
;     for (int i = 0; i < 8; ++i) { v[i] = *(const f32x4*)(W + (size_t)(k0 + r0 + 8 * i) * N + n0 + 4 * c4); gv[i] = gain ? gain[k0 + r0 + 8 * i] : 1.0f; }
; #pragma unroll
;     for (int i = 0; i < 8; ++i) { LAS float* d = scr + (r0 + 8 * i) * 33 + 4 * c4; d[0] = v[i][0] * gv[i]; d[1] = v[i][1] * gv[i]; d[2] = v[i][2] * gv[i]; d[3] = v[i][3] * gv[i]; }
;     asm volatile("s_waitcnt lgkmcnt(0)" ::: "memory");
;     const int c = lane & 7;
; #pragma unroll
;     for (int j = 0; j < 4; ++j) { const int n = (lane >> 3) + 8 * j; const LAS float* s = scr + (8 * c) * 33 + n;
;         v4u o; o.x = pk_bf16(s[0 * 33], s[1 * 33]); o.y = pk_bf16(s[2 * 33], s[3 * 33]); o.z = pk_bf16(s[4 * 33], s[5 * 33]); o.w = pk_bf16(s[6 * 33], s[7 * 33]);
;         *(v4u*)(WT + (size_t)(drow0 + n) * K + k0 + 8 * c) = o; }
;     asm volatile("s_waitcnt lgkmcnt(0)" ::: "memory");
; }
.LBB0_1394:
	s_andn2_b64 vcc, exec, s[8:9]
	s_cbranch_vccnz .LBB0_1396
	s_mov_b32 s6, 8
	s_ashr_i32 s7, s6, 31
	s_lshl_b64 s[6:7], s[6:7], 3
	s_add_u32 s6, s0, s6
	s_addc_u32 s7, s1, s7
	s_load_dwordx2 s[6:7], s[6:7], 0x0
	s_lshl_b32 s8, s26, 5
	s_and_b32 s8, s8, 0x3e0
	s_add_i32 s9, s29, 0x6880
	s_and_b32 s9, s9, 0x1ffc0
	s_lshl_b32 s12, s8, 2
	v_add_u32_e32 v0, s9, v32
	s_waitcnt lgkmcnt(0)
	s_add_u32 s6, s6, s12
	s_addc_u32 s7, s7, 0
	v_lshlrev_b32_e32 v36, 2, v34
	v_ashrrev_i32_e32 v1, 31, v0
	v_lshl_add_u64 v[2:3], s[6:7], 0, v[36:37]
	v_lshlrev_b64 v[0:1], 12, v[0:1]
	v_lshl_add_u64 v[28:29], v[2:3], 0, v[0:1]
	v_add_co_u32_e32 v4, vcc, s31, v28
	v_add_u32_e32 v33, v35, v89
	s_nop 0
	v_addc_co_u32_e32 v5, vcc, 0, v29, vcc
	v_add_co_u32_e32 v8, vcc, s34, v28
	global_load_dwordx4 v[0:3], v[28:29], off
	s_nop 0
	global_load_dwordx4 v[4:7], v[4:5], off
	v_addc_co_u32_e32 v9, vcc, 0, v29, vcc
	v_add_co_u32_e32 v12, vcc, s35, v28
	v_add_u32_e32 v36, 0x420, v33
	s_nop 0
	v_addc_co_u32_e32 v13, vcc, 0, v29, vcc
	v_add_co_u32_e32 v16, vcc, s36, v28
	global_load_dwordx4 v[8:11], v[8:9], off
	s_nop 0
	global_load_dwordx4 v[12:15], v[12:13], off
	v_addc_co_u32_e32 v17, vcc, 0, v29, vcc
	v_add_co_u32_e32 v20, vcc, s37, v28
	v_add_u32_e32 v39, 0x428, v33
	s_nop 0
	v_addc_co_u32_e32 v21, vcc, 0, v29, vcc
	global_load_dwordx4 v[16:19], v[16:17], off
	s_nop 0
	global_load_dwordx4 v[20:23], v[20:21], off
	v_add_co_u32_e32 v24, vcc, s38, v28
	v_add_u32_e32 v41, 0x840, v33
	s_nop 0
	v_addc_co_u32_e32 v25, vcc, 0, v29, vcc
	global_load_dwordx4 v[24:27], v[24:25], off
	v_add_co_u32_e32 v28, vcc, s39, v28
	v_add_u32_e32 v43, 0x848, v33
	s_nop 0
	v_addc_co_u32_e32 v29, vcc, 0, v29, vcc
	global_load_dwordx4 v[28:31], v[28:29], off
	v_add_u32_e32 v88, 0xc60, v33
	v_add_u32_e32 v92, 0xc68, v33
	v_add_u32_e32 v94, 0x1080, v33
	v_add_u32_e32 v95, 0x1088, v33
	v_add_u32_e32 v96, 0x14a0, v33
	v_add_u32_e32 v97, 0x14a8, v33
	v_add_u32_e32 v98, 0x18c0, v33
	v_add_u32_e32 v99, 0x18c8, v33
	v_add_u32_e32 v100, 0x1ce0, v33
	v_add_u32_e32 v101, 0x1ce8, v33
	v_add_u32_e32 v90, s8, v32
	v_ashrrev_i32_e32 v91, 31, v90
	s_lshl_b32 s12, s9, 1
	s_waitcnt vmcnt(0)
	ds_write2_b32 v33, v0, v1 offset1:1
	ds_write2_b32 v33, v2, v3 offset0:2 offset1:3
	ds_write2_b32 v36, v4, v5 offset1:1
	ds_write2_b32 v39, v6, v7 offset1:1
	ds_write2_b32 v41, v8, v9 offset1:1
	ds_write2_b32 v43, v10, v11 offset1:1
	ds_write2_b32 v88, v12, v13 offset1:1
	ds_write2_b32 v92, v14, v15 offset1:1
	ds_write2_b32 v94, v16, v17 offset1:1
	ds_write2_b32 v95, v18, v19 offset1:1
	ds_write2_b32 v96, v20, v21 offset1:1
	ds_write2_b32 v97, v22, v23 offset1:1
	ds_write2_b32 v98, v24, v25 offset1:1
	ds_write2_b32 v99, v26, v27 offset1:1
	ds_write2_b32 v100, v28, v29 offset1:1
	ds_write2_b32 v101, v30, v31 offset1:1
	s_waitcnt lgkmcnt(0)
	ds_read2_b32 v[4:5], v93 offset0:33 offset1:41
	ds_read2_b32 v[6:7], v93 offset1:8
	ds_read2_b32 v[8:9], v93 offset0:66 offset1:74
	ds_read2_b32 v[10:11], v93 offset0:99 offset1:107
	ds_read2_b32 v[12:13], v93 offset0:132 offset1:140
	ds_read2_b32 v[14:15], v93 offset0:165 offset1:173
	ds_read2_b32 v[16:17], v93 offset0:198 offset1:206
	ds_read2_b32 v[18:19], v93 offset0:231 offset1:239
	v_lshl_add_u64 v[20:21], v[80:81], 0, s[12:13]
	v_lshlrev_b64 v[22:23], 11, v[90:91]
	s_waitcnt lgkmcnt(6)
	v_cvt_pk_bf16_f32 v0, v6, v4
	s_waitcnt lgkmcnt(4)
	v_cvt_pk_bf16_f32 v1, v8, v10
	s_waitcnt lgkmcnt(2)
	v_cvt_pk_bf16_f32 v2, v12, v14
	s_waitcnt lgkmcnt(0)
	v_cvt_pk_bf16_f32 v3, v16, v18
	v_lshl_add_u64 v[22:23], v[20:21], 0, v[22:23]
	v_add_u32_e32 v4, s8, v38
	global_store_dwordx4 v[22:23], v[0:3], off sc1
	s_nop 1
	v_cvt_pk_bf16_f32 v0, v7, v5
	v_ashrrev_i32_e32 v5, 31, v4
	v_cvt_pk_bf16_f32 v1, v9, v11
	v_cvt_pk_bf16_f32 v2, v13, v15
	v_cvt_pk_bf16_f32 v3, v17, v19
	v_lshlrev_b64 v[4:5], 11, v[4:5]
	ds_read2_b32 v[6:7], v93 offset0:49 offset1:57
	ds_read2_b32 v[8:9], v93 offset0:16 offset1:24
	ds_read2_b32 v[10:11], v93 offset0:82 offset1:90
	ds_read2_b32 v[12:13], v93 offset0:115 offset1:123
	ds_read2_b32 v[14:15], v93 offset0:148 offset1:156
	ds_read2_b32 v[16:17], v93 offset0:181 offset1:189
	ds_read2_b32 v[18:19], v93 offset0:214 offset1:222
	ds_read2_b32 v[22:23], v93 offset0:247 offset1:255
	v_lshl_add_u64 v[4:5], v[20:21], 0, v[4:5]
	global_store_dwordx4 v[4:5], v[0:3], off sc1
	v_add_u32_e32 v4, s8, v40
	v_ashrrev_i32_e32 v5, 31, v4
	v_lshlrev_b64 v[4:5], 11, v[4:5]
	s_waitcnt lgkmcnt(6)
	v_cvt_pk_bf16_f32 v0, v8, v6
	s_waitcnt lgkmcnt(4)
	v_cvt_pk_bf16_f32 v1, v10, v12
	s_waitcnt lgkmcnt(2)
	v_cvt_pk_bf16_f32 v2, v14, v16
	s_waitcnt lgkmcnt(0)
	v_cvt_pk_bf16_f32 v3, v18, v22
	v_lshl_add_u64 v[4:5], v[20:21], 0, v[4:5]
	global_store_dwordx4 v[4:5], v[0:3], off sc1
	v_add_u32_e32 v4, s8, v42
	v_ashrrev_i32_e32 v5, 31, v4
	v_lshlrev_b64 v[4:5], 11, v[4:5]
	v_cvt_pk_bf16_f32 v0, v9, v7
	v_cvt_pk_bf16_f32 v1, v11, v13
	v_cvt_pk_bf16_f32 v2, v15, v17
	v_cvt_pk_bf16_f32 v3, v19, v23
	v_lshl_add_u64 v[4:5], v[20:21], 0, v[4:5]
	global_store_dwordx4 v[4:5], v[0:3], off sc1
	s_waitcnt lgkmcnt(0)

; __device__ __forceinline__ unsigned pk_bf16(float lo, float hi) { typedef __bf16 b2_t __attribute__((ext_vector_type(2))); f32x2 v = {lo, hi}; b2_t b = __builtin_convertvector(v, b2_t); return __builtin_bit_cast(unsigned, b); }
; #define LAS __attribute__((address_space(3)))
; __device__ __forceinline__ void transpose_tile(const float* W, const float* gain, int K, int N, int k0, int n0, bf16* WT, int drow0, LAS float* scr, int lane) {
;     f32x4 v[8]; float gv[8];
;     const int r0 = lane >> 3, c4 = lane & 7;
; #pragma unroll
;     for (int i = 0; i < 8; ++i) { v[i] = *(const f32x4*)(W + (size_t)(k0 + r0 + 8 * i) * N + n0 + 4 * c4); gv[i] = gain ? gain[k0 + r0 + 8 * i] : 1.0f; }
; #pragma unroll
;     for (int i = 0; i < 8; ++i) { LAS float* d = scr + (r0 + 8 * i) * 33 + 4 * c4; d[0] = v[i][0] * gv[i]; d[1] = v[i][1] * gv[i]; d[2] = v[i][2] * gv[i]; d[3] = v[i][3] * gv[i]; }
;     asm volatile("s_waitcnt lgkmcnt(0)" ::: "memory");
;     const int c = lane & 7;
; #pragma unroll
;     for (int j = 0; j < 4; ++j) { const int n = (lane >> 3) + 8 * j; const LAS float* s = scr + (8 * c) * 33 + n;
;         v4u o; o.x = pk_bf16(s[0 * 33], s[1 * 33]); o.y = pk_bf16(s[2 * 33], s[3 * 33]); o.z = pk_bf16(s[4 * 33], s[5 * 33]); o.w = pk_bf16(s[6 * 33], s[7 * 33]);
;         *(v4u*)(WT + (size_t)(drow0 + n) * K + k0 + 8 * c) = o; }
;     asm volatile("s_waitcnt lgkmcnt(0)" ::: "memory");
; }
.LBB0_1414:
	s_waitcnt vmcnt(0)
	v_pk_mul_f32 v[0:1], v[0:1], v[88:89] op_sel_hi:[1,0]
	v_add_u32_e32 v33, v35, v89
	ds_write2_b32 v33, v0, v1 offset1:1
	v_pk_mul_f32 v[0:1], v[2:3], v[88:89] op_sel_hi:[1,0]
	ds_write2_b32 v33, v0, v1 offset0:2 offset1:3
	v_pk_mul_f32 v[0:1], v[4:5], v[36:37] op_sel_hi:[1,0]
	v_add_u32_e32 v2, 0x420, v33
	ds_write2_b32 v2, v0, v1 offset1:1
	v_pk_mul_f32 v[0:1], v[6:7], v[36:37] op_sel_hi:[1,0]
	v_add_u32_e32 v2, 0x428, v33
	ds_write2_b32 v2, v0, v1 offset1:1
	v_pk_mul_f32 v[0:1], v[8:9], v[96:97] op_sel_hi:[1,0]
	v_add_u32_e32 v2, 0x840, v33
	ds_write2_b32 v2, v0, v1 offset1:1
	v_pk_mul_f32 v[0:1], v[10:11], v[96:97] op_sel_hi:[1,0]
	v_add_u32_e32 v2, 0x848, v33
	ds_write2_b32 v2, v0, v1 offset1:1
	v_pk_mul_f32 v[0:1], v[12:13], v[90:91] op_sel_hi:[1,0]
	v_add_u32_e32 v2, 0xc60, v33
	ds_write2_b32 v2, v0, v1 offset1:1
	v_pk_mul_f32 v[0:1], v[14:15], v[90:91] op_sel_hi:[1,0]
	v_add_u32_e32 v2, 0xc68, v33
	ds_write2_b32 v2, v0, v1 offset1:1
	v_pk_mul_f32 v[0:1], v[16:17], v[100:101] op_sel_hi:[1,0]
	v_add_u32_e32 v2, 0x1080, v33
	ds_write2_b32 v2, v0, v1 offset1:1
	v_pk_mul_f32 v[0:1], v[18:19], v[100:101] op_sel_hi:[1,0]
	v_add_u32_e32 v2, 0x1088, v33
	ds_write2_b32 v2, v0, v1 offset1:1
	v_pk_mul_f32 v[0:1], v[20:21], v[92:93] op_sel_hi:[1,0]
	v_add_u32_e32 v2, 0x14a0, v33
	ds_write2_b32 v2, v0, v1 offset1:1
	v_pk_mul_f32 v[0:1], v[22:23], v[92:93] op_sel_hi:[1,0]
	v_add_u32_e32 v2, 0x14a8, v33
	ds_write2_b32 v2, v0, v1 offset1:1
	v_pk_mul_f32 v[0:1], v[24:25], v[102:103] op_sel_hi:[1,0]
	v_add_u32_e32 v2, 0x18c0, v33
	ds_write2_b32 v2, v0, v1 offset1:1
	v_pk_mul_f32 v[0:1], v[26:27], v[102:103] op_sel_hi:[1,0]
	v_add_u32_e32 v2, 0x18c8, v33
	ds_write2_b32 v2, v0, v1 offset1:1
	v_pk_mul_f32 v[0:1], v[28:29], v[98:99] op_sel_hi:[1,0]
	v_add_u32_e32 v2, 0x1ce0, v33
	ds_write2_b32 v2, v0, v1 offset1:1
	v_pk_mul_f32 v[0:1], v[30:31], v[98:99] op_sel_hi:[1,0]
	v_add_u32_e32 v2, 0x1ce8, v33
	ds_write2_b32 v2, v0, v1 offset1:1
	s_waitcnt lgkmcnt(0)
	s_lshl_b32 s7, s7, 5
	ds_read2_b32 v[4:5], v93 offset0:33 offset1:41
	ds_read2_b32 v[6:7], v93 offset1:8
	ds_read2_b32 v[8:9], v93 offset0:66 offset1:74
	ds_read2_b32 v[10:11], v93 offset0:99 offset1:107
	ds_read2_b32 v[12:13], v93 offset0:132 offset1:140
	ds_read2_b32 v[14:15], v93 offset0:165 offset1:173
	ds_read2_b32 v[16:17], v93 offset0:198 offset1:206
	ds_read2_b32 v[18:19], v93 offset0:231 offset1:239
	s_and_b32 s7, 0xffff, s7
	s_and_b32 s6, 0xffff, s6
	v_add_u32_e32 v22, s7, v32
	s_lshl_b32 s12, s6, 1
	v_ashrrev_i32_e32 v23, 31, v22
	v_lshl_add_u64 v[20:21], v[82:83], 0, s[12:13]
	v_lshlrev_b64 v[22:23], 11, v[22:23]
	s_waitcnt lgkmcnt(6)
	v_cvt_pk_bf16_f32 v0, v6, v4
	s_waitcnt lgkmcnt(4)
	v_cvt_pk_bf16_f32 v1, v8, v10
	s_waitcnt lgkmcnt(2)
	v_cvt_pk_bf16_f32 v2, v12, v14
	s_waitcnt lgkmcnt(0)
	v_cvt_pk_bf16_f32 v3, v16, v18
	v_lshl_add_u64 v[22:23], v[20:21], 0, v[22:23]
	v_add_u32_e32 v4, s7, v38
	global_store_dwordx4 v[22:23], v[0:3], off sc1
	s_nop 1
	v_cvt_pk_bf16_f32 v0, v7, v5
	v_ashrrev_i32_e32 v5, 31, v4
	v_cvt_pk_bf16_f32 v1, v9, v11
	v_cvt_pk_bf16_f32 v2, v13, v15
	v_cvt_pk_bf16_f32 v3, v17, v19
	v_lshlrev_b64 v[4:5], 11, v[4:5]
	ds_read2_b32 v[6:7], v93 offset0:49 offset1:57
	ds_read2_b32 v[8:9], v93 offset0:16 offset1:24
	ds_read2_b32 v[10:11], v93 offset0:82 offset1:90
	ds_read2_b32 v[12:13], v93 offset0:115 offset1:123
	ds_read2_b32 v[14:15], v93 offset0:148 offset1:156
	ds_read2_b32 v[16:17], v93 offset0:181 offset1:189
	ds_read2_b32 v[18:19], v93 offset0:214 offset1:222
	ds_read2_b32 v[22:23], v93 offset0:247 offset1:255
	v_lshl_add_u64 v[4:5], v[20:21], 0, v[4:5]
	global_store_dwordx4 v[4:5], v[0:3], off sc1
	v_add_u32_e32 v4, s7, v40
	v_ashrrev_i32_e32 v5, 31, v4
	v_lshlrev_b64 v[4:5], 11, v[4:5]
	s_waitcnt lgkmcnt(6)
	v_cvt_pk_bf16_f32 v0, v8, v6
	s_waitcnt lgkmcnt(4)
	v_cvt_pk_bf16_f32 v1, v10, v12
	s_waitcnt lgkmcnt(2)
	v_cvt_pk_bf16_f32 v2, v14, v16
	s_waitcnt lgkmcnt(0)
	v_cvt_pk_bf16_f32 v3, v18, v22
	v_lshl_add_u64 v[4:5], v[20:21], 0, v[4:5]
	global_store_dwordx4 v[4:5], v[0:3], off sc1
	v_add_u32_e32 v4, s7, v42
	v_ashrrev_i32_e32 v5, 31, v4
	v_lshlrev_b64 v[4:5], 11, v[4:5]
	v_cvt_pk_bf16_f32 v0, v9, v7
	v_cvt_pk_bf16_f32 v1, v11, v13
	v_cvt_pk_bf16_f32 v2, v15, v17
	v_cvt_pk_bf16_f32 v3, v19, v23
	v_lshl_add_u64 v[4:5], v[20:21], 0, v[4:5]
	global_store_dwordx4 v[4:5], v[0:3], off sc1
	s_waitcnt lgkmcnt(0)

; __device__ __forceinline__ unsigned pk_bf16(float lo, float hi) { typedef __bf16 b2_t __attribute__((ext_vector_type(2))); f32x2 v = {lo, hi}; b2_t b = __builtin_convertvector(v, b2_t); return __builtin_bit_cast(unsigned, b); }
; #define LAS __attribute__((address_space(3)))
; __device__ __forceinline__ void transpose_tile(const float* W, const float* gain, int K, int N, int k0, int n0, bf16* WT, int drow0, LAS float* scr, int lane) {
;     f32x4 v[8]; float gv[8];
;     const int r0 = lane >> 3, c4 = lane & 7;
; #pragma unroll
;     for (int i = 0; i < 8; ++i) { v[i] = *(const f32x4*)(W + (size_t)(k0 + r0 + 8 * i) * N + n0 + 4 * c4); gv[i] = gain ? gain[k0 + r0 + 8 * i] : 1.0f; }
; #pragma unroll
;     for (int i = 0; i < 8; ++i) { LAS float* d = scr + (r0 + 8 * i) * 33 + 4 * c4; d[0] = v[i][0] * gv[i]; d[1] = v[i][1] * gv[i]; d[2] = v[i][2] * gv[i]; d[3] = v[i][3] * gv[i]; }
;     asm volatile("s_waitcnt lgkmcnt(0)" ::: "memory");
;     const int c = lane & 7;
; #pragma unroll
;     for (int j = 0; j < 4; ++j) { const int n = (lane >> 3) + 8 * j; const LAS float* s = scr + (8 * c) * 33 + n;
;         v4u o; o.x = pk_bf16(s[0 * 33], s[1 * 33]); o.y = pk_bf16(s[2 * 33], s[3 * 33]); o.z = pk_bf16(s[4 * 33], s[5 * 33]); o.w = pk_bf16(s[6 * 33], s[7 * 33]);
;         *(v4u*)(WT + (size_t)(drow0 + n) * K + k0 + 8 * c) = o; }
;     asm volatile("s_waitcnt lgkmcnt(0)" ::: "memory");
; }
.LBB0_1416:
	s_andn2_b64 vcc, exec, s[8:9]
	s_cbranch_vccnz .LBB0_1418
	s_mov_b32 s6, 3
	s_ashr_i32 s7, s6, 31
	s_lshl_b64 s[6:7], s[6:7], 3
	s_add_u32 s6, s0, s6
	s_addc_u32 s7, s1, s7
	s_load_dwordx2 s[6:7], s[6:7], 0x0
	s_lshl_b32 s8, s26, 5
	s_and_b32 s8, s8, 0x3e0
	s_add_i32 s9, s29, 0x7f80
	s_and_b32 s9, s9, 0x1ffc0
	s_lshl_b32 s12, s8, 2
	v_add_u32_e32 v0, s9, v32
	s_waitcnt lgkmcnt(0)
	s_add_u32 s6, s6, s12
	s_addc_u32 s7, s7, 0
	v_lshlrev_b32_e32 v36, 2, v34
	v_ashrrev_i32_e32 v1, 31, v0
	v_lshl_add_u64 v[2:3], s[6:7], 0, v[36:37]
	v_lshlrev_b64 v[0:1], 12, v[0:1]
	v_lshl_add_u64 v[28:29], v[2:3], 0, v[0:1]
	v_add_co_u32_e32 v4, vcc, s31, v28
	v_add_u32_e32 v33, v35, v89
	s_nop 0
	v_addc_co_u32_e32 v5, vcc, 0, v29, vcc
	v_add_co_u32_e32 v8, vcc, s34, v28
	global_load_dwordx4 v[0:3], v[28:29], off
	s_nop 0
	global_load_dwordx4 v[4:7], v[4:5], off
	v_addc_co_u32_e32 v9, vcc, 0, v29, vcc
	v_add_co_u32_e32 v12, vcc, s35, v28
	v_add_u32_e32 v36, 0x420, v33
	s_nop 0
	v_addc_co_u32_e32 v13, vcc, 0, v29, vcc
	v_add_co_u32_e32 v16, vcc, s36, v28
	global_load_dwordx4 v[8:11], v[8:9], off
	s_nop 0
	global_load_dwordx4 v[12:15], v[12:13], off
	v_addc_co_u32_e32 v17, vcc, 0, v29, vcc
	v_add_co_u32_e32 v20, vcc, s37, v28
	v_add_u32_e32 v39, 0x428, v33
	s_nop 0
	v_addc_co_u32_e32 v21, vcc, 0, v29, vcc
	global_load_dwordx4 v[16:19], v[16:17], off
	s_nop 0
	global_load_dwordx4 v[20:23], v[20:21], off
	v_add_co_u32_e32 v24, vcc, s38, v28
	v_add_u32_e32 v41, 0x840, v33
	s_nop 0
	v_addc_co_u32_e32 v25, vcc, 0, v29, vcc
	global_load_dwordx4 v[24:27], v[24:25], off
	v_add_co_u32_e32 v28, vcc, s39, v28
	v_add_u32_e32 v43, 0x848, v33
	s_nop 0
	v_addc_co_u32_e32 v29, vcc, 0, v29, vcc
	global_load_dwordx4 v[28:31], v[28:29], off
	v_add_u32_e32 v88, 0xc60, v33
	v_add_u32_e32 v90, 0xc68, v33
	v_add_u32_e32 v91, 0x1080, v33
	v_add_u32_e32 v92, 0x1088, v33
	v_add_u32_e32 v94, 0x14a0, v33
	v_add_u32_e32 v95, 0x14a8, v33
	v_add_u32_e32 v96, 0x18c0, v33
	v_add_u32_e32 v97, 0x18c8, v33
	v_add_u32_e32 v98, 0x1ce0, v33
	v_add_u32_e32 v99, 0x1ce8, v33
	s_lshl_b32 s12, s9, 1
	v_add_u32_e32 v100, s8, v32
	s_waitcnt vmcnt(0)
	ds_write2_b32 v33, v0, v1 offset1:1
	ds_write2_b32 v33, v2, v3 offset0:2 offset1:3
	ds_write2_b32 v36, v4, v5 offset1:1
	ds_write2_b32 v39, v6, v7 offset1:1
	ds_write2_b32 v41, v8, v9 offset1:1
	ds_write2_b32 v43, v10, v11 offset1:1
	ds_write2_b32 v88, v12, v13 offset1:1
	ds_write2_b32 v90, v14, v15 offset1:1
	ds_write2_b32 v91, v16, v17 offset1:1
	ds_write2_b32 v92, v18, v19 offset1:1
	ds_write2_b32 v94, v20, v21 offset1:1
	ds_write2_b32 v95, v22, v23 offset1:1
	ds_write2_b32 v96, v24, v25 offset1:1
	ds_write2_b32 v97, v26, v27 offset1:1
	ds_write2_b32 v98, v28, v29 offset1:1
	ds_write2_b32 v99, v30, v31 offset1:1
	s_waitcnt lgkmcnt(0)
	ds_read2_b32 v[4:5], v93 offset0:33 offset1:41
	ds_read2_b32 v[6:7], v93 offset1:8
	ds_read2_b32 v[8:9], v93 offset0:66 offset1:74
	ds_read2_b32 v[10:11], v93 offset0:99 offset1:107
	ds_read2_b32 v[12:13], v93 offset0:132 offset1:140
	ds_read2_b32 v[14:15], v93 offset0:165 offset1:173
	ds_read2_b32 v[16:17], v93 offset0:198 offset1:206
	ds_read2_b32 v[18:19], v93 offset0:231 offset1:239
	v_lshl_add_u64 v[20:21], v[84:85], 0, s[12:13]
	s_waitcnt lgkmcnt(6)
	v_cvt_pk_bf16_f32 v0, v6, v4
	s_waitcnt lgkmcnt(4)
	v_cvt_pk_bf16_f32 v1, v8, v10
	s_waitcnt lgkmcnt(2)
	v_cvt_pk_bf16_f32 v2, v12, v14
	s_waitcnt lgkmcnt(0)
	v_cvt_pk_bf16_f32 v3, v16, v18
	v_mad_i64_i32 v[22:23], s[6:7], v100, s40, v[20:21]
	global_store_dwordx4 v[22:23], v[0:3], off sc1
	v_add_u32_e32 v4, s8, v38
	s_nop 0
	v_cvt_pk_bf16_f32 v0, v7, v5
	v_cvt_pk_bf16_f32 v1, v9, v11
	v_cvt_pk_bf16_f32 v2, v13, v15
	v_cvt_pk_bf16_f32 v3, v17, v19
	ds_read2_b32 v[6:7], v93 offset0:49 offset1:57
	ds_read2_b32 v[8:9], v93 offset0:16 offset1:24
	ds_read2_b32 v[10:11], v93 offset0:82 offset1:90
	ds_read2_b32 v[12:13], v93 offset0:115 offset1:123
	ds_read2_b32 v[14:15], v93 offset0:148 offset1:156
	ds_read2_b32 v[16:17], v93 offset0:181 offset1:189
	ds_read2_b32 v[18:19], v93 offset0:214 offset1:222
	ds_read2_b32 v[22:23], v93 offset0:247 offset1:255
	v_mad_i64_i32 v[4:5], s[6:7], v4, s40, v[20:21]
	global_store_dwordx4 v[4:5], v[0:3], off sc1
	v_add_u32_e32 v4, s8, v40
	v_mad_i64_i32 v[4:5], s[6:7], v4, s40, v[20:21]
	s_waitcnt lgkmcnt(6)
	v_cvt_pk_bf16_f32 v0, v8, v6
	s_waitcnt lgkmcnt(4)
	v_cvt_pk_bf16_f32 v1, v10, v12
	s_waitcnt lgkmcnt(2)
	v_cvt_pk_bf16_f32 v2, v14, v16
	s_waitcnt lgkmcnt(0)
	v_cvt_pk_bf16_f32 v3, v18, v22
	global_store_dwordx4 v[4:5], v[0:3], off sc1
	v_add_u32_e32 v4, s8, v42
	v_mad_i64_i32 v[4:5], s[6:7], v4, s40, v[20:21]
	v_cvt_pk_bf16_f32 v0, v9, v7
	v_cvt_pk_bf16_f32 v1, v11, v13
	v_cvt_pk_bf16_f32 v2, v15, v17
	v_cvt_pk_bf16_f32 v3, v19, v23
	global_store_dwordx4 v[4:5], v[0:3], off sc1
	s_waitcnt lgkmcnt(0)

; __device__ __forceinline__ unsigned pk_bf16(float lo, float hi) { typedef __bf16 b2_t __attribute__((ext_vector_type(2))); f32x2 v = {lo, hi}; b2_t b = __builtin_convertvector(v, b2_t); return __builtin_bit_cast(unsigned, b); }
; #define LAS __attribute__((address_space(3)))
; __device__ __forceinline__ void transpose_tile(const float* W, const float* gain, int K, int N, int k0, int n0, bf16* WT, int drow0, LAS float* scr, int lane) {
;     f32x4 v[8]; float gv[8];
;     const int r0 = lane >> 3, c4 = lane & 7;
; #pragma unroll
;     for (int i = 0; i < 8; ++i) { v[i] = *(const f32x4*)(W + (size_t)(k0 + r0 + 8 * i) * N + n0 + 4 * c4); gv[i] = gain ? gain[k0 + r0 + 8 * i] : 1.0f; }
; #pragma unroll
;     for (int i = 0; i < 8; ++i) { LAS float* d = scr + (r0 + 8 * i) * 33 + 4 * c4; d[0] = v[i][0] * gv[i]; d[1] = v[i][1] * gv[i]; d[2] = v[i][2] * gv[i]; d[3] = v[i][3] * gv[i]; }
;     asm volatile("s_waitcnt lgkmcnt(0)" ::: "memory");
;     const int c = lane & 7;
; #pragma unroll
;     for (int j = 0; j < 4; ++j) { const int n = (lane >> 3) + 8 * j; const LAS float* s = scr + (8 * c) * 33 + n;
;         v4u o; o.x = pk_bf16(s[0 * 33], s[1 * 33]); o.y = pk_bf16(s[2 * 33], s[3 * 33]); o.z = pk_bf16(s[4 * 33], s[5 * 33]); o.w = pk_bf16(s[6 * 33], s[7 * 33]);
;         *(v4u*)(WT + (size_t)(drow0 + n) * K + k0 + 8 * c) = o; }
;     asm volatile("s_waitcnt lgkmcnt(0)" ::: "memory");
; }
; template <bool SWIGLU> __device__ __forceinline__ void transpose_item(const float* W, const float* gain, int K, int N, bf16* WT, LAS float* scr, int item, int lane) {
;     const int nblk = N / 32, kb = item / nblk, nb = item % nblk, n0 = 32 * nb;
;     int drow0 = n0;
;     if (SWIGLU) { const int up = n0 >= FF, f = up ? n0 - FF : n0; drow0 = 256 * (f >> 7) + (up ? 128 : 0) + (f & 127); }
.LBB0_1440:
	s_waitcnt vmcnt(0)
	v_pk_mul_f32 v[0:1], v[0:1], v[88:89] op_sel_hi:[1,0]
	v_add_u32_e32 v33, v35, v89
	ds_write2_b32 v33, v0, v1 offset1:1
	v_pk_mul_f32 v[0:1], v[2:3], v[88:89] op_sel_hi:[1,0]
	ds_write2_b32 v33, v0, v1 offset0:2 offset1:3
	v_pk_mul_f32 v[0:1], v[4:5], v[36:37] op_sel_hi:[1,0]
	v_add_u32_e32 v2, 0x420, v33
	ds_write2_b32 v2, v0, v1 offset1:1
	v_pk_mul_f32 v[0:1], v[6:7], v[36:37] op_sel_hi:[1,0]
	v_add_u32_e32 v2, 0x428, v33
	ds_write2_b32 v2, v0, v1 offset1:1
	v_pk_mul_f32 v[0:1], v[8:9], v[94:95] op_sel_hi:[1,0]
	v_add_u32_e32 v2, 0x840, v33
	ds_write2_b32 v2, v0, v1 offset1:1
	v_pk_mul_f32 v[0:1], v[10:11], v[94:95] op_sel_hi:[1,0]
	v_add_u32_e32 v2, 0x848, v33
	ds_write2_b32 v2, v0, v1 offset1:1
	v_pk_mul_f32 v[0:1], v[12:13], v[90:91] op_sel_hi:[1,0]
	v_add_u32_e32 v2, 0xc60, v33
	ds_write2_b32 v2, v0, v1 offset1:1
	v_pk_mul_f32 v[0:1], v[14:15], v[90:91] op_sel_hi:[1,0]
	v_add_u32_e32 v2, 0xc68, v33
	ds_write2_b32 v2, v0, v1 offset1:1
	v_pk_mul_f32 v[0:1], v[16:17], v[100:101] op_sel_hi:[1,0]
	v_add_u32_e32 v2, 0x1080, v33
	ds_write2_b32 v2, v0, v1 offset1:1
	v_pk_mul_f32 v[0:1], v[18:19], v[100:101] op_sel_hi:[1,0]
	v_add_u32_e32 v2, 0x1088, v33
	ds_write2_b32 v2, v0, v1 offset1:1
	v_pk_mul_f32 v[0:1], v[20:21], v[92:93] op_sel_hi:[1,0]
	v_add_u32_e32 v2, 0x14a0, v33
	ds_write2_b32 v2, v0, v1 offset1:1
	v_pk_mul_f32 v[0:1], v[22:23], v[92:93] op_sel_hi:[1,0]
	v_add_u32_e32 v2, 0x14a8, v33
	ds_write2_b32 v2, v0, v1 offset1:1
	v_pk_mul_f32 v[0:1], v[24:25], v[102:103] op_sel_hi:[1,0]
	v_add_u32_e32 v2, 0x18c0, v33
	s_mulk_i32 s6, 0xff50
	ds_write2_b32 v2, v0, v1 offset1:1
	v_pk_mul_f32 v[0:1], v[26:27], v[102:103] op_sel_hi:[1,0]
	v_add_u32_e32 v2, 0x18c8, v33
	s_add_i32 s6, s20, s6
	s_add_i32 s7, s14, 0xfffff500
	ds_write2_b32 v2, v0, v1 offset1:1
	v_pk_mul_f32 v[0:1], v[28:29], v[96:97] op_sel_hi:[1,0]
	v_add_u32_e32 v2, 0x1ce0, v33
	s_cmpk_gt_i32 s6, 0x57
	ds_write2_b32 v2, v0, v1 offset1:1
	v_pk_mul_f32 v[0:1], v[30:31], v[96:97] op_sel_hi:[1,0]
	v_add_u32_e32 v2, 0x1ce8, v33
	s_cselect_b32 s6, s7, s14
	ds_write2_b32 v2, v0, v1 offset1:1
	s_cselect_b32 s7, 0x80, 0
	s_lshl_b32 s8, s6, 1
	s_and_b32 s6, s6, 0x60
	s_waitcnt lgkmcnt(0)
	s_and_b32 s8, s8, 0xffffff00
	s_or_b32 s6, s6, s7
	ds_read2_b32 v[4:5], v93 offset0:33 offset1:41
	ds_read2_b32 v[6:7], v93 offset1:8
	ds_read2_b32 v[8:9], v93 offset0:66 offset1:74
	ds_read2_b32 v[10:11], v93 offset0:99 offset1:107
	ds_read2_b32 v[12:13], v93 offset0:132 offset1:140
	ds_read2_b32 v[14:15], v93 offset0:165 offset1:173
	ds_read2_b32 v[16:17], v93 offset0:198 offset1:206
	ds_read2_b32 v[18:19], v93 offset0:231 offset1:239
	s_or_b32 s6, s6, s8
	v_add_u32_e32 v22, s6, v32
	s_ashr_i32 s13, s12, 31
	v_ashrrev_i32_e32 v23, 31, v22
	v_lshl_add_u64 v[20:21], s[12:13], 1, v[86:87]
	v_lshlrev_b64 v[22:23], 11, v[22:23]
	s_waitcnt lgkmcnt(6)
	v_cvt_pk_bf16_f32 v0, v6, v4
	s_waitcnt lgkmcnt(4)
	v_cvt_pk_bf16_f32 v1, v8, v10
	s_waitcnt lgkmcnt(2)
	v_cvt_pk_bf16_f32 v2, v12, v14
	s_waitcnt lgkmcnt(0)
	v_cvt_pk_bf16_f32 v3, v16, v18
	v_lshl_add_u64 v[22:23], v[20:21], 0, v[22:23]
	v_add_u32_e32 v4, s6, v38
	global_store_dwordx4 v[22:23], v[0:3], off sc1
	s_nop 1
	v_cvt_pk_bf16_f32 v0, v7, v5
	v_ashrrev_i32_e32 v5, 31, v4
	v_cvt_pk_bf16_f32 v1, v9, v11
	v_cvt_pk_bf16_f32 v2, v13, v15
	v_cvt_pk_bf16_f32 v3, v17, v19
	v_lshlrev_b64 v[4:5], 11, v[4:5]
	ds_read2_b32 v[6:7], v93 offset0:49 offset1:57
	ds_read2_b32 v[8:9], v93 offset0:16 offset1:24
	ds_read2_b32 v[10:11], v93 offset0:82 offset1:90
	ds_read2_b32 v[12:13], v93 offset0:115 offset1:123
	ds_read2_b32 v[14:15], v93 offset0:148 offset1:156
	ds_read2_b32 v[16:17], v93 offset0:181 offset1:189
	ds_read2_b32 v[18:19], v93 offset0:214 offset1:222
	ds_read2_b32 v[22:23], v93 offset0:247 offset1:255
	v_lshl_add_u64 v[4:5], v[20:21], 0, v[4:5]
	global_store_dwordx4 v[4:5], v[0:3], off sc1
	v_add_u32_e32 v4, s6, v40
	v_ashrrev_i32_e32 v5, 31, v4
	v_lshlrev_b64 v[4:5], 11, v[4:5]
	s_waitcnt lgkmcnt(6)
	v_cvt_pk_bf16_f32 v0, v8, v6
	s_waitcnt lgkmcnt(4)
	v_cvt_pk_bf16_f32 v1, v10, v12
	s_waitcnt lgkmcnt(2)
	v_cvt_pk_bf16_f32 v2, v14, v16
	s_waitcnt lgkmcnt(0)
	v_cvt_pk_bf16_f32 v3, v18, v22
	v_lshl_add_u64 v[4:5], v[20:21], 0, v[4:5]
	global_store_dwordx4 v[4:5], v[0:3], off sc1
	v_add_u32_e32 v4, s6, v42
	v_ashrrev_i32_e32 v5, 31, v4
	v_lshlrev_b64 v[4:5], 11, v[4:5]
	v_cvt_pk_bf16_f32 v0, v9, v7
	v_cvt_pk_bf16_f32 v1, v11, v13
	v_cvt_pk_bf16_f32 v2, v15, v17
	v_cvt_pk_bf16_f32 v3, v19, v23
	v_lshl_add_u64 v[4:5], v[20:21], 0, v[4:5]
	global_store_dwordx4 v[4:5], v[0:3], off sc1
	s_waitcnt lgkmcnt(0)

; __device__ __forceinline__ unsigned pk_bf16(float lo, float hi) { typedef __bf16 b2_t __attribute__((ext_vector_type(2))); f32x2 v = {lo, hi}; b2_t b = __builtin_convertvector(v, b2_t); return __builtin_bit_cast(unsigned, b); }
; #define LAS __attribute__((address_space(3)))
; __device__ __forceinline__ void transpose_tile(const float* W, const float* gain, int K, int N, int k0, int n0, bf16* WT, int drow0, LAS float* scr, int lane) {
;     f32x4 v[8]; float gv[8];
;     const int r0 = lane >> 3, c4 = lane & 7;
; #pragma unroll
;     for (int i = 0; i < 8; ++i) { v[i] = *(const f32x4*)(W + (size_t)(k0 + r0 + 8 * i) * N + n0 + 4 * c4); gv[i] = gain ? gain[k0 + r0 + 8 * i] : 1.0f; }
; #pragma unroll
;     for (int i = 0; i < 8; ++i) { LAS float* d = scr + (r0 + 8 * i) * 33 + 4 * c4; d[0] = v[i][0] * gv[i]; d[1] = v[i][1] * gv[i]; d[2] = v[i][2] * gv[i]; d[3] = v[i][3] * gv[i]; }
;     asm volatile("s_waitcnt lgkmcnt(0)" ::: "memory");
;     const int c = lane & 7;
; #pragma unroll
;     for (int j = 0; j < 4; ++j) { const int n = (lane >> 3) + 8 * j; const LAS float* s = scr + (8 * c) * 33 + n;
;         v4u o; o.x = pk_bf16(s[0 * 33], s[1 * 33]); o.y = pk_bf16(s[2 * 33], s[3 * 33]); o.z = pk_bf16(s[4 * 33], s[5 * 33]); o.w = pk_bf16(s[6 * 33], s[7 * 33]);
;         *(v4u*)(WT + (size_t)(drow0 + n) * K + k0 + 8 * c) = o; }
;     asm volatile("s_waitcnt lgkmcnt(0)" ::: "memory");
; }
.LBB0_1442:
	s_cmpk_gt_i32 s20, 0xaff
	s_mov_b64 s[8:9], -1
	s_cbranch_scc0 .LBB0_1572
	s_cmpk_gt_u32 s20, 0x107f
	s_cbranch_scc0 .LBB0_1569
	s_cmpk_gt_u32 s20, 0x167f
	s_cbranch_scc0 .LBB0_1550
	s_cmpk_gt_u32 s20, 0x187f
	s_cbranch_scc0 .LBB0_1547
	s_cmpk_gt_u32 s20, 0x237f
	s_cbranch_scc0 .LBB0_1528
	s_cmpk_gt_u32 s20, 0x28ff
	s_cbranch_scc0 .LBB0_1525
	s_cmpk_gt_u32 s20, 0x33ff
	s_cbranch_scc0 .LBB0_1506
	s_cmpk_gt_u32 s20, 0x397f
	s_cbranch_scc0 .LBB0_1503
	s_cmpk_gt_u32 s20, 0x3d7f
	s_cbranch_scc0 .LBB0_1484
	s_cmpk_gt_u32 s20, 0x3f7f
	s_cbranch_scc0 .LBB0_1481
	s_cmpk_gt_u32 s20, 0x3f9f
	s_cbranch_scc0 .LBB0_1478
	s_cmpk_gt_u32 s20, 0x3fbf
	s_cbranch_scc0 .LBB0_1475
	s_cmpk_gt_u32 s20, 0x4abf
	s_cbranch_scc0 .LBB0_1456
	s_mov_b32 s6, 27
	s_ashr_i32 s7, s6, 31
	s_lshl_b64 s[6:7], s[6:7], 3
	s_add_u32 s6, s0, s6
	s_addc_u32 s7, s1, s7
	s_load_dwordx2 s[6:7], s[6:7], 0x0
	s_lshl_b32 s8, s20, 5
	s_and_b32 s8, s8, 0x3e0
	s_and_b32 s9, s22, 0x1ffc0
	s_lshl_b32 s10, s8, 2
	v_add_u32_e32 v0, s9, v32
	s_waitcnt lgkmcnt(0)
	s_add_u32 s6, s6, s10
	s_addc_u32 s7, s7, 0
	v_lshlrev_b32_e32 v36, 2, v34
	v_ashrrev_i32_e32 v1, 31, v0
	v_lshl_add_u64 v[2:3], s[6:7], 0, v[36:37]
	v_lshlrev_b64 v[0:1], 12, v[0:1]
	v_lshl_add_u64 v[28:29], v[2:3], 0, v[0:1]
	v_add_co_u32_e32 v4, vcc, s24, v28
	v_add_u32_e32 v33, v35, v89
	s_nop 0
	v_addc_co_u32_e32 v5, vcc, 0, v29, vcc
	v_add_co_u32_e32 v8, vcc, s25, v28
	global_load_dwordx4 v[0:3], v[28:29], off
	s_nop 0
	global_load_dwordx4 v[4:7], v[4:5], off
	v_addc_co_u32_e32 v9, vcc, 0, v29, vcc
	v_add_co_u32_e32 v12, vcc, s26, v28
	v_add_u32_e32 v36, 0x420, v33
	s_nop 0
	v_addc_co_u32_e32 v13, vcc, 0, v29, vcc
	v_add_co_u32_e32 v16, vcc, s27, v28
	global_load_dwordx4 v[8:11], v[8:9], off
	s_nop 0
	global_load_dwordx4 v[12:15], v[12:13], off
	v_addc_co_u32_e32 v17, vcc, 0, v29, vcc
	v_add_co_u32_e32 v20, vcc, s28, v28
	v_add_u32_e32 v39, 0x428, v33
	s_nop 0
	v_addc_co_u32_e32 v21, vcc, 0, v29, vcc
	global_load_dwordx4 v[16:19], v[16:17], off
	s_nop 0
	global_load_dwordx4 v[20:23], v[20:21], off
	v_add_co_u32_e32 v24, vcc, s29, v28
	v_add_u32_e32 v41, 0x840, v33
	s_nop 0
	v_addc_co_u32_e32 v25, vcc, 0, v29, vcc
	global_load_dwordx4 v[24:27], v[24:25], off
	v_add_co_u32_e32 v28, vcc, s30, v28
	v_add_u32_e32 v43, 0x848, v33
	s_nop 0
	v_addc_co_u32_e32 v29, vcc, 0, v29, vcc
	global_load_dwordx4 v[28:31], v[28:29], off
	v_add_u32_e32 v88, 0xc60, v33
	v_add_u32_e32 v92, 0xc68, v33
	v_add_u32_e32 v94, 0x1080, v33
	v_add_u32_e32 v95, 0x1088, v33
	v_add_u32_e32 v96, 0x14a0, v33
	v_add_u32_e32 v97, 0x14a8, v33
	v_add_u32_e32 v98, 0x18c0, v33
	v_add_u32_e32 v99, 0x18c8, v33
	v_add_u32_e32 v100, 0x1ce0, v33
	v_add_u32_e32 v101, 0x1ce8, v33
	s_lshl_b32 s10, s9, 1
	v_add_u32_e32 v102, s8, v32
	v_lshl_add_u64 v[90:91], v[44:45], 0, s[10:11]
	s_waitcnt vmcnt(0)
	ds_write2_b32 v33, v0, v1 offset1:1
	ds_write2_b32 v33, v2, v3 offset0:2 offset1:3
	ds_write2_b32 v36, v4, v5 offset1:1
	ds_write2_b32 v39, v6, v7 offset1:1
	ds_write2_b32 v41, v8, v9 offset1:1
	ds_write2_b32 v43, v10, v11 offset1:1
	ds_write2_b32 v88, v12, v13 offset1:1
	ds_write2_b32 v92, v14, v15 offset1:1
	ds_write2_b32 v94, v16, v17 offset1:1
	ds_write2_b32 v95, v18, v19 offset1:1
	ds_write2_b32 v96, v20, v21 offset1:1
	ds_write2_b32 v97, v22, v23 offset1:1
	ds_write2_b32 v98, v24, v25 offset1:1
	ds_write2_b32 v99, v26, v27 offset1:1
	ds_write2_b32 v100, v28, v29 offset1:1
	ds_write2_b32 v101, v30, v31 offset1:1
	s_waitcnt lgkmcnt(0)
	ds_read2_b32 v[4:5], v93 offset0:33 offset1:41
	ds_read2_b32 v[6:7], v93 offset1:8
	ds_read2_b32 v[8:9], v93 offset0:66 offset1:74
	ds_read2_b32 v[10:11], v93 offset0:99 offset1:107
	ds_read2_b32 v[12:13], v93 offset0:132 offset1:140
	ds_read2_b32 v[14:15], v93 offset0:165 offset1:173
	ds_read2_b32 v[16:17], v93 offset0:198 offset1:206
	ds_read2_b32 v[18:19], v93 offset0:231 offset1:239
	v_mad_i64_i32 v[20:21], s[6:7], v102, s31, v[90:91]
	s_waitcnt lgkmcnt(6)
	v_cvt_pk_bf16_f32 v0, v6, v4
	s_waitcnt lgkmcnt(4)
	v_cvt_pk_bf16_f32 v1, v8, v10
	s_waitcnt lgkmcnt(2)
	v_cvt_pk_bf16_f32 v2, v12, v14
	s_waitcnt lgkmcnt(0)
	v_cvt_pk_bf16_f32 v3, v16, v18
	global_store_dwordx4 v[20:21], v[0:3], off sc1
	v_add_u32_e32 v4, s8, v38
	s_nop 0
	v_cvt_pk_bf16_f32 v0, v7, v5
	v_cvt_pk_bf16_f32 v1, v9, v11
	v_cvt_pk_bf16_f32 v2, v13, v15
	v_cvt_pk_bf16_f32 v3, v17, v19
	ds_read2_b32 v[6:7], v93 offset0:49 offset1:57
	ds_read2_b32 v[8:9], v93 offset0:16 offset1:24
	ds_read2_b32 v[10:11], v93 offset0:82 offset1:90
	ds_read2_b32 v[12:13], v93 offset0:115 offset1:123
	ds_read2_b32 v[14:15], v93 offset0:148 offset1:156
	ds_read2_b32 v[16:17], v93 offset0:181 offset1:189
	ds_read2_b32 v[18:19], v93 offset0:214 offset1:222
	ds_read2_b32 v[20:21], v93 offset0:247 offset1:255
	v_mad_i64_i32 v[4:5], s[6:7], v4, s31, v[90:91]
	global_store_dwordx4 v[4:5], v[0:3], off sc1
	v_add_u32_e32 v4, s8, v40
	v_mad_i64_i32 v[4:5], s[6:7], v4, s31, v[90:91]
	s_waitcnt lgkmcnt(6)
	v_cvt_pk_bf16_f32 v0, v8, v6
	s_waitcnt lgkmcnt(4)
	v_cvt_pk_bf16_f32 v1, v10, v12
	s_waitcnt lgkmcnt(2)
	v_cvt_pk_bf16_f32 v2, v14, v16
	s_waitcnt lgkmcnt(0)
	v_cvt_pk_bf16_f32 v3, v18, v20
	global_store_dwordx4 v[4:5], v[0:3], off sc1
	v_add_u32_e32 v4, s8, v42
	v_mad_i64_i32 v[4:5], s[6:7], v4, s31, v[90:91]
	v_cvt_pk_bf16_f32 v0, v9, v7
	v_cvt_pk_bf16_f32 v1, v11, v13
	v_cvt_pk_bf16_f32 v2, v15, v17
	v_cvt_pk_bf16_f32 v3, v19, v21
	global_store_dwordx4 v[4:5], v[0:3], off sc1
	s_waitcnt lgkmcnt(0)
	s_mov_b64 s[8:9], 0

; __device__ __forceinline__ unsigned pk_bf16(float lo, float hi) { typedef __bf16 b2_t __attribute__((ext_vector_type(2))); f32x2 v = {lo, hi}; b2_t b = __builtin_convertvector(v, b2_t); return __builtin_bit_cast(unsigned, b); }
; #define LAS __attribute__((address_space(3)))
; __device__ __forceinline__ void transpose_tile(const float* W, const float* gain, int K, int N, int k0, int n0, bf16* WT, int drow0, LAS float* scr, int lane) {
;     f32x4 v[8]; float gv[8];
;     const int r0 = lane >> 3, c4 = lane & 7;
; #pragma unroll
;     for (int i = 0; i < 8; ++i) { v[i] = *(const f32x4*)(W + (size_t)(k0 + r0 + 8 * i) * N + n0 + 4 * c4); gv[i] = gain ? gain[k0 + r0 + 8 * i] : 1.0f; }
; #pragma unroll
;     for (int i = 0; i < 8; ++i) { LAS float* d = scr + (r0 + 8 * i) * 33 + 4 * c4; d[0] = v[i][0] * gv[i]; d[1] = v[i][1] * gv[i]; d[2] = v[i][2] * gv[i]; d[3] = v[i][3] * gv[i]; }
;     asm volatile("s_waitcnt lgkmcnt(0)" ::: "memory");
;     const int c = lane & 7;
; #pragma unroll
;     for (int j = 0; j < 4; ++j) { const int n = (lane >> 3) + 8 * j; const LAS float* s = scr + (8 * c) * 33 + n;
;         v4u o; o.x = pk_bf16(s[0 * 33], s[1 * 33]); o.y = pk_bf16(s[2 * 33], s[3 * 33]); o.z = pk_bf16(s[4 * 33], s[5 * 33]); o.w = pk_bf16(s[6 * 33], s[7 * 33]);
;         *(v4u*)(WT + (size_t)(drow0 + n) * K + k0 + 8 * c) = o; }
;     asm volatile("s_waitcnt lgkmcnt(0)" ::: "memory");
; }
; template <bool SWIGLU> __device__ __forceinline__ void transpose_item(const float* W, const float* gain, int K, int N, bf16* WT, LAS float* scr, int item, int lane) {
;     const int nblk = N / 32, kb = item / nblk, nb = item % nblk, n0 = 32 * nb;
;     int drow0 = n0;
;     if (SWIGLU) { const int up = n0 >= FF, f = up ? n0 - FF : n0; drow0 = 256 * (f >> 7) + (up ? 128 : 0) + (f & 127); }
.LBB0_1473:
	s_waitcnt vmcnt(0)
	v_pk_mul_f32 v[0:1], v[0:1], v[88:89] op_sel_hi:[1,0]
	v_add_u32_e32 v33, v35, v89
	ds_write2_b32 v33, v0, v1 offset1:1
	v_pk_mul_f32 v[0:1], v[2:3], v[88:89] op_sel_hi:[1,0]
	ds_write2_b32 v33, v0, v1 offset0:2 offset1:3
	v_pk_mul_f32 v[0:1], v[4:5], v[36:37] op_sel_hi:[1,0]
	v_add_u32_e32 v2, 0x420, v33
	ds_write2_b32 v2, v0, v1 offset1:1
	v_pk_mul_f32 v[0:1], v[6:7], v[36:37] op_sel_hi:[1,0]
	v_add_u32_e32 v2, 0x428, v33
	ds_write2_b32 v2, v0, v1 offset1:1
	v_pk_mul_f32 v[0:1], v[8:9], v[94:95] op_sel_hi:[1,0]
	v_add_u32_e32 v2, 0x840, v33
	ds_write2_b32 v2, v0, v1 offset1:1
	v_pk_mul_f32 v[0:1], v[10:11], v[94:95] op_sel_hi:[1,0]
	v_add_u32_e32 v2, 0x848, v33
	ds_write2_b32 v2, v0, v1 offset1:1
	v_pk_mul_f32 v[0:1], v[12:13], v[90:91] op_sel_hi:[1,0]
	v_add_u32_e32 v2, 0xc60, v33
	ds_write2_b32 v2, v0, v1 offset1:1
	v_pk_mul_f32 v[0:1], v[14:15], v[90:91] op_sel_hi:[1,0]
	v_add_u32_e32 v2, 0xc68, v33
	ds_write2_b32 v2, v0, v1 offset1:1
	v_pk_mul_f32 v[0:1], v[16:17], v[100:101] op_sel_hi:[1,0]
	v_add_u32_e32 v2, 0x1080, v33
	ds_write2_b32 v2, v0, v1 offset1:1
	v_pk_mul_f32 v[0:1], v[18:19], v[100:101] op_sel_hi:[1,0]
	v_add_u32_e32 v2, 0x1088, v33
	ds_write2_b32 v2, v0, v1 offset1:1
	v_pk_mul_f32 v[0:1], v[20:21], v[92:93] op_sel_hi:[1,0]
	v_add_u32_e32 v2, 0x14a0, v33
	ds_write2_b32 v2, v0, v1 offset1:1
	v_pk_mul_f32 v[0:1], v[22:23], v[92:93] op_sel_hi:[1,0]
	v_add_u32_e32 v2, 0x14a8, v33
	ds_write2_b32 v2, v0, v1 offset1:1
	v_pk_mul_f32 v[0:1], v[24:25], v[102:103] op_sel_hi:[1,0]
	v_add_u32_e32 v2, 0x18c0, v33
	s_and_b32 s8, 0xffff, s8
	ds_write2_b32 v2, v0, v1 offset1:1
	v_pk_mul_f32 v[0:1], v[26:27], v[102:103] op_sel_hi:[1,0]
	v_add_u32_e32 v2, 0x18c8, v33
	s_and_b32 s7, 0xffff, s7
	s_add_i32 s9, s8, 0xfffff500
	ds_write2_b32 v2, v0, v1 offset1:1
	v_pk_mul_f32 v[0:1], v[28:29], v[96:97] op_sel_hi:[1,0]
	v_add_u32_e32 v2, 0x1ce0, v33
	s_cmpk_gt_u32 s7, 0x57
	ds_write2_b32 v2, v0, v1 offset1:1
	v_pk_mul_f32 v[0:1], v[30:31], v[96:97] op_sel_hi:[1,0]
	v_add_u32_e32 v2, 0x1ce8, v33
	s_cselect_b32 s7, s9, s8
	ds_write2_b32 v2, v0, v1 offset1:1
	s_cselect_b32 s8, 0x80, 0
	s_lshl_b32 s9, s7, 1
	s_and_b32 s7, s7, 0x60
	s_waitcnt lgkmcnt(0)
	s_and_b32 s9, s9, 0xffffff00
	s_or_b32 s7, s7, s8
	ds_read2_b32 v[4:5], v93 offset0:33 offset1:41
	ds_read2_b32 v[6:7], v93 offset1:8
	ds_read2_b32 v[8:9], v93 offset0:66 offset1:74
	ds_read2_b32 v[10:11], v93 offset0:99 offset1:107
	ds_read2_b32 v[12:13], v93 offset0:132 offset1:140
	ds_read2_b32 v[14:15], v93 offset0:165 offset1:173
	ds_read2_b32 v[16:17], v93 offset0:198 offset1:206
	ds_read2_b32 v[18:19], v93 offset0:231 offset1:239
	s_or_b32 s7, s7, s9
	s_and_b32 s6, 0xffff, s6
	v_add_u32_e32 v22, s7, v32
	s_lshl_b32 s10, s6, 1
	v_ashrrev_i32_e32 v23, 31, v22
	v_lshl_add_u64 v[20:21], v[46:47], 0, s[10:11]
	v_lshlrev_b64 v[22:23], 11, v[22:23]
	s_waitcnt lgkmcnt(6)
	v_cvt_pk_bf16_f32 v0, v6, v4
	s_waitcnt lgkmcnt(4)
	v_cvt_pk_bf16_f32 v1, v8, v10
	s_waitcnt lgkmcnt(2)
	v_cvt_pk_bf16_f32 v2, v12, v14
	s_waitcnt lgkmcnt(0)
	v_cvt_pk_bf16_f32 v3, v16, v18
	v_lshl_add_u64 v[22:23], v[20:21], 0, v[22:23]
	v_add_u32_e32 v4, s7, v38
	global_store_dwordx4 v[22:23], v[0:3], off sc1
	s_nop 1
	v_cvt_pk_bf16_f32 v0, v7, v5
	v_ashrrev_i32_e32 v5, 31, v4
	v_cvt_pk_bf16_f32 v1, v9, v11
	v_cvt_pk_bf16_f32 v2, v13, v15
	v_cvt_pk_bf16_f32 v3, v17, v19
	v_lshlrev_b64 v[4:5], 11, v[4:5]
	ds_read2_b32 v[6:7], v93 offset0:49 offset1:57
	ds_read2_b32 v[8:9], v93 offset0:16 offset1:24
	ds_read2_b32 v[10:11], v93 offset0:82 offset1:90
	ds_read2_b32 v[12:13], v93 offset0:115 offset1:123
	ds_read2_b32 v[14:15], v93 offset0:148 offset1:156
	ds_read2_b32 v[16:17], v93 offset0:181 offset1:189
	ds_read2_b32 v[18:19], v93 offset0:214 offset1:222
	ds_read2_b32 v[22:23], v93 offset0:247 offset1:255
	v_lshl_add_u64 v[4:5], v[20:21], 0, v[4:5]
	global_store_dwordx4 v[4:5], v[0:3], off sc1
	v_add_u32_e32 v4, s7, v40
	v_ashrrev_i32_e32 v5, 31, v4
	v_lshlrev_b64 v[4:5], 11, v[4:5]
	s_waitcnt lgkmcnt(6)
	v_cvt_pk_bf16_f32 v0, v8, v6
	s_waitcnt lgkmcnt(4)
	v_cvt_pk_bf16_f32 v1, v10, v12
	s_waitcnt lgkmcnt(2)
	v_cvt_pk_bf16_f32 v2, v14, v16
	s_waitcnt lgkmcnt(0)
	v_cvt_pk_bf16_f32 v3, v18, v22
	v_lshl_add_u64 v[4:5], v[20:21], 0, v[4:5]
	global_store_dwordx4 v[4:5], v[0:3], off sc1
	v_add_u32_e32 v4, s7, v42
	v_ashrrev_i32_e32 v5, 31, v4
	v_lshlrev_b64 v[4:5], 11, v[4:5]
	v_cvt_pk_bf16_f32 v0, v9, v7
	v_cvt_pk_bf16_f32 v1, v11, v13
	v_cvt_pk_bf16_f32 v2, v15, v17
	v_cvt_pk_bf16_f32 v3, v19, v23
	v_lshl_add_u64 v[4:5], v[20:21], 0, v[4:5]
	global_store_dwordx4 v[4:5], v[0:3], off sc1
	s_waitcnt lgkmcnt(0)

; __device__ __forceinline__ unsigned pk_bf16(float lo, float hi) { typedef __bf16 b2_t __attribute__((ext_vector_type(2))); f32x2 v = {lo, hi}; b2_t b = __builtin_convertvector(v, b2_t); return __builtin_bit_cast(unsigned, b); }
; #define LAS __attribute__((address_space(3)))
; __device__ __forceinline__ void transpose_tile(const float* W, const float* gain, int K, int N, int k0, int n0, bf16* WT, int drow0, LAS float* scr, int lane) {
;     f32x4 v[8]; float gv[8];
;     const int r0 = lane >> 3, c4 = lane & 7;
; #pragma unroll
;     for (int i = 0; i < 8; ++i) { v[i] = *(const f32x4*)(W + (size_t)(k0 + r0 + 8 * i) * N + n0 + 4 * c4); gv[i] = gain ? gain[k0 + r0 + 8 * i] : 1.0f; }
; #pragma unroll
;     for (int i = 0; i < 8; ++i) { LAS float* d = scr + (r0 + 8 * i) * 33 + 4 * c4; d[0] = v[i][0] * gv[i]; d[1] = v[i][1] * gv[i]; d[2] = v[i][2] * gv[i]; d[3] = v[i][3] * gv[i]; }
;     asm volatile("s_waitcnt lgkmcnt(0)" ::: "memory");
;     const int c = lane & 7;
; #pragma unroll
;     for (int j = 0; j < 4; ++j) { const int n = (lane >> 3) + 8 * j; const LAS float* s = scr + (8 * c) * 33 + n;
;         v4u o; o.x = pk_bf16(s[0 * 33], s[1 * 33]); o.y = pk_bf16(s[2 * 33], s[3 * 33]); o.z = pk_bf16(s[4 * 33], s[5 * 33]); o.w = pk_bf16(s[6 * 33], s[7 * 33]);
;         *(v4u*)(WT + (size_t)(drow0 + n) * K + k0 + 8 * c) = o; }
;     asm volatile("s_waitcnt lgkmcnt(0)" ::: "memory");
; }
.LBB0_1475:
	s_andn2_b64 vcc, exec, s[8:9]
	s_cbranch_vccnz .LBB0_1477
	s_mov_b32 s6, 21
	s_ashr_i32 s7, s6, 31
	s_add_i32 s8, s20, 0xffffc060
	s_lshl_b64 s[6:7], s[6:7], 3
	s_add_u32 s6, s0, s6
	s_addc_u32 s7, s1, s7
	s_load_dwordx2 s[6:7], s[6:7], 0x0
	s_lshr_b32 s10, s8, 1
	s_lshl_b64 s[8:9], s[10:11], 14
	v_lshlrev_b32_e32 v36, 2, v34
	v_add_u32_e32 v33, v35, v89
	s_waitcnt lgkmcnt(0)
	s_add_u32 s6, s6, s8
	s_addc_u32 s7, s7, s9
	s_lshl_b32 s8, s20, 5
	s_and_b32 s8, s8, 32
	s_lshl_b32 s9, s8, 2
	s_add_u32 s6, s6, s9
	s_addc_u32 s7, s7, 0
	v_lshl_add_u64 v[28:29], s[6:7], 0, v[36:37]
	v_lshl_add_u64 v[0:1], v[28:29], 0, v[48:49]
	global_load_dwordx4 v[0:3], v[0:1], off
	v_lshl_add_u64 v[4:5], v[28:29], 0, v[50:51]
	global_load_dwordx4 v[4:7], v[4:5], off
	v_lshl_add_u64 v[8:9], v[28:29], 0, v[52:53]
	global_load_dwordx4 v[8:11], v[8:9], off
	v_lshl_add_u64 v[12:13], v[28:29], 0, v[54:55]
	global_load_dwordx4 v[12:15], v[12:13], off
	v_lshl_add_u64 v[16:17], v[28:29], 0, v[56:57]
	global_load_dwordx4 v[16:19], v[16:17], off
	v_lshl_add_u64 v[20:21], v[28:29], 0, v[58:59]
	global_load_dwordx4 v[20:23], v[20:21], off
	v_lshl_add_u64 v[24:25], v[28:29], 0, v[60:61]
	global_load_dwordx4 v[24:27], v[24:25], off
	v_lshl_add_u64 v[28:29], v[28:29], 0, v[62:63]
	global_load_dwordx4 v[28:31], v[28:29], off
	v_add_u32_e32 v36, 0x420, v33
	v_add_u32_e32 v39, 0x428, v33
	v_add_u32_e32 v41, 0x840, v33
	v_add_u32_e32 v43, 0x848, v33
	v_add_u32_e32 v88, 0xc60, v33
	v_add_u32_e32 v92, 0xc68, v33
	v_add_u32_e32 v97, 0x1080, v33
	v_add_u32_e32 v100, 0x1088, v33
	v_add_u32_e32 v101, 0x14a0, v33
	v_add_u32_e32 v102, 0x14a8, v33
	v_add_u32_e32 v103, 0x18c0, v33
	v_add_u32_e32 v104, 0x18c8, v33
	v_add_u32_e32 v105, 0x1ce0, v33
	v_add_u32_e32 v106, 0x1ce8, v33
	v_add_u32_e32 v90, s8, v32
	v_add_u32_e32 v94, s8, v38
	v_ashrrev_i32_e32 v91, 31, v90
	s_lshl_b64 s[6:7], s[10:11], 13
	v_ashrrev_i32_e32 v95, 31, v94
	v_lshlrev_b64 v[90:91], 7, v[90:91]
	v_lshl_add_u64 v[98:99], v[64:65], 0, s[6:7]
	v_add_u32_e32 v96, s8, v40
	v_lshlrev_b64 v[94:95], 7, v[94:95]
	v_lshl_add_u64 v[90:91], v[98:99], 0, v[90:91]
	v_lshl_add_u64 v[94:95], v[98:99], 0, v[94:95]
	s_waitcnt vmcnt(0)
	ds_write2_b32 v33, v0, v1 offset1:1
	ds_write2_b32 v33, v2, v3 offset0:2 offset1:3
	ds_write2_b32 v36, v4, v5 offset1:1
	ds_write2_b32 v39, v6, v7 offset1:1
	ds_write2_b32 v41, v8, v9 offset1:1
	ds_write2_b32 v43, v10, v11 offset1:1
	ds_write2_b32 v88, v12, v13 offset1:1
	ds_write2_b32 v92, v14, v15 offset1:1
	ds_write2_b32 v97, v16, v17 offset1:1
	ds_write2_b32 v100, v18, v19 offset1:1
	ds_write2_b32 v101, v20, v21 offset1:1
	ds_write2_b32 v102, v22, v23 offset1:1
	ds_write2_b32 v103, v24, v25 offset1:1
	ds_write2_b32 v104, v26, v27 offset1:1
	ds_write2_b32 v105, v28, v29 offset1:1
	ds_write2_b32 v106, v30, v31 offset1:1
	s_waitcnt lgkmcnt(0)
	ds_read2_b32 v[4:5], v93 offset0:33 offset1:41
	ds_read2_b32 v[6:7], v93 offset1:8
	ds_read2_b32 v[8:9], v93 offset0:66 offset1:74
	ds_read2_b32 v[10:11], v93 offset0:99 offset1:107
	ds_read2_b32 v[12:13], v93 offset0:132 offset1:140
	ds_read2_b32 v[14:15], v93 offset0:165 offset1:173
	ds_read2_b32 v[16:17], v93 offset0:198 offset1:206
	ds_read2_b32 v[18:19], v93 offset0:231 offset1:239
	ds_read2_b32 v[20:21], v93 offset0:49 offset1:57
	ds_read2_b32 v[22:23], v93 offset0:16 offset1:24
	ds_read2_b32 v[24:25], v93 offset0:82 offset1:90
	ds_read2_b32 v[26:27], v93 offset0:115 offset1:123
	ds_read2_b32 v[28:29], v93 offset0:148 offset1:156
	ds_read2_b32 v[30:31], v93 offset0:181 offset1:189
	ds_read2_b32 v[100:101], v93 offset0:214 offset1:222
	ds_read2_b32 v[102:103], v93 offset0:247 offset1:255
	s_waitcnt lgkmcnt(14)
	v_cvt_pk_bf16_f32 v0, v6, v4
	s_waitcnt lgkmcnt(12)
	v_cvt_pk_bf16_f32 v1, v8, v10
	s_waitcnt lgkmcnt(10)
	v_cvt_pk_bf16_f32 v2, v12, v14
	s_waitcnt lgkmcnt(8)
	v_cvt_pk_bf16_f32 v3, v16, v18
	v_cvt_pk_bf16_f32 v4, v7, v5
	v_cvt_pk_bf16_f32 v5, v9, v11
	v_cvt_pk_bf16_f32 v6, v13, v15
	v_cvt_pk_bf16_f32 v7, v17, v19
	global_store_dwordx4 v[90:91], v[0:3], off sc1
	global_store_dwordx4 v[94:95], v[4:7], off sc1
	v_ashrrev_i32_e32 v97, 31, v96
	v_lshlrev_b64 v[0:1], 7, v[96:97]
	v_add_u32_e32 v4, s8, v42
	v_ashrrev_i32_e32 v5, 31, v4
	s_waitcnt lgkmcnt(6)
	v_cvt_pk_bf16_f32 v8, v22, v20
	s_waitcnt lgkmcnt(4)
	v_cvt_pk_bf16_f32 v9, v24, v26
	s_waitcnt lgkmcnt(2)
	v_cvt_pk_bf16_f32 v10, v28, v30
	s_waitcnt lgkmcnt(0)
	v_cvt_pk_bf16_f32 v11, v100, v102
	v_lshl_add_u64 v[0:1], v[98:99], 0, v[0:1]
	v_lshlrev_b64 v[4:5], 7, v[4:5]
	global_store_dwordx4 v[0:1], v[8:11], off sc1
	v_cvt_pk_bf16_f32 v0, v23, v21
	v_cvt_pk_bf16_f32 v1, v25, v27
	v_cvt_pk_bf16_f32 v2, v29, v31
	v_cvt_pk_bf16_f32 v3, v101, v103
	v_lshl_add_u64 v[4:5], v[98:99], 0, v[4:5]
	global_store_dwordx4 v[4:5], v[0:3], off sc1
	s_waitcnt lgkmcnt(0)

; __device__ __forceinline__ unsigned pk_bf16(float lo, float hi) { typedef __bf16 b2_t __attribute__((ext_vector_type(2))); f32x2 v = {lo, hi}; b2_t b = __builtin_convertvector(v, b2_t); return __builtin_bit_cast(unsigned, b); }
; #define LAS __attribute__((address_space(3)))
; __device__ __forceinline__ void transpose_tile(const float* W, const float* gain, int K, int N, int k0, int n0, bf16* WT, int drow0, LAS float* scr, int lane) {
;     f32x4 v[8]; float gv[8];
;     const int r0 = lane >> 3, c4 = lane & 7;
; #pragma unroll
;     for (int i = 0; i < 8; ++i) { v[i] = *(const f32x4*)(W + (size_t)(k0 + r0 + 8 * i) * N + n0 + 4 * c4); gv[i] = gain ? gain[k0 + r0 + 8 * i] : 1.0f; }
; #pragma unroll
;     for (int i = 0; i < 8; ++i) { LAS float* d = scr + (r0 + 8 * i) * 33 + 4 * c4; d[0] = v[i][0] * gv[i]; d[1] = v[i][1] * gv[i]; d[2] = v[i][2] * gv[i]; d[3] = v[i][3] * gv[i]; }
;     asm volatile("s_waitcnt lgkmcnt(0)" ::: "memory");
;     const int c = lane & 7;
; #pragma unroll
;     for (int j = 0; j < 4; ++j) { const int n = (lane >> 3) + 8 * j; const LAS float* s = scr + (8 * c) * 33 + n;
;         v4u o; o.x = pk_bf16(s[0 * 33], s[1 * 33]); o.y = pk_bf16(s[2 * 33], s[3 * 33]); o.z = pk_bf16(s[4 * 33], s[5 * 33]); o.w = pk_bf16(s[6 * 33], s[7 * 33]);
;         *(v4u*)(WT + (size_t)(drow0 + n) * K + k0 + 8 * c) = o; }
;     asm volatile("s_waitcnt lgkmcnt(0)" ::: "memory");
; }
.LBB0_1478:
	s_andn2_b64 vcc, exec, s[8:9]
	s_cbranch_vccnz .LBB0_1480
	s_mov_b32 s6, 19
	s_ashr_i32 s7, s6, 31
	s_add_i32 s8, s20, 0xffffc080
	s_lshl_b64 s[6:7], s[6:7], 3
	s_add_u32 s6, s0, s6
	s_addc_u32 s7, s1, s7
	s_load_dwordx2 s[6:7], s[6:7], 0x0
	s_lshr_b32 s10, s8, 1
	s_lshl_b64 s[8:9], s[10:11], 14
	v_lshlrev_b32_e32 v36, 2, v34
	v_add_u32_e32 v33, v35, v89
	s_waitcnt lgkmcnt(0)
	s_add_u32 s6, s6, s8
	s_addc_u32 s7, s7, s9
	s_lshl_b32 s8, s20, 5
	s_and_b32 s8, s8, 32
	s_lshl_b32 s9, s8, 2
	s_add_u32 s6, s6, s9
	s_addc_u32 s7, s7, 0
	v_lshl_add_u64 v[28:29], s[6:7], 0, v[36:37]
	v_lshl_add_u64 v[0:1], v[28:29], 0, v[48:49]
	global_load_dwordx4 v[0:3], v[0:1], off
	v_lshl_add_u64 v[4:5], v[28:29], 0, v[50:51]
	global_load_dwordx4 v[4:7], v[4:5], off
	v_lshl_add_u64 v[8:9], v[28:29], 0, v[52:53]
	global_load_dwordx4 v[8:11], v[8:9], off
	v_lshl_add_u64 v[12:13], v[28:29], 0, v[54:55]
	global_load_dwordx4 v[12:15], v[12:13], off
	v_lshl_add_u64 v[16:17], v[28:29], 0, v[56:57]
	global_load_dwordx4 v[16:19], v[16:17], off
	v_lshl_add_u64 v[20:21], v[28:29], 0, v[58:59]
	global_load_dwordx4 v[20:23], v[20:21], off
	v_lshl_add_u64 v[24:25], v[28:29], 0, v[60:61]
	global_load_dwordx4 v[24:27], v[24:25], off
	v_lshl_add_u64 v[28:29], v[28:29], 0, v[62:63]
	global_load_dwordx4 v[28:31], v[28:29], off
	v_add_u32_e32 v36, 0x420, v33
	v_add_u32_e32 v39, 0x428, v33
	v_add_u32_e32 v41, 0x840, v33
	v_add_u32_e32 v43, 0x848, v33
	v_add_u32_e32 v88, 0xc60, v33
	v_add_u32_e32 v92, 0xc68, v33
	v_add_u32_e32 v97, 0x1080, v33
	v_add_u32_e32 v100, 0x1088, v33
	v_add_u32_e32 v101, 0x14a0, v33
	v_add_u32_e32 v102, 0x14a8, v33
	v_add_u32_e32 v103, 0x18c0, v33
	v_add_u32_e32 v104, 0x18c8, v33
	v_add_u32_e32 v105, 0x1ce0, v33
	v_add_u32_e32 v106, 0x1ce8, v33
	v_add_u32_e32 v90, s8, v32
	v_add_u32_e32 v94, s8, v38
	v_ashrrev_i32_e32 v91, 31, v90
	s_lshl_b64 s[6:7], s[10:11], 13
	v_ashrrev_i32_e32 v95, 31, v94
	v_lshlrev_b64 v[90:91], 7, v[90:91]
	v_lshl_add_u64 v[98:99], v[66:67], 0, s[6:7]
	v_add_u32_e32 v96, s8, v40
	v_lshlrev_b64 v[94:95], 7, v[94:95]
	v_lshl_add_u64 v[90:91], v[98:99], 0, v[90:91]
	v_lshl_add_u64 v[94:95], v[98:99], 0, v[94:95]
	s_waitcnt vmcnt(0)
	ds_write2_b32 v33, v0, v1 offset1:1
	ds_write2_b32 v33, v2, v3 offset0:2 offset1:3
	ds_write2_b32 v36, v4, v5 offset1:1
	ds_write2_b32 v39, v6, v7 offset1:1
	ds_write2_b32 v41, v8, v9 offset1:1
	ds_write2_b32 v43, v10, v11 offset1:1
	ds_write2_b32 v88, v12, v13 offset1:1
	ds_write2_b32 v92, v14, v15 offset1:1
	ds_write2_b32 v97, v16, v17 offset1:1
	ds_write2_b32 v100, v18, v19 offset1:1
	ds_write2_b32 v101, v20, v21 offset1:1
	ds_write2_b32 v102, v22, v23 offset1:1
	ds_write2_b32 v103, v24, v25 offset1:1
	ds_write2_b32 v104, v26, v27 offset1:1
	ds_write2_b32 v105, v28, v29 offset1:1
	ds_write2_b32 v106, v30, v31 offset1:1
	s_waitcnt lgkmcnt(0)
	ds_read2_b32 v[4:5], v93 offset0:33 offset1:41
	ds_read2_b32 v[6:7], v93 offset1:8
	ds_read2_b32 v[8:9], v93 offset0:66 offset1:74
	ds_read2_b32 v[10:11], v93 offset0:99 offset1:107
	ds_read2_b32 v[12:13], v93 offset0:132 offset1:140
	ds_read2_b32 v[14:15], v93 offset0:165 offset1:173
	ds_read2_b32 v[16:17], v93 offset0:198 offset1:206
	ds_read2_b32 v[18:19], v93 offset0:231 offset1:239
	ds_read2_b32 v[20:21], v93 offset0:49 offset1:57
	ds_read2_b32 v[22:23], v93 offset0:16 offset1:24
	ds_read2_b32 v[24:25], v93 offset0:82 offset1:90
	ds_read2_b32 v[26:27], v93 offset0:115 offset1:123
	ds_read2_b32 v[28:29], v93 offset0:148 offset1:156
	ds_read2_b32 v[30:31], v93 offset0:181 offset1:189
	ds_read2_b32 v[100:101], v93 offset0:214 offset1:222
	ds_read2_b32 v[102:103], v93 offset0:247 offset1:255
	s_waitcnt lgkmcnt(14)
	v_cvt_pk_bf16_f32 v0, v6, v4
	s_waitcnt lgkmcnt(12)
	v_cvt_pk_bf16_f32 v1, v8, v10
	s_waitcnt lgkmcnt(10)
	v_cvt_pk_bf16_f32 v2, v12, v14
	s_waitcnt lgkmcnt(8)
	v_cvt_pk_bf16_f32 v3, v16, v18
	v_cvt_pk_bf16_f32 v4, v7, v5
	v_cvt_pk_bf16_f32 v5, v9, v11
	v_cvt_pk_bf16_f32 v6, v13, v15
	v_cvt_pk_bf16_f32 v7, v17, v19
	global_store_dwordx4 v[90:91], v[0:3], off sc1
	global_store_dwordx4 v[94:95], v[4:7], off sc1
	v_ashrrev_i32_e32 v97, 31, v96
	v_lshlrev_b64 v[0:1], 7, v[96:97]
	v_add_u32_e32 v4, s8, v42
	v_ashrrev_i32_e32 v5, 31, v4
	s_waitcnt lgkmcnt(6)
	v_cvt_pk_bf16_f32 v8, v22, v20
	s_waitcnt lgkmcnt(4)
	v_cvt_pk_bf16_f32 v9, v24, v26
	s_waitcnt lgkmcnt(2)
	v_cvt_pk_bf16_f32 v10, v28, v30
	s_waitcnt lgkmcnt(0)
	v_cvt_pk_bf16_f32 v11, v100, v102
	v_lshl_add_u64 v[0:1], v[98:99], 0, v[0:1]
	v_lshlrev_b64 v[4:5], 7, v[4:5]
	global_store_dwordx4 v[0:1], v[8:11], off sc1
	v_cvt_pk_bf16_f32 v0, v23, v21
	v_cvt_pk_bf16_f32 v1, v25, v27
	v_cvt_pk_bf16_f32 v2, v29, v31
	v_cvt_pk_bf16_f32 v3, v101, v103
	v_lshl_add_u64 v[4:5], v[98:99], 0, v[4:5]
	global_store_dwordx4 v[4:5], v[0:3], off sc1
	s_waitcnt lgkmcnt(0)

; __device__ __forceinline__ unsigned pk_bf16(float lo, float hi) { typedef __bf16 b2_t __attribute__((ext_vector_type(2))); f32x2 v = {lo, hi}; b2_t b = __builtin_convertvector(v, b2_t); return __builtin_bit_cast(unsigned, b); }
; #define LAS __attribute__((address_space(3)))
; __device__ __forceinline__ void transpose_tile(const float* W, const float* gain, int K, int N, int k0, int n0, bf16* WT, int drow0, LAS float* scr, int lane) {
;     f32x4 v[8]; float gv[8];
;     const int r0 = lane >> 3, c4 = lane & 7;
; #pragma unroll
;     for (int i = 0; i < 8; ++i) { v[i] = *(const f32x4*)(W + (size_t)(k0 + r0 + 8 * i) * N + n0 + 4 * c4); gv[i] = gain ? gain[k0 + r0 + 8 * i] : 1.0f; }
; #pragma unroll
;     for (int i = 0; i < 8; ++i) { LAS float* d = scr + (r0 + 8 * i) * 33 + 4 * c4; d[0] = v[i][0] * gv[i]; d[1] = v[i][1] * gv[i]; d[2] = v[i][2] * gv[i]; d[3] = v[i][3] * gv[i]; }
;     asm volatile("s_waitcnt lgkmcnt(0)" ::: "memory");
;     const int c = lane & 7;
; #pragma unroll
;     for (int j = 0; j < 4; ++j) { const int n = (lane >> 3) + 8 * j; const LAS float* s = scr + (8 * c) * 33 + n;
;         v4u o; o.x = pk_bf16(s[0 * 33], s[1 * 33]); o.y = pk_bf16(s[2 * 33], s[3 * 33]); o.z = pk_bf16(s[4 * 33], s[5 * 33]); o.w = pk_bf16(s[6 * 33], s[7 * 33]);
;         *(v4u*)(WT + (size_t)(drow0 + n) * K + k0 + 8 * c) = o; }
;     asm volatile("s_waitcnt lgkmcnt(0)" ::: "memory");
; }
.LBB0_1481:
	s_andn2_b64 vcc, exec, s[8:9]
	s_cbranch_vccnz .LBB0_1483
	s_mov_b32 s6, 24
	s_ashr_i32 s7, s6, 31
	s_lshl_b64 s[6:7], s[6:7], 3
	s_add_u32 s6, s0, s6
	s_addc_u32 s7, s1, s7
	s_load_dwordx2 s[6:7], s[6:7], 0x0
	s_lshl_b32 s8, s20, 5
	s_and_b32 s8, s8, 0x3e0
	s_add_i32 s9, s22, 0x1a80
	s_and_b32 s9, s9, 0x1ffc0
	s_lshl_b32 s10, s8, 2
	v_add_u32_e32 v0, s9, v32
	s_waitcnt lgkmcnt(0)
	s_add_u32 s6, s6, s10
	s_addc_u32 s7, s7, 0
	v_lshlrev_b32_e32 v36, 2, v34
	v_ashrrev_i32_e32 v1, 31, v0
	v_lshl_add_u64 v[2:3], s[6:7], 0, v[36:37]
	v_lshlrev_b64 v[0:1], 12, v[0:1]
	v_lshl_add_u64 v[28:29], v[2:3], 0, v[0:1]
	v_add_co_u32_e32 v4, vcc, s24, v28
	v_add_u32_e32 v33, v35, v89
	s_nop 0
	v_addc_co_u32_e32 v5, vcc, 0, v29, vcc
	v_add_co_u32_e32 v8, vcc, s25, v28
	global_load_dwordx4 v[0:3], v[28:29], off
	s_nop 0
	global_load_dwordx4 v[4:7], v[4:5], off
	v_addc_co_u32_e32 v9, vcc, 0, v29, vcc
	v_add_co_u32_e32 v12, vcc, s26, v28
	v_add_u32_e32 v36, 0x420, v33
	s_nop 0
	v_addc_co_u32_e32 v13, vcc, 0, v29, vcc
	v_add_co_u32_e32 v16, vcc, s27, v28
	global_load_dwordx4 v[8:11], v[8:9], off
	s_nop 0
	global_load_dwordx4 v[12:15], v[12:13], off
	v_addc_co_u32_e32 v17, vcc, 0, v29, vcc
	v_add_co_u32_e32 v20, vcc, s28, v28
	v_add_u32_e32 v39, 0x428, v33
	s_nop 0
	v_addc_co_u32_e32 v21, vcc, 0, v29, vcc
	global_load_dwordx4 v[16:19], v[16:17], off
	s_nop 0
	global_load_dwordx4 v[20:23], v[20:21], off
	v_add_co_u32_e32 v24, vcc, s29, v28
	v_add_u32_e32 v41, 0x840, v33
	s_nop 0
	v_addc_co_u32_e32 v25, vcc, 0, v29, vcc
	global_load_dwordx4 v[24:27], v[24:25], off
	v_add_co_u32_e32 v28, vcc, s30, v28
	v_add_u32_e32 v43, 0x848, v33
	s_nop 0
	v_addc_co_u32_e32 v29, vcc, 0, v29, vcc
	global_load_dwordx4 v[28:31], v[28:29], off
	v_add_u32_e32 v88, 0xc60, v33
	v_add_u32_e32 v92, 0xc68, v33
	v_add_u32_e32 v94, 0x1080, v33
	v_add_u32_e32 v95, 0x1088, v33
	v_add_u32_e32 v96, 0x14a0, v33
	v_add_u32_e32 v97, 0x14a8, v33
	v_add_u32_e32 v98, 0x18c0, v33
	v_add_u32_e32 v99, 0x18c8, v33
	v_add_u32_e32 v100, 0x1ce0, v33
	v_add_u32_e32 v101, 0x1ce8, v33
	v_add_u32_e32 v90, s8, v32
	v_ashrrev_i32_e32 v91, 31, v90
	s_lshl_b32 s10, s9, 1
	s_waitcnt vmcnt(0)
	ds_write2_b32 v33, v0, v1 offset1:1
	ds_write2_b32 v33, v2, v3 offset0:2 offset1:3
	ds_write2_b32 v36, v4, v5 offset1:1
	ds_write2_b32 v39, v6, v7 offset1:1
	ds_write2_b32 v41, v8, v9 offset1:1
	ds_write2_b32 v43, v10, v11 offset1:1
	ds_write2_b32 v88, v12, v13 offset1:1
	ds_write2_b32 v92, v14, v15 offset1:1
	ds_write2_b32 v94, v16, v17 offset1:1
	ds_write2_b32 v95, v18, v19 offset1:1
	ds_write2_b32 v96, v20, v21 offset1:1
	ds_write2_b32 v97, v22, v23 offset1:1
	ds_write2_b32 v98, v24, v25 offset1:1
	ds_write2_b32 v99, v26, v27 offset1:1
	ds_write2_b32 v100, v28, v29 offset1:1
	ds_write2_b32 v101, v30, v31 offset1:1
	s_waitcnt lgkmcnt(0)
	ds_read2_b32 v[4:5], v93 offset0:33 offset1:41
	ds_read2_b32 v[6:7], v93 offset1:8
	ds_read2_b32 v[8:9], v93 offset0:66 offset1:74
	ds_read2_b32 v[10:11], v93 offset0:99 offset1:107
	ds_read2_b32 v[12:13], v93 offset0:132 offset1:140
	ds_read2_b32 v[14:15], v93 offset0:165 offset1:173
	ds_read2_b32 v[16:17], v93 offset0:198 offset1:206
	ds_read2_b32 v[18:19], v93 offset0:231 offset1:239
	v_lshl_add_u64 v[20:21], v[68:69], 0, s[10:11]
	v_lshlrev_b64 v[22:23], 11, v[90:91]
	s_waitcnt lgkmcnt(6)
	v_cvt_pk_bf16_f32 v0, v6, v4
	s_waitcnt lgkmcnt(4)
	v_cvt_pk_bf16_f32 v1, v8, v10
	s_waitcnt lgkmcnt(2)
	v_cvt_pk_bf16_f32 v2, v12, v14
	s_waitcnt lgkmcnt(0)
	v_cvt_pk_bf16_f32 v3, v16, v18
	v_lshl_add_u64 v[22:23], v[20:21], 0, v[22:23]
	v_add_u32_e32 v4, s8, v38
	global_store_dwordx4 v[22:23], v[0:3], off sc1
	s_nop 1
	v_cvt_pk_bf16_f32 v0, v7, v5
	v_ashrrev_i32_e32 v5, 31, v4
	v_cvt_pk_bf16_f32 v1, v9, v11
	v_cvt_pk_bf16_f32 v2, v13, v15
	v_cvt_pk_bf16_f32 v3, v17, v19
	v_lshlrev_b64 v[4:5], 11, v[4:5]
	ds_read2_b32 v[6:7], v93 offset0:49 offset1:57
	ds_read2_b32 v[8:9], v93 offset0:16 offset1:24
	ds_read2_b32 v[10:11], v93 offset0:82 offset1:90
	ds_read2_b32 v[12:13], v93 offset0:115 offset1:123
	ds_read2_b32 v[14:15], v93 offset0:148 offset1:156
	ds_read2_b32 v[16:17], v93 offset0:181 offset1:189
	ds_read2_b32 v[18:19], v93 offset0:214 offset1:222
	ds_read2_b32 v[22:23], v93 offset0:247 offset1:255
	v_lshl_add_u64 v[4:5], v[20:21], 0, v[4:5]
	global_store_dwordx4 v[4:5], v[0:3], off sc1
	v_add_u32_e32 v4, s8, v40
	v_ashrrev_i32_e32 v5, 31, v4
	v_lshlrev_b64 v[4:5], 11, v[4:5]
	s_waitcnt lgkmcnt(6)
	v_cvt_pk_bf16_f32 v0, v8, v6
	s_waitcnt lgkmcnt(4)
	v_cvt_pk_bf16_f32 v1, v10, v12
	s_waitcnt lgkmcnt(2)
	v_cvt_pk_bf16_f32 v2, v14, v16
	s_waitcnt lgkmcnt(0)
	v_cvt_pk_bf16_f32 v3, v18, v22
	v_lshl_add_u64 v[4:5], v[20:21], 0, v[4:5]
	global_store_dwordx4 v[4:5], v[0:3], off sc1
	v_add_u32_e32 v4, s8, v42
	v_ashrrev_i32_e32 v5, 31, v4
	v_lshlrev_b64 v[4:5], 11, v[4:5]
	v_cvt_pk_bf16_f32 v0, v9, v7
	v_cvt_pk_bf16_f32 v1, v11, v13
	v_cvt_pk_bf16_f32 v2, v15, v17
	v_cvt_pk_bf16_f32 v3, v19, v23
	v_lshl_add_u64 v[4:5], v[20:21], 0, v[4:5]
	global_store_dwordx4 v[4:5], v[0:3], off sc1
	s_waitcnt lgkmcnt(0)

; __device__ __forceinline__ unsigned pk_bf16(float lo, float hi) { typedef __bf16 b2_t __attribute__((ext_vector_type(2))); f32x2 v = {lo, hi}; b2_t b = __builtin_convertvector(v, b2_t); return __builtin_bit_cast(unsigned, b); }
; #define LAS __attribute__((address_space(3)))
; __device__ __forceinline__ void transpose_tile(const float* W, const float* gain, int K, int N, int k0, int n0, bf16* WT, int drow0, LAS float* scr, int lane) {
;     f32x4 v[8]; float gv[8];
;     const int r0 = lane >> 3, c4 = lane & 7;
; #pragma unroll
;     for (int i = 0; i < 8; ++i) { v[i] = *(const f32x4*)(W + (size_t)(k0 + r0 + 8 * i) * N + n0 + 4 * c4); gv[i] = gain ? gain[k0 + r0 + 8 * i] : 1.0f; }
; #pragma unroll
;     for (int i = 0; i < 8; ++i) { LAS float* d = scr + (r0 + 8 * i) * 33 + 4 * c4; d[0] = v[i][0] * gv[i]; d[1] = v[i][1] * gv[i]; d[2] = v[i][2] * gv[i]; d[3] = v[i][3] * gv[i]; }
;     asm volatile("s_waitcnt lgkmcnt(0)" ::: "memory");
;     const int c = lane & 7;
; #pragma unroll
;     for (int j = 0; j < 4; ++j) { const int n = (lane >> 3) + 8 * j; const LAS float* s = scr + (8 * c) * 33 + n;
;         v4u o; o.x = pk_bf16(s[0 * 33], s[1 * 33]); o.y = pk_bf16(s[2 * 33], s[3 * 33]); o.z = pk_bf16(s[4 * 33], s[5 * 33]); o.w = pk_bf16(s[6 * 33], s[7 * 33]);
;         *(v4u*)(WT + (size_t)(drow0 + n) * K + k0 + 8 * c) = o; }
;     asm volatile("s_waitcnt lgkmcnt(0)" ::: "memory");
; }
.LBB0_1501:
	s_waitcnt vmcnt(0)
	v_pk_mul_f32 v[0:1], v[0:1], v[88:89] op_sel_hi:[1,0]
	v_add_u32_e32 v33, v35, v89
	ds_write2_b32 v33, v0, v1 offset1:1
	v_pk_mul_f32 v[0:1], v[2:3], v[88:89] op_sel_hi:[1,0]
	ds_write2_b32 v33, v0, v1 offset0:2 offset1:3
	v_pk_mul_f32 v[0:1], v[4:5], v[36:37] op_sel_hi:[1,0]
	v_add_u32_e32 v2, 0x420, v33
	ds_write2_b32 v2, v0, v1 offset1:1
	v_pk_mul_f32 v[0:1], v[6:7], v[36:37] op_sel_hi:[1,0]
	v_add_u32_e32 v2, 0x428, v33
	ds_write2_b32 v2, v0, v1 offset1:1
	v_pk_mul_f32 v[0:1], v[8:9], v[94:95] op_sel_hi:[1,0]
	v_add_u32_e32 v2, 0x840, v33
	ds_write2_b32 v2, v0, v1 offset1:1
	v_pk_mul_f32 v[0:1], v[10:11], v[94:95] op_sel_hi:[1,0]
	v_add_u32_e32 v2, 0x848, v33
	ds_write2_b32 v2, v0, v1 offset1:1
	v_pk_mul_f32 v[0:1], v[12:13], v[92:93] op_sel_hi:[1,0]
	v_add_u32_e32 v2, 0xc60, v33
	ds_write2_b32 v2, v0, v1 offset1:1
	v_pk_mul_f32 v[0:1], v[14:15], v[92:93] op_sel_hi:[1,0]
	v_add_u32_e32 v2, 0xc68, v33
	ds_write2_b32 v2, v0, v1 offset1:1
	v_pk_mul_f32 v[0:1], v[16:17], v[98:99] op_sel_hi:[1,0]
	v_add_u32_e32 v2, 0x1080, v33
	ds_write2_b32 v2, v0, v1 offset1:1
	v_pk_mul_f32 v[0:1], v[18:19], v[98:99] op_sel_hi:[1,0]
	v_add_u32_e32 v2, 0x1088, v33
	ds_write2_b32 v2, v0, v1 offset1:1
	v_pk_mul_f32 v[0:1], v[20:21], v[96:97] op_sel_hi:[1,0]
	v_add_u32_e32 v2, 0x14a0, v33
	ds_write2_b32 v2, v0, v1 offset1:1
	v_pk_mul_f32 v[0:1], v[22:23], v[96:97] op_sel_hi:[1,0]
	v_add_u32_e32 v2, 0x14a8, v33
	ds_write2_b32 v2, v0, v1 offset1:1
	v_pk_mul_f32 v[0:1], v[24:25], v[102:103] op_sel_hi:[1,0]
	v_add_u32_e32 v2, 0x18c0, v33
	ds_write2_b32 v2, v0, v1 offset1:1
	v_pk_mul_f32 v[0:1], v[26:27], v[102:103] op_sel_hi:[1,0]
	v_add_u32_e32 v2, 0x18c8, v33
	ds_write2_b32 v2, v0, v1 offset1:1
	v_pk_mul_f32 v[0:1], v[28:29], v[100:101] op_sel_hi:[1,0]
	v_add_u32_e32 v2, 0x1ce0, v33
	ds_write2_b32 v2, v0, v1 offset1:1
	v_pk_mul_f32 v[0:1], v[30:31], v[100:101] op_sel_hi:[1,0]
	v_add_u32_e32 v2, 0x1ce8, v33
	ds_write2_b32 v2, v0, v1 offset1:1
	s_waitcnt lgkmcnt(0)
	ds_read2_b32 v[4:5], v93 offset0:33 offset1:41
	ds_read2_b32 v[6:7], v93 offset1:8
	ds_read2_b32 v[8:9], v93 offset0:66 offset1:74
	ds_read2_b32 v[10:11], v93 offset0:99 offset1:107
	ds_read2_b32 v[12:13], v93 offset0:132 offset1:140
	ds_read2_b32 v[14:15], v93 offset0:165 offset1:173
	ds_read2_b32 v[16:17], v93 offset0:198 offset1:206
	ds_read2_b32 v[18:19], v93 offset0:231 offset1:239
	s_and_b32 s7, 0xffff, s7
	v_add_u32_e32 v22, s7, v32
	s_lshl_b32 s10, s6, 1
	v_ashrrev_i32_e32 v23, 31, v22
	v_lshl_add_u64 v[20:21], v[70:71], 0, s[10:11]
	v_lshlrev_b64 v[22:23], 11, v[22:23]
	s_waitcnt lgkmcnt(6)
	v_cvt_pk_bf16_f32 v0, v6, v4
	s_waitcnt lgkmcnt(4)
	v_cvt_pk_bf16_f32 v1, v8, v10
	s_waitcnt lgkmcnt(2)
	v_cvt_pk_bf16_f32 v2, v12, v14
	s_waitcnt lgkmcnt(0)
	v_cvt_pk_bf16_f32 v3, v16, v18
	v_lshl_add_u64 v[22:23], v[20:21], 0, v[22:23]
	v_add_u32_e32 v4, s7, v38
	global_store_dwordx4 v[22:23], v[0:3], off sc1
	s_nop 1
	v_cvt_pk_bf16_f32 v0, v7, v5
	v_ashrrev_i32_e32 v5, 31, v4
	v_cvt_pk_bf16_f32 v1, v9, v11
	v_cvt_pk_bf16_f32 v2, v13, v15
	v_cvt_pk_bf16_f32 v3, v17, v19
	v_lshlrev_b64 v[4:5], 11, v[4:5]
	ds_read2_b32 v[6:7], v93 offset0:49 offset1:57
	ds_read2_b32 v[8:9], v93 offset0:16 offset1:24
	ds_read2_b32 v[10:11], v93 offset0:82 offset1:90
	ds_read2_b32 v[12:13], v93 offset0:115 offset1:123
	ds_read2_b32 v[14:15], v93 offset0:148 offset1:156
	ds_read2_b32 v[16:17], v93 offset0:181 offset1:189
	ds_read2_b32 v[18:19], v93 offset0:214 offset1:222
	ds_read2_b32 v[22:23], v93 offset0:247 offset1:255
	v_lshl_add_u64 v[4:5], v[20:21], 0, v[4:5]
	global_store_dwordx4 v[4:5], v[0:3], off sc1
	v_add_u32_e32 v4, s7, v40
	v_ashrrev_i32_e32 v5, 31, v4
	v_lshlrev_b64 v[4:5], 11, v[4:5]
	s_waitcnt lgkmcnt(6)
	v_cvt_pk_bf16_f32 v0, v8, v6
	s_waitcnt lgkmcnt(4)
	v_cvt_pk_bf16_f32 v1, v10, v12
	s_waitcnt lgkmcnt(2)
	v_cvt_pk_bf16_f32 v2, v14, v16
	s_waitcnt lgkmcnt(0)
	v_cvt_pk_bf16_f32 v3, v18, v22
	v_lshl_add_u64 v[4:5], v[20:21], 0, v[4:5]
	global_store_dwordx4 v[4:5], v[0:3], off sc1
	v_add_u32_e32 v4, s7, v42
	v_ashrrev_i32_e32 v5, 31, v4
	v_lshlrev_b64 v[4:5], 11, v[4:5]
	v_cvt_pk_bf16_f32 v0, v9, v7
	v_cvt_pk_bf16_f32 v1, v11, v13
	v_cvt_pk_bf16_f32 v2, v15, v17
	v_cvt_pk_bf16_f32 v3, v19, v23
	v_lshl_add_u64 v[4:5], v[20:21], 0, v[4:5]
	global_store_dwordx4 v[4:5], v[0:3], off sc1
	s_waitcnt lgkmcnt(0)

; __device__ __forceinline__ unsigned pk_bf16(float lo, float hi) { typedef __bf16 b2_t __attribute__((ext_vector_type(2))); f32x2 v = {lo, hi}; b2_t b = __builtin_convertvector(v, b2_t); return __builtin_bit_cast(unsigned, b); }
; #define LAS __attribute__((address_space(3)))
; __device__ __forceinline__ void transpose_tile(const float* W, const float* gain, int K, int N, int k0, int n0, bf16* WT, int drow0, LAS float* scr, int lane) {
;     f32x4 v[8]; float gv[8];
;     const int r0 = lane >> 3, c4 = lane & 7;
; #pragma unroll
;     for (int i = 0; i < 8; ++i) { v[i] = *(const f32x4*)(W + (size_t)(k0 + r0 + 8 * i) * N + n0 + 4 * c4); gv[i] = gain ? gain[k0 + r0 + 8 * i] : 1.0f; }
; #pragma unroll
;     for (int i = 0; i < 8; ++i) { LAS float* d = scr + (r0 + 8 * i) * 33 + 4 * c4; d[0] = v[i][0] * gv[i]; d[1] = v[i][1] * gv[i]; d[2] = v[i][2] * gv[i]; d[3] = v[i][3] * gv[i]; }
;     asm volatile("s_waitcnt lgkmcnt(0)" ::: "memory");
;     const int c = lane & 7;
; #pragma unroll
;     for (int j = 0; j < 4; ++j) { const int n = (lane >> 3) + 8 * j; const LAS float* s = scr + (8 * c) * 33 + n;
;         v4u o; o.x = pk_bf16(s[0 * 33], s[1 * 33]); o.y = pk_bf16(s[2 * 33], s[3 * 33]); o.z = pk_bf16(s[4 * 33], s[5 * 33]); o.w = pk_bf16(s[6 * 33], s[7 * 33]);
;         *(v4u*)(WT + (size_t)(drow0 + n) * K + k0 + 8 * c) = o; }
;     asm volatile("s_waitcnt lgkmcnt(0)" ::: "memory");
; }
; template <bool SWIGLU> __device__ __forceinline__ void transpose_item(const float* W, const float* gain, int K, int N, bf16* WT, LAS float* scr, int item, int lane) {
;     const int nblk = N / 32, kb = item / nblk, nb = item % nblk, n0 = 32 * nb;
;     int drow0 = n0;
;     if (SWIGLU) { const int up = n0 >= FF, f = up ? n0 - FF : n0; drow0 = 256 * (f >> 7) + (up ? 128 : 0) + (f & 127); }
;     transpose_tile(W, gain, K, N, 64 * kb, n0, WT, drow0, scr, lane);
; }
.LBB0_1503:
	s_andn2_b64 vcc, exec, s[8:9]
	s_cbranch_vccnz .LBB0_1505
	s_mov_b32 s6, 14
	s_ashr_i32 s7, s6, 31
	s_lshl_b64 s[6:7], s[6:7], 3
	s_add_u32 s6, s0, s6
	s_addc_u32 s7, s1, s7
	s_load_dwordx2 s[6:7], s[6:7], 0x0
	s_lshl_b32 s8, s20, 5
	s_and_b32 s8, s8, 0x3e0
	s_add_i32 s9, s22, 0x2d80
	s_and_b32 s9, s9, 0x1ffc0
	s_lshl_b32 s10, s8, 2
	v_add_u32_e32 v0, s9, v32
	s_waitcnt lgkmcnt(0)
	s_add_u32 s6, s6, s10
	s_addc_u32 s7, s7, 0
	v_lshlrev_b32_e32 v36, 2, v34
	v_ashrrev_i32_e32 v1, 31, v0
	v_lshl_add_u64 v[2:3], s[6:7], 0, v[36:37]
	v_lshlrev_b64 v[0:1], 12, v[0:1]
	v_lshl_add_u64 v[28:29], v[2:3], 0, v[0:1]
	v_add_co_u32_e32 v4, vcc, s24, v28
	v_add_u32_e32 v33, v35, v89
	s_nop 0
	v_addc_co_u32_e32 v5, vcc, 0, v29, vcc
	v_add_co_u32_e32 v8, vcc, s25, v28
	global_load_dwordx4 v[0:3], v[28:29], off
	s_nop 0
	global_load_dwordx4 v[4:7], v[4:5], off
	v_addc_co_u32_e32 v9, vcc, 0, v29, vcc
	v_add_co_u32_e32 v12, vcc, s26, v28
	v_add_u32_e32 v36, 0x420, v33
	s_nop 0
	v_addc_co_u32_e32 v13, vcc, 0, v29, vcc
	v_add_co_u32_e32 v16, vcc, s27, v28
	global_load_dwordx4 v[8:11], v[8:9], off
	s_nop 0
	global_load_dwordx4 v[12:15], v[12:13], off
	v_addc_co_u32_e32 v17, vcc, 0, v29, vcc
	v_add_co_u32_e32 v20, vcc, s28, v28
	v_add_u32_e32 v39, 0x428, v33
	s_nop 0
	v_addc_co_u32_e32 v21, vcc, 0, v29, vcc
	global_load_dwordx4 v[16:19], v[16:17], off
	s_nop 0
	global_load_dwordx4 v[20:23], v[20:21], off
	v_add_co_u32_e32 v24, vcc, s29, v28
	v_add_u32_e32 v41, 0x840, v33
	s_nop 0
	v_addc_co_u32_e32 v25, vcc, 0, v29, vcc
	global_load_dwordx4 v[24:27], v[24:25], off
	v_add_co_u32_e32 v28, vcc, s30, v28
	v_add_u32_e32 v43, 0x848, v33
	s_nop 0
	v_addc_co_u32_e32 v29, vcc, 0, v29, vcc
	global_load_dwordx4 v[28:31], v[28:29], off
	v_add_u32_e32 v88, 0xc60, v33
	v_add_u32_e32 v90, 0xc68, v33
	v_add_u32_e32 v91, 0x1080, v33
	v_add_u32_e32 v92, 0x1088, v33
	v_add_u32_e32 v94, 0x14a0, v33
	v_add_u32_e32 v95, 0x14a8, v33
	v_add_u32_e32 v96, 0x18c0, v33
	v_add_u32_e32 v97, 0x18c8, v33
	v_add_u32_e32 v98, 0x1ce0, v33
	v_add_u32_e32 v99, 0x1ce8, v33
	s_lshl_b32 s10, s9, 1
	v_add_u32_e32 v100, s8, v32
	s_waitcnt vmcnt(0)
	ds_write2_b32 v33, v0, v1 offset1:1
	ds_write2_b32 v33, v2, v3 offset0:2 offset1:3
	ds_write2_b32 v36, v4, v5 offset1:1
	ds_write2_b32 v39, v6, v7 offset1:1
	ds_write2_b32 v41, v8, v9 offset1:1
	ds_write2_b32 v43, v10, v11 offset1:1
	ds_write2_b32 v88, v12, v13 offset1:1
	ds_write2_b32 v90, v14, v15 offset1:1
	ds_write2_b32 v91, v16, v17 offset1:1
	ds_write2_b32 v92, v18, v19 offset1:1
	ds_write2_b32 v94, v20, v21 offset1:1
	ds_write2_b32 v95, v22, v23 offset1:1
	ds_write2_b32 v96, v24, v25 offset1:1
	ds_write2_b32 v97, v26, v27 offset1:1
	ds_write2_b32 v98, v28, v29 offset1:1
	ds_write2_b32 v99, v30, v31 offset1:1
	s_waitcnt lgkmcnt(0)
	ds_read2_b32 v[4:5], v93 offset0:33 offset1:41
	ds_read2_b32 v[6:7], v93 offset1:8
	ds_read2_b32 v[8:9], v93 offset0:66 offset1:74
	ds_read2_b32 v[10:11], v93 offset0:99 offset1:107
	ds_read2_b32 v[12:13], v93 offset0:132 offset1:140
	ds_read2_b32 v[14:15], v93 offset0:165 offset1:173
	ds_read2_b32 v[16:17], v93 offset0:198 offset1:206
	ds_read2_b32 v[18:19], v93 offset0:231 offset1:239
	v_lshl_add_u64 v[20:21], v[72:73], 0, s[10:11]
	s_waitcnt lgkmcnt(6)
	v_cvt_pk_bf16_f32 v0, v6, v4
	s_waitcnt lgkmcnt(4)
	v_cvt_pk_bf16_f32 v1, v8, v10
	s_waitcnt lgkmcnt(2)
	v_cvt_pk_bf16_f32 v2, v12, v14
	s_waitcnt lgkmcnt(0)
	v_cvt_pk_bf16_f32 v3, v16, v18
	v_mad_i64_i32 v[22:23], s[6:7], v100, s31, v[20:21]
	global_store_dwordx4 v[22:23], v[0:3], off sc1
	v_add_u32_e32 v4, s8, v38
	s_nop 0
	v_cvt_pk_bf16_f32 v0, v7, v5
	v_cvt_pk_bf16_f32 v1, v9, v11
	v_cvt_pk_bf16_f32 v2, v13, v15
	v_cvt_pk_bf16_f32 v3, v17, v19
	ds_read2_b32 v[6:7], v93 offset0:49 offset1:57
	ds_read2_b32 v[8:9], v93 offset0:16 offset1:24
	ds_read2_b32 v[10:11], v93 offset0:82 offset1:90
	ds_read2_b32 v[12:13], v93 offset0:115 offset1:123
	ds_read2_b32 v[14:15], v93 offset0:148 offset1:156
	ds_read2_b32 v[16:17], v93 offset0:181 offset1:189
	ds_read2_b32 v[18:19], v93 offset0:214 offset1:222
	ds_read2_b32 v[22:23], v93 offset0:247 offset1:255
	v_mad_i64_i32 v[4:5], s[6:7], v4, s31, v[20:21]
	global_store_dwordx4 v[4:5], v[0:3], off sc1
	v_add_u32_e32 v4, s8, v40
	v_mad_i64_i32 v[4:5], s[6:7], v4, s31, v[20:21]
	s_waitcnt lgkmcnt(6)
	v_cvt_pk_bf16_f32 v0, v8, v6
	s_waitcnt lgkmcnt(4)
	v_cvt_pk_bf16_f32 v1, v10, v12
	s_waitcnt lgkmcnt(2)
	v_cvt_pk_bf16_f32 v2, v14, v16
	s_waitcnt lgkmcnt(0)
	v_cvt_pk_bf16_f32 v3, v18, v22
	global_store_dwordx4 v[4:5], v[0:3], off sc1
	v_add_u32_e32 v4, s8, v42
	v_mad_i64_i32 v[4:5], s[6:7], v4, s31, v[20:21]
	v_cvt_pk_bf16_f32 v0, v9, v7
	v_cvt_pk_bf16_f32 v1, v11, v13
	v_cvt_pk_bf16_f32 v2, v15, v17
	v_cvt_pk_bf16_f32 v3, v19, v23
	global_store_dwordx4 v[4:5], v[0:3], off sc1
	s_waitcnt lgkmcnt(0)

; __device__ __forceinline__ unsigned pk_bf16(float lo, float hi) { typedef __bf16 b2_t __attribute__((ext_vector_type(2))); f32x2 v = {lo, hi}; b2_t b = __builtin_convertvector(v, b2_t); return __builtin_bit_cast(unsigned, b); }
; #define LAS __attribute__((address_space(3)))
; __device__ __forceinline__ void transpose_tile(const float* W, const float* gain, int K, int N, int k0, int n0, bf16* WT, int drow0, LAS float* scr, int lane) {
;     f32x4 v[8]; float gv[8];
;     const int r0 = lane >> 3, c4 = lane & 7;
; #pragma unroll
;     for (int i = 0; i < 8; ++i) { v[i] = *(const f32x4*)(W + (size_t)(k0 + r0 + 8 * i) * N + n0 + 4 * c4); gv[i] = gain ? gain[k0 + r0 + 8 * i] : 1.0f; }
; #pragma unroll
;     for (int i = 0; i < 8; ++i) { LAS float* d = scr + (r0 + 8 * i) * 33 + 4 * c4; d[0] = v[i][0] * gv[i]; d[1] = v[i][1] * gv[i]; d[2] = v[i][2] * gv[i]; d[3] = v[i][3] * gv[i]; }
;     asm volatile("s_waitcnt lgkmcnt(0)" ::: "memory");
;     const int c = lane & 7;
; #pragma unroll
;     for (int j = 0; j < 4; ++j) { const int n = (lane >> 3) + 8 * j; const LAS float* s = scr + (8 * c) * 33 + n;
;         v4u o; o.x = pk_bf16(s[0 * 33], s[1 * 33]); o.y = pk_bf16(s[2 * 33], s[3 * 33]); o.z = pk_bf16(s[4 * 33], s[5 * 33]); o.w = pk_bf16(s[6 * 33], s[7 * 33]);
;         *(v4u*)(WT + (size_t)(drow0 + n) * K + k0 + 8 * c) = o; }
;     asm volatile("s_waitcnt lgkmcnt(0)" ::: "memory");
; }
; template <bool SWIGLU> __device__ __forceinline__ void transpose_item(const float* W, const float* gain, int K, int N, bf16* WT, LAS float* scr, int item, int lane) {
;     const int nblk = N / 32, kb = item / nblk, nb = item % nblk, n0 = 32 * nb;
;     int drow0 = n0;
;     if (SWIGLU) { const int up = n0 >= FF, f = up ? n0 - FF : n0; drow0 = 256 * (f >> 7) + (up ? 128 : 0) + (f & 127); }
;     transpose_tile(W, gain, K, N, 64 * kb, n0, WT, drow0, scr, lane);
; }
.LBB0_1523:
	s_waitcnt vmcnt(0)
	v_pk_mul_f32 v[0:1], v[0:1], v[88:89] op_sel_hi:[1,0]
	v_add_u32_e32 v33, v35, v89
	ds_write2_b32 v33, v0, v1 offset1:1
	v_pk_mul_f32 v[0:1], v[2:3], v[88:89] op_sel_hi:[1,0]
	ds_write2_b32 v33, v0, v1 offset0:2 offset1:3
	v_pk_mul_f32 v[0:1], v[4:5], v[36:37] op_sel_hi:[1,0]
	v_add_u32_e32 v2, 0x420, v33
	ds_write2_b32 v2, v0, v1 offset1:1
	v_pk_mul_f32 v[0:1], v[6:7], v[36:37] op_sel_hi:[1,0]
	v_add_u32_e32 v2, 0x428, v33
	ds_write2_b32 v2, v0, v1 offset1:1
	v_pk_mul_f32 v[0:1], v[8:9], v[94:95] op_sel_hi:[1,0]
	v_add_u32_e32 v2, 0x840, v33
	ds_write2_b32 v2, v0, v1 offset1:1
	v_pk_mul_f32 v[0:1], v[10:11], v[94:95] op_sel_hi:[1,0]
	v_add_u32_e32 v2, 0x848, v33
	ds_write2_b32 v2, v0, v1 offset1:1
	v_pk_mul_f32 v[0:1], v[12:13], v[90:91] op_sel_hi:[1,0]
	v_add_u32_e32 v2, 0xc60, v33
	ds_write2_b32 v2, v0, v1 offset1:1
	v_pk_mul_f32 v[0:1], v[14:15], v[90:91] op_sel_hi:[1,0]
	v_add_u32_e32 v2, 0xc68, v33
	ds_write2_b32 v2, v0, v1 offset1:1
	v_pk_mul_f32 v[0:1], v[16:17], v[100:101] op_sel_hi:[1,0]
	v_add_u32_e32 v2, 0x1080, v33
	ds_write2_b32 v2, v0, v1 offset1:1
	v_pk_mul_f32 v[0:1], v[18:19], v[100:101] op_sel_hi:[1,0]
	v_add_u32_e32 v2, 0x1088, v33
	ds_write2_b32 v2, v0, v1 offset1:1
	v_pk_mul_f32 v[0:1], v[20:21], v[92:93] op_sel_hi:[1,0]
	v_add_u32_e32 v2, 0x14a0, v33
	ds_write2_b32 v2, v0, v1 offset1:1
	v_pk_mul_f32 v[0:1], v[22:23], v[92:93] op_sel_hi:[1,0]
	v_add_u32_e32 v2, 0x14a8, v33
	ds_write2_b32 v2, v0, v1 offset1:1
	v_pk_mul_f32 v[0:1], v[24:25], v[102:103] op_sel_hi:[1,0]
	v_add_u32_e32 v2, 0x18c0, v33
	s_and_b32 s8, 0xffff, s8
	ds_write2_b32 v2, v0, v1 offset1:1
	v_pk_mul_f32 v[0:1], v[26:27], v[102:103] op_sel_hi:[1,0]
	v_add_u32_e32 v2, 0x18c8, v33
	s_and_b32 s7, 0xffff, s7
	s_add_i32 s9, s8, 0xfffff500
	ds_write2_b32 v2, v0, v1 offset1:1
	v_pk_mul_f32 v[0:1], v[28:29], v[96:97] op_sel_hi:[1,0]
	v_add_u32_e32 v2, 0x1ce0, v33
	s_cmpk_gt_u32 s7, 0x57
	ds_write2_b32 v2, v0, v1 offset1:1
	v_pk_mul_f32 v[0:1], v[30:31], v[96:97] op_sel_hi:[1,0]
	v_add_u32_e32 v2, 0x1ce8, v33
	s_cselect_b32 s7, s9, s8
	ds_write2_b32 v2, v0, v1 offset1:1
	s_cselect_b32 s8, 0x80, 0
	s_lshl_b32 s9, s7, 1
	s_and_b32 s7, s7, 0x60
	s_waitcnt lgkmcnt(0)
	s_and_b32 s9, s9, 0xffffff00
	s_or_b32 s7, s7, s8
	ds_read2_b32 v[4:5], v93 offset0:33 offset1:41
	ds_read2_b32 v[6:7], v93 offset1:8
	ds_read2_b32 v[8:9], v93 offset0:66 offset1:74
	ds_read2_b32 v[10:11], v93 offset0:99 offset1:107
	ds_read2_b32 v[12:13], v93 offset0:132 offset1:140
	ds_read2_b32 v[14:15], v93 offset0:165 offset1:173
	ds_read2_b32 v[16:17], v93 offset0:198 offset1:206
	ds_read2_b32 v[18:19], v93 offset0:231 offset1:239
	s_or_b32 s7, s7, s9
	s_and_b32 s6, 0xffff, s6
	v_add_u32_e32 v22, s7, v32
	s_lshl_b32 s10, s6, 1
	v_ashrrev_i32_e32 v23, 31, v22
	v_lshl_add_u64 v[20:21], v[74:75], 0, s[10:11]
	v_lshlrev_b64 v[22:23], 11, v[22:23]
	s_waitcnt lgkmcnt(6)
	v_cvt_pk_bf16_f32 v0, v6, v4
	s_waitcnt lgkmcnt(4)
	v_cvt_pk_bf16_f32 v1, v8, v10
	s_waitcnt lgkmcnt(2)
	v_cvt_pk_bf16_f32 v2, v12, v14
	s_waitcnt lgkmcnt(0)
	v_cvt_pk_bf16_f32 v3, v16, v18
	v_lshl_add_u64 v[22:23], v[20:21], 0, v[22:23]
	v_add_u32_e32 v4, s7, v38
	global_store_dwordx4 v[22:23], v[0:3], off sc1
	s_nop 1
	v_cvt_pk_bf16_f32 v0, v7, v5
	v_ashrrev_i32_e32 v5, 31, v4
	v_cvt_pk_bf16_f32 v1, v9, v11
	v_cvt_pk_bf16_f32 v2, v13, v15
	v_cvt_pk_bf16_f32 v3, v17, v19
	v_lshlrev_b64 v[4:5], 11, v[4:5]
	ds_read2_b32 v[6:7], v93 offset0:49 offset1:57
	ds_read2_b32 v[8:9], v93 offset0:16 offset1:24
	ds_read2_b32 v[10:11], v93 offset0:82 offset1:90
	ds_read2_b32 v[12:13], v93 offset0:115 offset1:123
	ds_read2_b32 v[14:15], v93 offset0:148 offset1:156
	ds_read2_b32 v[16:17], v93 offset0:181 offset1:189
	ds_read2_b32 v[18:19], v93 offset0:214 offset1:222
	ds_read2_b32 v[22:23], v93 offset0:247 offset1:255
	v_lshl_add_u64 v[4:5], v[20:21], 0, v[4:5]
	global_store_dwordx4 v[4:5], v[0:3], off sc1
	v_add_u32_e32 v4, s7, v40
	v_ashrrev_i32_e32 v5, 31, v4
	v_lshlrev_b64 v[4:5], 11, v[4:5]
	s_waitcnt lgkmcnt(6)
	v_cvt_pk_bf16_f32 v0, v8, v6
	s_waitcnt lgkmcnt(4)
	v_cvt_pk_bf16_f32 v1, v10, v12
	s_waitcnt lgkmcnt(2)
	v_cvt_pk_bf16_f32 v2, v14, v16
	s_waitcnt lgkmcnt(0)
	v_cvt_pk_bf16_f32 v3, v18, v22
	v_lshl_add_u64 v[4:5], v[20:21], 0, v[4:5]
	global_store_dwordx4 v[4:5], v[0:3], off sc1
	v_add_u32_e32 v4, s7, v42
	v_ashrrev_i32_e32 v5, 31, v4
	v_lshlrev_b64 v[4:5], 11, v[4:5]
	v_cvt_pk_bf16_f32 v0, v9, v7
	v_cvt_pk_bf16_f32 v1, v11, v13
	v_cvt_pk_bf16_f32 v2, v15, v17
	v_cvt_pk_bf16_f32 v3, v19, v23
	v_lshl_add_u64 v[4:5], v[20:21], 0, v[4:5]
	global_store_dwordx4 v[4:5], v[0:3], off sc1
	s_waitcnt lgkmcnt(0)

; __device__ __forceinline__ unsigned pk_bf16(float lo, float hi) { typedef __bf16 b2_t __attribute__((ext_vector_type(2))); f32x2 v = {lo, hi}; b2_t b = __builtin_convertvector(v, b2_t); return __builtin_bit_cast(unsigned, b); }
; #define LAS __attribute__((address_space(3)))
; __device__ __forceinline__ void transpose_tile(const float* W, const float* gain, int K, int N, int k0, int n0, bf16* WT, int drow0, LAS float* scr, int lane) {
;     f32x4 v[8]; float gv[8];
;     const int r0 = lane >> 3, c4 = lane & 7;
; #pragma unroll
;     for (int i = 0; i < 8; ++i) { v[i] = *(const f32x4*)(W + (size_t)(k0 + r0 + 8 * i) * N + n0 + 4 * c4); gv[i] = gain ? gain[k0 + r0 + 8 * i] : 1.0f; }
; #pragma unroll
;     for (int i = 0; i < 8; ++i) { LAS float* d = scr + (r0 + 8 * i) * 33 + 4 * c4; d[0] = v[i][0] * gv[i]; d[1] = v[i][1] * gv[i]; d[2] = v[i][2] * gv[i]; d[3] = v[i][3] * gv[i]; }
;     asm volatile("s_waitcnt lgkmcnt(0)" ::: "memory");
;     const int c = lane & 7;
; #pragma unroll
;     for (int j = 0; j < 4; ++j) { const int n = (lane >> 3) + 8 * j; const LAS float* s = scr + (8 * c) * 33 + n;
;         v4u o; o.x = pk_bf16(s[0 * 33], s[1 * 33]); o.y = pk_bf16(s[2 * 33], s[3 * 33]); o.z = pk_bf16(s[4 * 33], s[5 * 33]); o.w = pk_bf16(s[6 * 33], s[7 * 33]);
;         *(v4u*)(WT + (size_t)(drow0 + n) * K + k0 + 8 * c) = o; }
;     asm volatile("s_waitcnt lgkmcnt(0)" ::: "memory");
; }
; template <bool SWIGLU> __device__ __forceinline__ void transpose_item(const float* W, const float* gain, int K, int N, bf16* WT, LAS float* scr, int item, int lane) {
;     const int nblk = N / 32, kb = item / nblk, nb = item % nblk, n0 = 32 * nb;
;     int drow0 = n0;
;     if (SWIGLU) { const int up = n0 >= FF, f = up ? n0 - FF : n0; drow0 = 256 * (f >> 7) + (up ? 128 : 0) + (f & 127); }
;     transpose_tile(W, gain, K, N, 64 * kb, n0, WT, drow0, scr, lane);
; }
.LBB0_1525:
	s_andn2_b64 vcc, exec, s[8:9]
	s_cbranch_vccnz .LBB0_1527
	s_mov_b32 s6, 11
	s_ashr_i32 s7, s6, 31
	s_lshl_b64 s[6:7], s[6:7], 3
	s_add_u32 s6, s0, s6
	s_addc_u32 s7, s1, s7
	s_load_dwordx2 s[6:7], s[6:7], 0x0
	s_lshl_b32 s8, s20, 5
	s_and_b32 s8, s8, 0x3e0
	s_add_i32 s9, s22, 0x4e80
	s_and_b32 s9, s9, 0x1ffc0
	s_lshl_b32 s10, s8, 2
	v_add_u32_e32 v0, s9, v32
	s_waitcnt lgkmcnt(0)
	s_add_u32 s6, s6, s10
	s_addc_u32 s7, s7, 0
	v_lshlrev_b32_e32 v36, 2, v34
	v_ashrrev_i32_e32 v1, 31, v0
	v_lshl_add_u64 v[2:3], s[6:7], 0, v[36:37]
	v_lshlrev_b64 v[0:1], 12, v[0:1]
	v_lshl_add_u64 v[28:29], v[2:3], 0, v[0:1]
	v_add_co_u32_e32 v4, vcc, s24, v28
	v_add_u32_e32 v33, v35, v89
	s_nop 0
	v_addc_co_u32_e32 v5, vcc, 0, v29, vcc
	v_add_co_u32_e32 v8, vcc, s25, v28
	global_load_dwordx4 v[0:3], v[28:29], off
	s_nop 0
	global_load_dwordx4 v[4:7], v[4:5], off
	v_addc_co_u32_e32 v9, vcc, 0, v29, vcc
	v_add_co_u32_e32 v12, vcc, s26, v28
	v_add_u32_e32 v36, 0x420, v33
	s_nop 0
	v_addc_co_u32_e32 v13, vcc, 0, v29, vcc
	v_add_co_u32_e32 v16, vcc, s27, v28
	global_load_dwordx4 v[8:11], v[8:9], off
	s_nop 0
	global_load_dwordx4 v[12:15], v[12:13], off
	v_addc_co_u32_e32 v17, vcc, 0, v29, vcc
	v_add_co_u32_e32 v20, vcc, s28, v28
	v_add_u32_e32 v39, 0x428, v33
	s_nop 0
	v_addc_co_u32_e32 v21, vcc, 0, v29, vcc
	global_load_dwordx4 v[16:19], v[16:17], off
	s_nop 0
	global_load_dwordx4 v[20:23], v[20:21], off
	v_add_co_u32_e32 v24, vcc, s29, v28
	v_add_u32_e32 v41, 0x840, v33
	s_nop 0
	v_addc_co_u32_e32 v25, vcc, 0, v29, vcc
	global_load_dwordx4 v[24:27], v[24:25], off
	v_add_co_u32_e32 v28, vcc, s30, v28
	v_add_u32_e32 v43, 0x848, v33
	s_nop 0
	v_addc_co_u32_e32 v29, vcc, 0, v29, vcc
	global_load_dwordx4 v[28:31], v[28:29], off
	v_add_u32_e32 v88, 0xc60, v33
	v_add_u32_e32 v90, 0xc68, v33
	v_add_u32_e32 v91, 0x1080, v33
	v_add_u32_e32 v92, 0x1088, v33
	v_add_u32_e32 v94, 0x14a0, v33
	v_add_u32_e32 v95, 0x14a8, v33
	v_add_u32_e32 v96, 0x18c0, v33
	v_add_u32_e32 v97, 0x18c8, v33
	v_add_u32_e32 v98, 0x1ce0, v33
	v_add_u32_e32 v99, 0x1ce8, v33
	s_lshl_b32 s10, s9, 1
	v_add_u32_e32 v100, s8, v32
	s_waitcnt vmcnt(0)
	ds_write2_b32 v33, v0, v1 offset1:1
	ds_write2_b32 v33, v2, v3 offset0:2 offset1:3
	ds_write2_b32 v36, v4, v5 offset1:1
	ds_write2_b32 v39, v6, v7 offset1:1
	ds_write2_b32 v41, v8, v9 offset1:1
	ds_write2_b32 v43, v10, v11 offset1:1
	ds_write2_b32 v88, v12, v13 offset1:1
	ds_write2_b32 v90, v14, v15 offset1:1
	ds_write2_b32 v91, v16, v17 offset1:1
	ds_write2_b32 v92, v18, v19 offset1:1
	ds_write2_b32 v94, v20, v21 offset1:1
	ds_write2_b32 v95, v22, v23 offset1:1
	ds_write2_b32 v96, v24, v25 offset1:1
	ds_write2_b32 v97, v26, v27 offset1:1
	ds_write2_b32 v98, v28, v29 offset1:1
	ds_write2_b32 v99, v30, v31 offset1:1
	s_waitcnt lgkmcnt(0)
	ds_read2_b32 v[4:5], v93 offset0:33 offset1:41
	ds_read2_b32 v[6:7], v93 offset1:8
	ds_read2_b32 v[8:9], v93 offset0:66 offset1:74
	ds_read2_b32 v[10:11], v93 offset0:99 offset1:107
	ds_read2_b32 v[12:13], v93 offset0:132 offset1:140
	ds_read2_b32 v[14:15], v93 offset0:165 offset1:173
	ds_read2_b32 v[16:17], v93 offset0:198 offset1:206
	ds_read2_b32 v[18:19], v93 offset0:231 offset1:239
	v_lshl_add_u64 v[20:21], v[76:77], 0, s[10:11]
	s_waitcnt lgkmcnt(6)
	v_cvt_pk_bf16_f32 v0, v6, v4
	s_waitcnt lgkmcnt(4)
	v_cvt_pk_bf16_f32 v1, v8, v10
	s_waitcnt lgkmcnt(2)
	v_cvt_pk_bf16_f32 v2, v12, v14
	s_waitcnt lgkmcnt(0)
	v_cvt_pk_bf16_f32 v3, v16, v18
	v_mad_i64_i32 v[22:23], s[6:7], v100, s31, v[20:21]
	global_store_dwordx4 v[22:23], v[0:3], off sc1
	v_add_u32_e32 v4, s8, v38
	s_nop 0
	v_cvt_pk_bf16_f32 v0, v7, v5
	v_cvt_pk_bf16_f32 v1, v9, v11
	v_cvt_pk_bf16_f32 v2, v13, v15
	v_cvt_pk_bf16_f32 v3, v17, v19
	ds_read2_b32 v[6:7], v93 offset0:49 offset1:57
	ds_read2_b32 v[8:9], v93 offset0:16 offset1:24
	ds_read2_b32 v[10:11], v93 offset0:82 offset1:90
	ds_read2_b32 v[12:13], v93 offset0:115 offset1:123
	ds_read2_b32 v[14:15], v93 offset0:148 offset1:156
	ds_read2_b32 v[16:17], v93 offset0:181 offset1:189
	ds_read2_b32 v[18:19], v93 offset0:214 offset1:222
	ds_read2_b32 v[22:23], v93 offset0:247 offset1:255
	v_mad_i64_i32 v[4:5], s[6:7], v4, s31, v[20:21]
	global_store_dwordx4 v[4:5], v[0:3], off sc1
	v_add_u32_e32 v4, s8, v40
	v_mad_i64_i32 v[4:5], s[6:7], v4, s31, v[20:21]
	s_waitcnt lgkmcnt(6)
	v_cvt_pk_bf16_f32 v0, v8, v6
	s_waitcnt lgkmcnt(4)
	v_cvt_pk_bf16_f32 v1, v10, v12
	s_waitcnt lgkmcnt(2)
	v_cvt_pk_bf16_f32 v2, v14, v16
	s_waitcnt lgkmcnt(0)
	v_cvt_pk_bf16_f32 v3, v18, v22
	global_store_dwordx4 v[4:5], v[0:3], off sc1
	v_add_u32_e32 v4, s8, v42
	v_mad_i64_i32 v[4:5], s[6:7], v4, s31, v[20:21]
	v_cvt_pk_bf16_f32 v0, v9, v7
	v_cvt_pk_bf16_f32 v1, v11, v13
	v_cvt_pk_bf16_f32 v2, v15, v17
	v_cvt_pk_bf16_f32 v3, v19, v23
	global_store_dwordx4 v[4:5], v[0:3], off sc1
	s_waitcnt lgkmcnt(0)

; __device__ __forceinline__ unsigned pk_bf16(float lo, float hi) { typedef __bf16 b2_t __attribute__((ext_vector_type(2))); f32x2 v = {lo, hi}; b2_t b = __builtin_convertvector(v, b2_t); return __builtin_bit_cast(unsigned, b); }
; #define LAS __attribute__((address_space(3)))
; __device__ __forceinline__ void transpose_tile(const float* W, const float* gain, int K, int N, int k0, int n0, bf16* WT, int drow0, LAS float* scr, int lane) {
;     f32x4 v[8]; float gv[8];
;     const int r0 = lane >> 3, c4 = lane & 7;
; #pragma unroll
;     for (int i = 0; i < 8; ++i) { v[i] = *(const f32x4*)(W + (size_t)(k0 + r0 + 8 * i) * N + n0 + 4 * c4); gv[i] = gain ? gain[k0 + r0 + 8 * i] : 1.0f; }
; #pragma unroll
;     for (int i = 0; i < 8; ++i) { LAS float* d = scr + (r0 + 8 * i) * 33 + 4 * c4; d[0] = v[i][0] * gv[i]; d[1] = v[i][1] * gv[i]; d[2] = v[i][2] * gv[i]; d[3] = v[i][3] * gv[i]; }
;     asm volatile("s_waitcnt lgkmcnt(0)" ::: "memory");
;     const int c = lane & 7;
; #pragma unroll
;     for (int j = 0; j < 4; ++j) { const int n = (lane >> 3) + 8 * j; const LAS float* s = scr + (8 * c) * 33 + n;
;         v4u o; o.x = pk_bf16(s[0 * 33], s[1 * 33]); o.y = pk_bf16(s[2 * 33], s[3 * 33]); o.z = pk_bf16(s[4 * 33], s[5 * 33]); o.w = pk_bf16(s[6 * 33], s[7 * 33]);
;         *(v4u*)(WT + (size_t)(drow0 + n) * K + k0 + 8 * c) = o; }
;     asm volatile("s_waitcnt lgkmcnt(0)" ::: "memory");
; }
; template <bool SWIGLU> __device__ __forceinline__ void transpose_item(const float* W, const float* gain, int K, int N, bf16* WT, LAS float* scr, int item, int lane) {
;     const int nblk = N / 32, kb = item / nblk, nb = item % nblk, n0 = 32 * nb;
;     int drow0 = n0;
;     if (SWIGLU) { const int up = n0 >= FF, f = up ? n0 - FF : n0; drow0 = 256 * (f >> 7) + (up ? 128 : 0) + (f & 127); }
;     transpose_tile(W, gain, K, N, 64 * kb, n0, WT, drow0, scr, lane);
; }
.LBB0_1545:
	s_waitcnt vmcnt(0)
	v_pk_mul_f32 v[0:1], v[0:1], v[88:89] op_sel_hi:[1,0]
	v_add_u32_e32 v33, v35, v89
	ds_write2_b32 v33, v0, v1 offset1:1
	v_pk_mul_f32 v[0:1], v[2:3], v[88:89] op_sel_hi:[1,0]
	ds_write2_b32 v33, v0, v1 offset0:2 offset1:3
	v_pk_mul_f32 v[0:1], v[4:5], v[36:37] op_sel_hi:[1,0]
	v_add_u32_e32 v2, 0x420, v33
	ds_write2_b32 v2, v0, v1 offset1:1
	v_pk_mul_f32 v[0:1], v[6:7], v[36:37] op_sel_hi:[1,0]
	v_add_u32_e32 v2, 0x428, v33
	ds_write2_b32 v2, v0, v1 offset1:1
	v_pk_mul_f32 v[0:1], v[8:9], v[94:95] op_sel_hi:[1,0]
	v_add_u32_e32 v2, 0x840, v33
	ds_write2_b32 v2, v0, v1 offset1:1
	v_pk_mul_f32 v[0:1], v[10:11], v[94:95] op_sel_hi:[1,0]
	v_add_u32_e32 v2, 0x848, v33
	ds_write2_b32 v2, v0, v1 offset1:1
	v_pk_mul_f32 v[0:1], v[12:13], v[90:91] op_sel_hi:[1,0]
	v_add_u32_e32 v2, 0xc60, v33
	ds_write2_b32 v2, v0, v1 offset1:1
	v_pk_mul_f32 v[0:1], v[14:15], v[90:91] op_sel_hi:[1,0]
	v_add_u32_e32 v2, 0xc68, v33
	ds_write2_b32 v2, v0, v1 offset1:1
	v_pk_mul_f32 v[0:1], v[16:17], v[100:101] op_sel_hi:[1,0]
	v_add_u32_e32 v2, 0x1080, v33
	ds_write2_b32 v2, v0, v1 offset1:1
	v_pk_mul_f32 v[0:1], v[18:19], v[100:101] op_sel_hi:[1,0]
	v_add_u32_e32 v2, 0x1088, v33
	ds_write2_b32 v2, v0, v1 offset1:1
	v_pk_mul_f32 v[0:1], v[20:21], v[92:93] op_sel_hi:[1,0]
	v_add_u32_e32 v2, 0x14a0, v33
	ds_write2_b32 v2, v0, v1 offset1:1
	v_pk_mul_f32 v[0:1], v[22:23], v[92:93] op_sel_hi:[1,0]
	v_add_u32_e32 v2, 0x14a8, v33
	ds_write2_b32 v2, v0, v1 offset1:1
	v_pk_mul_f32 v[0:1], v[24:25], v[102:103] op_sel_hi:[1,0]
	v_add_u32_e32 v2, 0x18c0, v33
	s_and_b32 s8, 0xffff, s8
	ds_write2_b32 v2, v0, v1 offset1:1
	v_pk_mul_f32 v[0:1], v[26:27], v[102:103] op_sel_hi:[1,0]
	v_add_u32_e32 v2, 0x18c8, v33
	s_and_b32 s7, 0xffff, s7
	s_add_i32 s9, s8, 0xfffff500
	ds_write2_b32 v2, v0, v1 offset1:1
	v_pk_mul_f32 v[0:1], v[28:29], v[96:97] op_sel_hi:[1,0]
	v_add_u32_e32 v2, 0x1ce0, v33
	s_cmpk_gt_u32 s7, 0x57
	ds_write2_b32 v2, v0, v1 offset1:1
	v_pk_mul_f32 v[0:1], v[30:31], v[96:97] op_sel_hi:[1,0]
	v_add_u32_e32 v2, 0x1ce8, v33
	s_cselect_b32 s7, s9, s8
	ds_write2_b32 v2, v0, v1 offset1:1
	s_cselect_b32 s8, 0x80, 0
	s_lshl_b32 s9, s7, 1
	s_and_b32 s7, s7, 0x60
	s_waitcnt lgkmcnt(0)
	s_and_b32 s9, s9, 0xffffff00
	s_or_b32 s7, s7, s8
	ds_read2_b32 v[4:5], v93 offset0:33 offset1:41
	ds_read2_b32 v[6:7], v93 offset1:8
	ds_read2_b32 v[8:9], v93 offset0:66 offset1:74
	ds_read2_b32 v[10:11], v93 offset0:99 offset1:107
	ds_read2_b32 v[12:13], v93 offset0:132 offset1:140
	ds_read2_b32 v[14:15], v93 offset0:165 offset1:173
	ds_read2_b32 v[16:17], v93 offset0:198 offset1:206
	ds_read2_b32 v[18:19], v93 offset0:231 offset1:239
	s_or_b32 s7, s7, s9
	s_and_b32 s6, 0xffff, s6
	v_add_u32_e32 v22, s7, v32
	s_lshl_b32 s10, s6, 1
	v_ashrrev_i32_e32 v23, 31, v22
	v_lshl_add_u64 v[20:21], v[78:79], 0, s[10:11]
	v_lshlrev_b64 v[22:23], 11, v[22:23]
	s_waitcnt lgkmcnt(6)
	v_cvt_pk_bf16_f32 v0, v6, v4
	s_waitcnt lgkmcnt(4)
	v_cvt_pk_bf16_f32 v1, v8, v10
	s_waitcnt lgkmcnt(2)
	v_cvt_pk_bf16_f32 v2, v12, v14
	s_waitcnt lgkmcnt(0)
	v_cvt_pk_bf16_f32 v3, v16, v18
	v_lshl_add_u64 v[22:23], v[20:21], 0, v[22:23]
	v_add_u32_e32 v4, s7, v38
	global_store_dwordx4 v[22:23], v[0:3], off sc1
	s_nop 1
	v_cvt_pk_bf16_f32 v0, v7, v5
	v_ashrrev_i32_e32 v5, 31, v4
	v_cvt_pk_bf16_f32 v1, v9, v11
	v_cvt_pk_bf16_f32 v2, v13, v15
	v_cvt_pk_bf16_f32 v3, v17, v19
	v_lshlrev_b64 v[4:5], 11, v[4:5]
	ds_read2_b32 v[6:7], v93 offset0:49 offset1:57
	ds_read2_b32 v[8:9], v93 offset0:16 offset1:24
	ds_read2_b32 v[10:11], v93 offset0:82 offset1:90
	ds_read2_b32 v[12:13], v93 offset0:115 offset1:123
	ds_read2_b32 v[14:15], v93 offset0:148 offset1:156
	ds_read2_b32 v[16:17], v93 offset0:181 offset1:189
	ds_read2_b32 v[18:19], v93 offset0:214 offset1:222
	ds_read2_b32 v[22:23], v93 offset0:247 offset1:255
	v_lshl_add_u64 v[4:5], v[20:21], 0, v[4:5]
	global_store_dwordx4 v[4:5], v[0:3], off sc1
	v_add_u32_e32 v4, s7, v40
	v_ashrrev_i32_e32 v5, 31, v4
	v_lshlrev_b64 v[4:5], 11, v[4:5]
	s_waitcnt lgkmcnt(6)
	v_cvt_pk_bf16_f32 v0, v8, v6
	s_waitcnt lgkmcnt(4)
	v_cvt_pk_bf16_f32 v1, v10, v12
	s_waitcnt lgkmcnt(2)
	v_cvt_pk_bf16_f32 v2, v14, v16
	s_waitcnt lgkmcnt(0)
	v_cvt_pk_bf16_f32 v3, v18, v22
	v_lshl_add_u64 v[4:5], v[20:21], 0, v[4:5]
	global_store_dwordx4 v[4:5], v[0:3], off sc1
	v_add_u32_e32 v4, s7, v42
	v_ashrrev_i32_e32 v5, 31, v4
	v_lshlrev_b64 v[4:5], 11, v[4:5]
	v_cvt_pk_bf16_f32 v0, v9, v7
	v_cvt_pk_bf16_f32 v1, v11, v13
	v_cvt_pk_bf16_f32 v2, v15, v17
	v_cvt_pk_bf16_f32 v3, v19, v23
	v_lshl_add_u64 v[4:5], v[20:21], 0, v[4:5]
	global_store_dwordx4 v[4:5], v[0:3], off sc1
	s_waitcnt lgkmcnt(0)

; __device__ __forceinline__ unsigned pk_bf16(float lo, float hi) { typedef __bf16 b2_t __attribute__((ext_vector_type(2))); f32x2 v = {lo, hi}; b2_t b = __builtin_convertvector(v, b2_t); return __builtin_bit_cast(unsigned, b); }
; #define LAS __attribute__((address_space(3)))
; __device__ __forceinline__ void transpose_tile(const float* W, const float* gain, int K, int N, int k0, int n0, bf16* WT, int drow0, LAS float* scr, int lane) {
;     f32x4 v[8]; float gv[8];
;     const int r0 = lane >> 3, c4 = lane & 7;
; #pragma unroll
;     for (int i = 0; i < 8; ++i) { v[i] = *(const f32x4*)(W + (size_t)(k0 + r0 + 8 * i) * N + n0 + 4 * c4); gv[i] = gain ? gain[k0 + r0 + 8 * i] : 1.0f; }
; #pragma unroll
;     for (int i = 0; i < 8; ++i) { LAS float* d = scr + (r0 + 8 * i) * 33 + 4 * c4; d[0] = v[i][0] * gv[i]; d[1] = v[i][1] * gv[i]; d[2] = v[i][2] * gv[i]; d[3] = v[i][3] * gv[i]; }
;     asm volatile("s_waitcnt lgkmcnt(0)" ::: "memory");
;     const int c = lane & 7;
; #pragma unroll
;     for (int j = 0; j < 4; ++j) { const int n = (lane >> 3) + 8 * j; const LAS float* s = scr + (8 * c) * 33 + n;
;         v4u o; o.x = pk_bf16(s[0 * 33], s[1 * 33]); o.y = pk_bf16(s[2 * 33], s[3 * 33]); o.z = pk_bf16(s[4 * 33], s[5 * 33]); o.w = pk_bf16(s[6 * 33], s[7 * 33]);
;         *(v4u*)(WT + (size_t)(drow0 + n) * K + k0 + 8 * c) = o; }
;     asm volatile("s_waitcnt lgkmcnt(0)" ::: "memory");
; }
; template <bool SWIGLU> __device__ __forceinline__ void transpose_item(const float* W, const float* gain, int K, int N, bf16* WT, LAS float* scr, int item, int lane) {
;     const int nblk = N / 32, kb = item / nblk, nb = item % nblk, n0 = 32 * nb;
;     int drow0 = n0;
;     if (SWIGLU) { const int up = n0 >= FF, f = up ? n0 - FF : n0; drow0 = 256 * (f >> 7) + (up ? 128 : 0) + (f & 127); }
;     transpose_tile(W, gain, K, N, 64 * kb, n0, WT, drow0, scr, lane);
; }
.LBB0_1547:
	s_andn2_b64 vcc, exec, s[8:9]
	s_cbranch_vccnz .LBB0_1549
	s_mov_b32 s6, 8
	s_ashr_i32 s7, s6, 31
	s_lshl_b64 s[6:7], s[6:7], 3
	s_add_u32 s6, s0, s6
	s_addc_u32 s7, s1, s7
	s_load_dwordx2 s[6:7], s[6:7], 0x0
	s_lshl_b32 s8, s20, 5
	s_and_b32 s8, s8, 0x3e0
	s_add_i32 s9, s22, 0x6880
	s_and_b32 s9, s9, 0x1ffc0
	s_lshl_b32 s10, s8, 2
	v_add_u32_e32 v0, s9, v32
	s_waitcnt lgkmcnt(0)
	s_add_u32 s6, s6, s10
	s_addc_u32 s7, s7, 0
	v_lshlrev_b32_e32 v36, 2, v34
	v_ashrrev_i32_e32 v1, 31, v0
	v_lshl_add_u64 v[2:3], s[6:7], 0, v[36:37]
	v_lshlrev_b64 v[0:1], 12, v[0:1]
	v_lshl_add_u64 v[28:29], v[2:3], 0, v[0:1]
	v_add_co_u32_e32 v4, vcc, s24, v28
	v_add_u32_e32 v33, v35, v89
	s_nop 0
	v_addc_co_u32_e32 v5, vcc, 0, v29, vcc
	v_add_co_u32_e32 v8, vcc, s25, v28
	global_load_dwordx4 v[0:3], v[28:29], off
	s_nop 0
	global_load_dwordx4 v[4:7], v[4:5], off
	v_addc_co_u32_e32 v9, vcc, 0, v29, vcc
	v_add_co_u32_e32 v12, vcc, s26, v28
	v_add_u32_e32 v36, 0x420, v33
	s_nop 0
	v_addc_co_u32_e32 v13, vcc, 0, v29, vcc
	v_add_co_u32_e32 v16, vcc, s27, v28
	global_load_dwordx4 v[8:11], v[8:9], off
	s_nop 0
	global_load_dwordx4 v[12:15], v[12:13], off
	v_addc_co_u32_e32 v17, vcc, 0, v29, vcc
	v_add_co_u32_e32 v20, vcc, s28, v28
	v_add_u32_e32 v39, 0x428, v33
	s_nop 0
	v_addc_co_u32_e32 v21, vcc, 0, v29, vcc
	global_load_dwordx4 v[16:19], v[16:17], off
	s_nop 0
	global_load_dwordx4 v[20:23], v[20:21], off
	v_add_co_u32_e32 v24, vcc, s29, v28
	v_add_u32_e32 v41, 0x840, v33
	s_nop 0
	v_addc_co_u32_e32 v25, vcc, 0, v29, vcc
	global_load_dwordx4 v[24:27], v[24:25], off
	v_add_co_u32_e32 v28, vcc, s30, v28
	v_add_u32_e32 v43, 0x848, v33
	s_nop 0
	v_addc_co_u32_e32 v29, vcc, 0, v29, vcc
	global_load_dwordx4 v[28:31], v[28:29], off
	v_add_u32_e32 v88, 0xc60, v33
	v_add_u32_e32 v92, 0xc68, v33
	v_add_u32_e32 v94, 0x1080, v33
	v_add_u32_e32 v95, 0x1088, v33
	v_add_u32_e32 v96, 0x14a0, v33
	v_add_u32_e32 v97, 0x14a8, v33
	v_add_u32_e32 v98, 0x18c0, v33
	v_add_u32_e32 v99, 0x18c8, v33
	v_add_u32_e32 v100, 0x1ce0, v33
	v_add_u32_e32 v101, 0x1ce8, v33
	v_add_u32_e32 v90, s8, v32
	v_ashrrev_i32_e32 v91, 31, v90
	s_lshl_b32 s10, s9, 1
	s_waitcnt vmcnt(0)
	ds_write2_b32 v33, v0, v1 offset1:1
	ds_write2_b32 v33, v2, v3 offset0:2 offset1:3
	ds_write2_b32 v36, v4, v5 offset1:1
	ds_write2_b32 v39, v6, v7 offset1:1
	ds_write2_b32 v41, v8, v9 offset1:1
	ds_write2_b32 v43, v10, v11 offset1:1
	ds_write2_b32 v88, v12, v13 offset1:1
	ds_write2_b32 v92, v14, v15 offset1:1
	ds_write2_b32 v94, v16, v17 offset1:1
	ds_write2_b32 v95, v18, v19 offset1:1
	ds_write2_b32 v96, v20, v21 offset1:1
	ds_write2_b32 v97, v22, v23 offset1:1
	ds_write2_b32 v98, v24, v25 offset1:1
	ds_write2_b32 v99, v26, v27 offset1:1
	ds_write2_b32 v100, v28, v29 offset1:1
	ds_write2_b32 v101, v30, v31 offset1:1
	s_waitcnt lgkmcnt(0)
	ds_read2_b32 v[4:5], v93 offset0:33 offset1:41
	ds_read2_b32 v[6:7], v93 offset1:8
	ds_read2_b32 v[8:9], v93 offset0:66 offset1:74
	ds_read2_b32 v[10:11], v93 offset0:99 offset1:107
	ds_read2_b32 v[12:13], v93 offset0:132 offset1:140
	ds_read2_b32 v[14:15], v93 offset0:165 offset1:173
	ds_read2_b32 v[16:17], v93 offset0:198 offset1:206
	ds_read2_b32 v[18:19], v93 offset0:231 offset1:239
	v_lshl_add_u64 v[20:21], v[80:81], 0, s[10:11]
	v_lshlrev_b64 v[22:23], 11, v[90:91]
	s_waitcnt lgkmcnt(6)
	v_cvt_pk_bf16_f32 v0, v6, v4
	s_waitcnt lgkmcnt(4)
	v_cvt_pk_bf16_f32 v1, v8, v10
	s_waitcnt lgkmcnt(2)
	v_cvt_pk_bf16_f32 v2, v12, v14
	s_waitcnt lgkmcnt(0)
	v_cvt_pk_bf16_f32 v3, v16, v18
	v_lshl_add_u64 v[22:23], v[20:21], 0, v[22:23]
	v_add_u32_e32 v4, s8, v38
	global_store_dwordx4 v[22:23], v[0:3], off sc1
	s_nop 1
	v_cvt_pk_bf16_f32 v0, v7, v5
	v_ashrrev_i32_e32 v5, 31, v4
	v_cvt_pk_bf16_f32 v1, v9, v11
	v_cvt_pk_bf16_f32 v2, v13, v15
	v_cvt_pk_bf16_f32 v3, v17, v19
	v_lshlrev_b64 v[4:5], 11, v[4:5]
	ds_read2_b32 v[6:7], v93 offset0:49 offset1:57
	ds_read2_b32 v[8:9], v93 offset0:16 offset1:24
	ds_read2_b32 v[10:11], v93 offset0:82 offset1:90
	ds_read2_b32 v[12:13], v93 offset0:115 offset1:123
	ds_read2_b32 v[14:15], v93 offset0:148 offset1:156
	ds_read2_b32 v[16:17], v93 offset0:181 offset1:189
	ds_read2_b32 v[18:19], v93 offset0:214 offset1:222
	ds_read2_b32 v[22:23], v93 offset0:247 offset1:255
	v_lshl_add_u64 v[4:5], v[20:21], 0, v[4:5]
	global_store_dwordx4 v[4:5], v[0:3], off sc1
	v_add_u32_e32 v4, s8, v40
	v_ashrrev_i32_e32 v5, 31, v4
	v_lshlrev_b64 v[4:5], 11, v[4:5]
	s_waitcnt lgkmcnt(6)
	v_cvt_pk_bf16_f32 v0, v8, v6
	s_waitcnt lgkmcnt(4)
	v_cvt_pk_bf16_f32 v1, v10, v12
	s_waitcnt lgkmcnt(2)
	v_cvt_pk_bf16_f32 v2, v14, v16
	s_waitcnt lgkmcnt(0)
	v_cvt_pk_bf16_f32 v3, v18, v22
	v_lshl_add_u64 v[4:5], v[20:21], 0, v[4:5]
	global_store_dwordx4 v[4:5], v[0:3], off sc1
	v_add_u32_e32 v4, s8, v42
	v_ashrrev_i32_e32 v5, 31, v4
	v_lshlrev_b64 v[4:5], 11, v[4:5]
	v_cvt_pk_bf16_f32 v0, v9, v7
	v_cvt_pk_bf16_f32 v1, v11, v13
	v_cvt_pk_bf16_f32 v2, v15, v17
	v_cvt_pk_bf16_f32 v3, v19, v23
	v_lshl_add_u64 v[4:5], v[20:21], 0, v[4:5]
	global_store_dwordx4 v[4:5], v[0:3], off sc1
	s_waitcnt lgkmcnt(0)

; __device__ __forceinline__ unsigned pk_bf16(float lo, float hi) { typedef __bf16 b2_t __attribute__((ext_vector_type(2))); f32x2 v = {lo, hi}; b2_t b = __builtin_convertvector(v, b2_t); return __builtin_bit_cast(unsigned, b); }
; #define LAS __attribute__((address_space(3)))
; __device__ __forceinline__ void transpose_tile(const float* W, const float* gain, int K, int N, int k0, int n0, bf16* WT, int drow0, LAS float* scr, int lane) {
;     f32x4 v[8]; float gv[8];
;     const int r0 = lane >> 3, c4 = lane & 7;
; #pragma unroll
;     for (int i = 0; i < 8; ++i) { v[i] = *(const f32x4*)(W + (size_t)(k0 + r0 + 8 * i) * N + n0 + 4 * c4); gv[i] = gain ? gain[k0 + r0 + 8 * i] : 1.0f; }
; #pragma unroll
;     for (int i = 0; i < 8; ++i) { LAS float* d = scr + (r0 + 8 * i) * 33 + 4 * c4; d[0] = v[i][0] * gv[i]; d[1] = v[i][1] * gv[i]; d[2] = v[i][2] * gv[i]; d[3] = v[i][3] * gv[i]; }
;     asm volatile("s_waitcnt lgkmcnt(0)" ::: "memory");
;     const int c = lane & 7;
; #pragma unroll
;     for (int j = 0; j < 4; ++j) { const int n = (lane >> 3) + 8 * j; const LAS float* s = scr + (8 * c) * 33 + n;
;         v4u o; o.x = pk_bf16(s[0 * 33], s[1 * 33]); o.y = pk_bf16(s[2 * 33], s[3 * 33]); o.z = pk_bf16(s[4 * 33], s[5 * 33]); o.w = pk_bf16(s[6 * 33], s[7 * 33]);
;         *(v4u*)(WT + (size_t)(drow0 + n) * K + k0 + 8 * c) = o; }
;     asm volatile("s_waitcnt lgkmcnt(0)" ::: "memory");
; }
; template <bool SWIGLU> __device__ __forceinline__ void transpose_item(const float* W, const float* gain, int K, int N, bf16* WT, LAS float* scr, int item, int lane) {
;     const int nblk = N / 32, kb = item / nblk, nb = item % nblk, n0 = 32 * nb;
;     int drow0 = n0;
;     if (SWIGLU) { const int up = n0 >= FF, f = up ? n0 - FF : n0; drow0 = 256 * (f >> 7) + (up ? 128 : 0) + (f & 127); }
;     transpose_tile(W, gain, K, N, 64 * kb, n0, WT, drow0, scr, lane);
; }
.LBB0_1567:
	s_waitcnt vmcnt(0)
	v_pk_mul_f32 v[0:1], v[0:1], v[88:89] op_sel_hi:[1,0]
	v_add_u32_e32 v33, v35, v89
	ds_write2_b32 v33, v0, v1 offset1:1
	v_pk_mul_f32 v[0:1], v[2:3], v[88:89] op_sel_hi:[1,0]
	ds_write2_b32 v33, v0, v1 offset0:2 offset1:3
	v_pk_mul_f32 v[0:1], v[4:5], v[36:37] op_sel_hi:[1,0]
	v_add_u32_e32 v2, 0x420, v33
	ds_write2_b32 v2, v0, v1 offset1:1
	v_pk_mul_f32 v[0:1], v[6:7], v[36:37] op_sel_hi:[1,0]
	v_add_u32_e32 v2, 0x428, v33
	ds_write2_b32 v2, v0, v1 offset1:1
	v_pk_mul_f32 v[0:1], v[8:9], v[96:97] op_sel_hi:[1,0]
	v_add_u32_e32 v2, 0x840, v33
	ds_write2_b32 v2, v0, v1 offset1:1
	v_pk_mul_f32 v[0:1], v[10:11], v[96:97] op_sel_hi:[1,0]
	v_add_u32_e32 v2, 0x848, v33
	ds_write2_b32 v2, v0, v1 offset1:1
	v_pk_mul_f32 v[0:1], v[12:13], v[90:91] op_sel_hi:[1,0]
	v_add_u32_e32 v2, 0xc60, v33
	ds_write2_b32 v2, v0, v1 offset1:1
	v_pk_mul_f32 v[0:1], v[14:15], v[90:91] op_sel_hi:[1,0]
	v_add_u32_e32 v2, 0xc68, v33
	ds_write2_b32 v2, v0, v1 offset1:1
	v_pk_mul_f32 v[0:1], v[16:17], v[100:101] op_sel_hi:[1,0]
	v_add_u32_e32 v2, 0x1080, v33
	ds_write2_b32 v2, v0, v1 offset1:1
	v_pk_mul_f32 v[0:1], v[18:19], v[100:101] op_sel_hi:[1,0]
	v_add_u32_e32 v2, 0x1088, v33
	ds_write2_b32 v2, v0, v1 offset1:1
	v_pk_mul_f32 v[0:1], v[20:21], v[92:93] op_sel_hi:[1,0]
	v_add_u32_e32 v2, 0x14a0, v33
	ds_write2_b32 v2, v0, v1 offset1:1
	v_pk_mul_f32 v[0:1], v[22:23], v[92:93] op_sel_hi:[1,0]
	v_add_u32_e32 v2, 0x14a8, v33
	ds_write2_b32 v2, v0, v1 offset1:1
	v_pk_mul_f32 v[0:1], v[24:25], v[102:103] op_sel_hi:[1,0]
	v_add_u32_e32 v2, 0x18c0, v33
	ds_write2_b32 v2, v0, v1 offset1:1
	v_pk_mul_f32 v[0:1], v[26:27], v[102:103] op_sel_hi:[1,0]
	v_add_u32_e32 v2, 0x18c8, v33
	ds_write2_b32 v2, v0, v1 offset1:1
	v_pk_mul_f32 v[0:1], v[28:29], v[98:99] op_sel_hi:[1,0]
	v_add_u32_e32 v2, 0x1ce0, v33
	ds_write2_b32 v2, v0, v1 offset1:1
	v_pk_mul_f32 v[0:1], v[30:31], v[98:99] op_sel_hi:[1,0]
	v_add_u32_e32 v2, 0x1ce8, v33
	ds_write2_b32 v2, v0, v1 offset1:1
	s_waitcnt lgkmcnt(0)
	s_lshl_b32 s7, s7, 5
	ds_read2_b32 v[4:5], v93 offset0:33 offset1:41
	ds_read2_b32 v[6:7], v93 offset1:8
	ds_read2_b32 v[8:9], v93 offset0:66 offset1:74
	ds_read2_b32 v[10:11], v93 offset0:99 offset1:107
	ds_read2_b32 v[12:13], v93 offset0:132 offset1:140
	ds_read2_b32 v[14:15], v93 offset0:165 offset1:173
	ds_read2_b32 v[16:17], v93 offset0:198 offset1:206
	ds_read2_b32 v[18:19], v93 offset0:231 offset1:239
	s_and_b32 s7, 0xffff, s7
	s_and_b32 s6, 0xffff, s6
	v_add_u32_e32 v22, s7, v32
	s_lshl_b32 s10, s6, 1
	v_ashrrev_i32_e32 v23, 31, v22
	v_lshl_add_u64 v[20:21], v[82:83], 0, s[10:11]
	v_lshlrev_b64 v[22:23], 11, v[22:23]
	s_waitcnt lgkmcnt(6)
	v_cvt_pk_bf16_f32 v0, v6, v4
	s_waitcnt lgkmcnt(4)
	v_cvt_pk_bf16_f32 v1, v8, v10
	s_waitcnt lgkmcnt(2)
	v_cvt_pk_bf16_f32 v2, v12, v14
	s_waitcnt lgkmcnt(0)
	v_cvt_pk_bf16_f32 v3, v16, v18
	v_lshl_add_u64 v[22:23], v[20:21], 0, v[22:23]
	v_add_u32_e32 v4, s7, v38
	global_store_dwordx4 v[22:23], v[0:3], off sc1
	s_nop 1
	v_cvt_pk_bf16_f32 v0, v7, v5
	v_ashrrev_i32_e32 v5, 31, v4
	v_cvt_pk_bf16_f32 v1, v9, v11
	v_cvt_pk_bf16_f32 v2, v13, v15
	v_cvt_pk_bf16_f32 v3, v17, v19
	v_lshlrev_b64 v[4:5], 11, v[4:5]
	ds_read2_b32 v[6:7], v93 offset0:49 offset1:57
	ds_read2_b32 v[8:9], v93 offset0:16 offset1:24
	ds_read2_b32 v[10:11], v93 offset0:82 offset1:90
	ds_read2_b32 v[12:13], v93 offset0:115 offset1:123
	ds_read2_b32 v[14:15], v93 offset0:148 offset1:156
	ds_read2_b32 v[16:17], v93 offset0:181 offset1:189
	ds_read2_b32 v[18:19], v93 offset0:214 offset1:222
	ds_read2_b32 v[22:23], v93 offset0:247 offset1:255
	v_lshl_add_u64 v[4:5], v[20:21], 0, v[4:5]
	global_store_dwordx4 v[4:5], v[0:3], off sc1
	v_add_u32_e32 v4, s7, v40
	v_ashrrev_i32_e32 v5, 31, v4
	v_lshlrev_b64 v[4:5], 11, v[4:5]
	s_waitcnt lgkmcnt(6)
	v_cvt_pk_bf16_f32 v0, v8, v6
	s_waitcnt lgkmcnt(4)
	v_cvt_pk_bf16_f32 v1, v10, v12
	s_waitcnt lgkmcnt(2)
	v_cvt_pk_bf16_f32 v2, v14, v16
	s_waitcnt lgkmcnt(0)
	v_cvt_pk_bf16_f32 v3, v18, v22
	v_lshl_add_u64 v[4:5], v[20:21], 0, v[4:5]
	global_store_dwordx4 v[4:5], v[0:3], off sc1
	v_add_u32_e32 v4, s7, v42
	v_ashrrev_i32_e32 v5, 31, v4
	v_lshlrev_b64 v[4:5], 11, v[4:5]
	v_cvt_pk_bf16_f32 v0, v9, v7
	v_cvt_pk_bf16_f32 v1, v11, v13
	v_cvt_pk_bf16_f32 v2, v15, v17
	v_cvt_pk_bf16_f32 v3, v19, v23
	v_lshl_add_u64 v[4:5], v[20:21], 0, v[4:5]
	global_store_dwordx4 v[4:5], v[0:3], off sc1
	s_waitcnt lgkmcnt(0)

; __device__ __forceinline__ unsigned pk_bf16(float lo, float hi) { typedef __bf16 b2_t __attribute__((ext_vector_type(2))); f32x2 v = {lo, hi}; b2_t b = __builtin_convertvector(v, b2_t); return __builtin_bit_cast(unsigned, b); }
; #define LAS __attribute__((address_space(3)))
; __device__ __forceinline__ void transpose_tile(const float* W, const float* gain, int K, int N, int k0, int n0, bf16* WT, int drow0, LAS float* scr, int lane) {
;     f32x4 v[8]; float gv[8];
;     const int r0 = lane >> 3, c4 = lane & 7;
; #pragma unroll
;     for (int i = 0; i < 8; ++i) { v[i] = *(const f32x4*)(W + (size_t)(k0 + r0 + 8 * i) * N + n0 + 4 * c4); gv[i] = gain ? gain[k0 + r0 + 8 * i] : 1.0f; }
; #pragma unroll
;     for (int i = 0; i < 8; ++i) { LAS float* d = scr + (r0 + 8 * i) * 33 + 4 * c4; d[0] = v[i][0] * gv[i]; d[1] = v[i][1] * gv[i]; d[2] = v[i][2] * gv[i]; d[3] = v[i][3] * gv[i]; }
;     asm volatile("s_waitcnt lgkmcnt(0)" ::: "memory");
;     const int c = lane & 7;
; #pragma unroll
;     for (int j = 0; j < 4; ++j) { const int n = (lane >> 3) + 8 * j; const LAS float* s = scr + (8 * c) * 33 + n;
;         v4u o; o.x = pk_bf16(s[0 * 33], s[1 * 33]); o.y = pk_bf16(s[2 * 33], s[3 * 33]); o.z = pk_bf16(s[4 * 33], s[5 * 33]); o.w = pk_bf16(s[6 * 33], s[7 * 33]);
;         *(v4u*)(WT + (size_t)(drow0 + n) * K + k0 + 8 * c) = o; }
;     asm volatile("s_waitcnt lgkmcnt(0)" ::: "memory");
; }
; template <bool SWIGLU> __device__ __forceinline__ void transpose_item(const float* W, const float* gain, int K, int N, bf16* WT, LAS float* scr, int item, int lane) {
;     const int nblk = N / 32, kb = item / nblk, nb = item % nblk, n0 = 32 * nb;
;     int drow0 = n0;
;     if (SWIGLU) { const int up = n0 >= FF, f = up ? n0 - FF : n0; drow0 = 256 * (f >> 7) + (up ? 128 : 0) + (f & 127); }
;     transpose_tile(W, gain, K, N, 64 * kb, n0, WT, drow0, scr, lane);
; }
.LBB0_1569:
	s_andn2_b64 vcc, exec, s[8:9]
	s_cbranch_vccnz .LBB0_1571
	s_mov_b32 s6, 3
	s_ashr_i32 s7, s6, 31
	s_lshl_b64 s[6:7], s[6:7], 3
	s_add_u32 s6, s0, s6
	s_addc_u32 s7, s1, s7
	s_load_dwordx2 s[6:7], s[6:7], 0x0
	s_lshl_b32 s8, s20, 5
	s_and_b32 s8, s8, 0x3e0
	s_add_i32 s9, s22, 0x7f80
	s_and_b32 s9, s9, 0x1ffc0
	s_lshl_b32 s10, s8, 2
	v_add_u32_e32 v0, s9, v32
	s_waitcnt lgkmcnt(0)
	s_add_u32 s6, s6, s10
	s_addc_u32 s7, s7, 0
	v_lshlrev_b32_e32 v36, 2, v34
	v_ashrrev_i32_e32 v1, 31, v0
	v_lshl_add_u64 v[2:3], s[6:7], 0, v[36:37]
	v_lshlrev_b64 v[0:1], 12, v[0:1]
	v_lshl_add_u64 v[28:29], v[2:3], 0, v[0:1]
	v_add_co_u32_e32 v4, vcc, s24, v28
	v_add_u32_e32 v33, v35, v89
	s_nop 0
	v_addc_co_u32_e32 v5, vcc, 0, v29, vcc
	v_add_co_u32_e32 v8, vcc, s25, v28
	global_load_dwordx4 v[0:3], v[28:29], off
	s_nop 0
	global_load_dwordx4 v[4:7], v[4:5], off
	v_addc_co_u32_e32 v9, vcc, 0, v29, vcc
	v_add_co_u32_e32 v12, vcc, s26, v28
	v_add_u32_e32 v36, 0x420, v33
	s_nop 0
	v_addc_co_u32_e32 v13, vcc, 0, v29, vcc
	v_add_co_u32_e32 v16, vcc, s27, v28
	global_load_dwordx4 v[8:11], v[8:9], off
	s_nop 0
	global_load_dwordx4 v[12:15], v[12:13], off
	v_addc_co_u32_e32 v17, vcc, 0, v29, vcc
	v_add_co_u32_e32 v20, vcc, s28, v28
	v_add_u32_e32 v39, 0x428, v33
	s_nop 0
	v_addc_co_u32_e32 v21, vcc, 0, v29, vcc
	global_load_dwordx4 v[16:19], v[16:17], off
	s_nop 0
	global_load_dwordx4 v[20:23], v[20:21], off
	v_add_co_u32_e32 v24, vcc, s29, v28
	v_add_u32_e32 v41, 0x840, v33
	s_nop 0
	v_addc_co_u32_e32 v25, vcc, 0, v29, vcc
	global_load_dwordx4 v[24:27], v[24:25], off
	v_add_co_u32_e32 v28, vcc, s30, v28
	v_add_u32_e32 v43, 0x848, v33
	s_nop 0
	v_addc_co_u32_e32 v29, vcc, 0, v29, vcc
	global_load_dwordx4 v[28:31], v[28:29], off
	v_add_u32_e32 v88, 0xc60, v33
	v_add_u32_e32 v90, 0xc68, v33
	v_add_u32_e32 v91, 0x1080, v33
	v_add_u32_e32 v92, 0x1088, v33
	v_add_u32_e32 v94, 0x14a0, v33
	v_add_u32_e32 v95, 0x14a8, v33
	v_add_u32_e32 v96, 0x18c0, v33
	v_add_u32_e32 v97, 0x18c8, v33
	v_add_u32_e32 v98, 0x1ce0, v33
	v_add_u32_e32 v99, 0x1ce8, v33
	s_lshl_b32 s10, s9, 1
	v_add_u32_e32 v100, s8, v32
	s_waitcnt vmcnt(0)
	ds_write2_b32 v33, v0, v1 offset1:1
	ds_write2_b32 v33, v2, v3 offset0:2 offset1:3
	ds_write2_b32 v36, v4, v5 offset1:1
	ds_write2_b32 v39, v6, v7 offset1:1
	ds_write2_b32 v41, v8, v9 offset1:1
	ds_write2_b32 v43, v10, v11 offset1:1
	ds_write2_b32 v88, v12, v13 offset1:1
	ds_write2_b32 v90, v14, v15 offset1:1
	ds_write2_b32 v91, v16, v17 offset1:1
	ds_write2_b32 v92, v18, v19 offset1:1
	ds_write2_b32 v94, v20, v21 offset1:1
	ds_write2_b32 v95, v22, v23 offset1:1
	ds_write2_b32 v96, v24, v25 offset1:1
	ds_write2_b32 v97, v26, v27 offset1:1
	ds_write2_b32 v98, v28, v29 offset1:1
	ds_write2_b32 v99, v30, v31 offset1:1
	s_waitcnt lgkmcnt(0)
	ds_read2_b32 v[4:5], v93 offset0:33 offset1:41
	ds_read2_b32 v[6:7], v93 offset1:8
	ds_read2_b32 v[8:9], v93 offset0:66 offset1:74
	ds_read2_b32 v[10:11], v93 offset0:99 offset1:107
	ds_read2_b32 v[12:13], v93 offset0:132 offset1:140
	ds_read2_b32 v[14:15], v93 offset0:165 offset1:173
	ds_read2_b32 v[16:17], v93 offset0:198 offset1:206
	ds_read2_b32 v[18:19], v93 offset0:231 offset1:239
	v_lshl_add_u64 v[20:21], v[84:85], 0, s[10:11]
	s_waitcnt lgkmcnt(6)
	v_cvt_pk_bf16_f32 v0, v6, v4
	s_waitcnt lgkmcnt(4)
	v_cvt_pk_bf16_f32 v1, v8, v10
	s_waitcnt lgkmcnt(2)
	v_cvt_pk_bf16_f32 v2, v12, v14
	s_waitcnt lgkmcnt(0)
	v_cvt_pk_bf16_f32 v3, v16, v18
	v_mad_i64_i32 v[22:23], s[6:7], v100, s31, v[20:21]
	global_store_dwordx4 v[22:23], v[0:3], off sc1
	v_add_u32_e32 v4, s8, v38
	s_nop 0
	v_cvt_pk_bf16_f32 v0, v7, v5
	v_cvt_pk_bf16_f32 v1, v9, v11
	v_cvt_pk_bf16_f32 v2, v13, v15
	v_cvt_pk_bf16_f32 v3, v17, v19
	ds_read2_b32 v[6:7], v93 offset0:49 offset1:57
	ds_read2_b32 v[8:9], v93 offset0:16 offset1:24
	ds_read2_b32 v[10:11], v93 offset0:82 offset1:90
	ds_read2_b32 v[12:13], v93 offset0:115 offset1:123
	ds_read2_b32 v[14:15], v93 offset0:148 offset1:156
	ds_read2_b32 v[16:17], v93 offset0:181 offset1:189
	ds_read2_b32 v[18:19], v93 offset0:214 offset1:222
	ds_read2_b32 v[22:23], v93 offset0:247 offset1:255
	v_mad_i64_i32 v[4:5], s[6:7], v4, s31, v[20:21]
	global_store_dwordx4 v[4:5], v[0:3], off sc1
	v_add_u32_e32 v4, s8, v40
	v_mad_i64_i32 v[4:5], s[6:7], v4, s31, v[20:21]
	s_waitcnt lgkmcnt(6)
	v_cvt_pk_bf16_f32 v0, v8, v6
	s_waitcnt lgkmcnt(4)
	v_cvt_pk_bf16_f32 v1, v10, v12
	s_waitcnt lgkmcnt(2)
	v_cvt_pk_bf16_f32 v2, v14, v16
	s_waitcnt lgkmcnt(0)
	v_cvt_pk_bf16_f32 v3, v18, v22
	global_store_dwordx4 v[4:5], v[0:3], off sc1
	v_add_u32_e32 v4, s8, v42
	v_mad_i64_i32 v[4:5], s[6:7], v4, s31, v[20:21]
	v_cvt_pk_bf16_f32 v0, v9, v7
	v_cvt_pk_bf16_f32 v1, v11, v13
	v_cvt_pk_bf16_f32 v2, v15, v17
	v_cvt_pk_bf16_f32 v3, v19, v23
	global_store_dwordx4 v[4:5], v[0:3], off sc1
	s_waitcnt lgkmcnt(0)
